# v055 plus fused residual epilogues: per-row sums across column lanes via v_permlane16_swap / v_permlane32_swap instead of ds_bpermute round trips (224 sites)
# speedup vs baseline: 1.0012x; 1.0012x over previous
;     __device__ __forceinline__ void fused(f32x4 (&acc)[2][2][4][2], const pg8::Unit& u, int wr, int wc, int fr, int fq, PG8_LAS unsigned char* lds, int wid, int lane) const {
;     ...
; #pragma unroll
;         for (int ai = 0; ai < 2; ++ai)
; #pragma unroll
;             for (int m = 0; m < 4; ++m) {
;                 float s = 0.f;
; #pragma unroll
;                 for (int bj = 0; bj < 2; ++bj)
; #pragma unroll
;                     for (int n = 0; n < 2; ++n) { const f32x4 x = acc[ai][bj][m][n]; s += (x[0] * x[0] + x[1] * x[1]) + (x[2] * x[2] + x[3] * x[3]); }
;                 s += __shfl_xor(s, 16); s += __shfl_xor(s, 32);
;                 if (fq == 0) red[(ai * 128 + wr * 64 + m * 16 + fr) * 4 + wc] = s;
;             }
.LBB0_888:
	v_mbcnt_lo_u32_b32 v96, -1, 0
	v_mbcnt_hi_u32_b32 v96, -1, v96
	v_and_b32_e32 v98, 64, v96
	v_xor_b32_e32 v97, 16, v96
	v_add_u32_e32 v98, 64, v98
	v_cmp_lt_i32_e32 vcc, v97, v98
	v_mul_f32_e32 v99, v143, v143
	v_fmac_f32_e32 v99, v142, v142
	v_cndmask_b32_e32 v97, v96, v97, vcc
	v_lshlrev_b32_e32 v145, 2, v97
	v_mul_f32_e32 v97, v141, v141
	v_fmac_f32_e32 v97, v140, v140
	v_add_f32_e32 v97, v97, v99
	v_mul_f32_e32 v99, v137, v137
	v_mul_f32_e32 v100, v139, v139
	v_fmac_f32_e32 v99, v136, v136
	v_fmac_f32_e32 v100, v138, v138
	v_add_f32_e32 v99, v99, v100
	v_add_f32_e32 v97, v97, v99
	v_mul_f32_e32 v99, v133, v133
	v_mul_f32_e32 v100, v135, v135
	v_fmac_f32_e32 v99, v132, v132
	v_fmac_f32_e32 v100, v134, v134
	v_add_f32_e32 v99, v99, v100
	v_add_f32_e32 v97, v97, v99
	v_mul_f32_e32 v99, v129, v129
	v_mul_f32_e32 v100, v131, v131
	v_fmac_f32_e32 v99, v128, v128
	v_fmac_f32_e32 v100, v130, v130
	v_add_f32_e32 v99, v99, v100
	v_add_f32_e32 v97, v97, v99
	v_mov_b32_e32 v99, v97
	s_nop 1
	v_permlane16_swap_b32 v99, v97
	s_nop 0
	v_xor_b32_e32 v100, 32, v96
	v_cmp_lt_i32_e32 vcc, v100, v98
	s_lshl_b32 s0, s41, 2
	v_cmp_gt_u32_e64 s[4:5], 16, v192
	v_cndmask_b32_e32 v96, v96, v100, vcc
	v_lshlrev_b32_e32 v147, 2, v96
	s_waitcnt lgkmcnt(0)
	v_add_f32_e32 v96, v97, v99
	v_mov_b32_e32 v97, v96
	s_nop 1
	v_permlane32_swap_b32 v97, v96
	s_nop 0
	s_add_i32 s22, s0, 0
	s_barrier
	s_and_saveexec_b64 s[0:1], s[4:5]
	v_readlane_b32 s44, v251, 15
	v_readlane_b32 s45, v251, 16
	v_readlane_b32 s46, v251, 17
	v_readlane_b32 s47, v251, 18
	s_cbranch_execz .LBB0_890
	s_lshl_b32 s3, s2, 10
	s_add_i32 s3, s22, s3
	s_waitcnt lgkmcnt(0)
	v_add_f32_e32 v96, v96, v97
	v_lshl_add_u32 v97, v161, 4, s3
	ds_write_b32 v97, v96
.LBB0_890:
	s_or_b64 exec, exec, s[0:1]
	v_mul_f32_e32 v96, v125, v125
	s_waitcnt lgkmcnt(0)
	v_mul_f32_e32 v97, v127, v127
	v_fmac_f32_e32 v96, v124, v124
	v_fmac_f32_e32 v97, v126, v126
	v_add_f32_e32 v96, v96, v97
	v_mul_f32_e32 v97, v121, v121
	v_mul_f32_e32 v98, v123, v123
	v_fmac_f32_e32 v97, v120, v120
	v_fmac_f32_e32 v98, v122, v122
	v_add_f32_e32 v97, v97, v98
	v_add_f32_e32 v96, v96, v97
	v_mul_f32_e32 v97, v117, v117
	v_mul_f32_e32 v98, v119, v119
	v_fmac_f32_e32 v97, v116, v116
	v_fmac_f32_e32 v98, v118, v118
	v_add_f32_e32 v97, v97, v98
	v_add_f32_e32 v96, v96, v97
	v_mul_f32_e32 v97, v113, v113
	v_mul_f32_e32 v98, v115, v115
	v_fmac_f32_e32 v97, v112, v112
	v_fmac_f32_e32 v98, v114, v114
	v_add_f32_e32 v97, v97, v98
	v_add_f32_e32 v96, v96, v97
	v_mov_b32_e32 v97, v96
	s_nop 1
	v_permlane16_swap_b32 v97, v96
	s_nop 0
	s_waitcnt lgkmcnt(0)
	v_add_f32_e32 v96, v96, v97
	v_mov_b32_e32 v97, v96
	s_nop 1
	v_permlane32_swap_b32 v97, v96
	s_nop 0
	s_and_saveexec_b64 s[0:1], s[4:5]
	s_cbranch_execz .LBB0_892
	s_lshl_b32 s3, s2, 10
	s_add_i32 s3, s22, s3
	s_waitcnt lgkmcnt(0)
	v_add_f32_e32 v96, v96, v97
	v_lshl_add_u32 v97, v161, 4, s3
	ds_write_b32 v97, v96 offset:256
.LBB0_892:
	s_or_b64 exec, exec, s[0:1]
	v_mul_f32_e32 v96, v93, v93
	s_waitcnt lgkmcnt(0)
	v_mul_f32_e32 v97, v95, v95
	v_fmac_f32_e32 v96, v92, v92
	v_fmac_f32_e32 v97, v94, v94
	v_add_f32_e32 v96, v96, v97
	v_mul_f32_e32 v97, v89, v89
	v_mul_f32_e32 v98, v91, v91
	v_fmac_f32_e32 v97, v88, v88
	v_fmac_f32_e32 v98, v90, v90
	v_add_f32_e32 v97, v97, v98
	v_add_f32_e32 v96, v96, v97
	v_mul_f32_e32 v97, v85, v85
	v_mul_f32_e32 v98, v87, v87
	v_fmac_f32_e32 v97, v84, v84
	v_fmac_f32_e32 v98, v86, v86
	v_add_f32_e32 v97, v97, v98
	v_add_f32_e32 v96, v96, v97
	v_mul_f32_e32 v97, v81, v81
	v_mul_f32_e32 v98, v83, v83
	v_fmac_f32_e32 v97, v80, v80
	v_fmac_f32_e32 v98, v82, v82
	v_add_f32_e32 v97, v97, v98
	v_add_f32_e32 v96, v96, v97
	v_mov_b32_e32 v97, v96
	s_nop 1
	v_permlane16_swap_b32 v97, v96
	s_nop 0
	s_waitcnt lgkmcnt(0)
	v_add_f32_e32 v96, v96, v97
	v_mov_b32_e32 v97, v96
	s_nop 1
	v_permlane32_swap_b32 v97, v96
	s_nop 0
	s_and_saveexec_b64 s[0:1], s[4:5]
	s_cbranch_execz .LBB0_894
	s_lshl_b32 s3, s2, 10
	s_add_i32 s3, s22, s3
	s_waitcnt lgkmcnt(0)
	v_add_f32_e32 v96, v96, v97
	v_lshl_add_u32 v97, v161, 4, s3
	ds_write_b32 v97, v96 offset:512
.LBB0_894:
	s_or_b64 exec, exec, s[0:1]
	v_mul_f32_e32 v96, v77, v77
	s_waitcnt lgkmcnt(0)
	v_mul_f32_e32 v97, v79, v79
	v_fmac_f32_e32 v96, v76, v76
	v_fmac_f32_e32 v97, v78, v78
	v_add_f32_e32 v96, v96, v97
	v_mul_f32_e32 v97, v73, v73
	v_mul_f32_e32 v98, v75, v75
	v_fmac_f32_e32 v97, v72, v72
	v_fmac_f32_e32 v98, v74, v74
	v_add_f32_e32 v97, v97, v98
	v_add_f32_e32 v96, v96, v97
	v_mul_f32_e32 v97, v69, v69
	v_mul_f32_e32 v98, v71, v71
	v_fmac_f32_e32 v97, v68, v68
	v_fmac_f32_e32 v98, v70, v70
	v_add_f32_e32 v97, v97, v98
	v_add_f32_e32 v96, v96, v97
	v_mul_f32_e32 v97, v65, v65
	v_mul_f32_e32 v98, v67, v67
	v_fmac_f32_e32 v97, v64, v64
	v_fmac_f32_e32 v98, v66, v66
	v_add_f32_e32 v97, v97, v98
	v_add_f32_e32 v96, v96, v97
	v_mov_b32_e32 v97, v96
	s_nop 1
	v_permlane16_swap_b32 v97, v96
	s_nop 0
	s_waitcnt lgkmcnt(0)
	v_add_f32_e32 v96, v96, v97
	v_mov_b32_e32 v97, v96
	s_nop 1
	v_permlane32_swap_b32 v97, v96
	s_nop 0
	s_and_saveexec_b64 s[0:1], s[4:5]
	s_cbranch_execz .LBB0_896
	s_lshl_b32 s3, s2, 10
	s_add_i32 s3, s22, s3
	s_waitcnt lgkmcnt(0)
	v_add_f32_e32 v96, v96, v97
	v_lshl_add_u32 v97, v161, 4, s3
	ds_write_b32 v97, v96 offset:768
;     __device__ __forceinline__ void fused(f32x4 (&acc)[2][2][4][2], const pg8::Unit& u, int wr, int wc, int fr, int fq, PG8_LAS unsigned char* lds, int wid, int lane) const {
;     ...
; #pragma unroll
;         for (int ai = 0; ai < 2; ++ai)
; #pragma unroll
;             for (int m = 0; m < 4; ++m) {
;                 float s = 0.f;
; #pragma unroll
;                 for (int bj = 0; bj < 2; ++bj)
; #pragma unroll
;                     for (int n = 0; n < 2; ++n) { const f32x4 x = acc[ai][bj][m][n]; s += (x[0] * x[0] + x[1] * x[1]) + (x[2] * x[2] + x[3] * x[3]); }
;                 s += __shfl_xor(s, 16); s += __shfl_xor(s, 32);
;                 if (fq == 0) red[(ai * 128 + wr * 64 + m * 16 + fr) * 4 + wc] = s;
;             }
.LBB0_896:
	s_or_b64 exec, exec, s[0:1]
	v_mul_f32_e32 v96, v61, v61
	s_waitcnt lgkmcnt(0)
	v_mul_f32_e32 v97, v63, v63
	v_fmac_f32_e32 v96, v60, v60
	v_fmac_f32_e32 v97, v62, v62
	v_add_f32_e32 v96, v96, v97
	v_mul_f32_e32 v97, v57, v57
	v_mul_f32_e32 v98, v59, v59
	v_fmac_f32_e32 v97, v56, v56
	v_fmac_f32_e32 v98, v58, v58
	v_add_f32_e32 v97, v97, v98
	v_add_f32_e32 v96, v96, v97
	v_mul_f32_e32 v97, v53, v53
	v_mul_f32_e32 v98, v55, v55
	v_fmac_f32_e32 v97, v52, v52
	v_fmac_f32_e32 v98, v54, v54
	v_add_f32_e32 v97, v97, v98
	v_add_f32_e32 v96, v96, v97
	v_mul_f32_e32 v97, v49, v49
	v_mul_f32_e32 v98, v51, v51
	v_fmac_f32_e32 v97, v48, v48
	v_fmac_f32_e32 v98, v50, v50
	v_add_f32_e32 v97, v97, v98
	v_add_f32_e32 v96, v96, v97
	v_mov_b32_e32 v97, v96
	s_nop 1
	v_permlane16_swap_b32 v97, v96
	s_nop 0
	s_waitcnt lgkmcnt(0)
	v_add_f32_e32 v96, v96, v97
	v_mov_b32_e32 v97, v96
	s_nop 1
	v_permlane32_swap_b32 v97, v96
	s_nop 0
	s_and_saveexec_b64 s[0:1], s[4:5]
	s_cbranch_execz .LBB0_898
	s_lshl_b32 s3, s2, 10
	s_add_i32 s3, s22, s3
	s_waitcnt lgkmcnt(0)
	v_add_f32_e32 v96, v96, v97
	v_lshl_add_u32 v97, v161, 4, s3
	ds_write_b32 v97, v96 offset:2048
.LBB0_898:
	s_or_b64 exec, exec, s[0:1]
	v_mul_f32_e32 v96, v45, v45
	s_waitcnt lgkmcnt(0)
	v_mul_f32_e32 v97, v47, v47
	v_fmac_f32_e32 v96, v44, v44
	v_fmac_f32_e32 v97, v46, v46
	v_add_f32_e32 v96, v96, v97
	v_mul_f32_e32 v97, v41, v41
	v_mul_f32_e32 v98, v43, v43
	v_fmac_f32_e32 v97, v40, v40
	v_fmac_f32_e32 v98, v42, v42
	v_add_f32_e32 v97, v97, v98
	v_add_f32_e32 v96, v96, v97
	v_mul_f32_e32 v97, v37, v37
	v_mul_f32_e32 v98, v39, v39
	v_fmac_f32_e32 v97, v36, v36
	v_fmac_f32_e32 v98, v38, v38
	v_add_f32_e32 v97, v97, v98
	v_add_f32_e32 v96, v96, v97
	v_mul_f32_e32 v97, v33, v33
	v_mul_f32_e32 v98, v35, v35
	v_fmac_f32_e32 v97, v32, v32
	v_fmac_f32_e32 v98, v34, v34
	v_add_f32_e32 v97, v97, v98
	v_add_f32_e32 v96, v96, v97
	v_mov_b32_e32 v97, v96
	s_nop 1
	v_permlane16_swap_b32 v97, v96
	s_nop 0
	s_waitcnt lgkmcnt(0)
	v_add_f32_e32 v96, v96, v97
	v_mov_b32_e32 v97, v96
	s_nop 1
	v_permlane32_swap_b32 v97, v96
	s_nop 0
	s_and_saveexec_b64 s[0:1], s[4:5]
	s_cbranch_execz .LBB0_900
	s_lshl_b32 s3, s2, 10
	s_add_i32 s3, s22, s3
	s_waitcnt lgkmcnt(0)
	v_add_f32_e32 v96, v96, v97
	v_lshl_add_u32 v97, v161, 4, s3
	ds_write_b32 v97, v96 offset:2304
.LBB0_900:
	s_or_b64 exec, exec, s[0:1]
	v_mul_f32_e32 v96, v29, v29
	s_waitcnt lgkmcnt(0)
	v_mul_f32_e32 v97, v31, v31
	v_fmac_f32_e32 v96, v28, v28
	v_fmac_f32_e32 v97, v30, v30
	v_add_f32_e32 v96, v96, v97
	v_mul_f32_e32 v97, v25, v25
	v_mul_f32_e32 v98, v27, v27
	v_fmac_f32_e32 v97, v24, v24
	v_fmac_f32_e32 v98, v26, v26
	v_add_f32_e32 v97, v97, v98
	v_add_f32_e32 v96, v96, v97
	v_mul_f32_e32 v97, v21, v21
	v_mul_f32_e32 v98, v23, v23
	v_fmac_f32_e32 v97, v20, v20
	v_fmac_f32_e32 v98, v22, v22
	v_add_f32_e32 v97, v97, v98
	v_add_f32_e32 v96, v96, v97
	v_mul_f32_e32 v97, v17, v17
	v_mul_f32_e32 v98, v19, v19
	v_fmac_f32_e32 v97, v16, v16
	v_fmac_f32_e32 v98, v18, v18
	v_add_f32_e32 v97, v97, v98
	v_add_f32_e32 v96, v96, v97
	v_mov_b32_e32 v97, v96
	s_nop 1
	v_permlane16_swap_b32 v97, v96
	s_nop 0
	s_waitcnt lgkmcnt(0)
	v_add_f32_e32 v96, v96, v97
	v_mov_b32_e32 v97, v96
	s_nop 1
	v_permlane32_swap_b32 v97, v96
	s_nop 0
	s_and_saveexec_b64 s[0:1], s[4:5]
	s_cbranch_execz .LBB0_902
	s_lshl_b32 s3, s2, 10
	s_add_i32 s3, s22, s3
	s_waitcnt lgkmcnt(0)
	v_add_f32_e32 v96, v96, v97
	v_lshl_add_u32 v97, v161, 4, s3
	ds_write_b32 v97, v96 offset:2560
.LBB0_902:
	s_or_b64 exec, exec, s[0:1]
	v_mul_f32_e32 v96, v13, v13
	s_waitcnt lgkmcnt(0)
	v_mul_f32_e32 v97, v15, v15
	v_fmac_f32_e32 v96, v12, v12
	v_fmac_f32_e32 v97, v14, v14
	v_add_f32_e32 v96, v96, v97
	v_mul_f32_e32 v97, v9, v9
	v_mul_f32_e32 v98, v11, v11
	v_fmac_f32_e32 v97, v8, v8
	v_fmac_f32_e32 v98, v10, v10
	v_add_f32_e32 v97, v97, v98
	v_add_f32_e32 v96, v96, v97
	v_mul_f32_e32 v97, v5, v5
	v_mul_f32_e32 v98, v7, v7
	v_fmac_f32_e32 v97, v4, v4
	v_fmac_f32_e32 v98, v6, v6
	v_add_f32_e32 v97, v97, v98
	v_add_f32_e32 v96, v96, v97
	v_mul_f32_e32 v97, v1, v1
	v_mul_f32_e32 v98, v3, v3
	v_fmac_f32_e32 v97, v0, v0
	v_fmac_f32_e32 v98, v2, v2
	v_add_f32_e32 v97, v97, v98
	v_add_f32_e32 v96, v96, v97
	v_mov_b32_e32 v97, v96
	s_nop 1
	v_permlane16_swap_b32 v97, v96
	s_nop 0
	s_waitcnt lgkmcnt(0)
	v_add_f32_e32 v96, v96, v97
	v_mov_b32_e32 v97, v96
	s_nop 1
	v_permlane32_swap_b32 v97, v96
	s_nop 0
	s_and_saveexec_b64 s[0:1], s[4:5]
	s_cbranch_execz .LBB0_904
	s_lshl_b32 s2, s2, 10
	s_add_i32 s2, s22, s2
	s_waitcnt lgkmcnt(0)
	v_add_f32_e32 v96, v96, v97
	v_lshl_add_u32 v97, v161, 4, s2
	ds_write_b32 v97, v96 offset:2816

; DI unsigned pk_bf16(float lo, float hi) { f32x2 v = {lo, hi}; bf16x2_t b = __builtin_convertvector(v, bf16x2_t); return __builtin_bit_cast(unsigned, b); }
; DI float bflo(unsigned w) { return __uint_as_float(w << 16); }
; DI float bfhi(unsigned w) { return __uint_as_float(w & 0xffff0000u); }
;     __device__ __forceinline__ void fused(f32x4 (&acc)[2][2][4][2], const pg8::Unit& u, int wr, int wc, int fr, int fq, PG8_LAS unsigned char* lds, int wid, int lane) const {
;     ...
;         const int colb = u.pn * 256 + wc * 32 + 8 * fq;
;         f32x4 gv[2][2];
; #pragma unroll
;         for (int bj = 0; bj < 2; ++bj)
; #pragma unroll
;             for (int n = 0; n < 2; ++n) gv[bj][n] = *(const f32x4*)(gA + colb + bj * 128 + 4 * n);
; #pragma unroll
;         for (int ai = 0; ai < 2; ++ai)
; #pragma unroll
;             for (int m = 0; m < 4; ++m) {
;                 const int rl = ai * 128 + wr * 64 + m * 16 + fr; const size_t row = (size_t)u.pm * 256 + rl;
;                 const float rm = 1.f / sqrtf(__hip_atomic_load(ssqm + row, __ATOMIC_RELAXED, __HIP_MEMORY_SCOPE_AGENT) * (1.f / DM) + RMS_EPS);
;                 float sh = 0.f;
; #pragma unroll
;                 for (int bj = 0; bj < 2; ++bj) {
;                     const size_t off = row * DM + colb + bj * 128;
;                     f32x4 h0, h1;
;                     if (IN16) { const u32x4 hw = *(const u32x4*)((const bf16_t*)hin + off); h0 = (f32x4){bflo(hw.x), bfhi(hw.x), bflo(hw.y), bfhi(hw.y)}; h1 = (f32x4){bflo(hw.z), bfhi(hw.z), bflo(hw.w), bfhi(hw.w)}; }
;                     else { h0 = *(const f32x4*)((const float*)hin + off); h1 = *(const f32x4*)((const float*)hin + off + 4); }
;                     h0 = h0 + acc[ai][bj][m][0] * rm * gv[bj][0]; h1 = h1 + acc[ai][bj][m][1] * rm * gv[bj][1];
;                     sh += ((h0[0] * h0[0] + h0[1] * h0[1]) + (h0[2] * h0[2] + h0[3] * h0[3])) + ((h1[0] * h1[0] + h1[1] * h1[1]) + (h1[2] * h1[2] + h1[3] * h1[3]));
;                     if (OUT16) { u32x4 w; w.x = pk_bf16(h0[0], h0[1]); w.y = pk_bf16(h0[2], h0[3]); w.z = pk_bf16(h1[0], h1[1]); w.w = pk_bf16(h1[2], h1[3]); *(u32x4*)((bf16_t*)hout + off) = w; }
;                     else { *(f32x4*)((float*)hout + off) = h0; *(f32x4*)((float*)hout + off + 4) = h1; }
;                 }
;                 if (ssqh) { sh += __shfl_xor(sh, 16); sh += __shfl_xor(sh, 32); if (fq == 0) red[rl * 4 + wc] = sh; }
.LBB0_911:
	s_or_b64 exec, exec, s[0:1]
	s_lshl_b32 s0, s41, 5
	s_lshl_b32 s1, s33, 8
	s_or_b32 s0, s1, s0
	v_mov_b32_e32 v159, 0
	v_or_b32_e32 v156, s0, v160
	s_lshl_b64 s[18:19], s[16:17], 8
	v_mov_b32_e32 v153, v159
	v_ashrrev_i32_e32 v157, 31, v156
	v_lshl_add_u64 v[168:169], s[18:19], 0, v[152:153]
	v_lshl_add_u64 v[100:101], v[156:157], 2, s[14:15]
	v_lshl_add_u64 v[170:171], v[168:169], 2, s[12:13]
	s_barrier
	global_load_dwordx4 v[104:107], v[100:101], off offset:16
	global_load_dwordx4 v[108:111], v[100:101], off
	global_load_dwordx4 v[96:99], v[100:101], off offset:528
	s_nop 0
	global_load_dwordx4 v[100:103], v[100:101], off offset:512
	v_lshlrev_b64 v[168:169], 10, v[168:169]
	global_load_dword v151, v[170:171], off sc1
	v_lshl_add_u64 v[176:177], v[168:169], 0, v[156:157]
	v_lshl_add_u64 v[178:179], v[176:177], 2, s[36:37]
	global_load_dwordx4 v[168:171], v[178:179], off
	global_load_dwordx4 v[172:175], v[178:179], off offset:16
	v_mov_b32_e32 v153, 0x358637bd
	s_mov_b32 s2, 0xf800000
	v_lshlrev_b64 v[176:177], 1, v[176:177]
	s_waitcnt vmcnt(2)
	v_fmamk_f32 v151, v151, 0x3a800000, v153
	v_mul_f32_e32 v158, 0x4f800000, v151
	v_cmp_gt_f32_e32 vcc, s2, v151
	s_nop 1
	v_cndmask_b32_e32 v158, v151, v158, vcc
	v_sqrt_f32_e32 v180, v158
	v_mov_b32_e32 v151, 0x260
	v_add_u32_e32 v181, -1, v180
	v_add_u32_e32 v182, 1, v180
	v_fma_f32 v183, -v181, v180, v158
	v_fma_f32 v184, -v182, v180, v158
	v_cmp_ge_f32_e64 s[0:1], 0, v183
	s_nop 1
	v_cndmask_b32_e64 v180, v180, v181, s[0:1]
	v_cmp_lt_f32_e64 s[0:1], 0, v184
	s_nop 1
	v_cndmask_b32_e64 v180, v180, v182, s[0:1]
	v_mul_f32_e32 v181, 0x37800000, v180
	v_cndmask_b32_e32 v180, v180, v181, vcc
	v_cmp_class_f32_e32 vcc, v158, v151
	s_nop 1
	v_cndmask_b32_e32 v158, v180, v158, vcc
	v_div_scale_f32 v182, s[0:1], v158, v158, 1.0
	v_rcp_f32_e32 v183, v182
	v_div_scale_f32 v184, vcc, 1.0, v158, 1.0
	v_lshl_add_u64 v[180:181], s[10:11], 0, v[176:177]
	v_fma_f32 v185, -v182, v183, 1.0
	v_fmac_f32_e32 v183, v185, v183
	v_mul_f32_e32 v185, v184, v183
	v_fma_f32 v186, -v182, v185, v184
	v_fmac_f32_e32 v185, v186, v183
	v_fma_f32 v182, -v182, v185, v184
	v_div_fmas_f32 v182, v182, v183, v185
	v_div_fixup_f32 v158, v182, v158, 1.0
	v_pk_mul_f32 v[140:141], v[140:141], v[158:159] op_sel_hi:[1,0]
	v_pk_mul_f32 v[142:143], v[142:143], v[158:159] op_sel_hi:[1,0]
	v_pk_mul_f32 v[136:137], v[136:137], v[158:159] op_sel_hi:[1,0]
	v_pk_mul_f32 v[138:139], v[138:139], v[158:159] op_sel_hi:[1,0]
	s_waitcnt vmcnt(1)
	v_pk_fma_f32 v[170:171], v[110:111], v[142:143], v[170:171]
	v_pk_fma_f32 v[168:169], v[108:109], v[140:141], v[168:169]
	s_waitcnt vmcnt(0)
	v_pk_fma_f32 v[174:175], v[106:107], v[138:139], v[174:175]
	v_pk_fma_f32 v[172:173], v[104:105], v[136:137], v[172:173]
	v_cvt_pk_bf16_f32 v136, v168, v169
	v_cvt_pk_bf16_f32 v137, v170, v171
	v_cvt_pk_bf16_f32 v138, v172, v173
	v_cvt_pk_bf16_f32 v139, v174, v175
	global_store_dwordx4 v[180:181], v[136:139], off
	global_load_dwordx4 v[136:139], v[178:179], off offset:512
	s_nop 0
	global_load_dwordx4 v[140:143], v[178:179], off offset:528
	v_pk_mul_f32 v[132:133], v[132:133], v[158:159] op_sel_hi:[1,0]
	v_pk_mul_f32 v[134:135], v[134:135], v[158:159] op_sel_hi:[1,0]
	v_pk_mul_f32 v[128:129], v[128:129], v[158:159] op_sel_hi:[1,0]
	v_pk_mul_f32 v[130:131], v[130:131], v[158:159] op_sel_hi:[1,0]
	v_mul_f32_e32 v158, v169, v169
	v_mul_f32_e32 v169, v171, v171
	v_mul_f32_e32 v171, v173, v173
	v_mul_f32_e32 v173, v175, v175
	v_fmac_f32_e32 v158, v168, v168
	v_fmac_f32_e32 v169, v170, v170
	v_fmac_f32_e32 v171, v172, v172
	v_fmac_f32_e32 v173, v174, v174
	v_add_f32_e32 v158, v158, v169
	v_add_f32_e32 v168, v171, v173
	v_add_f32_e32 v158, v158, v168
	v_or_b32_e32 v176, 0x100, v176
	s_waitcnt vmcnt(1)
	v_pk_fma_f32 v[134:135], v[102:103], v[134:135], v[138:139]
	v_pk_fma_f32 v[132:133], v[100:101], v[132:133], v[136:137]
	s_waitcnt vmcnt(0)
	v_pk_fma_f32 v[136:137], v[98:99], v[130:131], v[142:143]
	v_pk_fma_f32 v[128:129], v[96:97], v[128:129], v[140:141]
	v_mul_f32_e32 v130, v133, v133
	v_mul_f32_e32 v131, v135, v135
	v_mul_f32_e32 v138, v129, v129
	v_mul_f32_e32 v139, v137, v137
	v_fmac_f32_e32 v130, v132, v132
	v_fmac_f32_e32 v131, v134, v134
	v_fmac_f32_e32 v138, v128, v128
	v_fmac_f32_e32 v139, v136, v136
	v_add_f32_e32 v130, v130, v131
	v_add_f32_e32 v131, v138, v139
	v_add_f32_e32 v130, v130, v131
	v_add_f32_e32 v138, v158, v130
	v_mov_b32_e32 v139, v138
	s_nop 1
	v_permlane16_swap_b32 v139, v138
	s_nop 0
	v_cvt_pk_bf16_f32 v130, v132, v133
	v_cvt_pk_bf16_f32 v132, v128, v129
	v_cvt_pk_bf16_f32 v131, v134, v135
	v_cvt_pk_bf16_f32 v133, v136, v137
	s_waitcnt lgkmcnt(0)
	v_add_f32_e32 v128, v138, v139
	v_mov_b32_e32 v129, v128
	s_nop 1
	v_permlane32_swap_b32 v129, v128
	s_nop 0
	v_lshl_add_u64 v[134:135], s[10:11], 0, v[176:177]
	global_store_dwordx4 v[134:135], v[130:133], off
	s_and_saveexec_b64 s[0:1], s[4:5]
	s_cbranch_execz .LBB0_913
	v_lshl_add_u32 v130, v152, 4, s22
	s_waitcnt lgkmcnt(0)
	v_add_f32_e32 v128, v128, v129
	ds_write_b32 v130, v128
; DI unsigned pk_bf16(float lo, float hi) { f32x2 v = {lo, hi}; bf16x2_t b = __builtin_convertvector(v, bf16x2_t); return __builtin_bit_cast(unsigned, b); }
; DI float bflo(unsigned w) { return __uint_as_float(w << 16); }
; DI float bfhi(unsigned w) { return __uint_as_float(w & 0xffff0000u); }
;     __device__ __forceinline__ void fused(f32x4 (&acc)[2][2][4][2], const pg8::Unit& u, int wr, int wc, int fr, int fq, PG8_LAS unsigned char* lds, int wid, int lane) const {
;     ...
;         for (int ai = 0; ai < 2; ++ai)
; #pragma unroll
;             for (int m = 0; m < 4; ++m) {
;                 const int rl = ai * 128 + wr * 64 + m * 16 + fr; const size_t row = (size_t)u.pm * 256 + rl;
;                 const float rm = 1.f / sqrtf(__hip_atomic_load(ssqm + row, __ATOMIC_RELAXED, __HIP_MEMORY_SCOPE_AGENT) * (1.f / DM) + RMS_EPS);
;                 float sh = 0.f;
; #pragma unroll
;                 for (int bj = 0; bj < 2; ++bj) {
;                     const size_t off = row * DM + colb + bj * 128;
;                     f32x4 h0, h1;
;                     if (IN16) { const u32x4 hw = *(const u32x4*)((const bf16_t*)hin + off); h0 = (f32x4){bflo(hw.x), bfhi(hw.x), bflo(hw.y), bfhi(hw.y)}; h1 = (f32x4){bflo(hw.z), bfhi(hw.z), bflo(hw.w), bfhi(hw.w)}; }
;                     else { h0 = *(const f32x4*)((const float*)hin + off); h1 = *(const f32x4*)((const float*)hin + off + 4); }
;                     h0 = h0 + acc[ai][bj][m][0] * rm * gv[bj][0]; h1 = h1 + acc[ai][bj][m][1] * rm * gv[bj][1];
;                     sh += ((h0[0] * h0[0] + h0[1] * h0[1]) + (h0[2] * h0[2] + h0[3] * h0[3])) + ((h1[0] * h1[0] + h1[1] * h1[1]) + (h1[2] * h1[2] + h1[3] * h1[3]));
;                     if (OUT16) { u32x4 w; w.x = pk_bf16(h0[0], h0[1]); w.y = pk_bf16(h0[2], h0[3]); w.z = pk_bf16(h1[0], h1[1]); w.w = pk_bf16(h1[2], h1[3]); *(u32x4*)((bf16_t*)hout + off) = w; }
;                     else { *(f32x4*)((float*)hout + off) = h0; *(f32x4*)((float*)hout + off + 4) = h1; }
;                 }
;                 if (ssqh) { sh += __shfl_xor(sh, 16); sh += __shfl_xor(sh, 32); if (fq == 0) red[rl * 4 + wc] = sh; }
.LBB0_913:
	s_or_b64 exec, exec, s[0:1]
	v_or_b32_e32 v158, 16, v152
	s_waitcnt lgkmcnt(0)
	v_lshl_add_u64 v[128:129], s[18:19], 0, v[158:159]
	v_lshl_add_u64 v[130:131], v[128:129], 2, s[12:13]
	global_load_dword v140, v[130:131], off sc1
	v_lshlrev_b64 v[128:129], 10, v[128:129]
	v_lshl_add_u64 v[136:137], v[128:129], 0, v[156:157]
	v_lshl_add_u64 v[138:139], v[136:137], 2, s[36:37]
	global_load_dwordx4 v[128:131], v[138:139], off
	global_load_dwordx4 v[132:135], v[138:139], off offset:16
	v_lshlrev_b64 v[136:137], 1, v[136:137]
	s_waitcnt vmcnt(2)
	v_fmac_f32_e32 v153, 0x3a800000, v140
	v_mul_f32_e32 v140, 0x4f800000, v153
	v_cmp_gt_f32_e32 vcc, s2, v153
	s_nop 1
	v_cndmask_b32_e32 v140, v153, v140, vcc
	v_sqrt_f32_e32 v141, v140
	s_nop 0
	v_add_u32_e32 v142, -1, v141
	v_add_u32_e32 v143, 1, v141
	v_fma_f32 v153, -v142, v141, v140
	v_fma_f32 v159, -v143, v141, v140
	v_cmp_ge_f32_e64 s[0:1], 0, v153
	s_nop 1
	v_cndmask_b32_e64 v141, v141, v142, s[0:1]
	v_cmp_lt_f32_e64 s[0:1], 0, v159
	s_nop 1
	v_cndmask_b32_e64 v141, v141, v143, s[0:1]
	v_mul_f32_e32 v142, 0x37800000, v141
	v_cndmask_b32_e32 v141, v141, v142, vcc
	v_cmp_class_f32_e32 vcc, v140, v151
	s_nop 1
	v_cndmask_b32_e32 v142, v141, v140, vcc
	v_div_scale_f32 v143, s[0:1], v142, v142, 1.0
	v_rcp_f32_e32 v151, v143
	v_div_scale_f32 v153, vcc, 1.0, v142, 1.0
	v_lshl_add_u64 v[140:141], s[10:11], 0, v[136:137]
	v_fma_f32 v159, -v143, v151, 1.0
	v_fmac_f32_e32 v151, v159, v151
	v_mul_f32_e32 v159, v153, v151
	v_fma_f32 v168, -v143, v159, v153
	v_fmac_f32_e32 v159, v168, v151
	v_fma_f32 v143, -v143, v159, v153
	v_div_fmas_f32 v143, v143, v151, v159
	v_div_fixup_f32 v142, v143, v142, 1.0
	v_pk_mul_f32 v[124:125], v[124:125], v[142:143] op_sel_hi:[1,0]
	v_pk_mul_f32 v[126:127], v[126:127], v[142:143] op_sel_hi:[1,0]
	v_pk_mul_f32 v[120:121], v[120:121], v[142:143] op_sel_hi:[1,0]
	v_pk_mul_f32 v[122:123], v[122:123], v[142:143] op_sel_hi:[1,0]
	s_waitcnt vmcnt(1)
	v_pk_fma_f32 v[130:131], v[110:111], v[126:127], v[130:131]
	v_pk_fma_f32 v[128:129], v[108:109], v[124:125], v[128:129]
	s_waitcnt vmcnt(0)
	v_pk_fma_f32 v[134:135], v[106:107], v[122:123], v[134:135]
	v_pk_fma_f32 v[132:133], v[104:105], v[120:121], v[132:133]
	v_cvt_pk_bf16_f32 v120, v128, v129
	v_cvt_pk_bf16_f32 v121, v130, v131
	v_cvt_pk_bf16_f32 v122, v132, v133
	v_cvt_pk_bf16_f32 v123, v134, v135
	global_store_dwordx4 v[140:141], v[120:123], off
	global_load_dwordx4 v[120:123], v[138:139], off offset:512
	s_nop 0
	global_load_dwordx4 v[124:127], v[138:139], off offset:528
	v_pk_mul_f32 v[116:117], v[116:117], v[142:143] op_sel_hi:[1,0]
	v_pk_mul_f32 v[118:119], v[118:119], v[142:143] op_sel_hi:[1,0]
	v_pk_mul_f32 v[112:113], v[112:113], v[142:143] op_sel_hi:[1,0]
	v_pk_mul_f32 v[114:115], v[114:115], v[142:143] op_sel_hi:[1,0]
	v_mul_f32_e32 v129, v129, v129
	v_mul_f32_e32 v131, v131, v131
	v_mul_f32_e32 v133, v133, v133
	v_mul_f32_e32 v135, v135, v135
	v_fmac_f32_e32 v129, v128, v128
	v_fmac_f32_e32 v131, v130, v130
	v_fmac_f32_e32 v133, v132, v132
	v_fmac_f32_e32 v135, v134, v134
	v_add_f32_e32 v128, v129, v131
	v_add_f32_e32 v129, v133, v135
	v_add_f32_e32 v128, v128, v129
	v_or_b32_e32 v136, 0x100, v136
	s_waitcnt vmcnt(1)
	v_pk_fma_f32 v[118:119], v[102:103], v[118:119], v[122:123]
	v_pk_fma_f32 v[116:117], v[100:101], v[116:117], v[120:121]
	s_waitcnt vmcnt(0)
	v_pk_fma_f32 v[120:121], v[98:99], v[114:115], v[126:127]
	v_pk_fma_f32 v[112:113], v[96:97], v[112:113], v[124:125]
	v_mul_f32_e32 v114, v117, v117
	v_mul_f32_e32 v115, v119, v119
	v_mul_f32_e32 v122, v113, v113
	v_mul_f32_e32 v123, v121, v121
	v_fmac_f32_e32 v114, v116, v116
	v_fmac_f32_e32 v115, v118, v118
	v_fmac_f32_e32 v122, v112, v112
	v_fmac_f32_e32 v123, v120, v120
	v_add_f32_e32 v114, v114, v115
	v_add_f32_e32 v115, v122, v123
	v_add_f32_e32 v114, v114, v115
	v_add_f32_e32 v122, v128, v114
	v_mov_b32_e32 v123, v122
	s_nop 1
	v_permlane16_swap_b32 v123, v122
	s_nop 0
	v_cvt_pk_bf16_f32 v114, v116, v117
	v_cvt_pk_bf16_f32 v116, v112, v113
	v_cvt_pk_bf16_f32 v115, v118, v119
	v_cvt_pk_bf16_f32 v117, v120, v121
	s_waitcnt lgkmcnt(0)
	v_add_f32_e32 v112, v122, v123
	v_mov_b32_e32 v113, v112
	s_nop 1
	v_permlane32_swap_b32 v113, v112
	s_nop 0
	v_lshl_add_u64 v[118:119], s[10:11], 0, v[136:137]
	global_store_dwordx4 v[118:119], v[114:117], off
	s_and_saveexec_b64 s[0:1], s[4:5]
	s_cbranch_execz .LBB0_915
	v_lshl_add_u32 v114, v158, 4, s22
	s_waitcnt lgkmcnt(0)
	v_add_f32_e32 v112, v112, v113
	ds_write_b32 v114, v112
; DI unsigned pk_bf16(float lo, float hi) { f32x2 v = {lo, hi}; bf16x2_t b = __builtin_convertvector(v, bf16x2_t); return __builtin_bit_cast(unsigned, b); }
; DI float bflo(unsigned w) { return __uint_as_float(w << 16); }
; DI float bfhi(unsigned w) { return __uint_as_float(w & 0xffff0000u); }
;     __device__ __forceinline__ void fused(f32x4 (&acc)[2][2][4][2], const pg8::Unit& u, int wr, int wc, int fr, int fq, PG8_LAS unsigned char* lds, int wid, int lane) const {
;     ...
;         for (int ai = 0; ai < 2; ++ai)
; #pragma unroll
;             for (int m = 0; m < 4; ++m) {
;                 const int rl = ai * 128 + wr * 64 + m * 16 + fr; const size_t row = (size_t)u.pm * 256 + rl;
;                 const float rm = 1.f / sqrtf(__hip_atomic_load(ssqm + row, __ATOMIC_RELAXED, __HIP_MEMORY_SCOPE_AGENT) * (1.f / DM) + RMS_EPS);
;                 float sh = 0.f;
; #pragma unroll
;                 for (int bj = 0; bj < 2; ++bj) {
;                     const size_t off = row * DM + colb + bj * 128;
;                     f32x4 h0, h1;
;                     if (IN16) { const u32x4 hw = *(const u32x4*)((const bf16_t*)hin + off); h0 = (f32x4){bflo(hw.x), bfhi(hw.x), bflo(hw.y), bfhi(hw.y)}; h1 = (f32x4){bflo(hw.z), bfhi(hw.z), bflo(hw.w), bfhi(hw.w)}; }
;                     else { h0 = *(const f32x4*)((const float*)hin + off); h1 = *(const f32x4*)((const float*)hin + off + 4); }
;                     h0 = h0 + acc[ai][bj][m][0] * rm * gv[bj][0]; h1 = h1 + acc[ai][bj][m][1] * rm * gv[bj][1];
;                     sh += ((h0[0] * h0[0] + h0[1] * h0[1]) + (h0[2] * h0[2] + h0[3] * h0[3])) + ((h1[0] * h1[0] + h1[1] * h1[1]) + (h1[2] * h1[2] + h1[3] * h1[3]));
;                     if (OUT16) { u32x4 w; w.x = pk_bf16(h0[0], h0[1]); w.y = pk_bf16(h0[2], h0[3]); w.z = pk_bf16(h1[0], h1[1]); w.w = pk_bf16(h1[2], h1[3]); *(u32x4*)((bf16_t*)hout + off) = w; }
;                     else { *(f32x4*)((float*)hout + off) = h0; *(f32x4*)((float*)hout + off + 4) = h1; }
;                 }
;                 if (ssqh) { sh += __shfl_xor(sh, 16); sh += __shfl_xor(sh, 32); if (fq == 0) red[rl * 4 + wc] = sh; }
.LBB0_915:
	s_or_b64 exec, exec, s[0:1]
	v_or_b32_e32 v112, 32, v152
	s_waitcnt lgkmcnt(0)
	v_mov_b32_e32 v113, 0
	v_lshl_add_u64 v[114:115], s[18:19], 0, v[112:113]
	v_lshl_add_u64 v[116:117], v[114:115], 2, s[12:13]
	global_load_dword v128, v[116:117], off sc1
	v_lshlrev_b64 v[114:115], 10, v[114:115]
	v_lshl_add_u64 v[124:125], v[114:115], 0, v[156:157]
	v_lshl_add_u64 v[126:127], v[124:125], 2, s[36:37]
	global_load_dwordx4 v[116:119], v[126:127], off
	global_load_dwordx4 v[120:123], v[126:127], off offset:16
	v_mov_b32_e32 v115, 0x358637bd
	v_lshlrev_b64 v[124:125], 1, v[124:125]
	s_waitcnt vmcnt(2)
	v_fmamk_f32 v114, v128, 0x3a800000, v115
	v_mul_f32_e32 v128, 0x4f800000, v114
	v_cmp_gt_f32_e32 vcc, s2, v114
	s_nop 1
	v_cndmask_b32_e32 v128, v114, v128, vcc
	v_sqrt_f32_e32 v129, v128
	v_mov_b32_e32 v114, 0x260
	v_add_u32_e32 v130, -1, v129
	v_add_u32_e32 v131, 1, v129
	v_fma_f32 v132, -v130, v129, v128
	v_fma_f32 v133, -v131, v129, v128
	v_cmp_ge_f32_e64 s[0:1], 0, v132
	s_nop 1
	v_cndmask_b32_e64 v129, v129, v130, s[0:1]
	v_cmp_lt_f32_e64 s[0:1], 0, v133
	s_nop 1
	v_cndmask_b32_e64 v129, v129, v131, s[0:1]
	v_mul_f32_e32 v130, 0x37800000, v129
	v_cndmask_b32_e32 v129, v129, v130, vcc
	v_cmp_class_f32_e32 vcc, v128, v114
	s_nop 1
	v_cndmask_b32_e32 v130, v129, v128, vcc
	v_div_scale_f32 v131, s[0:1], v130, v130, 1.0
	v_rcp_f32_e32 v132, v131
	v_div_scale_f32 v133, vcc, 1.0, v130, 1.0
	v_lshl_add_u64 v[128:129], s[10:11], 0, v[124:125]
	v_fma_f32 v134, -v131, v132, 1.0
	v_fmac_f32_e32 v132, v134, v132
	v_mul_f32_e32 v134, v133, v132
	v_fma_f32 v135, -v131, v134, v133
	v_fmac_f32_e32 v134, v135, v132
	v_fma_f32 v131, -v131, v134, v133
	v_div_fmas_f32 v131, v131, v132, v134
	v_div_fixup_f32 v130, v131, v130, 1.0
	v_pk_mul_f32 v[92:93], v[92:93], v[130:131] op_sel_hi:[1,0]
	v_pk_mul_f32 v[94:95], v[94:95], v[130:131] op_sel_hi:[1,0]
	v_pk_mul_f32 v[88:89], v[88:89], v[130:131] op_sel_hi:[1,0]
	v_pk_mul_f32 v[90:91], v[90:91], v[130:131] op_sel_hi:[1,0]
	s_waitcnt vmcnt(1)
	v_pk_fma_f32 v[118:119], v[110:111], v[94:95], v[118:119]
	v_pk_fma_f32 v[116:117], v[108:109], v[92:93], v[116:117]
	s_waitcnt vmcnt(0)
	v_pk_fma_f32 v[122:123], v[106:107], v[90:91], v[122:123]
	v_pk_fma_f32 v[120:121], v[104:105], v[88:89], v[120:121]
	v_cvt_pk_bf16_f32 v88, v116, v117
	v_cvt_pk_bf16_f32 v89, v118, v119
	v_cvt_pk_bf16_f32 v90, v120, v121
	v_cvt_pk_bf16_f32 v91, v122, v123
	global_store_dwordx4 v[128:129], v[88:91], off
	global_load_dwordx4 v[88:91], v[126:127], off offset:512
	s_nop 0
	global_load_dwordx4 v[92:95], v[126:127], off offset:528
	v_pk_mul_f32 v[84:85], v[84:85], v[130:131] op_sel_hi:[1,0]
	v_pk_mul_f32 v[86:87], v[86:87], v[130:131] op_sel_hi:[1,0]
	v_pk_mul_f32 v[80:81], v[80:81], v[130:131] op_sel_hi:[1,0]
	v_pk_mul_f32 v[82:83], v[82:83], v[130:131] op_sel_hi:[1,0]
	v_mul_f32_e32 v117, v117, v117
	v_mul_f32_e32 v119, v119, v119
	v_mul_f32_e32 v121, v121, v121
	v_mul_f32_e32 v123, v123, v123
	v_fmac_f32_e32 v117, v116, v116
	v_fmac_f32_e32 v119, v118, v118
	v_fmac_f32_e32 v121, v120, v120
	v_fmac_f32_e32 v123, v122, v122
	v_add_f32_e32 v116, v117, v119
	v_add_f32_e32 v117, v121, v123
	v_add_f32_e32 v116, v116, v117
	v_or_b32_e32 v124, 0x100, v124
	s_waitcnt vmcnt(1)
	v_pk_fma_f32 v[86:87], v[102:103], v[86:87], v[90:91]
	v_pk_fma_f32 v[84:85], v[100:101], v[84:85], v[88:89]
	s_waitcnt vmcnt(0)
	v_pk_fma_f32 v[88:89], v[98:99], v[82:83], v[94:95]
	v_pk_fma_f32 v[80:81], v[96:97], v[80:81], v[92:93]
	v_mul_f32_e32 v82, v85, v85
	v_mul_f32_e32 v83, v87, v87
	v_mul_f32_e32 v90, v81, v81
	v_mul_f32_e32 v91, v89, v89
	v_fmac_f32_e32 v82, v84, v84
	v_fmac_f32_e32 v83, v86, v86
	v_fmac_f32_e32 v90, v80, v80
	v_fmac_f32_e32 v91, v88, v88
	v_add_f32_e32 v82, v82, v83
	v_add_f32_e32 v83, v90, v91
	v_add_f32_e32 v82, v82, v83
	v_add_f32_e32 v90, v116, v82
	v_mov_b32_e32 v91, v90
	s_nop 1
	v_permlane16_swap_b32 v91, v90
	s_nop 0
	v_cvt_pk_bf16_f32 v82, v84, v85
	v_cvt_pk_bf16_f32 v84, v80, v81
	v_cvt_pk_bf16_f32 v83, v86, v87
	v_cvt_pk_bf16_f32 v85, v88, v89
	s_waitcnt lgkmcnt(0)
	v_add_f32_e32 v80, v90, v91
	v_mov_b32_e32 v81, v80
	s_nop 1
	v_permlane32_swap_b32 v81, v80
	s_nop 0
	v_lshl_add_u64 v[86:87], s[10:11], 0, v[124:125]
	global_store_dwordx4 v[86:87], v[82:85], off
	s_and_saveexec_b64 s[0:1], s[4:5]
	s_cbranch_execz .LBB0_917
	v_lshl_add_u32 v82, v112, 4, s22
	s_waitcnt lgkmcnt(0)
	v_add_f32_e32 v80, v80, v81
	ds_write_b32 v82, v80
; DI unsigned pk_bf16(float lo, float hi) { f32x2 v = {lo, hi}; bf16x2_t b = __builtin_convertvector(v, bf16x2_t); return __builtin_bit_cast(unsigned, b); }
; DI float bflo(unsigned w) { return __uint_as_float(w << 16); }
; DI float bfhi(unsigned w) { return __uint_as_float(w & 0xffff0000u); }
;     __device__ __forceinline__ void fused(f32x4 (&acc)[2][2][4][2], const pg8::Unit& u, int wr, int wc, int fr, int fq, PG8_LAS unsigned char* lds, int wid, int lane) const {
;     ...
;         for (int ai = 0; ai < 2; ++ai)
; #pragma unroll
;             for (int m = 0; m < 4; ++m) {
;                 const int rl = ai * 128 + wr * 64 + m * 16 + fr; const size_t row = (size_t)u.pm * 256 + rl;
;                 const float rm = 1.f / sqrtf(__hip_atomic_load(ssqm + row, __ATOMIC_RELAXED, __HIP_MEMORY_SCOPE_AGENT) * (1.f / DM) + RMS_EPS);
;                 float sh = 0.f;
; #pragma unroll
;                 for (int bj = 0; bj < 2; ++bj) {
;                     const size_t off = row * DM + colb + bj * 128;
;                     f32x4 h0, h1;
;                     if (IN16) { const u32x4 hw = *(const u32x4*)((const bf16_t*)hin + off); h0 = (f32x4){bflo(hw.x), bfhi(hw.x), bflo(hw.y), bfhi(hw.y)}; h1 = (f32x4){bflo(hw.z), bfhi(hw.z), bflo(hw.w), bfhi(hw.w)}; }
;                     else { h0 = *(const f32x4*)((const float*)hin + off); h1 = *(const f32x4*)((const float*)hin + off + 4); }
;                     h0 = h0 + acc[ai][bj][m][0] * rm * gv[bj][0]; h1 = h1 + acc[ai][bj][m][1] * rm * gv[bj][1];
;                     sh += ((h0[0] * h0[0] + h0[1] * h0[1]) + (h0[2] * h0[2] + h0[3] * h0[3])) + ((h1[0] * h1[0] + h1[1] * h1[1]) + (h1[2] * h1[2] + h1[3] * h1[3]));
;                     if (OUT16) { u32x4 w; w.x = pk_bf16(h0[0], h0[1]); w.y = pk_bf16(h0[2], h0[3]); w.z = pk_bf16(h1[0], h1[1]); w.w = pk_bf16(h1[2], h1[3]); *(u32x4*)((bf16_t*)hout + off) = w; }
;                     else { *(f32x4*)((float*)hout + off) = h0; *(f32x4*)((float*)hout + off + 4) = h1; }
;                 }
;                 if (ssqh) { sh += __shfl_xor(sh, 16); sh += __shfl_xor(sh, 32); if (fq == 0) red[rl * 4 + wc] = sh; }
.LBB0_917:
	s_or_b64 exec, exec, s[0:1]
	v_or_b32_e32 v112, 48, v152
	s_waitcnt lgkmcnt(0)
	v_lshl_add_u64 v[80:81], s[18:19], 0, v[112:113]
	v_lshl_add_u64 v[82:83], v[80:81], 2, s[12:13]
	global_load_dword v92, v[82:83], off sc1
	v_lshlrev_b64 v[80:81], 10, v[80:81]
	v_lshl_add_u64 v[88:89], v[80:81], 0, v[156:157]
	v_lshl_add_u64 v[90:91], v[88:89], 2, s[36:37]
	global_load_dwordx4 v[80:83], v[90:91], off
	global_load_dwordx4 v[84:87], v[90:91], off offset:16
	v_lshlrev_b64 v[88:89], 1, v[88:89]
	s_waitcnt vmcnt(2)
	v_fmac_f32_e32 v115, 0x3a800000, v92
	v_mul_f32_e32 v92, 0x4f800000, v115
	v_cmp_gt_f32_e32 vcc, s2, v115
	s_nop 1
	v_cndmask_b32_e32 v92, v115, v92, vcc
	v_sqrt_f32_e32 v93, v92
	s_nop 0
	v_add_u32_e32 v94, -1, v93
	v_add_u32_e32 v95, 1, v93
	v_fma_f32 v113, -v94, v93, v92
	v_fma_f32 v115, -v95, v93, v92
	v_cmp_ge_f32_e64 s[0:1], 0, v113
	s_nop 1
	v_cndmask_b32_e64 v93, v93, v94, s[0:1]
	v_cmp_lt_f32_e64 s[0:1], 0, v115
	s_nop 1
	v_cndmask_b32_e64 v93, v93, v95, s[0:1]
	v_mul_f32_e32 v94, 0x37800000, v93
	v_cndmask_b32_e32 v93, v93, v94, vcc
	v_cmp_class_f32_e32 vcc, v92, v114
	s_nop 1
	v_cndmask_b32_e32 v94, v93, v92, vcc
	v_div_scale_f32 v95, s[0:1], v94, v94, 1.0
	v_rcp_f32_e32 v113, v95
	v_div_scale_f32 v114, vcc, 1.0, v94, 1.0
	v_lshl_add_u64 v[92:93], s[10:11], 0, v[88:89]
	v_fma_f32 v115, -v95, v113, 1.0
	v_fmac_f32_e32 v113, v115, v113
	v_mul_f32_e32 v115, v114, v113
	v_fma_f32 v116, -v95, v115, v114
	v_fmac_f32_e32 v115, v116, v113
	v_fma_f32 v95, -v95, v115, v114
	v_div_fmas_f32 v95, v95, v113, v115
	v_div_fixup_f32 v94, v95, v94, 1.0
	v_pk_mul_f32 v[76:77], v[76:77], v[94:95] op_sel_hi:[1,0]
	v_pk_mul_f32 v[78:79], v[78:79], v[94:95] op_sel_hi:[1,0]
	v_pk_mul_f32 v[72:73], v[72:73], v[94:95] op_sel_hi:[1,0]
	v_pk_mul_f32 v[74:75], v[74:75], v[94:95] op_sel_hi:[1,0]
	s_waitcnt vmcnt(1)
	v_pk_fma_f32 v[82:83], v[110:111], v[78:79], v[82:83]
	v_pk_fma_f32 v[80:81], v[108:109], v[76:77], v[80:81]
	s_waitcnt vmcnt(0)
	v_pk_fma_f32 v[86:87], v[106:107], v[74:75], v[86:87]
	v_pk_fma_f32 v[84:85], v[104:105], v[72:73], v[84:85]
	v_cvt_pk_bf16_f32 v72, v80, v81
	v_cvt_pk_bf16_f32 v73, v82, v83
	v_cvt_pk_bf16_f32 v74, v84, v85
	v_cvt_pk_bf16_f32 v75, v86, v87
	global_store_dwordx4 v[92:93], v[72:75], off
	global_load_dwordx4 v[72:75], v[90:91], off offset:512
	s_nop 0
	global_load_dwordx4 v[76:79], v[90:91], off offset:528
	v_pk_mul_f32 v[68:69], v[68:69], v[94:95] op_sel_hi:[1,0]
	v_pk_mul_f32 v[70:71], v[70:71], v[94:95] op_sel_hi:[1,0]
	v_pk_mul_f32 v[64:65], v[64:65], v[94:95] op_sel_hi:[1,0]
	v_pk_mul_f32 v[66:67], v[66:67], v[94:95] op_sel_hi:[1,0]
	v_mul_f32_e32 v81, v81, v81
	v_mul_f32_e32 v83, v83, v83
	v_mul_f32_e32 v85, v85, v85
	v_mul_f32_e32 v87, v87, v87
	v_fmac_f32_e32 v81, v80, v80
	v_fmac_f32_e32 v83, v82, v82
	v_fmac_f32_e32 v85, v84, v84
	v_fmac_f32_e32 v87, v86, v86
	v_add_f32_e32 v80, v81, v83
	v_add_f32_e32 v81, v85, v87
	v_add_f32_e32 v80, v80, v81
	v_or_b32_e32 v88, 0x100, v88
	s_waitcnt vmcnt(1)
	v_pk_fma_f32 v[70:71], v[102:103], v[70:71], v[74:75]
	v_pk_fma_f32 v[68:69], v[100:101], v[68:69], v[72:73]
	s_waitcnt vmcnt(0)
	v_pk_fma_f32 v[72:73], v[98:99], v[66:67], v[78:79]
	v_pk_fma_f32 v[64:65], v[96:97], v[64:65], v[76:77]
	v_mul_f32_e32 v66, v69, v69
	v_mul_f32_e32 v67, v71, v71
	v_mul_f32_e32 v74, v65, v65
	v_mul_f32_e32 v75, v73, v73
	v_fmac_f32_e32 v66, v68, v68
	v_fmac_f32_e32 v67, v70, v70
	v_fmac_f32_e32 v74, v64, v64
	v_fmac_f32_e32 v75, v72, v72
	v_add_f32_e32 v66, v66, v67
	v_add_f32_e32 v67, v74, v75
	v_add_f32_e32 v66, v66, v67
	v_add_f32_e32 v74, v80, v66
	v_mov_b32_e32 v75, v74
	s_nop 1
	v_permlane16_swap_b32 v75, v74
	s_nop 0
	v_cvt_pk_bf16_f32 v66, v68, v69
	v_cvt_pk_bf16_f32 v68, v64, v65
	v_cvt_pk_bf16_f32 v67, v70, v71
	v_cvt_pk_bf16_f32 v69, v72, v73
	s_waitcnt lgkmcnt(0)
	v_add_f32_e32 v64, v74, v75
	v_mov_b32_e32 v65, v64
	s_nop 1
	v_permlane32_swap_b32 v65, v64
	s_nop 0
	v_lshl_add_u64 v[70:71], s[10:11], 0, v[88:89]
	global_store_dwordx4 v[70:71], v[66:69], off
	s_and_saveexec_b64 s[0:1], s[4:5]
	s_cbranch_execz .LBB0_919
	v_lshl_add_u32 v66, v112, 4, s22
	s_waitcnt lgkmcnt(0)
	v_add_f32_e32 v64, v64, v65
	ds_write_b32 v66, v64
.LBB0_919:
	s_or_b64 exec, exec, s[0:1]
	v_add_u32_e32 v64, 0x80, v152
	s_waitcnt lgkmcnt(0)
	v_mov_b32_e32 v65, 0
	v_lshl_add_u64 v[66:67], s[18:19], 0, v[64:65]
	v_lshl_add_u64 v[68:69], v[66:67], 2, s[12:13]
	global_load_dword v80, v[68:69], off sc1
	v_lshlrev_b64 v[66:67], 10, v[66:67]
	v_lshl_add_u64 v[76:77], v[66:67], 0, v[156:157]
	v_lshl_add_u64 v[78:79], v[76:77], 2, s[36:37]
	global_load_dwordx4 v[68:71], v[78:79], off
	global_load_dwordx4 v[72:75], v[78:79], off offset:16
	v_mov_b32_e32 v67, 0x358637bd
	v_lshlrev_b64 v[76:77], 1, v[76:77]
	s_waitcnt vmcnt(2)
	v_fmamk_f32 v66, v80, 0x3a800000, v67
	v_mul_f32_e32 v80, 0x4f800000, v66
	v_cmp_gt_f32_e32 vcc, s2, v66
	s_nop 1
	v_cndmask_b32_e32 v80, v66, v80, vcc
	v_sqrt_f32_e32 v81, v80
	v_mov_b32_e32 v66, 0x260
	v_add_u32_e32 v82, -1, v81
	v_add_u32_e32 v83, 1, v81
	v_fma_f32 v84, -v82, v81, v80
	v_fma_f32 v85, -v83, v81, v80
	v_cmp_ge_f32_e64 s[0:1], 0, v84
	s_nop 1
	v_cndmask_b32_e64 v81, v81, v82, s[0:1]
	v_cmp_lt_f32_e64 s[0:1], 0, v85
	s_nop 1
	v_cndmask_b32_e64 v81, v81, v83, s[0:1]
	v_mul_f32_e32 v82, 0x37800000, v81
	v_cndmask_b32_e32 v81, v81, v82, vcc
	v_cmp_class_f32_e32 vcc, v80, v66
	s_nop 1
	v_cndmask_b32_e32 v82, v81, v80, vcc
	v_div_scale_f32 v83, s[0:1], v82, v82, 1.0
	v_rcp_f32_e32 v84, v83
	v_div_scale_f32 v85, vcc, 1.0, v82, 1.0
	v_lshl_add_u64 v[80:81], s[10:11], 0, v[76:77]
	v_fma_f32 v86, -v83, v84, 1.0
	v_fmac_f32_e32 v84, v86, v84
	v_mul_f32_e32 v86, v85, v84
	v_fma_f32 v87, -v83, v86, v85
	v_fmac_f32_e32 v86, v87, v84
	v_fma_f32 v83, -v83, v86, v85
	v_div_fmas_f32 v83, v83, v84, v86
	v_div_fixup_f32 v82, v83, v82, 1.0
	v_pk_mul_f32 v[60:61], v[60:61], v[82:83] op_sel_hi:[1,0]
	v_pk_mul_f32 v[62:63], v[62:63], v[82:83] op_sel_hi:[1,0]
	v_pk_mul_f32 v[56:57], v[56:57], v[82:83] op_sel_hi:[1,0]
	v_pk_mul_f32 v[58:59], v[58:59], v[82:83] op_sel_hi:[1,0]
	s_waitcnt vmcnt(1)
; DI unsigned pk_bf16(float lo, float hi) { f32x2 v = {lo, hi}; bf16x2_t b = __builtin_convertvector(v, bf16x2_t); return __builtin_bit_cast(unsigned, b); }
; DI float bflo(unsigned w) { return __uint_as_float(w << 16); }
; DI float bfhi(unsigned w) { return __uint_as_float(w & 0xffff0000u); }
;     __device__ __forceinline__ void fused(f32x4 (&acc)[2][2][4][2], const pg8::Unit& u, int wr, int wc, int fr, int fq, PG8_LAS unsigned char* lds, int wid, int lane) const {
;     ...
;         for (int ai = 0; ai < 2; ++ai)
; #pragma unroll
;             for (int m = 0; m < 4; ++m) {
;                 const int rl = ai * 128 + wr * 64 + m * 16 + fr; const size_t row = (size_t)u.pm * 256 + rl;
;                 const float rm = 1.f / sqrtf(__hip_atomic_load(ssqm + row, __ATOMIC_RELAXED, __HIP_MEMORY_SCOPE_AGENT) * (1.f / DM) + RMS_EPS);
;                 float sh = 0.f;
; #pragma unroll
;                 for (int bj = 0; bj < 2; ++bj) {
;                     const size_t off = row * DM + colb + bj * 128;
;                     f32x4 h0, h1;
;                     if (IN16) { const u32x4 hw = *(const u32x4*)((const bf16_t*)hin + off); h0 = (f32x4){bflo(hw.x), bfhi(hw.x), bflo(hw.y), bfhi(hw.y)}; h1 = (f32x4){bflo(hw.z), bfhi(hw.z), bflo(hw.w), bfhi(hw.w)}; }
;                     else { h0 = *(const f32x4*)((const float*)hin + off); h1 = *(const f32x4*)((const float*)hin + off + 4); }
;                     h0 = h0 + acc[ai][bj][m][0] * rm * gv[bj][0]; h1 = h1 + acc[ai][bj][m][1] * rm * gv[bj][1];
;                     sh += ((h0[0] * h0[0] + h0[1] * h0[1]) + (h0[2] * h0[2] + h0[3] * h0[3])) + ((h1[0] * h1[0] + h1[1] * h1[1]) + (h1[2] * h1[2] + h1[3] * h1[3]));
;                     if (OUT16) { u32x4 w; w.x = pk_bf16(h0[0], h0[1]); w.y = pk_bf16(h0[2], h0[3]); w.z = pk_bf16(h1[0], h1[1]); w.w = pk_bf16(h1[2], h1[3]); *(u32x4*)((bf16_t*)hout + off) = w; }
;                     else { *(f32x4*)((float*)hout + off) = h0; *(f32x4*)((float*)hout + off + 4) = h1; }
;                 }
;                 if (ssqh) { sh += __shfl_xor(sh, 16); sh += __shfl_xor(sh, 32); if (fq == 0) red[rl * 4 + wc] = sh; }
	v_pk_fma_f32 v[70:71], v[110:111], v[62:63], v[70:71]
	v_pk_fma_f32 v[68:69], v[108:109], v[60:61], v[68:69]
	s_waitcnt vmcnt(0)
	v_pk_fma_f32 v[74:75], v[106:107], v[58:59], v[74:75]
	v_pk_fma_f32 v[72:73], v[104:105], v[56:57], v[72:73]
	v_cvt_pk_bf16_f32 v56, v68, v69
	v_cvt_pk_bf16_f32 v57, v70, v71
	v_cvt_pk_bf16_f32 v58, v72, v73
	v_cvt_pk_bf16_f32 v59, v74, v75
	global_store_dwordx4 v[80:81], v[56:59], off
	global_load_dwordx4 v[56:59], v[78:79], off offset:512
	s_nop 0
	global_load_dwordx4 v[60:63], v[78:79], off offset:528
	v_pk_mul_f32 v[52:53], v[52:53], v[82:83] op_sel_hi:[1,0]
	v_pk_mul_f32 v[54:55], v[54:55], v[82:83] op_sel_hi:[1,0]
	v_pk_mul_f32 v[48:49], v[48:49], v[82:83] op_sel_hi:[1,0]
	v_pk_mul_f32 v[50:51], v[50:51], v[82:83] op_sel_hi:[1,0]
	v_mul_f32_e32 v69, v69, v69
	v_mul_f32_e32 v71, v71, v71
	v_mul_f32_e32 v73, v73, v73
	v_mul_f32_e32 v75, v75, v75
	v_fmac_f32_e32 v69, v68, v68
	v_fmac_f32_e32 v71, v70, v70
	v_fmac_f32_e32 v73, v72, v72
	v_fmac_f32_e32 v75, v74, v74
	v_add_f32_e32 v68, v69, v71
	v_add_f32_e32 v69, v73, v75
	v_add_f32_e32 v68, v68, v69
	v_or_b32_e32 v76, 0x100, v76
	s_waitcnt vmcnt(1)
	v_pk_fma_f32 v[54:55], v[102:103], v[54:55], v[58:59]
	v_pk_fma_f32 v[52:53], v[100:101], v[52:53], v[56:57]
	s_waitcnt vmcnt(0)
	v_pk_fma_f32 v[56:57], v[98:99], v[50:51], v[62:63]
	v_pk_fma_f32 v[48:49], v[96:97], v[48:49], v[60:61]
	v_mul_f32_e32 v50, v53, v53
	v_mul_f32_e32 v51, v55, v55
	v_mul_f32_e32 v58, v49, v49
	v_mul_f32_e32 v59, v57, v57
	v_fmac_f32_e32 v50, v52, v52
	v_fmac_f32_e32 v51, v54, v54
	v_fmac_f32_e32 v58, v48, v48
	v_fmac_f32_e32 v59, v56, v56
	v_add_f32_e32 v50, v50, v51
	v_add_f32_e32 v51, v58, v59
	v_add_f32_e32 v50, v50, v51
	v_add_f32_e32 v58, v68, v50
	v_mov_b32_e32 v59, v58
	s_nop 1
	v_permlane16_swap_b32 v59, v58
	s_nop 0
	v_cvt_pk_bf16_f32 v50, v52, v53
	v_cvt_pk_bf16_f32 v52, v48, v49
	v_cvt_pk_bf16_f32 v51, v54, v55
	v_cvt_pk_bf16_f32 v53, v56, v57
	s_waitcnt lgkmcnt(0)
	v_add_f32_e32 v48, v58, v59
	v_mov_b32_e32 v49, v48
	s_nop 1
	v_permlane32_swap_b32 v49, v48
	s_nop 0
	v_lshl_add_u64 v[54:55], s[10:11], 0, v[76:77]
	global_store_dwordx4 v[54:55], v[50:53], off
	s_and_saveexec_b64 s[0:1], s[4:5]
	s_cbranch_execz .LBB0_921
	v_lshl_add_u32 v50, v64, 4, s22
	s_waitcnt lgkmcnt(0)
	v_add_f32_e32 v48, v48, v49
	ds_write_b32 v50, v48
.LBB0_921:
	s_or_b64 exec, exec, s[0:1]
	v_add_u32_e32 v64, 0x90, v152
	s_waitcnt lgkmcnt(0)
	v_lshl_add_u64 v[48:49], s[18:19], 0, v[64:65]
	v_lshl_add_u64 v[50:51], v[48:49], 2, s[12:13]
	global_load_dword v60, v[50:51], off sc1
	v_lshlrev_b64 v[48:49], 10, v[48:49]
	v_lshl_add_u64 v[56:57], v[48:49], 0, v[156:157]
	v_lshl_add_u64 v[58:59], v[56:57], 2, s[36:37]
	global_load_dwordx4 v[48:51], v[58:59], off
	global_load_dwordx4 v[52:55], v[58:59], off offset:16
	v_lshlrev_b64 v[56:57], 1, v[56:57]
	s_waitcnt vmcnt(2)
	v_fmac_f32_e32 v67, 0x3a800000, v60
	v_mul_f32_e32 v60, 0x4f800000, v67
	v_cmp_gt_f32_e32 vcc, s2, v67
	s_nop 1
	v_cndmask_b32_e32 v60, v67, v60, vcc
	v_sqrt_f32_e32 v61, v60
	s_nop 0
	v_add_u32_e32 v62, -1, v61
	v_add_u32_e32 v63, 1, v61
	v_fma_f32 v65, -v62, v61, v60
	v_fma_f32 v67, -v63, v61, v60
	v_cmp_ge_f32_e64 s[0:1], 0, v65
	s_nop 1
	v_cndmask_b32_e64 v61, v61, v62, s[0:1]
	v_cmp_lt_f32_e64 s[0:1], 0, v67
	s_nop 1
	v_cndmask_b32_e64 v61, v61, v63, s[0:1]
	v_mul_f32_e32 v62, 0x37800000, v61
	v_cndmask_b32_e32 v61, v61, v62, vcc
	v_cmp_class_f32_e32 vcc, v60, v66
	s_nop 1
	v_cndmask_b32_e32 v62, v61, v60, vcc
	v_div_scale_f32 v63, s[0:1], v62, v62, 1.0
	v_rcp_f32_e32 v65, v63
	v_div_scale_f32 v66, vcc, 1.0, v62, 1.0
	v_lshl_add_u64 v[60:61], s[10:11], 0, v[56:57]
	v_fma_f32 v67, -v63, v65, 1.0
	v_fmac_f32_e32 v65, v67, v65
	v_mul_f32_e32 v67, v66, v65
	v_fma_f32 v68, -v63, v67, v66
	v_fmac_f32_e32 v67, v68, v65
	v_fma_f32 v63, -v63, v67, v66
	v_div_fmas_f32 v63, v63, v65, v67
	v_div_fixup_f32 v62, v63, v62, 1.0
	v_pk_mul_f32 v[44:45], v[44:45], v[62:63] op_sel_hi:[1,0]
	v_pk_mul_f32 v[46:47], v[46:47], v[62:63] op_sel_hi:[1,0]
	v_pk_mul_f32 v[40:41], v[40:41], v[62:63] op_sel_hi:[1,0]
	v_pk_mul_f32 v[42:43], v[42:43], v[62:63] op_sel_hi:[1,0]
	s_waitcnt vmcnt(1)
	v_pk_fma_f32 v[50:51], v[110:111], v[46:47], v[50:51]
	v_pk_fma_f32 v[48:49], v[108:109], v[44:45], v[48:49]
	s_waitcnt vmcnt(0)
	v_pk_fma_f32 v[54:55], v[106:107], v[42:43], v[54:55]
	v_pk_fma_f32 v[52:53], v[104:105], v[40:41], v[52:53]
	v_cvt_pk_bf16_f32 v40, v48, v49
	v_cvt_pk_bf16_f32 v41, v50, v51
	v_cvt_pk_bf16_f32 v42, v52, v53
	v_cvt_pk_bf16_f32 v43, v54, v55
	global_store_dwordx4 v[60:61], v[40:43], off
	global_load_dwordx4 v[40:43], v[58:59], off offset:512
	s_nop 0
	global_load_dwordx4 v[44:47], v[58:59], off offset:528
	v_pk_mul_f32 v[36:37], v[36:37], v[62:63] op_sel_hi:[1,0]
	v_pk_mul_f32 v[38:39], v[38:39], v[62:63] op_sel_hi:[1,0]
	v_pk_mul_f32 v[32:33], v[32:33], v[62:63] op_sel_hi:[1,0]
	v_pk_mul_f32 v[34:35], v[34:35], v[62:63] op_sel_hi:[1,0]
	v_mul_f32_e32 v49, v49, v49
	v_mul_f32_e32 v51, v51, v51
	v_mul_f32_e32 v53, v53, v53
	v_mul_f32_e32 v55, v55, v55
	v_fmac_f32_e32 v49, v48, v48
	v_fmac_f32_e32 v51, v50, v50
	v_fmac_f32_e32 v53, v52, v52
	v_fmac_f32_e32 v55, v54, v54
	v_add_f32_e32 v48, v49, v51
	v_add_f32_e32 v49, v53, v55
	v_add_f32_e32 v48, v48, v49
	v_or_b32_e32 v56, 0x100, v56
	s_waitcnt vmcnt(1)
	v_pk_fma_f32 v[38:39], v[102:103], v[38:39], v[42:43]
	v_pk_fma_f32 v[36:37], v[100:101], v[36:37], v[40:41]
	s_waitcnt vmcnt(0)
	v_pk_fma_f32 v[40:41], v[98:99], v[34:35], v[46:47]
	v_pk_fma_f32 v[32:33], v[96:97], v[32:33], v[44:45]
	v_mul_f32_e32 v34, v37, v37
	v_mul_f32_e32 v35, v39, v39
	v_mul_f32_e32 v42, v33, v33
	v_mul_f32_e32 v43, v41, v41
	v_fmac_f32_e32 v34, v36, v36
	v_fmac_f32_e32 v35, v38, v38
	v_fmac_f32_e32 v42, v32, v32
	v_fmac_f32_e32 v43, v40, v40
	v_add_f32_e32 v34, v34, v35
	v_add_f32_e32 v35, v42, v43
	v_add_f32_e32 v34, v34, v35
	v_add_f32_e32 v42, v48, v34
	v_mov_b32_e32 v43, v42
	s_nop 1
	v_permlane16_swap_b32 v43, v42
	s_nop 0
	v_cvt_pk_bf16_f32 v34, v36, v37
	v_cvt_pk_bf16_f32 v36, v32, v33
	v_cvt_pk_bf16_f32 v35, v38, v39
	v_cvt_pk_bf16_f32 v37, v40, v41
	s_waitcnt lgkmcnt(0)
	v_add_f32_e32 v32, v42, v43
	v_mov_b32_e32 v33, v32
	s_nop 1
	v_permlane32_swap_b32 v33, v32
	s_nop 0
	v_lshl_add_u64 v[38:39], s[10:11], 0, v[56:57]
	global_store_dwordx4 v[38:39], v[34:37], off
	s_and_saveexec_b64 s[0:1], s[4:5]
	s_cbranch_execz .LBB0_923
	v_lshl_add_u32 v34, v64, 4, s22
	s_waitcnt lgkmcnt(0)
	v_add_f32_e32 v32, v32, v33
	ds_write_b32 v34, v32
; DI unsigned pk_bf16(float lo, float hi) { f32x2 v = {lo, hi}; bf16x2_t b = __builtin_convertvector(v, bf16x2_t); return __builtin_bit_cast(unsigned, b); }
; DI float bflo(unsigned w) { return __uint_as_float(w << 16); }
; DI float bfhi(unsigned w) { return __uint_as_float(w & 0xffff0000u); }
;     __device__ __forceinline__ void fused(f32x4 (&acc)[2][2][4][2], const pg8::Unit& u, int wr, int wc, int fr, int fq, PG8_LAS unsigned char* lds, int wid, int lane) const {
;     ...
;                 const int rl = ai * 128 + wr * 64 + m * 16 + fr; const size_t row = (size_t)u.pm * 256 + rl;
;                 const float rm = 1.f / sqrtf(__hip_atomic_load(ssqm + row, __ATOMIC_RELAXED, __HIP_MEMORY_SCOPE_AGENT) * (1.f / DM) + RMS_EPS);
;                 float sh = 0.f;
; #pragma unroll
;                 for (int bj = 0; bj < 2; ++bj) {
;                     const size_t off = row * DM + colb + bj * 128;
;                     f32x4 h0, h1;
;                     if (IN16) { const u32x4 hw = *(const u32x4*)((const bf16_t*)hin + off); h0 = (f32x4){bflo(hw.x), bfhi(hw.x), bflo(hw.y), bfhi(hw.y)}; h1 = (f32x4){bflo(hw.z), bfhi(hw.z), bflo(hw.w), bfhi(hw.w)}; }
;                     else { h0 = *(const f32x4*)((const float*)hin + off); h1 = *(const f32x4*)((const float*)hin + off + 4); }
;                     h0 = h0 + acc[ai][bj][m][0] * rm * gv[bj][0]; h1 = h1 + acc[ai][bj][m][1] * rm * gv[bj][1];
;                     sh += ((h0[0] * h0[0] + h0[1] * h0[1]) + (h0[2] * h0[2] + h0[3] * h0[3])) + ((h1[0] * h1[0] + h1[1] * h1[1]) + (h1[2] * h1[2] + h1[3] * h1[3]));
;                     if (OUT16) { u32x4 w; w.x = pk_bf16(h0[0], h0[1]); w.y = pk_bf16(h0[2], h0[3]); w.z = pk_bf16(h1[0], h1[1]); w.w = pk_bf16(h1[2], h1[3]); *(u32x4*)((bf16_t*)hout + off) = w; }
;                     else { *(f32x4*)((float*)hout + off) = h0; *(f32x4*)((float*)hout + off + 4) = h1; }
;                 }
;                 if (ssqh) { sh += __shfl_xor(sh, 16); sh += __shfl_xor(sh, 32); if (fq == 0) red[rl * 4 + wc] = sh; }
.LBB0_923:
	s_or_b64 exec, exec, s[0:1]
	v_add_u32_e32 v32, 0xa0, v152
	s_waitcnt lgkmcnt(0)
	v_mov_b32_e32 v33, 0
	v_lshl_add_u64 v[34:35], s[18:19], 0, v[32:33]
	v_lshl_add_u64 v[36:37], v[34:35], 2, s[12:13]
	global_load_dword v48, v[36:37], off sc1
	v_lshlrev_b64 v[34:35], 10, v[34:35]
	v_lshl_add_u64 v[44:45], v[34:35], 0, v[156:157]
	v_lshl_add_u64 v[46:47], v[44:45], 2, s[36:37]
	global_load_dwordx4 v[36:39], v[46:47], off
	global_load_dwordx4 v[40:43], v[46:47], off offset:16
	v_mov_b32_e32 v35, 0x358637bd
	v_lshlrev_b64 v[44:45], 1, v[44:45]
	s_waitcnt vmcnt(2)
	v_fmamk_f32 v34, v48, 0x3a800000, v35
	v_mul_f32_e32 v48, 0x4f800000, v34
	v_cmp_gt_f32_e32 vcc, s2, v34
	s_nop 1
	v_cndmask_b32_e32 v48, v34, v48, vcc
	v_sqrt_f32_e32 v49, v48
	v_mov_b32_e32 v34, 0x260
	v_add_u32_e32 v50, -1, v49
	v_add_u32_e32 v51, 1, v49
	v_fma_f32 v52, -v50, v49, v48
	v_fma_f32 v53, -v51, v49, v48
	v_cmp_ge_f32_e64 s[0:1], 0, v52
	s_nop 1
	v_cndmask_b32_e64 v49, v49, v50, s[0:1]
	v_cmp_lt_f32_e64 s[0:1], 0, v53
	s_nop 1
	v_cndmask_b32_e64 v49, v49, v51, s[0:1]
	v_mul_f32_e32 v50, 0x37800000, v49
	v_cndmask_b32_e32 v49, v49, v50, vcc
	v_cmp_class_f32_e32 vcc, v48, v34
	s_nop 1
	v_cndmask_b32_e32 v50, v49, v48, vcc
	v_div_scale_f32 v51, s[0:1], v50, v50, 1.0
	v_rcp_f32_e32 v52, v51
	v_div_scale_f32 v53, vcc, 1.0, v50, 1.0
	v_lshl_add_u64 v[48:49], s[10:11], 0, v[44:45]
	v_fma_f32 v54, -v51, v52, 1.0
	v_fmac_f32_e32 v52, v54, v52
	v_mul_f32_e32 v54, v53, v52
	v_fma_f32 v55, -v51, v54, v53
	v_fmac_f32_e32 v54, v55, v52
	v_fma_f32 v51, -v51, v54, v53
	v_div_fmas_f32 v51, v51, v52, v54
	v_div_fixup_f32 v50, v51, v50, 1.0
	v_pk_mul_f32 v[28:29], v[28:29], v[50:51] op_sel_hi:[1,0]
	v_pk_mul_f32 v[30:31], v[30:31], v[50:51] op_sel_hi:[1,0]
	v_pk_mul_f32 v[24:25], v[24:25], v[50:51] op_sel_hi:[1,0]
	v_pk_mul_f32 v[26:27], v[26:27], v[50:51] op_sel_hi:[1,0]
	s_waitcnt vmcnt(1)
	v_pk_fma_f32 v[38:39], v[110:111], v[30:31], v[38:39]
	v_pk_fma_f32 v[36:37], v[108:109], v[28:29], v[36:37]
	s_waitcnt vmcnt(0)
	v_pk_fma_f32 v[42:43], v[106:107], v[26:27], v[42:43]
	v_pk_fma_f32 v[40:41], v[104:105], v[24:25], v[40:41]
	v_cvt_pk_bf16_f32 v24, v36, v37
	v_cvt_pk_bf16_f32 v25, v38, v39
	v_cvt_pk_bf16_f32 v26, v40, v41
	v_cvt_pk_bf16_f32 v27, v42, v43
	global_store_dwordx4 v[48:49], v[24:27], off
	global_load_dwordx4 v[24:27], v[46:47], off offset:512
	s_nop 0
	global_load_dwordx4 v[28:31], v[46:47], off offset:528
	v_pk_mul_f32 v[20:21], v[20:21], v[50:51] op_sel_hi:[1,0]
	v_pk_mul_f32 v[22:23], v[22:23], v[50:51] op_sel_hi:[1,0]
	v_pk_mul_f32 v[16:17], v[16:17], v[50:51] op_sel_hi:[1,0]
	v_pk_mul_f32 v[18:19], v[18:19], v[50:51] op_sel_hi:[1,0]
	v_mul_f32_e32 v37, v37, v37
	v_mul_f32_e32 v39, v39, v39
	v_mul_f32_e32 v41, v41, v41
	v_mul_f32_e32 v43, v43, v43
	v_fmac_f32_e32 v37, v36, v36
	v_fmac_f32_e32 v39, v38, v38
	v_fmac_f32_e32 v41, v40, v40
	v_fmac_f32_e32 v43, v42, v42
	v_add_f32_e32 v36, v37, v39
	v_add_f32_e32 v37, v41, v43
	v_add_f32_e32 v36, v36, v37
	v_or_b32_e32 v44, 0x100, v44
	s_waitcnt vmcnt(1)
	v_pk_fma_f32 v[22:23], v[102:103], v[22:23], v[26:27]
	v_pk_fma_f32 v[20:21], v[100:101], v[20:21], v[24:25]
	s_waitcnt vmcnt(0)
	v_pk_fma_f32 v[24:25], v[98:99], v[18:19], v[30:31]
	v_pk_fma_f32 v[16:17], v[96:97], v[16:17], v[28:29]
	v_mul_f32_e32 v18, v21, v21
	v_mul_f32_e32 v19, v23, v23
	v_mul_f32_e32 v26, v17, v17
	v_mul_f32_e32 v27, v25, v25
	v_fmac_f32_e32 v18, v20, v20
	v_fmac_f32_e32 v19, v22, v22
	v_fmac_f32_e32 v26, v16, v16
	v_fmac_f32_e32 v27, v24, v24
	v_add_f32_e32 v18, v18, v19
	v_add_f32_e32 v19, v26, v27
	v_add_f32_e32 v18, v18, v19
	v_add_f32_e32 v26, v36, v18
	v_mov_b32_e32 v27, v26
	s_nop 1
	v_permlane16_swap_b32 v27, v26
	s_nop 0
	v_cvt_pk_bf16_f32 v18, v20, v21
	v_cvt_pk_bf16_f32 v20, v16, v17
	v_cvt_pk_bf16_f32 v19, v22, v23
	v_cvt_pk_bf16_f32 v21, v24, v25
	s_waitcnt lgkmcnt(0)
	v_add_f32_e32 v16, v26, v27
	v_mov_b32_e32 v17, v16
	s_nop 1
	v_permlane32_swap_b32 v17, v16
	s_nop 0
	v_lshl_add_u64 v[22:23], s[10:11], 0, v[44:45]
	global_store_dwordx4 v[22:23], v[18:21], off
	s_and_saveexec_b64 s[0:1], s[4:5]
	s_cbranch_execz .LBB0_925
	v_lshl_add_u32 v18, v32, 4, s22
	s_waitcnt lgkmcnt(0)
	v_add_f32_e32 v16, v16, v17
	ds_write_b32 v18, v16
; DI unsigned pk_bf16(float lo, float hi) { f32x2 v = {lo, hi}; bf16x2_t b = __builtin_convertvector(v, bf16x2_t); return __builtin_bit_cast(unsigned, b); }
; DI float bflo(unsigned w) { return __uint_as_float(w << 16); }
; DI float bfhi(unsigned w) { return __uint_as_float(w & 0xffff0000u); }
;     __device__ __forceinline__ void fused(f32x4 (&acc)[2][2][4][2], const pg8::Unit& u, int wr, int wc, int fr, int fq, PG8_LAS unsigned char* lds, int wid, int lane) const {
;     ...
;                 const int rl = ai * 128 + wr * 64 + m * 16 + fr; const size_t row = (size_t)u.pm * 256 + rl;
;                 const float rm = 1.f / sqrtf(__hip_atomic_load(ssqm + row, __ATOMIC_RELAXED, __HIP_MEMORY_SCOPE_AGENT) * (1.f / DM) + RMS_EPS);
;                 float sh = 0.f;
; #pragma unroll
;                 for (int bj = 0; bj < 2; ++bj) {
;                     const size_t off = row * DM + colb + bj * 128;
;                     f32x4 h0, h1;
;                     if (IN16) { const u32x4 hw = *(const u32x4*)((const bf16_t*)hin + off); h0 = (f32x4){bflo(hw.x), bfhi(hw.x), bflo(hw.y), bfhi(hw.y)}; h1 = (f32x4){bflo(hw.z), bfhi(hw.z), bflo(hw.w), bfhi(hw.w)}; }
;                     else { h0 = *(const f32x4*)((const float*)hin + off); h1 = *(const f32x4*)((const float*)hin + off + 4); }
;                     h0 = h0 + acc[ai][bj][m][0] * rm * gv[bj][0]; h1 = h1 + acc[ai][bj][m][1] * rm * gv[bj][1];
;                     sh += ((h0[0] * h0[0] + h0[1] * h0[1]) + (h0[2] * h0[2] + h0[3] * h0[3])) + ((h1[0] * h1[0] + h1[1] * h1[1]) + (h1[2] * h1[2] + h1[3] * h1[3]));
;                     if (OUT16) { u32x4 w; w.x = pk_bf16(h0[0], h0[1]); w.y = pk_bf16(h0[2], h0[3]); w.z = pk_bf16(h1[0], h1[1]); w.w = pk_bf16(h1[2], h1[3]); *(u32x4*)((bf16_t*)hout + off) = w; }
;                     else { *(f32x4*)((float*)hout + off) = h0; *(f32x4*)((float*)hout + off + 4) = h1; }
;                 }
;                 if (ssqh) { sh += __shfl_xor(sh, 16); sh += __shfl_xor(sh, 32); if (fq == 0) red[rl * 4 + wc] = sh; }
.LBB0_925:
	s_or_b64 exec, exec, s[0:1]
	v_add_u32_e32 v32, 0xb0, v152
	s_waitcnt lgkmcnt(0)
	v_lshl_add_u64 v[16:17], s[18:19], 0, v[32:33]
	v_lshl_add_u64 v[18:19], v[16:17], 2, s[12:13]
	global_load_dword v28, v[18:19], off sc1
	v_lshlrev_b64 v[16:17], 10, v[16:17]
	v_lshl_add_u64 v[24:25], v[16:17], 0, v[156:157]
	v_lshl_add_u64 v[26:27], v[24:25], 2, s[36:37]
	global_load_dwordx4 v[16:19], v[26:27], off
	global_load_dwordx4 v[20:23], v[26:27], off offset:16
	v_lshlrev_b64 v[24:25], 1, v[24:25]
	s_waitcnt vmcnt(2)
	v_fmac_f32_e32 v35, 0x3a800000, v28
	v_mul_f32_e32 v28, 0x4f800000, v35
	v_cmp_gt_f32_e32 vcc, s2, v35
	s_nop 1
	v_cndmask_b32_e32 v28, v35, v28, vcc
	v_sqrt_f32_e32 v29, v28
	s_nop 0
	v_add_u32_e32 v30, -1, v29
	v_add_u32_e32 v31, 1, v29
	v_fma_f32 v33, -v30, v29, v28
	v_fma_f32 v35, -v31, v29, v28
	v_cmp_ge_f32_e64 s[0:1], 0, v33
	s_nop 1
	v_cndmask_b32_e64 v29, v29, v30, s[0:1]
	v_cmp_lt_f32_e64 s[0:1], 0, v35
	s_nop 1
	v_cndmask_b32_e64 v29, v29, v31, s[0:1]
	v_mul_f32_e32 v30, 0x37800000, v29
	v_cndmask_b32_e32 v29, v29, v30, vcc
	v_cmp_class_f32_e32 vcc, v28, v34
	s_nop 1
	v_cndmask_b32_e32 v30, v29, v28, vcc
	v_div_scale_f32 v31, s[0:1], v30, v30, 1.0
	v_rcp_f32_e32 v33, v31
	v_div_scale_f32 v34, vcc, 1.0, v30, 1.0
	v_lshl_add_u64 v[28:29], s[10:11], 0, v[24:25]
	v_fma_f32 v35, -v31, v33, 1.0
	v_fmac_f32_e32 v33, v35, v33
	v_mul_f32_e32 v35, v34, v33
	v_fma_f32 v36, -v31, v35, v34
	v_fmac_f32_e32 v35, v36, v33
	v_fma_f32 v31, -v31, v35, v34
	v_div_fmas_f32 v31, v31, v33, v35
	v_div_fixup_f32 v30, v31, v30, 1.0
	v_pk_mul_f32 v[12:13], v[12:13], v[30:31] op_sel_hi:[1,0]
	v_pk_mul_f32 v[14:15], v[14:15], v[30:31] op_sel_hi:[1,0]
	v_pk_mul_f32 v[8:9], v[8:9], v[30:31] op_sel_hi:[1,0]
	v_pk_mul_f32 v[10:11], v[10:11], v[30:31] op_sel_hi:[1,0]
	s_waitcnt vmcnt(1)
	v_pk_fma_f32 v[18:19], v[110:111], v[14:15], v[18:19]
	v_pk_fma_f32 v[16:17], v[108:109], v[12:13], v[16:17]
	s_waitcnt vmcnt(0)
	v_pk_fma_f32 v[22:23], v[106:107], v[10:11], v[22:23]
	v_pk_fma_f32 v[20:21], v[104:105], v[8:9], v[20:21]
	v_cvt_pk_bf16_f32 v8, v16, v17
	v_cvt_pk_bf16_f32 v9, v18, v19
	v_cvt_pk_bf16_f32 v10, v20, v21
	v_cvt_pk_bf16_f32 v11, v22, v23
	global_store_dwordx4 v[28:29], v[8:11], off
	global_load_dwordx4 v[8:11], v[26:27], off offset:512
	s_nop 0
	global_load_dwordx4 v[12:15], v[26:27], off offset:528
	v_pk_mul_f32 v[4:5], v[4:5], v[30:31] op_sel_hi:[1,0]
	v_pk_mul_f32 v[6:7], v[6:7], v[30:31] op_sel_hi:[1,0]
	v_pk_mul_f32 v[0:1], v[0:1], v[30:31] op_sel_hi:[1,0]
	v_pk_mul_f32 v[2:3], v[2:3], v[30:31] op_sel_hi:[1,0]
	v_mul_f32_e32 v17, v17, v17
	v_mul_f32_e32 v19, v19, v19
	v_mul_f32_e32 v21, v21, v21
	v_mul_f32_e32 v23, v23, v23
	v_fmac_f32_e32 v17, v16, v16
	v_fmac_f32_e32 v19, v18, v18
	v_fmac_f32_e32 v21, v20, v20
	v_fmac_f32_e32 v23, v22, v22
	v_add_f32_e32 v16, v17, v19
	v_add_f32_e32 v17, v21, v23
	v_add_f32_e32 v16, v16, v17
	v_or_b32_e32 v24, 0x100, v24
	s_waitcnt vmcnt(1)
	v_pk_fma_f32 v[6:7], v[102:103], v[6:7], v[10:11]
	v_pk_fma_f32 v[4:5], v[100:101], v[4:5], v[8:9]
	s_waitcnt vmcnt(0)
	v_pk_fma_f32 v[8:9], v[98:99], v[2:3], v[14:15]
	v_pk_fma_f32 v[0:1], v[96:97], v[0:1], v[12:13]
	v_mul_f32_e32 v2, v5, v5
	v_mul_f32_e32 v3, v7, v7
	v_mul_f32_e32 v10, v1, v1
	v_mul_f32_e32 v11, v9, v9
	v_fmac_f32_e32 v2, v4, v4
	v_fmac_f32_e32 v3, v6, v6
	v_fmac_f32_e32 v10, v0, v0
	v_fmac_f32_e32 v11, v8, v8
	v_add_f32_e32 v2, v2, v3
	v_add_f32_e32 v3, v10, v11
	v_add_f32_e32 v2, v2, v3
	v_add_f32_e32 v10, v16, v2
	v_mov_b32_e32 v11, v10
	s_nop 1
	v_permlane16_swap_b32 v11, v10
	s_nop 0
	v_cvt_pk_bf16_f32 v2, v4, v5
	v_cvt_pk_bf16_f32 v4, v0, v1
	v_cvt_pk_bf16_f32 v3, v6, v7
	v_cvt_pk_bf16_f32 v5, v8, v9
	s_waitcnt lgkmcnt(0)
	v_add_f32_e32 v0, v10, v11
	v_mov_b32_e32 v1, v0
	s_nop 1
	v_permlane32_swap_b32 v1, v0
	s_nop 0
	v_lshl_add_u64 v[6:7], s[10:11], 0, v[24:25]
	global_store_dwordx4 v[6:7], v[2:5], off
	s_and_saveexec_b64 s[0:1], s[4:5]
	s_cbranch_execz .LBB0_927
	v_lshl_add_u32 v2, v32, 4, s22
	s_waitcnt lgkmcnt(0)
	v_add_f32_e32 v0, v0, v1
	ds_write_b32 v2, v0

;     __device__ __forceinline__ void fused(f32x4 (&acc)[2][2][4][2], const pg8::Unit& u, int wr, int wc, int fr, int fq, PG8_LAS unsigned char* lds, int wid, int lane) const {
;     ...
;         for (int ai = 0; ai < 2; ++ai)
; #pragma unroll
;             for (int m = 0; m < 4; ++m) {
;                 float s = 0.f;
; #pragma unroll
;                 for (int bj = 0; bj < 2; ++bj)
; #pragma unroll
;                     for (int n = 0; n < 2; ++n) { const f32x4 x = acc[ai][bj][m][n]; s += (x[0] * x[0] + x[1] * x[1]) + (x[2] * x[2] + x[3] * x[3]); }
;                 s += __shfl_xor(s, 16); s += __shfl_xor(s, 32);
;                 if (fq == 0) red[(ai * 128 + wr * 64 + m * 16 + fr) * 4 + wc] = s;
;             }
;         __syncthreads();
.LBB0_943:
	v_mbcnt_lo_u32_b32 v96, -1, 0
	v_mbcnt_hi_u32_b32 v96, -1, v96
	v_and_b32_e32 v98, 64, v96
	v_xor_b32_e32 v97, 16, v96
	v_add_u32_e32 v98, 64, v98
	v_cmp_lt_i32_e32 vcc, v97, v98
	v_mul_f32_e32 v99, v143, v143
	v_fmac_f32_e32 v99, v142, v142
	v_cndmask_b32_e32 v97, v96, v97, vcc
	v_lshlrev_b32_e32 v150, 2, v97
	v_mul_f32_e32 v97, v141, v141
	v_fmac_f32_e32 v97, v140, v140
	v_add_f32_e32 v97, v97, v99
	v_mul_f32_e32 v99, v137, v137
	v_mul_f32_e32 v100, v139, v139
	v_fmac_f32_e32 v99, v136, v136
	v_fmac_f32_e32 v100, v138, v138
	v_add_f32_e32 v99, v99, v100
	v_add_f32_e32 v97, v97, v99
	v_mul_f32_e32 v99, v133, v133
	v_mul_f32_e32 v100, v135, v135
	v_fmac_f32_e32 v99, v132, v132
	v_fmac_f32_e32 v100, v134, v134
	v_add_f32_e32 v99, v99, v100
	v_add_f32_e32 v97, v97, v99
	v_mul_f32_e32 v99, v129, v129
	v_mul_f32_e32 v100, v131, v131
	v_fmac_f32_e32 v99, v128, v128
	v_fmac_f32_e32 v100, v130, v130
	v_add_f32_e32 v99, v99, v100
	v_add_f32_e32 v97, v97, v99
	v_mov_b32_e32 v99, v97
	s_nop 1
	v_permlane16_swap_b32 v99, v97
	s_nop 0
	v_xor_b32_e32 v100, 32, v96
	v_cmp_lt_i32_e32 vcc, v100, v98
	s_lshl_b32 s0, s30, 2
	v_cmp_gt_u32_e64 s[4:5], 16, v192
	v_cndmask_b32_e32 v96, v96, v100, vcc
	v_lshlrev_b32_e32 v151, 2, v96
	s_waitcnt lgkmcnt(0)
	v_add_f32_e32 v96, v97, v99
	v_mov_b32_e32 v97, v96
	s_nop 1
	v_permlane32_swap_b32 v97, v96
	s_nop 0
	s_add_i32 s22, s0, 0
	s_barrier
	s_and_saveexec_b64 s[0:1], s[4:5]
	v_readlane_b32 s44, v251, 15
	v_readlane_b32 s45, v251, 16
	v_readlane_b32 s46, v251, 17
	v_readlane_b32 s47, v251, 18
	s_cbranch_execz .LBB0_945
	s_lshl_b32 s6, s3, 10
	s_add_i32 s6, s22, s6
	s_waitcnt lgkmcnt(0)
	v_add_f32_e32 v96, v96, v97
	v_lshl_add_u32 v97, v161, 4, s6
	ds_write_b32 v97, v96
.LBB0_945:
	s_or_b64 exec, exec, s[0:1]
	v_mul_f32_e32 v96, v125, v125
	s_waitcnt lgkmcnt(0)
	v_mul_f32_e32 v97, v127, v127
	v_fmac_f32_e32 v96, v124, v124
	v_fmac_f32_e32 v97, v126, v126
	v_add_f32_e32 v96, v96, v97
	v_mul_f32_e32 v97, v121, v121
	v_mul_f32_e32 v98, v123, v123
	v_fmac_f32_e32 v97, v120, v120
	v_fmac_f32_e32 v98, v122, v122
	v_add_f32_e32 v97, v97, v98
	v_add_f32_e32 v96, v96, v97
	v_mul_f32_e32 v97, v117, v117
	v_mul_f32_e32 v98, v119, v119
	v_fmac_f32_e32 v97, v116, v116
	v_fmac_f32_e32 v98, v118, v118
	v_add_f32_e32 v97, v97, v98
	v_add_f32_e32 v96, v96, v97
	v_mul_f32_e32 v97, v113, v113
	v_mul_f32_e32 v98, v115, v115
	v_fmac_f32_e32 v97, v112, v112
	v_fmac_f32_e32 v98, v114, v114
	v_add_f32_e32 v97, v97, v98
	v_add_f32_e32 v96, v96, v97
	v_mov_b32_e32 v97, v96
	s_nop 1
	v_permlane16_swap_b32 v97, v96
	s_nop 0
	s_waitcnt lgkmcnt(0)
	v_add_f32_e32 v96, v96, v97
	v_mov_b32_e32 v97, v96
	s_nop 1
	v_permlane32_swap_b32 v97, v96
	s_nop 0
	s_and_saveexec_b64 s[0:1], s[4:5]
	s_cbranch_execz .LBB0_947
	s_lshl_b32 s6, s3, 10
	s_add_i32 s6, s22, s6
	s_waitcnt lgkmcnt(0)
	v_add_f32_e32 v96, v96, v97
	v_lshl_add_u32 v97, v161, 4, s6
	ds_write_b32 v97, v96 offset:256
.LBB0_947:
	s_or_b64 exec, exec, s[0:1]
	v_mul_f32_e32 v96, v93, v93
	s_waitcnt lgkmcnt(0)
	v_mul_f32_e32 v97, v95, v95
	v_fmac_f32_e32 v96, v92, v92
	v_fmac_f32_e32 v97, v94, v94
	v_add_f32_e32 v96, v96, v97
	v_mul_f32_e32 v97, v89, v89
	v_mul_f32_e32 v98, v91, v91
	v_fmac_f32_e32 v97, v88, v88
	v_fmac_f32_e32 v98, v90, v90
	v_add_f32_e32 v97, v97, v98
	v_add_f32_e32 v96, v96, v97
	v_mul_f32_e32 v97, v85, v85
	v_mul_f32_e32 v98, v87, v87
	v_fmac_f32_e32 v97, v84, v84
	v_fmac_f32_e32 v98, v86, v86
	v_add_f32_e32 v97, v97, v98
	v_add_f32_e32 v96, v96, v97
	v_mul_f32_e32 v97, v81, v81
	v_mul_f32_e32 v98, v83, v83
	v_fmac_f32_e32 v97, v80, v80
	v_fmac_f32_e32 v98, v82, v82
	v_add_f32_e32 v97, v97, v98
	v_add_f32_e32 v96, v96, v97
	v_mov_b32_e32 v97, v96
	s_nop 1
	v_permlane16_swap_b32 v97, v96
	s_nop 0
	s_waitcnt lgkmcnt(0)
	v_add_f32_e32 v96, v96, v97
	v_mov_b32_e32 v97, v96
	s_nop 1
	v_permlane32_swap_b32 v97, v96
	s_nop 0
	s_and_saveexec_b64 s[0:1], s[4:5]
	s_cbranch_execz .LBB0_949
	s_lshl_b32 s6, s3, 10
	s_add_i32 s6, s22, s6
	s_waitcnt lgkmcnt(0)
	v_add_f32_e32 v96, v96, v97
	v_lshl_add_u32 v97, v161, 4, s6
	ds_write_b32 v97, v96 offset:512
.LBB0_949:
	s_or_b64 exec, exec, s[0:1]
	v_mul_f32_e32 v96, v77, v77
	s_waitcnt lgkmcnt(0)
	v_mul_f32_e32 v97, v79, v79
	v_fmac_f32_e32 v96, v76, v76
	v_fmac_f32_e32 v97, v78, v78
	v_add_f32_e32 v96, v96, v97
	v_mul_f32_e32 v97, v73, v73
	v_mul_f32_e32 v98, v75, v75
	v_fmac_f32_e32 v97, v72, v72
	v_fmac_f32_e32 v98, v74, v74
	v_add_f32_e32 v97, v97, v98
	v_add_f32_e32 v96, v96, v97
	v_mul_f32_e32 v97, v69, v69
	v_mul_f32_e32 v98, v71, v71
	v_fmac_f32_e32 v97, v68, v68
	v_fmac_f32_e32 v98, v70, v70
	v_add_f32_e32 v97, v97, v98
	v_add_f32_e32 v96, v96, v97
	v_mul_f32_e32 v97, v65, v65
	v_mul_f32_e32 v98, v67, v67
	v_fmac_f32_e32 v97, v64, v64
	v_fmac_f32_e32 v98, v66, v66
	v_add_f32_e32 v97, v97, v98
	v_add_f32_e32 v96, v96, v97
	v_mov_b32_e32 v97, v96
	s_nop 1
	v_permlane16_swap_b32 v97, v96
	s_nop 0
	s_waitcnt lgkmcnt(0)
	v_add_f32_e32 v96, v96, v97
	v_mov_b32_e32 v97, v96
	s_nop 1
	v_permlane32_swap_b32 v97, v96
	s_nop 0
	s_and_saveexec_b64 s[0:1], s[4:5]
	s_cbranch_execz .LBB0_951
	s_lshl_b32 s6, s3, 10
	s_add_i32 s6, s22, s6
	s_waitcnt lgkmcnt(0)
	v_add_f32_e32 v96, v96, v97
	v_lshl_add_u32 v97, v161, 4, s6
	ds_write_b32 v97, v96 offset:768
;     __device__ __forceinline__ void fused(f32x4 (&acc)[2][2][4][2], const pg8::Unit& u, int wr, int wc, int fr, int fq, PG8_LAS unsigned char* lds, int wid, int lane) const {
;     ...
;         for (int ai = 0; ai < 2; ++ai)
; #pragma unroll
;             for (int m = 0; m < 4; ++m) {
;                 float s = 0.f;
; #pragma unroll
;                 for (int bj = 0; bj < 2; ++bj)
; #pragma unroll
;                     for (int n = 0; n < 2; ++n) { const f32x4 x = acc[ai][bj][m][n]; s += (x[0] * x[0] + x[1] * x[1]) + (x[2] * x[2] + x[3] * x[3]); }
;                 s += __shfl_xor(s, 16); s += __shfl_xor(s, 32);
;                 if (fq == 0) red[(ai * 128 + wr * 64 + m * 16 + fr) * 4 + wc] = s;
;             }
.LBB0_951:
	s_or_b64 exec, exec, s[0:1]
	v_mul_f32_e32 v96, v61, v61
	s_waitcnt lgkmcnt(0)
	v_mul_f32_e32 v97, v63, v63
	v_fmac_f32_e32 v96, v60, v60
	v_fmac_f32_e32 v97, v62, v62
	v_add_f32_e32 v96, v96, v97
	v_mul_f32_e32 v97, v57, v57
	v_mul_f32_e32 v98, v59, v59
	v_fmac_f32_e32 v97, v56, v56
	v_fmac_f32_e32 v98, v58, v58
	v_add_f32_e32 v97, v97, v98
	v_add_f32_e32 v96, v96, v97
	v_mul_f32_e32 v97, v53, v53
	v_mul_f32_e32 v98, v55, v55
	v_fmac_f32_e32 v97, v52, v52
	v_fmac_f32_e32 v98, v54, v54
	v_add_f32_e32 v97, v97, v98
	v_add_f32_e32 v96, v96, v97
	v_mul_f32_e32 v97, v49, v49
	v_mul_f32_e32 v98, v51, v51
	v_fmac_f32_e32 v97, v48, v48
	v_fmac_f32_e32 v98, v50, v50
	v_add_f32_e32 v97, v97, v98
	v_add_f32_e32 v96, v96, v97
	v_mov_b32_e32 v97, v96
	s_nop 1
	v_permlane16_swap_b32 v97, v96
	s_nop 0
	s_waitcnt lgkmcnt(0)
	v_add_f32_e32 v96, v96, v97
	v_mov_b32_e32 v97, v96
	s_nop 1
	v_permlane32_swap_b32 v97, v96
	s_nop 0
	s_and_saveexec_b64 s[0:1], s[4:5]
	s_cbranch_execz .LBB0_953
	s_lshl_b32 s6, s3, 10
	s_add_i32 s6, s22, s6
	s_waitcnt lgkmcnt(0)
	v_add_f32_e32 v96, v96, v97
	v_lshl_add_u32 v97, v161, 4, s6
	ds_write_b32 v97, v96 offset:2048
.LBB0_953:
	s_or_b64 exec, exec, s[0:1]
	v_mul_f32_e32 v96, v45, v45
	s_waitcnt lgkmcnt(0)
	v_mul_f32_e32 v97, v47, v47
	v_fmac_f32_e32 v96, v44, v44
	v_fmac_f32_e32 v97, v46, v46
	v_add_f32_e32 v96, v96, v97
	v_mul_f32_e32 v97, v41, v41
	v_mul_f32_e32 v98, v43, v43
	v_fmac_f32_e32 v97, v40, v40
	v_fmac_f32_e32 v98, v42, v42
	v_add_f32_e32 v97, v97, v98
	v_add_f32_e32 v96, v96, v97
	v_mul_f32_e32 v97, v37, v37
	v_mul_f32_e32 v98, v39, v39
	v_fmac_f32_e32 v97, v36, v36
	v_fmac_f32_e32 v98, v38, v38
	v_add_f32_e32 v97, v97, v98
	v_add_f32_e32 v96, v96, v97
	v_mul_f32_e32 v97, v33, v33
	v_mul_f32_e32 v98, v35, v35
	v_fmac_f32_e32 v97, v32, v32
	v_fmac_f32_e32 v98, v34, v34
	v_add_f32_e32 v97, v97, v98
	v_add_f32_e32 v96, v96, v97
	v_mov_b32_e32 v97, v96
	s_nop 1
	v_permlane16_swap_b32 v97, v96
	s_nop 0
	s_waitcnt lgkmcnt(0)
	v_add_f32_e32 v96, v96, v97
	v_mov_b32_e32 v97, v96
	s_nop 1
	v_permlane32_swap_b32 v97, v96
	s_nop 0
	s_and_saveexec_b64 s[0:1], s[4:5]
	s_cbranch_execz .LBB0_955
	s_lshl_b32 s6, s3, 10
	s_add_i32 s6, s22, s6
	s_waitcnt lgkmcnt(0)
	v_add_f32_e32 v96, v96, v97
	v_lshl_add_u32 v97, v161, 4, s6
	ds_write_b32 v97, v96 offset:2304
.LBB0_955:
	s_or_b64 exec, exec, s[0:1]
	v_mul_f32_e32 v96, v29, v29
	s_waitcnt lgkmcnt(0)
	v_mul_f32_e32 v97, v31, v31
	v_fmac_f32_e32 v96, v28, v28
	v_fmac_f32_e32 v97, v30, v30
	v_add_f32_e32 v96, v96, v97
	v_mul_f32_e32 v97, v25, v25
	v_mul_f32_e32 v98, v27, v27
	v_fmac_f32_e32 v97, v24, v24
	v_fmac_f32_e32 v98, v26, v26
	v_add_f32_e32 v97, v97, v98
	v_add_f32_e32 v96, v96, v97
	v_mul_f32_e32 v97, v21, v21
	v_mul_f32_e32 v98, v23, v23
	v_fmac_f32_e32 v97, v20, v20
	v_fmac_f32_e32 v98, v22, v22
	v_add_f32_e32 v97, v97, v98
	v_add_f32_e32 v96, v96, v97
	v_mul_f32_e32 v97, v17, v17
	v_mul_f32_e32 v98, v19, v19
	v_fmac_f32_e32 v97, v16, v16
	v_fmac_f32_e32 v98, v18, v18
	v_add_f32_e32 v97, v97, v98
	v_add_f32_e32 v96, v96, v97
	v_mov_b32_e32 v97, v96
	s_nop 1
	v_permlane16_swap_b32 v97, v96
	s_nop 0
	s_waitcnt lgkmcnt(0)
	v_add_f32_e32 v96, v96, v97
	v_mov_b32_e32 v97, v96
	s_nop 1
	v_permlane32_swap_b32 v97, v96
	s_nop 0
	s_and_saveexec_b64 s[0:1], s[4:5]
	s_cbranch_execz .LBB0_957
	s_lshl_b32 s6, s3, 10
	s_add_i32 s6, s22, s6
	s_waitcnt lgkmcnt(0)
	v_add_f32_e32 v96, v96, v97
	v_lshl_add_u32 v97, v161, 4, s6
	ds_write_b32 v97, v96 offset:2560
.LBB0_957:
	s_or_b64 exec, exec, s[0:1]
	v_mul_f32_e32 v96, v13, v13
	s_waitcnt lgkmcnt(0)
	v_mul_f32_e32 v97, v15, v15
	v_fmac_f32_e32 v96, v12, v12
	v_fmac_f32_e32 v97, v14, v14
	v_add_f32_e32 v96, v96, v97
	v_mul_f32_e32 v97, v9, v9
	v_mul_f32_e32 v98, v11, v11
	v_fmac_f32_e32 v97, v8, v8
	v_fmac_f32_e32 v98, v10, v10
	v_add_f32_e32 v97, v97, v98
	v_add_f32_e32 v96, v96, v97
	v_mul_f32_e32 v97, v5, v5
	v_mul_f32_e32 v98, v7, v7
	v_fmac_f32_e32 v97, v4, v4
	v_fmac_f32_e32 v98, v6, v6
	v_add_f32_e32 v97, v97, v98
	v_add_f32_e32 v96, v96, v97
	v_mul_f32_e32 v97, v1, v1
	v_mul_f32_e32 v98, v3, v3
	v_fmac_f32_e32 v97, v0, v0
	v_fmac_f32_e32 v98, v2, v2
	v_add_f32_e32 v97, v97, v98
	v_add_f32_e32 v96, v96, v97
	v_mov_b32_e32 v97, v96
	s_nop 1
	v_permlane16_swap_b32 v97, v96
	s_nop 0
	s_waitcnt lgkmcnt(0)
	v_add_f32_e32 v96, v96, v97
	v_mov_b32_e32 v97, v96
	s_nop 1
	v_permlane32_swap_b32 v97, v96
	s_nop 0
	s_and_saveexec_b64 s[0:1], s[4:5]
	s_cbranch_execz .LBB0_959
	s_lshl_b32 s3, s3, 10
	s_add_i32 s3, s22, s3
	s_waitcnt lgkmcnt(0)
	v_add_f32_e32 v96, v96, v97
	v_lshl_add_u32 v97, v161, 4, s3
	ds_write_b32 v97, v96 offset:2816

; DI unsigned pk_bf16(float lo, float hi) { f32x2 v = {lo, hi}; bf16x2_t b = __builtin_convertvector(v, bf16x2_t); return __builtin_bit_cast(unsigned, b); }
; DI float bflo(unsigned w) { return __uint_as_float(w << 16); }
; DI float bfhi(unsigned w) { return __uint_as_float(w & 0xffff0000u); }
;     __device__ __forceinline__ void fused(f32x4 (&acc)[2][2][4][2], const pg8::Unit& u, int wr, int wc, int fr, int fq, PG8_LAS unsigned char* lds, int wid, int lane) const {
;     ...
;         const int colb = u.pn * 256 + wc * 32 + 8 * fq;
;         f32x4 gv[2][2];
; #pragma unroll
;         for (int bj = 0; bj < 2; ++bj)
; #pragma unroll
;             for (int n = 0; n < 2; ++n) gv[bj][n] = *(const f32x4*)(gA + colb + bj * 128 + 4 * n);
; #pragma unroll
;         for (int ai = 0; ai < 2; ++ai)
; #pragma unroll
;             for (int m = 0; m < 4; ++m) {
;                 const int rl = ai * 128 + wr * 64 + m * 16 + fr; const size_t row = (size_t)u.pm * 256 + rl;
;                 const float rm = 1.f / sqrtf(__hip_atomic_load(ssqm + row, __ATOMIC_RELAXED, __HIP_MEMORY_SCOPE_AGENT) * (1.f / DM) + RMS_EPS);
;                 float sh = 0.f;
; #pragma unroll
;                 for (int bj = 0; bj < 2; ++bj) {
;                     const size_t off = row * DM + colb + bj * 128;
;                     f32x4 h0, h1;
;                     if (IN16) { const u32x4 hw = *(const u32x4*)((const bf16_t*)hin + off); h0 = (f32x4){bflo(hw.x), bfhi(hw.x), bflo(hw.y), bfhi(hw.y)}; h1 = (f32x4){bflo(hw.z), bfhi(hw.z), bflo(hw.w), bfhi(hw.w)}; }
;                     else { h0 = *(const f32x4*)((const float*)hin + off); h1 = *(const f32x4*)((const float*)hin + off + 4); }
;                     h0 = h0 + acc[ai][bj][m][0] * rm * gv[bj][0]; h1 = h1 + acc[ai][bj][m][1] * rm * gv[bj][1];
;                     sh += ((h0[0] * h0[0] + h0[1] * h0[1]) + (h0[2] * h0[2] + h0[3] * h0[3])) + ((h1[0] * h1[0] + h1[1] * h1[1]) + (h1[2] * h1[2] + h1[3] * h1[3]));
;                     if (OUT16) { u32x4 w; w.x = pk_bf16(h0[0], h0[1]); w.y = pk_bf16(h0[2], h0[3]); w.z = pk_bf16(h1[0], h1[1]); w.w = pk_bf16(h1[2], h1[3]); *(u32x4*)((bf16_t*)hout + off) = w; }
;                     else { *(f32x4*)((float*)hout + off) = h0; *(f32x4*)((float*)hout + off + 4) = h1; }
;                 }
;                 if (ssqh) { sh += __shfl_xor(sh, 16); sh += __shfl_xor(sh, 32); if (fq == 0) red[rl * 4 + wc] = sh; }
.LBB0_966:
	s_or_b64 exec, exec, s[0:1]
	s_lshl_b32 s0, s30, 5
	s_lshl_b32 s1, s33, 8
	s_or_b32 s0, s1, s0
	v_or_b32_e32 v146, s0, v160
	v_ashrrev_i32_e32 v147, 31, v146
	v_mov_b32_e32 v149, 0
	v_lshl_add_u64 v[100:101], v[146:147], 2, s[14:15]
	s_lshl_b64 s[14:15], s[16:17], 8
	v_mov_b32_e32 v153, v149
	v_lshl_add_u64 v[156:157], s[14:15], 0, v[152:153]
	v_lshl_add_u64 v[158:159], v[156:157], 2, s[12:13]
	s_barrier
	global_load_dwordx4 v[104:107], v[100:101], off offset:16
	global_load_dwordx4 v[108:111], v[100:101], off
	global_load_dwordx4 v[96:99], v[100:101], off offset:528
	s_nop 0
	global_load_dwordx4 v[100:103], v[100:101], off offset:512
	v_lshlrev_b64 v[156:157], 10, v[156:157]
	global_load_dword v148, v[158:159], off sc1
	v_lshl_add_u64 v[164:165], v[156:157], 0, v[146:147]
	v_lshl_add_u64 v[166:167], v[164:165], 2, s[36:37]
	global_load_dwordx4 v[156:159], v[166:167], off
	global_load_dwordx4 v[160:163], v[166:167], off offset:16
	v_mov_b32_e32 v155, 0x358637bd
	s_mov_b32 s2, 0xf800000
	v_lshlrev_b64 v[164:165], 1, v[164:165]
	s_waitcnt vmcnt(2)
	v_fmamk_f32 v148, v148, 0x3a800000, v155
	v_mul_f32_e32 v153, 0x4f800000, v148
	v_cmp_gt_f32_e32 vcc, s2, v148
	s_nop 1
	v_cndmask_b32_e32 v148, v148, v153, vcc
	v_sqrt_f32_e32 v168, v148
	v_mov_b32_e32 v153, 0x260
	v_add_u32_e32 v169, -1, v168
	v_add_u32_e32 v170, 1, v168
	v_fma_f32 v171, -v169, v168, v148
	v_fma_f32 v172, -v170, v168, v148
	v_cmp_ge_f32_e64 s[0:1], 0, v171
	s_nop 1
	v_cndmask_b32_e64 v168, v168, v169, s[0:1]
	v_cmp_lt_f32_e64 s[0:1], 0, v172
	s_nop 1
	v_cndmask_b32_e64 v168, v168, v170, s[0:1]
	v_mul_f32_e32 v169, 0x37800000, v168
	v_cndmask_b32_e32 v168, v168, v169, vcc
	v_cmp_class_f32_e32 vcc, v148, v153
	s_nop 1
	v_cndmask_b32_e32 v148, v168, v148, vcc
	v_div_scale_f32 v170, s[0:1], v148, v148, 1.0
	v_rcp_f32_e32 v171, v170
	v_div_scale_f32 v172, vcc, 1.0, v148, 1.0
	v_lshl_add_u64 v[168:169], s[10:11], 0, v[164:165]
	v_fma_f32 v173, -v170, v171, 1.0
	v_fmac_f32_e32 v171, v173, v171
	v_mul_f32_e32 v173, v172, v171
	v_fma_f32 v174, -v170, v173, v172
	v_fmac_f32_e32 v173, v174, v171
	v_fma_f32 v170, -v170, v173, v172
	v_div_fmas_f32 v170, v170, v171, v173
	v_div_fixup_f32 v148, v170, v148, 1.0
	v_pk_mul_f32 v[140:141], v[140:141], v[148:149] op_sel_hi:[1,0]
	v_pk_mul_f32 v[142:143], v[142:143], v[148:149] op_sel_hi:[1,0]
	v_pk_mul_f32 v[136:137], v[136:137], v[148:149] op_sel_hi:[1,0]
	v_pk_mul_f32 v[138:139], v[138:139], v[148:149] op_sel_hi:[1,0]
	s_waitcnt vmcnt(1)
	v_pk_fma_f32 v[158:159], v[110:111], v[142:143], v[158:159]
	v_pk_fma_f32 v[156:157], v[108:109], v[140:141], v[156:157]
	s_waitcnt vmcnt(0)
	v_pk_fma_f32 v[162:163], v[106:107], v[138:139], v[162:163]
	v_pk_fma_f32 v[160:161], v[104:105], v[136:137], v[160:161]
	v_cvt_pk_bf16_f32 v136, v156, v157
	v_cvt_pk_bf16_f32 v137, v158, v159
	v_cvt_pk_bf16_f32 v138, v160, v161
	v_cvt_pk_bf16_f32 v139, v162, v163
	global_store_dwordx4 v[168:169], v[136:139], off
	global_load_dwordx4 v[136:139], v[166:167], off offset:512
	s_nop 0
	global_load_dwordx4 v[140:143], v[166:167], off offset:528
	v_pk_mul_f32 v[132:133], v[132:133], v[148:149] op_sel_hi:[1,0]
	v_pk_mul_f32 v[134:135], v[134:135], v[148:149] op_sel_hi:[1,0]
	v_pk_mul_f32 v[128:129], v[128:129], v[148:149] op_sel_hi:[1,0]
	v_pk_mul_f32 v[130:131], v[130:131], v[148:149] op_sel_hi:[1,0]
	v_mul_f32_e32 v148, v157, v157
	v_mul_f32_e32 v157, v159, v159
	v_mul_f32_e32 v159, v161, v161
	v_mul_f32_e32 v161, v163, v163
	v_fmac_f32_e32 v148, v156, v156
	v_fmac_f32_e32 v157, v158, v158
	v_fmac_f32_e32 v159, v160, v160
	v_fmac_f32_e32 v161, v162, v162
	v_add_f32_e32 v148, v148, v157
	v_add_f32_e32 v156, v159, v161
	v_add_f32_e32 v148, v148, v156
	v_or_b32_e32 v164, 0x100, v164
	s_waitcnt vmcnt(1)
	v_pk_fma_f32 v[134:135], v[102:103], v[134:135], v[138:139]
	v_pk_fma_f32 v[132:133], v[100:101], v[132:133], v[136:137]
	s_waitcnt vmcnt(0)
	v_pk_fma_f32 v[136:137], v[98:99], v[130:131], v[142:143]
	v_pk_fma_f32 v[128:129], v[96:97], v[128:129], v[140:141]
	v_mul_f32_e32 v130, v133, v133
	v_mul_f32_e32 v131, v135, v135
	v_mul_f32_e32 v138, v129, v129
	v_mul_f32_e32 v139, v137, v137
	v_fmac_f32_e32 v130, v132, v132
	v_fmac_f32_e32 v131, v134, v134
	v_fmac_f32_e32 v138, v128, v128
	v_fmac_f32_e32 v139, v136, v136
	v_add_f32_e32 v130, v130, v131
	v_add_f32_e32 v131, v138, v139
	v_add_f32_e32 v130, v130, v131
	v_add_f32_e32 v138, v148, v130
	v_mov_b32_e32 v139, v138
	s_nop 1
	v_permlane16_swap_b32 v139, v138
	s_nop 0
	v_cvt_pk_bf16_f32 v130, v132, v133
	v_cvt_pk_bf16_f32 v132, v128, v129
	v_cvt_pk_bf16_f32 v131, v134, v135
	v_cvt_pk_bf16_f32 v133, v136, v137
	s_waitcnt lgkmcnt(0)
	v_add_f32_e32 v128, v138, v139
	v_mov_b32_e32 v129, v128
	s_nop 1
	v_permlane32_swap_b32 v129, v128
	s_nop 0
	v_lshl_add_u64 v[134:135], s[10:11], 0, v[164:165]
	global_store_dwordx4 v[134:135], v[130:133], off
	s_and_saveexec_b64 s[0:1], s[4:5]
	s_cbranch_execz .LBB0_968
	v_lshl_add_u32 v130, v152, 4, s22
	s_waitcnt lgkmcnt(0)
	v_add_f32_e32 v128, v128, v129
	ds_write_b32 v130, v128
; DI unsigned pk_bf16(float lo, float hi) { f32x2 v = {lo, hi}; bf16x2_t b = __builtin_convertvector(v, bf16x2_t); return __builtin_bit_cast(unsigned, b); }
; DI float bflo(unsigned w) { return __uint_as_float(w << 16); }
; DI float bfhi(unsigned w) { return __uint_as_float(w & 0xffff0000u); }
;     __device__ __forceinline__ void fused(f32x4 (&acc)[2][2][4][2], const pg8::Unit& u, int wr, int wc, int fr, int fq, PG8_LAS unsigned char* lds, int wid, int lane) const {
;     ...
;                 const int rl = ai * 128 + wr * 64 + m * 16 + fr; const size_t row = (size_t)u.pm * 256 + rl;
;                 const float rm = 1.f / sqrtf(__hip_atomic_load(ssqm + row, __ATOMIC_RELAXED, __HIP_MEMORY_SCOPE_AGENT) * (1.f / DM) + RMS_EPS);
;                 float sh = 0.f;
; #pragma unroll
;                 for (int bj = 0; bj < 2; ++bj) {
;                     const size_t off = row * DM + colb + bj * 128;
;                     f32x4 h0, h1;
;                     if (IN16) { const u32x4 hw = *(const u32x4*)((const bf16_t*)hin + off); h0 = (f32x4){bflo(hw.x), bfhi(hw.x), bflo(hw.y), bfhi(hw.y)}; h1 = (f32x4){bflo(hw.z), bfhi(hw.z), bflo(hw.w), bfhi(hw.w)}; }
;                     else { h0 = *(const f32x4*)((const float*)hin + off); h1 = *(const f32x4*)((const float*)hin + off + 4); }
;                     h0 = h0 + acc[ai][bj][m][0] * rm * gv[bj][0]; h1 = h1 + acc[ai][bj][m][1] * rm * gv[bj][1];
;                     sh += ((h0[0] * h0[0] + h0[1] * h0[1]) + (h0[2] * h0[2] + h0[3] * h0[3])) + ((h1[0] * h1[0] + h1[1] * h1[1]) + (h1[2] * h1[2] + h1[3] * h1[3]));
;                     if (OUT16) { u32x4 w; w.x = pk_bf16(h0[0], h0[1]); w.y = pk_bf16(h0[2], h0[3]); w.z = pk_bf16(h1[0], h1[1]); w.w = pk_bf16(h1[2], h1[3]); *(u32x4*)((bf16_t*)hout + off) = w; }
;                     else { *(f32x4*)((float*)hout + off) = h0; *(f32x4*)((float*)hout + off + 4) = h1; }
;                 }
;                 if (ssqh) { sh += __shfl_xor(sh, 16); sh += __shfl_xor(sh, 32); if (fq == 0) red[rl * 4 + wc] = sh; }
.LBB0_968:
	s_or_b64 exec, exec, s[0:1]
	v_or_b32_e32 v148, 16, v152
	s_waitcnt lgkmcnt(0)
	v_lshl_add_u64 v[128:129], s[14:15], 0, v[148:149]
	v_lshl_add_u64 v[130:131], v[128:129], 2, s[12:13]
	global_load_dword v140, v[130:131], off sc1
	v_lshlrev_b64 v[128:129], 10, v[128:129]
	v_lshl_add_u64 v[136:137], v[128:129], 0, v[146:147]
	v_lshl_add_u64 v[138:139], v[136:137], 2, s[36:37]
	global_load_dwordx4 v[128:131], v[138:139], off
	global_load_dwordx4 v[132:135], v[138:139], off offset:16
	v_lshlrev_b64 v[136:137], 1, v[136:137]
	s_waitcnt vmcnt(2)
	v_fmac_f32_e32 v155, 0x3a800000, v140
	v_mul_f32_e32 v140, 0x4f800000, v155
	v_cmp_gt_f32_e32 vcc, s2, v155
	s_nop 1
	v_cndmask_b32_e32 v140, v155, v140, vcc
	v_sqrt_f32_e32 v141, v140
	s_nop 0
	v_add_u32_e32 v142, -1, v141
	v_add_u32_e32 v143, 1, v141
	v_fma_f32 v149, -v142, v141, v140
	v_fma_f32 v155, -v143, v141, v140
	v_cmp_ge_f32_e64 s[0:1], 0, v149
	s_nop 1
	v_cndmask_b32_e64 v141, v141, v142, s[0:1]
	v_cmp_lt_f32_e64 s[0:1], 0, v155
	s_nop 1
	v_cndmask_b32_e64 v141, v141, v143, s[0:1]
	v_mul_f32_e32 v142, 0x37800000, v141
	v_cndmask_b32_e32 v141, v141, v142, vcc
	v_cmp_class_f32_e32 vcc, v140, v153
	s_nop 1
	v_cndmask_b32_e32 v142, v141, v140, vcc
	v_div_scale_f32 v143, s[0:1], v142, v142, 1.0
	v_rcp_f32_e32 v149, v143
	v_div_scale_f32 v153, vcc, 1.0, v142, 1.0
	v_lshl_add_u64 v[140:141], s[10:11], 0, v[136:137]
	v_fma_f32 v155, -v143, v149, 1.0
	v_fmac_f32_e32 v149, v155, v149
	v_mul_f32_e32 v155, v153, v149
	v_fma_f32 v156, -v143, v155, v153
	v_fmac_f32_e32 v155, v156, v149
	v_fma_f32 v143, -v143, v155, v153
	v_div_fmas_f32 v143, v143, v149, v155
	v_div_fixup_f32 v142, v143, v142, 1.0
	v_pk_mul_f32 v[124:125], v[124:125], v[142:143] op_sel_hi:[1,0]
	v_pk_mul_f32 v[126:127], v[126:127], v[142:143] op_sel_hi:[1,0]
	v_pk_mul_f32 v[120:121], v[120:121], v[142:143] op_sel_hi:[1,0]
	v_pk_mul_f32 v[122:123], v[122:123], v[142:143] op_sel_hi:[1,0]
	s_waitcnt vmcnt(1)
	v_pk_fma_f32 v[130:131], v[110:111], v[126:127], v[130:131]
	v_pk_fma_f32 v[128:129], v[108:109], v[124:125], v[128:129]
	s_waitcnt vmcnt(0)
	v_pk_fma_f32 v[134:135], v[106:107], v[122:123], v[134:135]
	v_pk_fma_f32 v[132:133], v[104:105], v[120:121], v[132:133]
	v_cvt_pk_bf16_f32 v120, v128, v129
	v_cvt_pk_bf16_f32 v121, v130, v131
	v_cvt_pk_bf16_f32 v122, v132, v133
	v_cvt_pk_bf16_f32 v123, v134, v135
	global_store_dwordx4 v[140:141], v[120:123], off
	global_load_dwordx4 v[120:123], v[138:139], off offset:512
	s_nop 0
	global_load_dwordx4 v[124:127], v[138:139], off offset:528
	v_pk_mul_f32 v[116:117], v[116:117], v[142:143] op_sel_hi:[1,0]
	v_pk_mul_f32 v[118:119], v[118:119], v[142:143] op_sel_hi:[1,0]
	v_pk_mul_f32 v[112:113], v[112:113], v[142:143] op_sel_hi:[1,0]
	v_pk_mul_f32 v[114:115], v[114:115], v[142:143] op_sel_hi:[1,0]
	v_mul_f32_e32 v129, v129, v129
	v_mul_f32_e32 v131, v131, v131
	v_mul_f32_e32 v133, v133, v133
	v_mul_f32_e32 v135, v135, v135
	v_fmac_f32_e32 v129, v128, v128
	v_fmac_f32_e32 v131, v130, v130
	v_fmac_f32_e32 v133, v132, v132
	v_fmac_f32_e32 v135, v134, v134
	v_add_f32_e32 v128, v129, v131
	v_add_f32_e32 v129, v133, v135
	v_add_f32_e32 v128, v128, v129
	v_or_b32_e32 v136, 0x100, v136
	s_waitcnt vmcnt(1)
	v_pk_fma_f32 v[118:119], v[102:103], v[118:119], v[122:123]
	v_pk_fma_f32 v[116:117], v[100:101], v[116:117], v[120:121]
	s_waitcnt vmcnt(0)
	v_pk_fma_f32 v[120:121], v[98:99], v[114:115], v[126:127]
	v_pk_fma_f32 v[112:113], v[96:97], v[112:113], v[124:125]
	v_mul_f32_e32 v114, v117, v117
	v_mul_f32_e32 v115, v119, v119
	v_mul_f32_e32 v122, v113, v113
	v_mul_f32_e32 v123, v121, v121
	v_fmac_f32_e32 v114, v116, v116
	v_fmac_f32_e32 v115, v118, v118
	v_fmac_f32_e32 v122, v112, v112
	v_fmac_f32_e32 v123, v120, v120
	v_add_f32_e32 v114, v114, v115
	v_add_f32_e32 v115, v122, v123
	v_add_f32_e32 v114, v114, v115
	v_add_f32_e32 v122, v128, v114
	v_mov_b32_e32 v123, v122
	s_nop 1
	v_permlane16_swap_b32 v123, v122
	s_nop 0
	v_cvt_pk_bf16_f32 v114, v116, v117
	v_cvt_pk_bf16_f32 v116, v112, v113
	v_cvt_pk_bf16_f32 v115, v118, v119
	v_cvt_pk_bf16_f32 v117, v120, v121
	s_waitcnt lgkmcnt(0)
	v_add_f32_e32 v112, v122, v123
	v_mov_b32_e32 v113, v112
	s_nop 1
	v_permlane32_swap_b32 v113, v112
	s_nop 0
	v_lshl_add_u64 v[118:119], s[10:11], 0, v[136:137]
	global_store_dwordx4 v[118:119], v[114:117], off
	s_and_saveexec_b64 s[0:1], s[4:5]
	s_cbranch_execz .LBB0_970
	v_lshl_add_u32 v114, v148, 4, s22
	s_waitcnt lgkmcnt(0)
	v_add_f32_e32 v112, v112, v113
	ds_write_b32 v114, v112
; DI unsigned pk_bf16(float lo, float hi) { f32x2 v = {lo, hi}; bf16x2_t b = __builtin_convertvector(v, bf16x2_t); return __builtin_bit_cast(unsigned, b); }
; DI float bflo(unsigned w) { return __uint_as_float(w << 16); }
; DI float bfhi(unsigned w) { return __uint_as_float(w & 0xffff0000u); }
;     __device__ __forceinline__ void fused(f32x4 (&acc)[2][2][4][2], const pg8::Unit& u, int wr, int wc, int fr, int fq, PG8_LAS unsigned char* lds, int wid, int lane) const {
;     ...
;                 const int rl = ai * 128 + wr * 64 + m * 16 + fr; const size_t row = (size_t)u.pm * 256 + rl;
;                 const float rm = 1.f / sqrtf(__hip_atomic_load(ssqm + row, __ATOMIC_RELAXED, __HIP_MEMORY_SCOPE_AGENT) * (1.f / DM) + RMS_EPS);
;                 float sh = 0.f;
; #pragma unroll
;                 for (int bj = 0; bj < 2; ++bj) {
;                     const size_t off = row * DM + colb + bj * 128;
;                     f32x4 h0, h1;
;                     if (IN16) { const u32x4 hw = *(const u32x4*)((const bf16_t*)hin + off); h0 = (f32x4){bflo(hw.x), bfhi(hw.x), bflo(hw.y), bfhi(hw.y)}; h1 = (f32x4){bflo(hw.z), bfhi(hw.z), bflo(hw.w), bfhi(hw.w)}; }
;                     else { h0 = *(const f32x4*)((const float*)hin + off); h1 = *(const f32x4*)((const float*)hin + off + 4); }
;                     h0 = h0 + acc[ai][bj][m][0] * rm * gv[bj][0]; h1 = h1 + acc[ai][bj][m][1] * rm * gv[bj][1];
;                     sh += ((h0[0] * h0[0] + h0[1] * h0[1]) + (h0[2] * h0[2] + h0[3] * h0[3])) + ((h1[0] * h1[0] + h1[1] * h1[1]) + (h1[2] * h1[2] + h1[3] * h1[3]));
;                     if (OUT16) { u32x4 w; w.x = pk_bf16(h0[0], h0[1]); w.y = pk_bf16(h0[2], h0[3]); w.z = pk_bf16(h1[0], h1[1]); w.w = pk_bf16(h1[2], h1[3]); *(u32x4*)((bf16_t*)hout + off) = w; }
;                     else { *(f32x4*)((float*)hout + off) = h0; *(f32x4*)((float*)hout + off + 4) = h1; }
;                 }
;                 if (ssqh) { sh += __shfl_xor(sh, 16); sh += __shfl_xor(sh, 32); if (fq == 0) red[rl * 4 + wc] = sh; }
.LBB0_970:
	s_or_b64 exec, exec, s[0:1]
	v_or_b32_e32 v112, 32, v152
	s_waitcnt lgkmcnt(0)
	v_mov_b32_e32 v113, 0
	v_lshl_add_u64 v[114:115], s[14:15], 0, v[112:113]
	v_lshl_add_u64 v[116:117], v[114:115], 2, s[12:13]
	global_load_dword v128, v[116:117], off sc1
	v_lshlrev_b64 v[114:115], 10, v[114:115]
	v_lshl_add_u64 v[124:125], v[114:115], 0, v[146:147]
	v_lshl_add_u64 v[126:127], v[124:125], 2, s[36:37]
	global_load_dwordx4 v[116:119], v[126:127], off
	global_load_dwordx4 v[120:123], v[126:127], off offset:16
	v_mov_b32_e32 v115, 0x358637bd
	v_lshlrev_b64 v[124:125], 1, v[124:125]
	s_waitcnt vmcnt(2)
	v_fmamk_f32 v114, v128, 0x3a800000, v115
	v_mul_f32_e32 v128, 0x4f800000, v114
	v_cmp_gt_f32_e32 vcc, s2, v114
	s_nop 1
	v_cndmask_b32_e32 v128, v114, v128, vcc
	v_sqrt_f32_e32 v129, v128
	v_mov_b32_e32 v114, 0x260
	v_add_u32_e32 v130, -1, v129
	v_add_u32_e32 v131, 1, v129
	v_fma_f32 v132, -v130, v129, v128
	v_fma_f32 v133, -v131, v129, v128
	v_cmp_ge_f32_e64 s[0:1], 0, v132
	s_nop 1
	v_cndmask_b32_e64 v129, v129, v130, s[0:1]
	v_cmp_lt_f32_e64 s[0:1], 0, v133
	s_nop 1
	v_cndmask_b32_e64 v129, v129, v131, s[0:1]
	v_mul_f32_e32 v130, 0x37800000, v129
	v_cndmask_b32_e32 v129, v129, v130, vcc
	v_cmp_class_f32_e32 vcc, v128, v114
	s_nop 1
	v_cndmask_b32_e32 v130, v129, v128, vcc
	v_div_scale_f32 v131, s[0:1], v130, v130, 1.0
	v_rcp_f32_e32 v132, v131
	v_div_scale_f32 v133, vcc, 1.0, v130, 1.0
	v_lshl_add_u64 v[128:129], s[10:11], 0, v[124:125]
	v_fma_f32 v134, -v131, v132, 1.0
	v_fmac_f32_e32 v132, v134, v132
	v_mul_f32_e32 v134, v133, v132
	v_fma_f32 v135, -v131, v134, v133
	v_fmac_f32_e32 v134, v135, v132
	v_fma_f32 v131, -v131, v134, v133
	v_div_fmas_f32 v131, v131, v132, v134
	v_div_fixup_f32 v130, v131, v130, 1.0
	v_pk_mul_f32 v[92:93], v[92:93], v[130:131] op_sel_hi:[1,0]
	v_pk_mul_f32 v[94:95], v[94:95], v[130:131] op_sel_hi:[1,0]
	v_pk_mul_f32 v[88:89], v[88:89], v[130:131] op_sel_hi:[1,0]
	v_pk_mul_f32 v[90:91], v[90:91], v[130:131] op_sel_hi:[1,0]
	s_waitcnt vmcnt(1)
	v_pk_fma_f32 v[118:119], v[110:111], v[94:95], v[118:119]
	v_pk_fma_f32 v[116:117], v[108:109], v[92:93], v[116:117]
	s_waitcnt vmcnt(0)
	v_pk_fma_f32 v[122:123], v[106:107], v[90:91], v[122:123]
	v_pk_fma_f32 v[120:121], v[104:105], v[88:89], v[120:121]
	v_cvt_pk_bf16_f32 v88, v116, v117
	v_cvt_pk_bf16_f32 v89, v118, v119
	v_cvt_pk_bf16_f32 v90, v120, v121
	v_cvt_pk_bf16_f32 v91, v122, v123
	global_store_dwordx4 v[128:129], v[88:91], off
	global_load_dwordx4 v[88:91], v[126:127], off offset:512
	s_nop 0
	global_load_dwordx4 v[92:95], v[126:127], off offset:528
	v_pk_mul_f32 v[84:85], v[84:85], v[130:131] op_sel_hi:[1,0]
	v_pk_mul_f32 v[86:87], v[86:87], v[130:131] op_sel_hi:[1,0]
	v_pk_mul_f32 v[80:81], v[80:81], v[130:131] op_sel_hi:[1,0]
	v_pk_mul_f32 v[82:83], v[82:83], v[130:131] op_sel_hi:[1,0]
	v_mul_f32_e32 v117, v117, v117
	v_mul_f32_e32 v119, v119, v119
	v_mul_f32_e32 v121, v121, v121
	v_mul_f32_e32 v123, v123, v123
	v_fmac_f32_e32 v117, v116, v116
	v_fmac_f32_e32 v119, v118, v118
	v_fmac_f32_e32 v121, v120, v120
	v_fmac_f32_e32 v123, v122, v122
	v_add_f32_e32 v116, v117, v119
	v_add_f32_e32 v117, v121, v123
	v_add_f32_e32 v116, v116, v117
	v_or_b32_e32 v124, 0x100, v124
	s_waitcnt vmcnt(1)
	v_pk_fma_f32 v[86:87], v[102:103], v[86:87], v[90:91]
	v_pk_fma_f32 v[84:85], v[100:101], v[84:85], v[88:89]
	s_waitcnt vmcnt(0)
	v_pk_fma_f32 v[88:89], v[98:99], v[82:83], v[94:95]
	v_pk_fma_f32 v[80:81], v[96:97], v[80:81], v[92:93]
	v_mul_f32_e32 v82, v85, v85
	v_mul_f32_e32 v83, v87, v87
	v_mul_f32_e32 v90, v81, v81
	v_mul_f32_e32 v91, v89, v89
	v_fmac_f32_e32 v82, v84, v84
	v_fmac_f32_e32 v83, v86, v86
	v_fmac_f32_e32 v90, v80, v80
	v_fmac_f32_e32 v91, v88, v88
	v_add_f32_e32 v82, v82, v83
	v_add_f32_e32 v83, v90, v91
	v_add_f32_e32 v82, v82, v83
	v_add_f32_e32 v90, v116, v82
	v_mov_b32_e32 v91, v90
	s_nop 1
	v_permlane16_swap_b32 v91, v90
	s_nop 0
	v_cvt_pk_bf16_f32 v82, v84, v85
	v_cvt_pk_bf16_f32 v84, v80, v81
	v_cvt_pk_bf16_f32 v83, v86, v87
	v_cvt_pk_bf16_f32 v85, v88, v89
	s_waitcnt lgkmcnt(0)
	v_add_f32_e32 v80, v90, v91
	v_mov_b32_e32 v81, v80
	s_nop 1
	v_permlane32_swap_b32 v81, v80
	s_nop 0
	v_lshl_add_u64 v[86:87], s[10:11], 0, v[124:125]
	global_store_dwordx4 v[86:87], v[82:85], off
	s_and_saveexec_b64 s[0:1], s[4:5]
	s_cbranch_execz .LBB0_972
	v_lshl_add_u32 v82, v112, 4, s22
	s_waitcnt lgkmcnt(0)
	v_add_f32_e32 v80, v80, v81
	ds_write_b32 v82, v80
; DI unsigned pk_bf16(float lo, float hi) { f32x2 v = {lo, hi}; bf16x2_t b = __builtin_convertvector(v, bf16x2_t); return __builtin_bit_cast(unsigned, b); }
; DI float bflo(unsigned w) { return __uint_as_float(w << 16); }
; DI float bfhi(unsigned w) { return __uint_as_float(w & 0xffff0000u); }
;     __device__ __forceinline__ void fused(f32x4 (&acc)[2][2][4][2], const pg8::Unit& u, int wr, int wc, int fr, int fq, PG8_LAS unsigned char* lds, int wid, int lane) const {
;     ...
;                 const int rl = ai * 128 + wr * 64 + m * 16 + fr; const size_t row = (size_t)u.pm * 256 + rl;
;                 const float rm = 1.f / sqrtf(__hip_atomic_load(ssqm + row, __ATOMIC_RELAXED, __HIP_MEMORY_SCOPE_AGENT) * (1.f / DM) + RMS_EPS);
;                 float sh = 0.f;
; #pragma unroll
;                 for (int bj = 0; bj < 2; ++bj) {
;                     const size_t off = row * DM + colb + bj * 128;
;                     f32x4 h0, h1;
;                     if (IN16) { const u32x4 hw = *(const u32x4*)((const bf16_t*)hin + off); h0 = (f32x4){bflo(hw.x), bfhi(hw.x), bflo(hw.y), bfhi(hw.y)}; h1 = (f32x4){bflo(hw.z), bfhi(hw.z), bflo(hw.w), bfhi(hw.w)}; }
;                     else { h0 = *(const f32x4*)((const float*)hin + off); h1 = *(const f32x4*)((const float*)hin + off + 4); }
;                     h0 = h0 + acc[ai][bj][m][0] * rm * gv[bj][0]; h1 = h1 + acc[ai][bj][m][1] * rm * gv[bj][1];
;                     sh += ((h0[0] * h0[0] + h0[1] * h0[1]) + (h0[2] * h0[2] + h0[3] * h0[3])) + ((h1[0] * h1[0] + h1[1] * h1[1]) + (h1[2] * h1[2] + h1[3] * h1[3]));
;                     if (OUT16) { u32x4 w; w.x = pk_bf16(h0[0], h0[1]); w.y = pk_bf16(h0[2], h0[3]); w.z = pk_bf16(h1[0], h1[1]); w.w = pk_bf16(h1[2], h1[3]); *(u32x4*)((bf16_t*)hout + off) = w; }
;                     else { *(f32x4*)((float*)hout + off) = h0; *(f32x4*)((float*)hout + off + 4) = h1; }
;                 }
;                 if (ssqh) { sh += __shfl_xor(sh, 16); sh += __shfl_xor(sh, 32); if (fq == 0) red[rl * 4 + wc] = sh; }
.LBB0_972:
	s_or_b64 exec, exec, s[0:1]
	v_or_b32_e32 v112, 48, v152
	s_waitcnt lgkmcnt(0)
	v_lshl_add_u64 v[80:81], s[14:15], 0, v[112:113]
	v_lshl_add_u64 v[82:83], v[80:81], 2, s[12:13]
	global_load_dword v92, v[82:83], off sc1
	v_lshlrev_b64 v[80:81], 10, v[80:81]
	v_lshl_add_u64 v[88:89], v[80:81], 0, v[146:147]
	v_lshl_add_u64 v[90:91], v[88:89], 2, s[36:37]
	global_load_dwordx4 v[80:83], v[90:91], off
	global_load_dwordx4 v[84:87], v[90:91], off offset:16
	v_lshlrev_b64 v[88:89], 1, v[88:89]
	s_waitcnt vmcnt(2)
	v_fmac_f32_e32 v115, 0x3a800000, v92
	v_mul_f32_e32 v92, 0x4f800000, v115
	v_cmp_gt_f32_e32 vcc, s2, v115
	s_nop 1
	v_cndmask_b32_e32 v92, v115, v92, vcc
	v_sqrt_f32_e32 v93, v92
	s_nop 0
	v_add_u32_e32 v94, -1, v93
	v_add_u32_e32 v95, 1, v93
	v_fma_f32 v113, -v94, v93, v92
	v_fma_f32 v115, -v95, v93, v92
	v_cmp_ge_f32_e64 s[0:1], 0, v113
	s_nop 1
	v_cndmask_b32_e64 v93, v93, v94, s[0:1]
	v_cmp_lt_f32_e64 s[0:1], 0, v115
	s_nop 1
	v_cndmask_b32_e64 v93, v93, v95, s[0:1]
	v_mul_f32_e32 v94, 0x37800000, v93
	v_cndmask_b32_e32 v93, v93, v94, vcc
	v_cmp_class_f32_e32 vcc, v92, v114
	s_nop 1
	v_cndmask_b32_e32 v94, v93, v92, vcc
	v_div_scale_f32 v95, s[0:1], v94, v94, 1.0
	v_rcp_f32_e32 v113, v95
	v_div_scale_f32 v114, vcc, 1.0, v94, 1.0
	v_lshl_add_u64 v[92:93], s[10:11], 0, v[88:89]
	v_fma_f32 v115, -v95, v113, 1.0
	v_fmac_f32_e32 v113, v115, v113
	v_mul_f32_e32 v115, v114, v113
	v_fma_f32 v116, -v95, v115, v114
	v_fmac_f32_e32 v115, v116, v113
	v_fma_f32 v95, -v95, v115, v114
	v_div_fmas_f32 v95, v95, v113, v115
	v_div_fixup_f32 v94, v95, v94, 1.0
	v_pk_mul_f32 v[76:77], v[76:77], v[94:95] op_sel_hi:[1,0]
	v_pk_mul_f32 v[78:79], v[78:79], v[94:95] op_sel_hi:[1,0]
	v_pk_mul_f32 v[72:73], v[72:73], v[94:95] op_sel_hi:[1,0]
	v_pk_mul_f32 v[74:75], v[74:75], v[94:95] op_sel_hi:[1,0]
	s_waitcnt vmcnt(1)
	v_pk_fma_f32 v[82:83], v[110:111], v[78:79], v[82:83]
	v_pk_fma_f32 v[80:81], v[108:109], v[76:77], v[80:81]
	s_waitcnt vmcnt(0)
	v_pk_fma_f32 v[86:87], v[106:107], v[74:75], v[86:87]
	v_pk_fma_f32 v[84:85], v[104:105], v[72:73], v[84:85]
	v_cvt_pk_bf16_f32 v72, v80, v81
	v_cvt_pk_bf16_f32 v73, v82, v83
	v_cvt_pk_bf16_f32 v74, v84, v85
	v_cvt_pk_bf16_f32 v75, v86, v87
	global_store_dwordx4 v[92:93], v[72:75], off
	global_load_dwordx4 v[72:75], v[90:91], off offset:512
	s_nop 0
	global_load_dwordx4 v[76:79], v[90:91], off offset:528
	v_pk_mul_f32 v[68:69], v[68:69], v[94:95] op_sel_hi:[1,0]
	v_pk_mul_f32 v[70:71], v[70:71], v[94:95] op_sel_hi:[1,0]
	v_pk_mul_f32 v[64:65], v[64:65], v[94:95] op_sel_hi:[1,0]
	v_pk_mul_f32 v[66:67], v[66:67], v[94:95] op_sel_hi:[1,0]
	v_mul_f32_e32 v81, v81, v81
	v_mul_f32_e32 v83, v83, v83
	v_mul_f32_e32 v85, v85, v85
	v_mul_f32_e32 v87, v87, v87
	v_fmac_f32_e32 v81, v80, v80
	v_fmac_f32_e32 v83, v82, v82
	v_fmac_f32_e32 v85, v84, v84
	v_fmac_f32_e32 v87, v86, v86
	v_add_f32_e32 v80, v81, v83
	v_add_f32_e32 v81, v85, v87
	v_add_f32_e32 v80, v80, v81
	v_or_b32_e32 v88, 0x100, v88
	s_waitcnt vmcnt(1)
	v_pk_fma_f32 v[70:71], v[102:103], v[70:71], v[74:75]
	v_pk_fma_f32 v[68:69], v[100:101], v[68:69], v[72:73]
	s_waitcnt vmcnt(0)
	v_pk_fma_f32 v[72:73], v[98:99], v[66:67], v[78:79]
	v_pk_fma_f32 v[64:65], v[96:97], v[64:65], v[76:77]
	v_mul_f32_e32 v66, v69, v69
	v_mul_f32_e32 v67, v71, v71
	v_mul_f32_e32 v74, v65, v65
	v_mul_f32_e32 v75, v73, v73
	v_fmac_f32_e32 v66, v68, v68
	v_fmac_f32_e32 v67, v70, v70
	v_fmac_f32_e32 v74, v64, v64
	v_fmac_f32_e32 v75, v72, v72
	v_add_f32_e32 v66, v66, v67
	v_add_f32_e32 v67, v74, v75
	v_add_f32_e32 v66, v66, v67
	v_add_f32_e32 v74, v80, v66
	v_mov_b32_e32 v75, v74
	s_nop 1
	v_permlane16_swap_b32 v75, v74
	s_nop 0
	v_cvt_pk_bf16_f32 v66, v68, v69
	v_cvt_pk_bf16_f32 v68, v64, v65
	v_cvt_pk_bf16_f32 v67, v70, v71
	v_cvt_pk_bf16_f32 v69, v72, v73
	s_waitcnt lgkmcnt(0)
	v_add_f32_e32 v64, v74, v75
	v_mov_b32_e32 v65, v64
	s_nop 1
	v_permlane32_swap_b32 v65, v64
	s_nop 0
	v_lshl_add_u64 v[70:71], s[10:11], 0, v[88:89]
	global_store_dwordx4 v[70:71], v[66:69], off
	s_and_saveexec_b64 s[0:1], s[4:5]
	s_cbranch_execz .LBB0_974
	v_lshl_add_u32 v66, v112, 4, s22
	s_waitcnt lgkmcnt(0)
	v_add_f32_e32 v64, v64, v65
	ds_write_b32 v66, v64
.LBB0_974:
	s_or_b64 exec, exec, s[0:1]
	v_add_u32_e32 v64, 0x80, v152
	s_waitcnt lgkmcnt(0)
	v_mov_b32_e32 v65, 0
	v_lshl_add_u64 v[66:67], s[14:15], 0, v[64:65]
	v_lshl_add_u64 v[68:69], v[66:67], 2, s[12:13]
	global_load_dword v80, v[68:69], off sc1
	v_lshlrev_b64 v[66:67], 10, v[66:67]
	v_lshl_add_u64 v[76:77], v[66:67], 0, v[146:147]
	v_lshl_add_u64 v[78:79], v[76:77], 2, s[36:37]
	global_load_dwordx4 v[68:71], v[78:79], off
	global_load_dwordx4 v[72:75], v[78:79], off offset:16
	v_mov_b32_e32 v67, 0x358637bd
	v_lshlrev_b64 v[76:77], 1, v[76:77]
	s_waitcnt vmcnt(2)
	v_fmamk_f32 v66, v80, 0x3a800000, v67
	v_mul_f32_e32 v80, 0x4f800000, v66
	v_cmp_gt_f32_e32 vcc, s2, v66
	s_nop 1
	v_cndmask_b32_e32 v80, v66, v80, vcc
	v_sqrt_f32_e32 v81, v80
	v_mov_b32_e32 v66, 0x260
	v_add_u32_e32 v82, -1, v81
	v_add_u32_e32 v83, 1, v81
	v_fma_f32 v84, -v82, v81, v80
	v_fma_f32 v85, -v83, v81, v80
	v_cmp_ge_f32_e64 s[0:1], 0, v84
	s_nop 1
	v_cndmask_b32_e64 v81, v81, v82, s[0:1]
	v_cmp_lt_f32_e64 s[0:1], 0, v85
	s_nop 1
	v_cndmask_b32_e64 v81, v81, v83, s[0:1]
	v_mul_f32_e32 v82, 0x37800000, v81
	v_cndmask_b32_e32 v81, v81, v82, vcc
	v_cmp_class_f32_e32 vcc, v80, v66
	s_nop 1
	v_cndmask_b32_e32 v82, v81, v80, vcc
	v_div_scale_f32 v83, s[0:1], v82, v82, 1.0
	v_rcp_f32_e32 v84, v83
	v_div_scale_f32 v85, vcc, 1.0, v82, 1.0
	v_lshl_add_u64 v[80:81], s[10:11], 0, v[76:77]
	v_fma_f32 v86, -v83, v84, 1.0
	v_fmac_f32_e32 v84, v86, v84
	v_mul_f32_e32 v86, v85, v84
	v_fma_f32 v87, -v83, v86, v85
	v_fmac_f32_e32 v86, v87, v84
	v_fma_f32 v83, -v83, v86, v85
	v_div_fmas_f32 v83, v83, v84, v86
	v_div_fixup_f32 v82, v83, v82, 1.0
	v_pk_mul_f32 v[60:61], v[60:61], v[82:83] op_sel_hi:[1,0]
	v_pk_mul_f32 v[62:63], v[62:63], v[82:83] op_sel_hi:[1,0]
	v_pk_mul_f32 v[56:57], v[56:57], v[82:83] op_sel_hi:[1,0]
	v_pk_mul_f32 v[58:59], v[58:59], v[82:83] op_sel_hi:[1,0]
	s_waitcnt vmcnt(1)
; DI unsigned pk_bf16(float lo, float hi) { f32x2 v = {lo, hi}; bf16x2_t b = __builtin_convertvector(v, bf16x2_t); return __builtin_bit_cast(unsigned, b); }
; DI float bflo(unsigned w) { return __uint_as_float(w << 16); }
; DI float bfhi(unsigned w) { return __uint_as_float(w & 0xffff0000u); }
;     __device__ __forceinline__ void fused(f32x4 (&acc)[2][2][4][2], const pg8::Unit& u, int wr, int wc, int fr, int fq, PG8_LAS unsigned char* lds, int wid, int lane) const {
;     ...
;                 const int rl = ai * 128 + wr * 64 + m * 16 + fr; const size_t row = (size_t)u.pm * 256 + rl;
;                 const float rm = 1.f / sqrtf(__hip_atomic_load(ssqm + row, __ATOMIC_RELAXED, __HIP_MEMORY_SCOPE_AGENT) * (1.f / DM) + RMS_EPS);
;                 float sh = 0.f;
; #pragma unroll
;                 for (int bj = 0; bj < 2; ++bj) {
;                     const size_t off = row * DM + colb + bj * 128;
;                     f32x4 h0, h1;
;                     if (IN16) { const u32x4 hw = *(const u32x4*)((const bf16_t*)hin + off); h0 = (f32x4){bflo(hw.x), bfhi(hw.x), bflo(hw.y), bfhi(hw.y)}; h1 = (f32x4){bflo(hw.z), bfhi(hw.z), bflo(hw.w), bfhi(hw.w)}; }
;                     else { h0 = *(const f32x4*)((const float*)hin + off); h1 = *(const f32x4*)((const float*)hin + off + 4); }
;                     h0 = h0 + acc[ai][bj][m][0] * rm * gv[bj][0]; h1 = h1 + acc[ai][bj][m][1] * rm * gv[bj][1];
;                     sh += ((h0[0] * h0[0] + h0[1] * h0[1]) + (h0[2] * h0[2] + h0[3] * h0[3])) + ((h1[0] * h1[0] + h1[1] * h1[1]) + (h1[2] * h1[2] + h1[3] * h1[3]));
;                     if (OUT16) { u32x4 w; w.x = pk_bf16(h0[0], h0[1]); w.y = pk_bf16(h0[2], h0[3]); w.z = pk_bf16(h1[0], h1[1]); w.w = pk_bf16(h1[2], h1[3]); *(u32x4*)((bf16_t*)hout + off) = w; }
;                     else { *(f32x4*)((float*)hout + off) = h0; *(f32x4*)((float*)hout + off + 4) = h1; }
;                 }
;                 if (ssqh) { sh += __shfl_xor(sh, 16); sh += __shfl_xor(sh, 32); if (fq == 0) red[rl * 4 + wc] = sh; }
	v_pk_fma_f32 v[70:71], v[110:111], v[62:63], v[70:71]
	v_pk_fma_f32 v[68:69], v[108:109], v[60:61], v[68:69]
	s_waitcnt vmcnt(0)
	v_pk_fma_f32 v[74:75], v[106:107], v[58:59], v[74:75]
	v_pk_fma_f32 v[72:73], v[104:105], v[56:57], v[72:73]
	v_cvt_pk_bf16_f32 v56, v68, v69
	v_cvt_pk_bf16_f32 v57, v70, v71
	v_cvt_pk_bf16_f32 v58, v72, v73
	v_cvt_pk_bf16_f32 v59, v74, v75
	global_store_dwordx4 v[80:81], v[56:59], off
	global_load_dwordx4 v[56:59], v[78:79], off offset:512
	s_nop 0
	global_load_dwordx4 v[60:63], v[78:79], off offset:528
	v_pk_mul_f32 v[52:53], v[52:53], v[82:83] op_sel_hi:[1,0]
	v_pk_mul_f32 v[54:55], v[54:55], v[82:83] op_sel_hi:[1,0]
	v_pk_mul_f32 v[48:49], v[48:49], v[82:83] op_sel_hi:[1,0]
	v_pk_mul_f32 v[50:51], v[50:51], v[82:83] op_sel_hi:[1,0]
	v_mul_f32_e32 v69, v69, v69
	v_mul_f32_e32 v71, v71, v71
	v_mul_f32_e32 v73, v73, v73
	v_mul_f32_e32 v75, v75, v75
	v_fmac_f32_e32 v69, v68, v68
	v_fmac_f32_e32 v71, v70, v70
	v_fmac_f32_e32 v73, v72, v72
	v_fmac_f32_e32 v75, v74, v74
	v_add_f32_e32 v68, v69, v71
	v_add_f32_e32 v69, v73, v75
	v_add_f32_e32 v68, v68, v69
	v_or_b32_e32 v76, 0x100, v76
	s_waitcnt vmcnt(1)
	v_pk_fma_f32 v[54:55], v[102:103], v[54:55], v[58:59]
	v_pk_fma_f32 v[52:53], v[100:101], v[52:53], v[56:57]
	s_waitcnt vmcnt(0)
	v_pk_fma_f32 v[56:57], v[98:99], v[50:51], v[62:63]
	v_pk_fma_f32 v[48:49], v[96:97], v[48:49], v[60:61]
	v_mul_f32_e32 v50, v53, v53
	v_mul_f32_e32 v51, v55, v55
	v_mul_f32_e32 v58, v49, v49
	v_mul_f32_e32 v59, v57, v57
	v_fmac_f32_e32 v50, v52, v52
	v_fmac_f32_e32 v51, v54, v54
	v_fmac_f32_e32 v58, v48, v48
	v_fmac_f32_e32 v59, v56, v56
	v_add_f32_e32 v50, v50, v51
	v_add_f32_e32 v51, v58, v59
	v_add_f32_e32 v50, v50, v51
	v_add_f32_e32 v58, v68, v50
	v_mov_b32_e32 v59, v58
	s_nop 1
	v_permlane16_swap_b32 v59, v58
	s_nop 0
	v_cvt_pk_bf16_f32 v50, v52, v53
	v_cvt_pk_bf16_f32 v52, v48, v49
	v_cvt_pk_bf16_f32 v51, v54, v55
	v_cvt_pk_bf16_f32 v53, v56, v57
	s_waitcnt lgkmcnt(0)
	v_add_f32_e32 v48, v58, v59
	v_mov_b32_e32 v49, v48
	s_nop 1
	v_permlane32_swap_b32 v49, v48
	s_nop 0
	v_lshl_add_u64 v[54:55], s[10:11], 0, v[76:77]
	global_store_dwordx4 v[54:55], v[50:53], off
	s_and_saveexec_b64 s[0:1], s[4:5]
	s_cbranch_execz .LBB0_976
	v_lshl_add_u32 v50, v64, 4, s22
	s_waitcnt lgkmcnt(0)
	v_add_f32_e32 v48, v48, v49
	ds_write_b32 v50, v48
.LBB0_976:
	s_or_b64 exec, exec, s[0:1]
	v_add_u32_e32 v64, 0x90, v152
	s_waitcnt lgkmcnt(0)
	v_lshl_add_u64 v[48:49], s[14:15], 0, v[64:65]
	v_lshl_add_u64 v[50:51], v[48:49], 2, s[12:13]
	global_load_dword v60, v[50:51], off sc1
	v_lshlrev_b64 v[48:49], 10, v[48:49]
	v_lshl_add_u64 v[56:57], v[48:49], 0, v[146:147]
	v_lshl_add_u64 v[58:59], v[56:57], 2, s[36:37]
	global_load_dwordx4 v[48:51], v[58:59], off
	global_load_dwordx4 v[52:55], v[58:59], off offset:16
	v_lshlrev_b64 v[56:57], 1, v[56:57]
	s_waitcnt vmcnt(2)
	v_fmac_f32_e32 v67, 0x3a800000, v60
	v_mul_f32_e32 v60, 0x4f800000, v67
	v_cmp_gt_f32_e32 vcc, s2, v67
	s_nop 1
	v_cndmask_b32_e32 v60, v67, v60, vcc
	v_sqrt_f32_e32 v61, v60
	s_nop 0
	v_add_u32_e32 v62, -1, v61
	v_add_u32_e32 v63, 1, v61
	v_fma_f32 v65, -v62, v61, v60
	v_fma_f32 v67, -v63, v61, v60
	v_cmp_ge_f32_e64 s[0:1], 0, v65
	s_nop 1
	v_cndmask_b32_e64 v61, v61, v62, s[0:1]
	v_cmp_lt_f32_e64 s[0:1], 0, v67
	s_nop 1
	v_cndmask_b32_e64 v61, v61, v63, s[0:1]
	v_mul_f32_e32 v62, 0x37800000, v61
	v_cndmask_b32_e32 v61, v61, v62, vcc
	v_cmp_class_f32_e32 vcc, v60, v66
	s_nop 1
	v_cndmask_b32_e32 v62, v61, v60, vcc
	v_div_scale_f32 v63, s[0:1], v62, v62, 1.0
	v_rcp_f32_e32 v65, v63
	v_div_scale_f32 v66, vcc, 1.0, v62, 1.0
	v_lshl_add_u64 v[60:61], s[10:11], 0, v[56:57]
	v_fma_f32 v67, -v63, v65, 1.0
	v_fmac_f32_e32 v65, v67, v65
	v_mul_f32_e32 v67, v66, v65
	v_fma_f32 v68, -v63, v67, v66
	v_fmac_f32_e32 v67, v68, v65
	v_fma_f32 v63, -v63, v67, v66
	v_div_fmas_f32 v63, v63, v65, v67
	v_div_fixup_f32 v62, v63, v62, 1.0
	v_pk_mul_f32 v[44:45], v[44:45], v[62:63] op_sel_hi:[1,0]
	v_pk_mul_f32 v[46:47], v[46:47], v[62:63] op_sel_hi:[1,0]
	v_pk_mul_f32 v[40:41], v[40:41], v[62:63] op_sel_hi:[1,0]
	v_pk_mul_f32 v[42:43], v[42:43], v[62:63] op_sel_hi:[1,0]
	s_waitcnt vmcnt(1)
	v_pk_fma_f32 v[50:51], v[110:111], v[46:47], v[50:51]
	v_pk_fma_f32 v[48:49], v[108:109], v[44:45], v[48:49]
	s_waitcnt vmcnt(0)
	v_pk_fma_f32 v[54:55], v[106:107], v[42:43], v[54:55]
	v_pk_fma_f32 v[52:53], v[104:105], v[40:41], v[52:53]
	v_cvt_pk_bf16_f32 v40, v48, v49
	v_cvt_pk_bf16_f32 v41, v50, v51
	v_cvt_pk_bf16_f32 v42, v52, v53
	v_cvt_pk_bf16_f32 v43, v54, v55
	global_store_dwordx4 v[60:61], v[40:43], off
	global_load_dwordx4 v[40:43], v[58:59], off offset:512
	s_nop 0
	global_load_dwordx4 v[44:47], v[58:59], off offset:528
	v_pk_mul_f32 v[36:37], v[36:37], v[62:63] op_sel_hi:[1,0]
	v_pk_mul_f32 v[38:39], v[38:39], v[62:63] op_sel_hi:[1,0]
	v_pk_mul_f32 v[32:33], v[32:33], v[62:63] op_sel_hi:[1,0]
	v_pk_mul_f32 v[34:35], v[34:35], v[62:63] op_sel_hi:[1,0]
	v_mul_f32_e32 v49, v49, v49
	v_mul_f32_e32 v51, v51, v51
	v_mul_f32_e32 v53, v53, v53
	v_mul_f32_e32 v55, v55, v55
	v_fmac_f32_e32 v49, v48, v48
	v_fmac_f32_e32 v51, v50, v50
	v_fmac_f32_e32 v53, v52, v52
	v_fmac_f32_e32 v55, v54, v54
	v_add_f32_e32 v48, v49, v51
	v_add_f32_e32 v49, v53, v55
	v_add_f32_e32 v48, v48, v49
	v_or_b32_e32 v56, 0x100, v56
	s_waitcnt vmcnt(1)
	v_pk_fma_f32 v[38:39], v[102:103], v[38:39], v[42:43]
	v_pk_fma_f32 v[36:37], v[100:101], v[36:37], v[40:41]
	s_waitcnt vmcnt(0)
	v_pk_fma_f32 v[40:41], v[98:99], v[34:35], v[46:47]
	v_pk_fma_f32 v[32:33], v[96:97], v[32:33], v[44:45]
	v_mul_f32_e32 v34, v37, v37
	v_mul_f32_e32 v35, v39, v39
	v_mul_f32_e32 v42, v33, v33
	v_mul_f32_e32 v43, v41, v41
	v_fmac_f32_e32 v34, v36, v36
	v_fmac_f32_e32 v35, v38, v38
	v_fmac_f32_e32 v42, v32, v32
	v_fmac_f32_e32 v43, v40, v40
	v_add_f32_e32 v34, v34, v35
	v_add_f32_e32 v35, v42, v43
	v_add_f32_e32 v34, v34, v35
	v_add_f32_e32 v42, v48, v34
	v_mov_b32_e32 v43, v42
	s_nop 1
	v_permlane16_swap_b32 v43, v42
	s_nop 0
	v_cvt_pk_bf16_f32 v34, v36, v37
	v_cvt_pk_bf16_f32 v36, v32, v33
	v_cvt_pk_bf16_f32 v35, v38, v39
	v_cvt_pk_bf16_f32 v37, v40, v41
	s_waitcnt lgkmcnt(0)
	v_add_f32_e32 v32, v42, v43
	v_mov_b32_e32 v33, v32
	s_nop 1
	v_permlane32_swap_b32 v33, v32
	s_nop 0
	v_lshl_add_u64 v[38:39], s[10:11], 0, v[56:57]
	global_store_dwordx4 v[38:39], v[34:37], off
	s_and_saveexec_b64 s[0:1], s[4:5]
	s_cbranch_execz .LBB0_978
	v_lshl_add_u32 v34, v64, 4, s22
	s_waitcnt lgkmcnt(0)
	v_add_f32_e32 v32, v32, v33
	ds_write_b32 v34, v32
; DI unsigned pk_bf16(float lo, float hi) { f32x2 v = {lo, hi}; bf16x2_t b = __builtin_convertvector(v, bf16x2_t); return __builtin_bit_cast(unsigned, b); }
; DI float bflo(unsigned w) { return __uint_as_float(w << 16); }
; DI float bfhi(unsigned w) { return __uint_as_float(w & 0xffff0000u); }
;     __device__ __forceinline__ void fused(f32x4 (&acc)[2][2][4][2], const pg8::Unit& u, int wr, int wc, int fr, int fq, PG8_LAS unsigned char* lds, int wid, int lane) const {
;     ...
;                 const int rl = ai * 128 + wr * 64 + m * 16 + fr; const size_t row = (size_t)u.pm * 256 + rl;
;                 const float rm = 1.f / sqrtf(__hip_atomic_load(ssqm + row, __ATOMIC_RELAXED, __HIP_MEMORY_SCOPE_AGENT) * (1.f / DM) + RMS_EPS);
;                 float sh = 0.f;
; #pragma unroll
;                 for (int bj = 0; bj < 2; ++bj) {
;                     const size_t off = row * DM + colb + bj * 128;
;                     f32x4 h0, h1;
;                     if (IN16) { const u32x4 hw = *(const u32x4*)((const bf16_t*)hin + off); h0 = (f32x4){bflo(hw.x), bfhi(hw.x), bflo(hw.y), bfhi(hw.y)}; h1 = (f32x4){bflo(hw.z), bfhi(hw.z), bflo(hw.w), bfhi(hw.w)}; }
;                     else { h0 = *(const f32x4*)((const float*)hin + off); h1 = *(const f32x4*)((const float*)hin + off + 4); }
;                     h0 = h0 + acc[ai][bj][m][0] * rm * gv[bj][0]; h1 = h1 + acc[ai][bj][m][1] * rm * gv[bj][1];
;                     sh += ((h0[0] * h0[0] + h0[1] * h0[1]) + (h0[2] * h0[2] + h0[3] * h0[3])) + ((h1[0] * h1[0] + h1[1] * h1[1]) + (h1[2] * h1[2] + h1[3] * h1[3]));
;                     if (OUT16) { u32x4 w; w.x = pk_bf16(h0[0], h0[1]); w.y = pk_bf16(h0[2], h0[3]); w.z = pk_bf16(h1[0], h1[1]); w.w = pk_bf16(h1[2], h1[3]); *(u32x4*)((bf16_t*)hout + off) = w; }
;                     else { *(f32x4*)((float*)hout + off) = h0; *(f32x4*)((float*)hout + off + 4) = h1; }
;                 }
;                 if (ssqh) { sh += __shfl_xor(sh, 16); sh += __shfl_xor(sh, 32); if (fq == 0) red[rl * 4 + wc] = sh; }
.LBB0_978:
	s_or_b64 exec, exec, s[0:1]
	v_add_u32_e32 v32, 0xa0, v152
	s_waitcnt lgkmcnt(0)
	v_mov_b32_e32 v33, 0
	v_lshl_add_u64 v[34:35], s[14:15], 0, v[32:33]
	v_lshl_add_u64 v[36:37], v[34:35], 2, s[12:13]
	global_load_dword v48, v[36:37], off sc1
	v_lshlrev_b64 v[34:35], 10, v[34:35]
	v_lshl_add_u64 v[44:45], v[34:35], 0, v[146:147]
	v_lshl_add_u64 v[46:47], v[44:45], 2, s[36:37]
	global_load_dwordx4 v[36:39], v[46:47], off
	global_load_dwordx4 v[40:43], v[46:47], off offset:16
	v_mov_b32_e32 v35, 0x358637bd
	v_lshlrev_b64 v[44:45], 1, v[44:45]
	s_waitcnt vmcnt(2)
	v_fmamk_f32 v34, v48, 0x3a800000, v35
	v_mul_f32_e32 v48, 0x4f800000, v34
	v_cmp_gt_f32_e32 vcc, s2, v34
	s_nop 1
	v_cndmask_b32_e32 v48, v34, v48, vcc
	v_sqrt_f32_e32 v49, v48
	v_mov_b32_e32 v34, 0x260
	v_add_u32_e32 v50, -1, v49
	v_add_u32_e32 v51, 1, v49
	v_fma_f32 v52, -v50, v49, v48
	v_fma_f32 v53, -v51, v49, v48
	v_cmp_ge_f32_e64 s[0:1], 0, v52
	s_nop 1
	v_cndmask_b32_e64 v49, v49, v50, s[0:1]
	v_cmp_lt_f32_e64 s[0:1], 0, v53
	s_nop 1
	v_cndmask_b32_e64 v49, v49, v51, s[0:1]
	v_mul_f32_e32 v50, 0x37800000, v49
	v_cndmask_b32_e32 v49, v49, v50, vcc
	v_cmp_class_f32_e32 vcc, v48, v34
	s_nop 1
	v_cndmask_b32_e32 v50, v49, v48, vcc
	v_div_scale_f32 v51, s[0:1], v50, v50, 1.0
	v_rcp_f32_e32 v52, v51
	v_div_scale_f32 v53, vcc, 1.0, v50, 1.0
	v_lshl_add_u64 v[48:49], s[10:11], 0, v[44:45]
	v_fma_f32 v54, -v51, v52, 1.0
	v_fmac_f32_e32 v52, v54, v52
	v_mul_f32_e32 v54, v53, v52
	v_fma_f32 v55, -v51, v54, v53
	v_fmac_f32_e32 v54, v55, v52
	v_fma_f32 v51, -v51, v54, v53
	v_div_fmas_f32 v51, v51, v52, v54
	v_div_fixup_f32 v50, v51, v50, 1.0
	v_pk_mul_f32 v[28:29], v[28:29], v[50:51] op_sel_hi:[1,0]
	v_pk_mul_f32 v[30:31], v[30:31], v[50:51] op_sel_hi:[1,0]
	v_pk_mul_f32 v[24:25], v[24:25], v[50:51] op_sel_hi:[1,0]
	v_pk_mul_f32 v[26:27], v[26:27], v[50:51] op_sel_hi:[1,0]
	s_waitcnt vmcnt(1)
	v_pk_fma_f32 v[38:39], v[110:111], v[30:31], v[38:39]
	v_pk_fma_f32 v[36:37], v[108:109], v[28:29], v[36:37]
	s_waitcnt vmcnt(0)
	v_pk_fma_f32 v[42:43], v[106:107], v[26:27], v[42:43]
	v_pk_fma_f32 v[40:41], v[104:105], v[24:25], v[40:41]
	v_cvt_pk_bf16_f32 v24, v36, v37
	v_cvt_pk_bf16_f32 v25, v38, v39
	v_cvt_pk_bf16_f32 v26, v40, v41
	v_cvt_pk_bf16_f32 v27, v42, v43
	global_store_dwordx4 v[48:49], v[24:27], off
	global_load_dwordx4 v[24:27], v[46:47], off offset:512
	s_nop 0
	global_load_dwordx4 v[28:31], v[46:47], off offset:528
	v_pk_mul_f32 v[20:21], v[20:21], v[50:51] op_sel_hi:[1,0]
	v_pk_mul_f32 v[22:23], v[22:23], v[50:51] op_sel_hi:[1,0]
	v_pk_mul_f32 v[16:17], v[16:17], v[50:51] op_sel_hi:[1,0]
	v_pk_mul_f32 v[18:19], v[18:19], v[50:51] op_sel_hi:[1,0]
	v_mul_f32_e32 v37, v37, v37
	v_mul_f32_e32 v39, v39, v39
	v_mul_f32_e32 v41, v41, v41
	v_mul_f32_e32 v43, v43, v43
	v_fmac_f32_e32 v37, v36, v36
	v_fmac_f32_e32 v39, v38, v38
	v_fmac_f32_e32 v41, v40, v40
	v_fmac_f32_e32 v43, v42, v42
	v_add_f32_e32 v36, v37, v39
	v_add_f32_e32 v37, v41, v43
	v_add_f32_e32 v36, v36, v37
	v_or_b32_e32 v44, 0x100, v44
	s_waitcnt vmcnt(1)
	v_pk_fma_f32 v[22:23], v[102:103], v[22:23], v[26:27]
	v_pk_fma_f32 v[20:21], v[100:101], v[20:21], v[24:25]
	s_waitcnt vmcnt(0)
	v_pk_fma_f32 v[24:25], v[98:99], v[18:19], v[30:31]
	v_pk_fma_f32 v[16:17], v[96:97], v[16:17], v[28:29]
	v_mul_f32_e32 v18, v21, v21
	v_mul_f32_e32 v19, v23, v23
	v_mul_f32_e32 v26, v17, v17
	v_mul_f32_e32 v27, v25, v25
	v_fmac_f32_e32 v18, v20, v20
	v_fmac_f32_e32 v19, v22, v22
	v_fmac_f32_e32 v26, v16, v16
	v_fmac_f32_e32 v27, v24, v24
	v_add_f32_e32 v18, v18, v19
	v_add_f32_e32 v19, v26, v27
	v_add_f32_e32 v18, v18, v19
	v_add_f32_e32 v26, v36, v18
	v_mov_b32_e32 v27, v26
	s_nop 1
	v_permlane16_swap_b32 v27, v26
	s_nop 0
	v_cvt_pk_bf16_f32 v18, v20, v21
	v_cvt_pk_bf16_f32 v20, v16, v17
	v_cvt_pk_bf16_f32 v19, v22, v23
	v_cvt_pk_bf16_f32 v21, v24, v25
	s_waitcnt lgkmcnt(0)
	v_add_f32_e32 v16, v26, v27
	v_mov_b32_e32 v17, v16
	s_nop 1
	v_permlane32_swap_b32 v17, v16
	s_nop 0
	v_lshl_add_u64 v[22:23], s[10:11], 0, v[44:45]
	global_store_dwordx4 v[22:23], v[18:21], off
	s_and_saveexec_b64 s[0:1], s[4:5]
	s_cbranch_execz .LBB0_980
	v_lshl_add_u32 v18, v32, 4, s22
	s_waitcnt lgkmcnt(0)
	v_add_f32_e32 v16, v16, v17
	ds_write_b32 v18, v16
; DI unsigned pk_bf16(float lo, float hi) { f32x2 v = {lo, hi}; bf16x2_t b = __builtin_convertvector(v, bf16x2_t); return __builtin_bit_cast(unsigned, b); }
; DI float bflo(unsigned w) { return __uint_as_float(w << 16); }
; DI float bfhi(unsigned w) { return __uint_as_float(w & 0xffff0000u); }
;     __device__ __forceinline__ void fused(f32x4 (&acc)[2][2][4][2], const pg8::Unit& u, int wr, int wc, int fr, int fq, PG8_LAS unsigned char* lds, int wid, int lane) const {
;     ...
;                 const int rl = ai * 128 + wr * 64 + m * 16 + fr; const size_t row = (size_t)u.pm * 256 + rl;
;                 const float rm = 1.f / sqrtf(__hip_atomic_load(ssqm + row, __ATOMIC_RELAXED, __HIP_MEMORY_SCOPE_AGENT) * (1.f / DM) + RMS_EPS);
;                 float sh = 0.f;
; #pragma unroll
;                 for (int bj = 0; bj < 2; ++bj) {
;                     const size_t off = row * DM + colb + bj * 128;
;                     f32x4 h0, h1;
;                     if (IN16) { const u32x4 hw = *(const u32x4*)((const bf16_t*)hin + off); h0 = (f32x4){bflo(hw.x), bfhi(hw.x), bflo(hw.y), bfhi(hw.y)}; h1 = (f32x4){bflo(hw.z), bfhi(hw.z), bflo(hw.w), bfhi(hw.w)}; }
;                     else { h0 = *(const f32x4*)((const float*)hin + off); h1 = *(const f32x4*)((const float*)hin + off + 4); }
;                     h0 = h0 + acc[ai][bj][m][0] * rm * gv[bj][0]; h1 = h1 + acc[ai][bj][m][1] * rm * gv[bj][1];
;                     sh += ((h0[0] * h0[0] + h0[1] * h0[1]) + (h0[2] * h0[2] + h0[3] * h0[3])) + ((h1[0] * h1[0] + h1[1] * h1[1]) + (h1[2] * h1[2] + h1[3] * h1[3]));
;                     if (OUT16) { u32x4 w; w.x = pk_bf16(h0[0], h0[1]); w.y = pk_bf16(h0[2], h0[3]); w.z = pk_bf16(h1[0], h1[1]); w.w = pk_bf16(h1[2], h1[3]); *(u32x4*)((bf16_t*)hout + off) = w; }
;                     else { *(f32x4*)((float*)hout + off) = h0; *(f32x4*)((float*)hout + off + 4) = h1; }
;                 }
;                 if (ssqh) { sh += __shfl_xor(sh, 16); sh += __shfl_xor(sh, 32); if (fq == 0) red[rl * 4 + wc] = sh; }
;             }
;         if (ssqh) { __syncthreads(); if (tid < 256) atomicAdd(ssqh + u.pm * 256 + tid, (red[tid * 4] + red[tid * 4 + 1]) + (red[tid * 4 + 2] + red[tid * 4 + 3])); }
.LBB0_980:
	s_or_b64 exec, exec, s[0:1]
	v_add_u32_e32 v32, 0xb0, v152
	s_waitcnt lgkmcnt(0)
	v_lshl_add_u64 v[16:17], s[14:15], 0, v[32:33]
	v_lshl_add_u64 v[18:19], v[16:17], 2, s[12:13]
	global_load_dword v28, v[18:19], off sc1
	v_lshlrev_b64 v[16:17], 10, v[16:17]
	v_lshl_add_u64 v[24:25], v[16:17], 0, v[146:147]
	v_lshl_add_u64 v[26:27], v[24:25], 2, s[36:37]
	global_load_dwordx4 v[16:19], v[26:27], off
	global_load_dwordx4 v[20:23], v[26:27], off offset:16
	v_lshlrev_b64 v[24:25], 1, v[24:25]
	s_waitcnt vmcnt(2)
	v_fmac_f32_e32 v35, 0x3a800000, v28
	v_mul_f32_e32 v28, 0x4f800000, v35
	v_cmp_gt_f32_e32 vcc, s2, v35
	s_nop 1
	v_cndmask_b32_e32 v28, v35, v28, vcc
	v_sqrt_f32_e32 v29, v28
	s_nop 0
	v_add_u32_e32 v30, -1, v29
	v_add_u32_e32 v31, 1, v29
	v_fma_f32 v33, -v30, v29, v28
	v_fma_f32 v35, -v31, v29, v28
	v_cmp_ge_f32_e64 s[0:1], 0, v33
	s_nop 1
	v_cndmask_b32_e64 v29, v29, v30, s[0:1]
	v_cmp_lt_f32_e64 s[0:1], 0, v35
	s_nop 1
	v_cndmask_b32_e64 v29, v29, v31, s[0:1]
	v_mul_f32_e32 v30, 0x37800000, v29
	v_cndmask_b32_e32 v29, v29, v30, vcc
	v_cmp_class_f32_e32 vcc, v28, v34
	s_nop 1
	v_cndmask_b32_e32 v30, v29, v28, vcc
	v_div_scale_f32 v31, s[0:1], v30, v30, 1.0
	v_rcp_f32_e32 v33, v31
	v_div_scale_f32 v34, vcc, 1.0, v30, 1.0
	v_lshl_add_u64 v[28:29], s[10:11], 0, v[24:25]
	v_fma_f32 v35, -v31, v33, 1.0
	v_fmac_f32_e32 v33, v35, v33
	v_mul_f32_e32 v35, v34, v33
	v_fma_f32 v36, -v31, v35, v34
	v_fmac_f32_e32 v35, v36, v33
	v_fma_f32 v31, -v31, v35, v34
	v_div_fmas_f32 v31, v31, v33, v35
	v_div_fixup_f32 v30, v31, v30, 1.0
	v_pk_mul_f32 v[12:13], v[12:13], v[30:31] op_sel_hi:[1,0]
	v_pk_mul_f32 v[14:15], v[14:15], v[30:31] op_sel_hi:[1,0]
	v_pk_mul_f32 v[8:9], v[8:9], v[30:31] op_sel_hi:[1,0]
	v_pk_mul_f32 v[10:11], v[10:11], v[30:31] op_sel_hi:[1,0]
	s_waitcnt vmcnt(1)
	v_pk_fma_f32 v[18:19], v[110:111], v[14:15], v[18:19]
	v_pk_fma_f32 v[16:17], v[108:109], v[12:13], v[16:17]
	s_waitcnt vmcnt(0)
	v_pk_fma_f32 v[22:23], v[106:107], v[10:11], v[22:23]
	v_pk_fma_f32 v[20:21], v[104:105], v[8:9], v[20:21]
	v_cvt_pk_bf16_f32 v8, v16, v17
	v_cvt_pk_bf16_f32 v9, v18, v19
	v_cvt_pk_bf16_f32 v10, v20, v21
	v_cvt_pk_bf16_f32 v11, v22, v23
	global_store_dwordx4 v[28:29], v[8:11], off
	global_load_dwordx4 v[8:11], v[26:27], off offset:512
	s_nop 0
	global_load_dwordx4 v[12:15], v[26:27], off offset:528
	v_pk_mul_f32 v[4:5], v[4:5], v[30:31] op_sel_hi:[1,0]
	v_pk_mul_f32 v[6:7], v[6:7], v[30:31] op_sel_hi:[1,0]
	v_pk_mul_f32 v[0:1], v[0:1], v[30:31] op_sel_hi:[1,0]
	v_pk_mul_f32 v[2:3], v[2:3], v[30:31] op_sel_hi:[1,0]
	v_mul_f32_e32 v17, v17, v17
	v_mul_f32_e32 v19, v19, v19
	v_mul_f32_e32 v21, v21, v21
	v_mul_f32_e32 v23, v23, v23
	v_fmac_f32_e32 v17, v16, v16
	v_fmac_f32_e32 v19, v18, v18
	v_fmac_f32_e32 v21, v20, v20
	v_fmac_f32_e32 v23, v22, v22
	v_add_f32_e32 v16, v17, v19
	v_add_f32_e32 v17, v21, v23
	v_add_f32_e32 v16, v16, v17
	v_or_b32_e32 v24, 0x100, v24
	s_waitcnt vmcnt(1)
	v_pk_fma_f32 v[6:7], v[102:103], v[6:7], v[10:11]
	v_pk_fma_f32 v[4:5], v[100:101], v[4:5], v[8:9]
	s_waitcnt vmcnt(0)
	v_pk_fma_f32 v[8:9], v[98:99], v[2:3], v[14:15]
	v_pk_fma_f32 v[0:1], v[96:97], v[0:1], v[12:13]
	v_mul_f32_e32 v2, v5, v5
	v_mul_f32_e32 v3, v7, v7
	v_mul_f32_e32 v10, v1, v1
	v_mul_f32_e32 v11, v9, v9
	v_fmac_f32_e32 v2, v4, v4
	v_fmac_f32_e32 v3, v6, v6
	v_fmac_f32_e32 v10, v0, v0
	v_fmac_f32_e32 v11, v8, v8
	v_add_f32_e32 v2, v2, v3
	v_add_f32_e32 v3, v10, v11
	v_add_f32_e32 v2, v2, v3
	v_add_f32_e32 v10, v16, v2
	v_mov_b32_e32 v11, v10
	s_nop 1
	v_permlane16_swap_b32 v11, v10
	s_nop 0
	v_cvt_pk_bf16_f32 v2, v4, v5
	v_cvt_pk_bf16_f32 v4, v0, v1
	v_cvt_pk_bf16_f32 v3, v6, v7
	v_cvt_pk_bf16_f32 v5, v8, v9
	s_waitcnt lgkmcnt(0)
	v_add_f32_e32 v0, v10, v11
	v_mov_b32_e32 v1, v0
	s_nop 1
	v_permlane32_swap_b32 v1, v0
	s_nop 0
	v_lshl_add_u64 v[6:7], s[10:11], 0, v[24:25]
	global_store_dwordx4 v[6:7], v[2:5], off
	s_and_saveexec_b64 s[0:1], s[4:5]
	s_cbranch_execz .LBB0_982
	v_lshl_add_u32 v2, v32, 4, s22
	s_waitcnt lgkmcnt(0)
	v_add_f32_e32 v0, v0, v1
	ds_write_b32 v2, v0

;     __device__ __forceinline__ void fused(f32x4 (&acc)[2][2][4][2], const pg8::Unit& u, int wr, int wc, int fr, int fq, PG8_LAS unsigned char* lds, int wid, int lane) const {
;     ...
;         for (int ai = 0; ai < 2; ++ai)
; #pragma unroll
;             for (int m = 0; m < 4; ++m) {
;                 float s = 0.f;
; #pragma unroll
;                 for (int bj = 0; bj < 2; ++bj)
; #pragma unroll
;                     for (int n = 0; n < 2; ++n) { const f32x4 x = acc[ai][bj][m][n]; s += (x[0] * x[0] + x[1] * x[1]) + (x[2] * x[2] + x[3] * x[3]); }
;                 s += __shfl_xor(s, 16); s += __shfl_xor(s, 32);
;                 if (fq == 0) red[(ai * 128 + wr * 64 + m * 16 + fr) * 4 + wc] = s;
;             }
;         __syncthreads();
.LBB0_1124:
	v_mbcnt_lo_u32_b32 v96, -1, 0
	v_mbcnt_hi_u32_b32 v96, -1, v96
	v_and_b32_e32 v98, 64, v96
	v_xor_b32_e32 v97, 16, v96
	v_add_u32_e32 v98, 64, v98
	v_cmp_lt_i32_e32 vcc, v97, v98
	v_mul_f32_e32 v99, v143, v143
	v_fmac_f32_e32 v99, v142, v142
	v_cndmask_b32_e32 v97, v96, v97, vcc
	v_lshlrev_b32_e32 v145, 2, v97
	v_mul_f32_e32 v97, v141, v141
	v_fmac_f32_e32 v97, v140, v140
	v_add_f32_e32 v97, v97, v99
	v_mul_f32_e32 v99, v137, v137
	v_mul_f32_e32 v100, v139, v139
	v_fmac_f32_e32 v99, v136, v136
	v_fmac_f32_e32 v100, v138, v138
	v_add_f32_e32 v99, v99, v100
	v_add_f32_e32 v97, v97, v99
	v_mul_f32_e32 v99, v133, v133
	v_mul_f32_e32 v100, v135, v135
	v_fmac_f32_e32 v99, v132, v132
	v_fmac_f32_e32 v100, v134, v134
	v_add_f32_e32 v99, v99, v100
	v_add_f32_e32 v97, v97, v99
	v_mul_f32_e32 v99, v129, v129
	v_mul_f32_e32 v100, v131, v131
	v_fmac_f32_e32 v99, v128, v128
	v_fmac_f32_e32 v100, v130, v130
	v_add_f32_e32 v99, v99, v100
	v_add_f32_e32 v97, v97, v99
	v_mov_b32_e32 v99, v97
	s_nop 1
	v_permlane16_swap_b32 v99, v97
	s_nop 0
	v_xor_b32_e32 v100, 32, v96
	v_cmp_lt_i32_e32 vcc, v100, v98
	s_lshl_b32 s0, s37, 2
	v_cmp_gt_u32_e64 s[4:5], 16, v192
	v_cndmask_b32_e32 v96, v96, v100, vcc
	v_lshlrev_b32_e32 v147, 2, v96
	s_waitcnt lgkmcnt(0)
	v_add_f32_e32 v96, v97, v99
	v_mov_b32_e32 v97, v96
	s_nop 1
	v_permlane32_swap_b32 v97, v96
	s_nop 0
	s_add_i32 s22, s0, 0
	s_barrier
	s_and_saveexec_b64 s[0:1], s[4:5]
	v_readlane_b32 s44, v251, 15
	v_readlane_b32 s45, v251, 16
	v_readlane_b32 s46, v251, 17
	v_readlane_b32 s47, v251, 18
	s_cbranch_execz .LBB0_1126
	s_lshl_b32 s3, s2, 10
	s_add_i32 s3, s22, s3
	s_waitcnt lgkmcnt(0)
	v_add_f32_e32 v96, v96, v97
	v_lshl_add_u32 v97, v161, 4, s3
	ds_write_b32 v97, v96

; DI unsigned pk_bf16(float lo, float hi) { f32x2 v = {lo, hi}; bf16x2_t b = __builtin_convertvector(v, bf16x2_t); return __builtin_bit_cast(unsigned, b); }
; DI float bflo(unsigned w) { return __uint_as_float(w << 16); }
; DI float bfhi(unsigned w) { return __uint_as_float(w & 0xffff0000u); }
;     __device__ __forceinline__ void fused(f32x4 (&acc)[2][2][4][2], const pg8::Unit& u, int wr, int wc, int fr, int fq, PG8_LAS unsigned char* lds, int wid, int lane) const {
;     ...
;         const int colb = u.pn * 256 + wc * 32 + 8 * fq;
;         f32x4 gv[2][2];
; #pragma unroll
;         for (int bj = 0; bj < 2; ++bj)
; #pragma unroll
;             for (int n = 0; n < 2; ++n) gv[bj][n] = *(const f32x4*)(gA + colb + bj * 128 + 4 * n);
; #pragma unroll
;         for (int ai = 0; ai < 2; ++ai)
; #pragma unroll
;             for (int m = 0; m < 4; ++m) {
;                 const int rl = ai * 128 + wr * 64 + m * 16 + fr; const size_t row = (size_t)u.pm * 256 + rl;
;                 const float rm = 1.f / sqrtf(__hip_atomic_load(ssqm + row, __ATOMIC_RELAXED, __HIP_MEMORY_SCOPE_AGENT) * (1.f / DM) + RMS_EPS);
;                 float sh = 0.f;
; #pragma unroll
;                 for (int bj = 0; bj < 2; ++bj) {
;                     const size_t off = row * DM + colb + bj * 128;
;                     f32x4 h0, h1;
;                     if (IN16) { const u32x4 hw = *(const u32x4*)((const bf16_t*)hin + off); h0 = (f32x4){bflo(hw.x), bfhi(hw.x), bflo(hw.y), bfhi(hw.y)}; h1 = (f32x4){bflo(hw.z), bfhi(hw.z), bflo(hw.w), bfhi(hw.w)}; }
;                     else { h0 = *(const f32x4*)((const float*)hin + off); h1 = *(const f32x4*)((const float*)hin + off + 4); }
;                     h0 = h0 + acc[ai][bj][m][0] * rm * gv[bj][0]; h1 = h1 + acc[ai][bj][m][1] * rm * gv[bj][1];
;                     sh += ((h0[0] * h0[0] + h0[1] * h0[1]) + (h0[2] * h0[2] + h0[3] * h0[3])) + ((h1[0] * h1[0] + h1[1] * h1[1]) + (h1[2] * h1[2] + h1[3] * h1[3]));
;                     if (OUT16) { u32x4 w; w.x = pk_bf16(h0[0], h0[1]); w.y = pk_bf16(h0[2], h0[3]); w.z = pk_bf16(h1[0], h1[1]); w.w = pk_bf16(h1[2], h1[3]); *(u32x4*)((bf16_t*)hout + off) = w; }
;                     else { *(f32x4*)((float*)hout + off) = h0; *(f32x4*)((float*)hout + off + 4) = h1; }
;                 }
;                 if (ssqh) { sh += __shfl_xor(sh, 16); sh += __shfl_xor(sh, 32); if (fq == 0) red[rl * 4 + wc] = sh; }
.LBB0_1147:
	s_or_b64 exec, exec, s[0:1]
	s_lshl_b32 s0, s37, 5
	s_lshl_b32 s1, s33, 8
	s_or_b32 s0, s1, s0
	v_mov_b32_e32 v159, 0
	v_or_b32_e32 v156, s0, v160
	s_lshl_b64 s[18:19], s[16:17], 8
	v_mov_b32_e32 v153, v159
	v_ashrrev_i32_e32 v157, 31, v156
	v_lshl_add_u64 v[168:169], s[18:19], 0, v[152:153]
	v_lshl_add_u64 v[108:109], v[156:157], 2, s[14:15]
	v_lshl_add_u64 v[170:171], v[168:169], 2, s[12:13]
	s_barrier
	global_load_dwordx4 v[100:103], v[108:109], off offset:16
	global_load_dwordx4 v[104:107], v[108:109], off
	global_load_dwordx4 v[96:99], v[108:109], off offset:528
	s_nop 0
	global_load_dwordx4 v[108:111], v[108:109], off offset:512
	v_lshlrev_b64 v[168:169], 11, v[168:169]
	global_load_dword v158, v[170:171], off sc1
	v_lshl_add_u64 v[168:169], s[10:11], 0, v[168:169]
	v_lshl_add_u64 v[176:177], v[156:157], 1, v[168:169]
	global_load_dwordx4 v[168:171], v[176:177], off
	global_load_dwordx4 v[172:175], v[176:177], off offset:256
	v_mov_b32_e32 v153, 0x358637bd
	s_mov_b32 s2, 0xf800000
	v_mov_b32_e32 v151, 0x260
	s_waitcnt vmcnt(2)
	v_fmamk_f32 v158, v158, 0x3a800000, v153
	v_mul_f32_e32 v184, 0x4f800000, v158
	v_cmp_gt_f32_e32 vcc, s2, v158
	s_waitcnt vmcnt(1)
	v_lshlrev_b32_e32 v178, 16, v168
	v_and_b32_e32 v179, 0xffff0000, v168
	v_cndmask_b32_e32 v158, v158, v184, vcc
	v_sqrt_f32_e32 v186, v158
	v_lshlrev_b32_e32 v168, 16, v169
	v_and_b32_e32 v169, 0xffff0000, v169
	v_lshlrev_b32_e32 v180, 16, v170
	v_add_u32_e32 v187, -1, v186
	v_add_u32_e32 v188, 1, v186
	v_fma_f32 v189, -v187, v186, v158
	v_fma_f32 v190, -v188, v186, v158
	v_cmp_ge_f32_e64 s[0:1], 0, v189
	v_and_b32_e32 v181, 0xffff0000, v170
	v_lshlrev_b32_e32 v170, 16, v171
	v_cndmask_b32_e64 v186, v186, v187, s[0:1]
	v_cmp_lt_f32_e64 s[0:1], 0, v190
	v_and_b32_e32 v171, 0xffff0000, v171
	s_waitcnt vmcnt(0)
	v_lshlrev_b32_e32 v182, 16, v172
	v_cndmask_b32_e64 v186, v186, v188, s[0:1]
	v_mul_f32_e32 v187, 0x37800000, v186
	v_cndmask_b32_e32 v186, v186, v187, vcc
	v_cmp_class_f32_e32 vcc, v158, v151
	v_and_b32_e32 v183, 0xffff0000, v172
	v_lshlrev_b32_e32 v172, 16, v173
	v_cndmask_b32_e32 v158, v186, v158, vcc
	v_div_scale_f32 v186, s[0:1], v158, v158, 1.0
	v_rcp_f32_e32 v187, v186
	v_div_scale_f32 v188, vcc, 1.0, v158, 1.0
	v_and_b32_e32 v173, 0xffff0000, v173
	v_fma_f32 v189, -v186, v187, 1.0
	v_fmac_f32_e32 v187, v189, v187
	v_mul_f32_e32 v189, v188, v187
	v_fma_f32 v190, -v186, v189, v188
	v_fmac_f32_e32 v189, v190, v187
	v_fma_f32 v186, -v186, v189, v188
	v_div_fmas_f32 v186, v186, v187, v189
	v_div_fixup_f32 v158, v186, v158, 1.0
	v_lshlrev_b32_e32 v184, 16, v174
	v_and_b32_e32 v185, 0xffff0000, v174
	v_lshlrev_b32_e32 v174, 16, v175
	v_and_b32_e32 v175, 0xffff0000, v175
	v_pk_mul_f32 v[140:141], v[140:141], v[158:159] op_sel_hi:[1,0]
	v_pk_mul_f32 v[142:143], v[142:143], v[158:159] op_sel_hi:[1,0]
	v_pk_mul_f32 v[136:137], v[136:137], v[158:159] op_sel_hi:[1,0]
	v_pk_mul_f32 v[138:139], v[138:139], v[158:159] op_sel_hi:[1,0]
	v_pk_mul_f32 v[132:133], v[132:133], v[158:159] op_sel_hi:[1,0]
	v_pk_mul_f32 v[134:135], v[134:135], v[158:159] op_sel_hi:[1,0]
	v_pk_mul_f32 v[128:129], v[128:129], v[158:159] op_sel_hi:[1,0]
	v_pk_mul_f32 v[130:131], v[130:131], v[158:159] op_sel_hi:[1,0]
	v_pk_fma_f32 v[142:143], v[106:107], v[142:143], v[168:169]
	v_pk_fma_f32 v[140:141], v[104:105], v[140:141], v[178:179]
	v_pk_fma_f32 v[138:139], v[102:103], v[138:139], v[170:171]
	v_pk_fma_f32 v[136:137], v[100:101], v[136:137], v[180:181]
	v_pk_fma_f32 v[134:135], v[110:111], v[134:135], v[172:173]
	v_pk_fma_f32 v[132:133], v[108:109], v[132:133], v[182:183]
	v_pk_fma_f32 v[168:169], v[98:99], v[130:131], v[174:175]
	v_pk_fma_f32 v[170:171], v[96:97], v[128:129], v[184:185]
	v_cvt_pk_bf16_f32 v128, v140, v141
	v_cvt_pk_bf16_f32 v129, v142, v143
	v_mul_f32_e32 v130, v141, v141
	v_mul_f32_e32 v131, v143, v143
	v_mul_f32_e32 v141, v137, v137
	v_mul_f32_e32 v143, v139, v139
	v_mul_f32_e32 v158, v133, v133
	v_mul_f32_e32 v172, v135, v135
	v_mul_f32_e32 v173, v171, v171
	v_mul_f32_e32 v174, v169, v169
	v_fmac_f32_e32 v130, v140, v140
	v_fmac_f32_e32 v131, v142, v142
	v_fmac_f32_e32 v141, v136, v136
	v_fmac_f32_e32 v143, v138, v138
	v_fmac_f32_e32 v158, v132, v132
	v_fmac_f32_e32 v172, v134, v134
	v_fmac_f32_e32 v173, v170, v170
	v_fmac_f32_e32 v174, v168, v168
	v_add_f32_e32 v130, v130, v131
	v_add_f32_e32 v131, v141, v143
	v_add_f32_e32 v140, v158, v172
	v_add_f32_e32 v141, v173, v174
	v_add_f32_e32 v130, v130, v131
	v_add_f32_e32 v131, v140, v141
	v_add_f32_e32 v140, v130, v131
	v_mov_b32_e32 v141, v140
	s_nop 1
	v_permlane16_swap_b32 v141, v140
	s_nop 0
	v_cvt_pk_bf16_f32 v130, v136, v137
	v_cvt_pk_bf16_f32 v131, v138, v139
	global_store_dwordx4 v[176:177], v[128:131], off
	s_waitcnt lgkmcnt(0)
	s_nop 0
	v_add_f32_e32 v128, v140, v141
	v_mov_b32_e32 v129, v128
	s_nop 1
	v_permlane32_swap_b32 v129, v128
	s_nop 0
	v_cvt_pk_bf16_f32 v130, v132, v133
	v_cvt_pk_bf16_f32 v131, v134, v135
	v_cvt_pk_bf16_f32 v132, v170, v171
	v_cvt_pk_bf16_f32 v133, v168, v169
	global_store_dwordx4 v[176:177], v[130:133], off offset:256
	s_and_saveexec_b64 s[0:1], s[4:5]
	s_cbranch_execz .LBB0_1149
	v_lshl_add_u32 v130, v152, 4, s22
	s_waitcnt lgkmcnt(0)
	v_add_f32_e32 v128, v128, v129
	ds_write_b32 v130, v128
; DI unsigned pk_bf16(float lo, float hi) { f32x2 v = {lo, hi}; bf16x2_t b = __builtin_convertvector(v, bf16x2_t); return __builtin_bit_cast(unsigned, b); }
; DI float bflo(unsigned w) { return __uint_as_float(w << 16); }
; DI float bfhi(unsigned w) { return __uint_as_float(w & 0xffff0000u); }
;     __device__ __forceinline__ void fused(f32x4 (&acc)[2][2][4][2], const pg8::Unit& u, int wr, int wc, int fr, int fq, PG8_LAS unsigned char* lds, int wid, int lane) const {
;     ...
;                 const int rl = ai * 128 + wr * 64 + m * 16 + fr; const size_t row = (size_t)u.pm * 256 + rl;
;                 const float rm = 1.f / sqrtf(__hip_atomic_load(ssqm + row, __ATOMIC_RELAXED, __HIP_MEMORY_SCOPE_AGENT) * (1.f / DM) + RMS_EPS);
;                 float sh = 0.f;
; #pragma unroll
;                 for (int bj = 0; bj < 2; ++bj) {
;                     const size_t off = row * DM + colb + bj * 128;
;                     f32x4 h0, h1;
;                     if (IN16) { const u32x4 hw = *(const u32x4*)((const bf16_t*)hin + off); h0 = (f32x4){bflo(hw.x), bfhi(hw.x), bflo(hw.y), bfhi(hw.y)}; h1 = (f32x4){bflo(hw.z), bfhi(hw.z), bflo(hw.w), bfhi(hw.w)}; }
;                     else { h0 = *(const f32x4*)((const float*)hin + off); h1 = *(const f32x4*)((const float*)hin + off + 4); }
;                     h0 = h0 + acc[ai][bj][m][0] * rm * gv[bj][0]; h1 = h1 + acc[ai][bj][m][1] * rm * gv[bj][1];
;                     sh += ((h0[0] * h0[0] + h0[1] * h0[1]) + (h0[2] * h0[2] + h0[3] * h0[3])) + ((h1[0] * h1[0] + h1[1] * h1[1]) + (h1[2] * h1[2] + h1[3] * h1[3]));
;                     if (OUT16) { u32x4 w; w.x = pk_bf16(h0[0], h0[1]); w.y = pk_bf16(h0[2], h0[3]); w.z = pk_bf16(h1[0], h1[1]); w.w = pk_bf16(h1[2], h1[3]); *(u32x4*)((bf16_t*)hout + off) = w; }
;                     else { *(f32x4*)((float*)hout + off) = h0; *(f32x4*)((float*)hout + off + 4) = h1; }
;                 }
;                 if (ssqh) { sh += __shfl_xor(sh, 16); sh += __shfl_xor(sh, 32); if (fq == 0) red[rl * 4 + wc] = sh; }
.LBB0_1149:
	s_or_b64 exec, exec, s[0:1]
	v_or_b32_e32 v158, 16, v152
	s_waitcnt lgkmcnt(0)
	v_lshl_add_u64 v[128:129], s[18:19], 0, v[158:159]
	v_lshl_add_u64 v[130:131], v[128:129], 2, s[12:13]
	global_load_dword v138, v[130:131], off sc1
	v_lshlrev_b64 v[128:129], 11, v[128:129]
	v_lshl_add_u64 v[128:129], s[10:11], 0, v[128:129]
	v_lshl_add_u64 v[136:137], v[156:157], 1, v[128:129]
	global_load_dwordx4 v[128:131], v[136:137], off
	global_load_dwordx4 v[132:135], v[136:137], off offset:256
	s_waitcnt vmcnt(2)
	v_fmac_f32_e32 v153, 0x3a800000, v138
	v_mul_f32_e32 v138, 0x4f800000, v153
	v_cmp_gt_f32_e32 vcc, s2, v153
	s_waitcnt vmcnt(1)
	v_and_b32_e32 v139, 0xffff0000, v128
	v_lshlrev_b32_e32 v140, 16, v130
	v_cndmask_b32_e32 v153, v153, v138, vcc
	v_sqrt_f32_e32 v159, v153
	v_lshlrev_b32_e32 v138, 16, v128
	v_lshlrev_b32_e32 v128, 16, v129
	v_and_b32_e32 v129, 0xffff0000, v129
	v_add_u32_e32 v170, -1, v159
	v_add_u32_e32 v171, 1, v159
	v_fma_f32 v172, -v170, v159, v153
	v_fma_f32 v173, -v171, v159, v153
	v_cmp_ge_f32_e64 s[0:1], 0, v172
	v_and_b32_e32 v141, 0xffff0000, v130
	v_lshlrev_b32_e32 v130, 16, v131
	v_cndmask_b32_e64 v159, v159, v170, s[0:1]
	v_cmp_lt_f32_e64 s[0:1], 0, v173
	v_and_b32_e32 v131, 0xffff0000, v131
	s_waitcnt vmcnt(0)
	v_lshlrev_b32_e32 v142, 16, v132
	v_cndmask_b32_e64 v159, v159, v171, s[0:1]
	v_mul_f32_e32 v170, 0x37800000, v159
	v_cndmask_b32_e32 v159, v159, v170, vcc
	v_cmp_class_f32_e32 vcc, v153, v151
	v_and_b32_e32 v143, 0xffff0000, v132
	v_lshlrev_b32_e32 v132, 16, v133
	v_cndmask_b32_e32 v151, v159, v153, vcc
	v_div_scale_f32 v153, s[0:1], v151, v151, 1.0
	v_rcp_f32_e32 v159, v153
	v_div_scale_f32 v170, vcc, 1.0, v151, 1.0
	v_and_b32_e32 v133, 0xffff0000, v133
	v_fma_f32 v171, -v153, v159, 1.0
	v_fmac_f32_e32 v159, v171, v159
	v_mul_f32_e32 v171, v170, v159
	v_fma_f32 v172, -v153, v171, v170
	v_fmac_f32_e32 v171, v172, v159
	v_fma_f32 v153, -v153, v171, v170
	v_div_fmas_f32 v153, v153, v159, v171
	v_div_fixup_f32 v170, v153, v151, 1.0
	v_lshlrev_b32_e32 v168, 16, v134
	v_and_b32_e32 v169, 0xffff0000, v134
	v_lshlrev_b32_e32 v134, 16, v135
	v_and_b32_e32 v135, 0xffff0000, v135
	v_pk_mul_f32 v[124:125], v[124:125], v[170:171] op_sel_hi:[1,0]
	v_pk_mul_f32 v[126:127], v[126:127], v[170:171] op_sel_hi:[1,0]
	v_pk_mul_f32 v[120:121], v[120:121], v[170:171] op_sel_hi:[1,0]
	v_pk_mul_f32 v[122:123], v[122:123], v[170:171] op_sel_hi:[1,0]
	v_pk_mul_f32 v[116:117], v[116:117], v[170:171] op_sel_hi:[1,0]
	v_pk_mul_f32 v[118:119], v[118:119], v[170:171] op_sel_hi:[1,0]
	v_pk_mul_f32 v[112:113], v[112:113], v[170:171] op_sel_hi:[1,0]
	v_pk_mul_f32 v[114:115], v[114:115], v[170:171] op_sel_hi:[1,0]
	v_pk_fma_f32 v[126:127], v[106:107], v[126:127], v[128:129]
	v_pk_fma_f32 v[124:125], v[104:105], v[124:125], v[138:139]
	v_pk_fma_f32 v[122:123], v[102:103], v[122:123], v[130:131]
	v_pk_fma_f32 v[120:121], v[100:101], v[120:121], v[140:141]
	v_pk_fma_f32 v[118:119], v[110:111], v[118:119], v[132:133]
	v_pk_fma_f32 v[116:117], v[108:109], v[116:117], v[142:143]
	v_pk_fma_f32 v[128:129], v[98:99], v[114:115], v[134:135]
	v_pk_fma_f32 v[130:131], v[96:97], v[112:113], v[168:169]
	v_cvt_pk_bf16_f32 v112, v124, v125
	v_cvt_pk_bf16_f32 v113, v126, v127
	v_mul_f32_e32 v114, v125, v125
	v_mul_f32_e32 v115, v127, v127
	v_mul_f32_e32 v125, v121, v121
	v_mul_f32_e32 v127, v123, v123
	v_mul_f32_e32 v132, v117, v117
	v_mul_f32_e32 v133, v119, v119
	v_mul_f32_e32 v134, v131, v131
	v_mul_f32_e32 v135, v129, v129
	v_fmac_f32_e32 v114, v124, v124
	v_fmac_f32_e32 v115, v126, v126
	v_fmac_f32_e32 v125, v120, v120
	v_fmac_f32_e32 v127, v122, v122
	v_fmac_f32_e32 v132, v116, v116
	v_fmac_f32_e32 v133, v118, v118
	v_fmac_f32_e32 v134, v130, v130
	v_fmac_f32_e32 v135, v128, v128
	v_add_f32_e32 v114, v114, v115
	v_add_f32_e32 v115, v125, v127
	v_add_f32_e32 v124, v132, v133
	v_add_f32_e32 v125, v134, v135
	v_add_f32_e32 v114, v114, v115
	v_add_f32_e32 v115, v124, v125
	v_add_f32_e32 v124, v114, v115
	v_mov_b32_e32 v125, v124
	s_nop 1
	v_permlane16_swap_b32 v125, v124
	s_nop 0
	v_cvt_pk_bf16_f32 v114, v120, v121
	v_cvt_pk_bf16_f32 v115, v122, v123
	global_store_dwordx4 v[136:137], v[112:115], off
	s_waitcnt lgkmcnt(0)
	s_nop 0
	v_add_f32_e32 v112, v124, v125
	v_mov_b32_e32 v113, v112
	s_nop 1
	v_permlane32_swap_b32 v113, v112
	s_nop 0
	v_cvt_pk_bf16_f32 v114, v116, v117
	v_cvt_pk_bf16_f32 v115, v118, v119
	v_cvt_pk_bf16_f32 v116, v130, v131
	v_cvt_pk_bf16_f32 v117, v128, v129
	global_store_dwordx4 v[136:137], v[114:117], off offset:256
	s_and_saveexec_b64 s[0:1], s[4:5]
	s_cbranch_execz .LBB0_1151
	v_lshl_add_u32 v114, v158, 4, s22
	s_waitcnt lgkmcnt(0)
	v_add_f32_e32 v112, v112, v113
	ds_write_b32 v114, v112
; DI unsigned pk_bf16(float lo, float hi) { f32x2 v = {lo, hi}; bf16x2_t b = __builtin_convertvector(v, bf16x2_t); return __builtin_bit_cast(unsigned, b); }
; DI float bflo(unsigned w) { return __uint_as_float(w << 16); }
; DI float bfhi(unsigned w) { return __uint_as_float(w & 0xffff0000u); }
;     __device__ __forceinline__ void fused(f32x4 (&acc)[2][2][4][2], const pg8::Unit& u, int wr, int wc, int fr, int fq, PG8_LAS unsigned char* lds, int wid, int lane) const {
;     ...
;                 const int rl = ai * 128 + wr * 64 + m * 16 + fr; const size_t row = (size_t)u.pm * 256 + rl;
;                 const float rm = 1.f / sqrtf(__hip_atomic_load(ssqm + row, __ATOMIC_RELAXED, __HIP_MEMORY_SCOPE_AGENT) * (1.f / DM) + RMS_EPS);
;                 float sh = 0.f;
; #pragma unroll
;                 for (int bj = 0; bj < 2; ++bj) {
;                     const size_t off = row * DM + colb + bj * 128;
;                     f32x4 h0, h1;
;                     if (IN16) { const u32x4 hw = *(const u32x4*)((const bf16_t*)hin + off); h0 = (f32x4){bflo(hw.x), bfhi(hw.x), bflo(hw.y), bfhi(hw.y)}; h1 = (f32x4){bflo(hw.z), bfhi(hw.z), bflo(hw.w), bfhi(hw.w)}; }
;                     else { h0 = *(const f32x4*)((const float*)hin + off); h1 = *(const f32x4*)((const float*)hin + off + 4); }
;                     h0 = h0 + acc[ai][bj][m][0] * rm * gv[bj][0]; h1 = h1 + acc[ai][bj][m][1] * rm * gv[bj][1];
;                     sh += ((h0[0] * h0[0] + h0[1] * h0[1]) + (h0[2] * h0[2] + h0[3] * h0[3])) + ((h1[0] * h1[0] + h1[1] * h1[1]) + (h1[2] * h1[2] + h1[3] * h1[3]));
;                     if (OUT16) { u32x4 w; w.x = pk_bf16(h0[0], h0[1]); w.y = pk_bf16(h0[2], h0[3]); w.z = pk_bf16(h1[0], h1[1]); w.w = pk_bf16(h1[2], h1[3]); *(u32x4*)((bf16_t*)hout + off) = w; }
;                     else { *(f32x4*)((float*)hout + off) = h0; *(f32x4*)((float*)hout + off + 4) = h1; }
;                 }
;                 if (ssqh) { sh += __shfl_xor(sh, 16); sh += __shfl_xor(sh, 32); if (fq == 0) red[rl * 4 + wc] = sh; }
.LBB0_1151:
	s_or_b64 exec, exec, s[0:1]
	v_or_b32_e32 v112, 32, v152
	s_waitcnt lgkmcnt(0)
	v_mov_b32_e32 v113, 0
	v_lshl_add_u64 v[114:115], s[18:19], 0, v[112:113]
	v_lshl_add_u64 v[116:117], v[114:115], 2, s[12:13]
	global_load_dword v126, v[116:117], off sc1
	v_lshlrev_b64 v[114:115], 11, v[114:115]
	v_lshl_add_u64 v[114:115], s[10:11], 0, v[114:115]
	v_lshl_add_u64 v[124:125], v[156:157], 1, v[114:115]
	global_load_dwordx4 v[116:119], v[124:125], off
	global_load_dwordx4 v[120:123], v[124:125], off offset:256
	v_mov_b32_e32 v115, 0x358637bd
	v_mov_b32_e32 v114, 0x260
	s_waitcnt vmcnt(2)
	v_fmamk_f32 v126, v126, 0x3a800000, v115
	v_mul_f32_e32 v127, 0x4f800000, v126
	v_cmp_gt_f32_e32 vcc, s2, v126
	s_waitcnt vmcnt(1)
	v_lshlrev_b32_e32 v128, 16, v118
	v_and_b32_e32 v129, 0xffff0000, v118
	v_cndmask_b32_e32 v134, v126, v127, vcc
	v_sqrt_f32_e32 v135, v134
	v_lshlrev_b32_e32 v126, 16, v116
	v_and_b32_e32 v127, 0xffff0000, v116
	v_lshlrev_b32_e32 v116, 16, v117
	v_add_u32_e32 v136, -1, v135
	v_add_u32_e32 v137, 1, v135
	v_fma_f32 v138, -v136, v135, v134
	v_fma_f32 v139, -v137, v135, v134
	v_cmp_ge_f32_e64 s[0:1], 0, v138
	v_and_b32_e32 v117, 0xffff0000, v117
	v_lshlrev_b32_e32 v118, 16, v119
	v_cndmask_b32_e64 v135, v135, v136, s[0:1]
	v_cmp_lt_f32_e64 s[0:1], 0, v139
	v_and_b32_e32 v119, 0xffff0000, v119
	s_waitcnt vmcnt(0)
	v_lshlrev_b32_e32 v130, 16, v120
	v_cndmask_b32_e64 v135, v135, v137, s[0:1]
	v_mul_f32_e32 v136, 0x37800000, v135
	v_cndmask_b32_e32 v135, v135, v136, vcc
	v_cmp_class_f32_e32 vcc, v134, v114
	v_and_b32_e32 v131, 0xffff0000, v120
	v_lshlrev_b32_e32 v120, 16, v121
	v_cndmask_b32_e32 v134, v135, v134, vcc
	v_div_scale_f32 v135, s[0:1], v134, v134, 1.0
	v_rcp_f32_e32 v136, v135
	v_div_scale_f32 v137, vcc, 1.0, v134, 1.0
	v_and_b32_e32 v121, 0xffff0000, v121
	v_fma_f32 v138, -v135, v136, 1.0
	v_fmac_f32_e32 v136, v138, v136
	v_mul_f32_e32 v138, v137, v136
	v_fma_f32 v139, -v135, v138, v137
	v_fmac_f32_e32 v138, v139, v136
	v_fma_f32 v135, -v135, v138, v137
	v_div_fmas_f32 v135, v135, v136, v138
	v_div_fixup_f32 v134, v135, v134, 1.0
	v_lshlrev_b32_e32 v132, 16, v122
	v_and_b32_e32 v133, 0xffff0000, v122
	v_lshlrev_b32_e32 v122, 16, v123
	v_and_b32_e32 v123, 0xffff0000, v123
	v_pk_mul_f32 v[92:93], v[92:93], v[134:135] op_sel_hi:[1,0]
	v_pk_mul_f32 v[94:95], v[94:95], v[134:135] op_sel_hi:[1,0]
	v_pk_mul_f32 v[88:89], v[88:89], v[134:135] op_sel_hi:[1,0]
	v_pk_mul_f32 v[90:91], v[90:91], v[134:135] op_sel_hi:[1,0]
	v_pk_mul_f32 v[84:85], v[84:85], v[134:135] op_sel_hi:[1,0]
	v_pk_mul_f32 v[86:87], v[86:87], v[134:135] op_sel_hi:[1,0]
	v_pk_mul_f32 v[80:81], v[80:81], v[134:135] op_sel_hi:[1,0]
	v_pk_mul_f32 v[82:83], v[82:83], v[134:135] op_sel_hi:[1,0]
	v_pk_fma_f32 v[94:95], v[106:107], v[94:95], v[116:117]
	v_pk_fma_f32 v[92:93], v[104:105], v[92:93], v[126:127]
	v_pk_fma_f32 v[90:91], v[102:103], v[90:91], v[118:119]
	v_pk_fma_f32 v[88:89], v[100:101], v[88:89], v[128:129]
	v_pk_fma_f32 v[86:87], v[110:111], v[86:87], v[120:121]
	v_pk_fma_f32 v[84:85], v[108:109], v[84:85], v[130:131]
	v_pk_fma_f32 v[116:117], v[98:99], v[82:83], v[122:123]
	v_pk_fma_f32 v[118:119], v[96:97], v[80:81], v[132:133]
	v_cvt_pk_bf16_f32 v80, v92, v93
	v_cvt_pk_bf16_f32 v81, v94, v95
	v_mul_f32_e32 v82, v93, v93
	v_mul_f32_e32 v83, v95, v95
	v_mul_f32_e32 v93, v89, v89
	v_mul_f32_e32 v95, v91, v91
	v_mul_f32_e32 v120, v85, v85
	v_mul_f32_e32 v121, v87, v87
	v_mul_f32_e32 v122, v119, v119
	v_mul_f32_e32 v123, v117, v117
	v_fmac_f32_e32 v82, v92, v92
	v_fmac_f32_e32 v83, v94, v94
	v_fmac_f32_e32 v93, v88, v88
	v_fmac_f32_e32 v95, v90, v90
	v_fmac_f32_e32 v120, v84, v84
	v_fmac_f32_e32 v121, v86, v86
	v_fmac_f32_e32 v122, v118, v118
	v_fmac_f32_e32 v123, v116, v116
	v_add_f32_e32 v82, v82, v83
	v_add_f32_e32 v83, v93, v95
	v_add_f32_e32 v92, v120, v121
	v_add_f32_e32 v93, v122, v123
	v_add_f32_e32 v82, v82, v83
	v_add_f32_e32 v83, v92, v93
	v_add_f32_e32 v92, v82, v83
	v_mov_b32_e32 v93, v92
	s_nop 1
	v_permlane16_swap_b32 v93, v92
	s_nop 0
	v_cvt_pk_bf16_f32 v82, v88, v89
	v_cvt_pk_bf16_f32 v83, v90, v91
	global_store_dwordx4 v[124:125], v[80:83], off
	s_waitcnt lgkmcnt(0)
	s_nop 0
	v_add_f32_e32 v80, v92, v93
	v_mov_b32_e32 v81, v80
	s_nop 1
	v_permlane32_swap_b32 v81, v80
	s_nop 0
	v_cvt_pk_bf16_f32 v82, v84, v85
	v_cvt_pk_bf16_f32 v83, v86, v87
	v_cvt_pk_bf16_f32 v84, v118, v119
	v_cvt_pk_bf16_f32 v85, v116, v117
	global_store_dwordx4 v[124:125], v[82:85], off offset:256
	s_and_saveexec_b64 s[0:1], s[4:5]
	s_cbranch_execz .LBB0_1153
	v_lshl_add_u32 v82, v112, 4, s22
	s_waitcnt lgkmcnt(0)
	v_add_f32_e32 v80, v80, v81
	ds_write_b32 v82, v80
; DI unsigned pk_bf16(float lo, float hi) { f32x2 v = {lo, hi}; bf16x2_t b = __builtin_convertvector(v, bf16x2_t); return __builtin_bit_cast(unsigned, b); }
; DI float bflo(unsigned w) { return __uint_as_float(w << 16); }
; DI float bfhi(unsigned w) { return __uint_as_float(w & 0xffff0000u); }
;     __device__ __forceinline__ void fused(f32x4 (&acc)[2][2][4][2], const pg8::Unit& u, int wr, int wc, int fr, int fq, PG8_LAS unsigned char* lds, int wid, int lane) const {
;     ...
;                 const int rl = ai * 128 + wr * 64 + m * 16 + fr; const size_t row = (size_t)u.pm * 256 + rl;
;                 const float rm = 1.f / sqrtf(__hip_atomic_load(ssqm + row, __ATOMIC_RELAXED, __HIP_MEMORY_SCOPE_AGENT) * (1.f / DM) + RMS_EPS);
;                 float sh = 0.f;
; #pragma unroll
;                 for (int bj = 0; bj < 2; ++bj) {
;                     const size_t off = row * DM + colb + bj * 128;
;                     f32x4 h0, h1;
;                     if (IN16) { const u32x4 hw = *(const u32x4*)((const bf16_t*)hin + off); h0 = (f32x4){bflo(hw.x), bfhi(hw.x), bflo(hw.y), bfhi(hw.y)}; h1 = (f32x4){bflo(hw.z), bfhi(hw.z), bflo(hw.w), bfhi(hw.w)}; }
;                     else { h0 = *(const f32x4*)((const float*)hin + off); h1 = *(const f32x4*)((const float*)hin + off + 4); }
;                     h0 = h0 + acc[ai][bj][m][0] * rm * gv[bj][0]; h1 = h1 + acc[ai][bj][m][1] * rm * gv[bj][1];
;                     sh += ((h0[0] * h0[0] + h0[1] * h0[1]) + (h0[2] * h0[2] + h0[3] * h0[3])) + ((h1[0] * h1[0] + h1[1] * h1[1]) + (h1[2] * h1[2] + h1[3] * h1[3]));
;                     if (OUT16) { u32x4 w; w.x = pk_bf16(h0[0], h0[1]); w.y = pk_bf16(h0[2], h0[3]); w.z = pk_bf16(h1[0], h1[1]); w.w = pk_bf16(h1[2], h1[3]); *(u32x4*)((bf16_t*)hout + off) = w; }
;                     else { *(f32x4*)((float*)hout + off) = h0; *(f32x4*)((float*)hout + off + 4) = h1; }
;                 }
;                 if (ssqh) { sh += __shfl_xor(sh, 16); sh += __shfl_xor(sh, 32); if (fq == 0) red[rl * 4 + wc] = sh; }
.LBB0_1153:
	s_or_b64 exec, exec, s[0:1]
	v_or_b32_e32 v112, 48, v152
	s_waitcnt lgkmcnt(0)
	v_lshl_add_u64 v[80:81], s[18:19], 0, v[112:113]
	v_lshl_add_u64 v[82:83], v[80:81], 2, s[12:13]
	global_load_dword v90, v[82:83], off sc1
	v_lshlrev_b64 v[80:81], 11, v[80:81]
	v_lshl_add_u64 v[80:81], s[10:11], 0, v[80:81]
	v_lshl_add_u64 v[88:89], v[156:157], 1, v[80:81]
	global_load_dwordx4 v[80:83], v[88:89], off
	global_load_dwordx4 v[84:87], v[88:89], off offset:256
	s_waitcnt vmcnt(2)
	v_fmac_f32_e32 v115, 0x3a800000, v90
	v_mul_f32_e32 v90, 0x4f800000, v115
	v_cmp_gt_f32_e32 vcc, s2, v115
	s_waitcnt vmcnt(1)
	v_and_b32_e32 v91, 0xffff0000, v80
	v_lshlrev_b32_e32 v92, 16, v82
	v_cndmask_b32_e32 v113, v115, v90, vcc
	v_sqrt_f32_e32 v115, v113
	v_lshlrev_b32_e32 v90, 16, v80
	v_lshlrev_b32_e32 v80, 16, v81
	v_and_b32_e32 v81, 0xffff0000, v81
	v_add_u32_e32 v118, -1, v115
	v_add_u32_e32 v119, 1, v115
	v_fma_f32 v120, -v118, v115, v113
	v_fma_f32 v121, -v119, v115, v113
	v_cmp_ge_f32_e64 s[0:1], 0, v120
	v_and_b32_e32 v93, 0xffff0000, v82
	v_lshlrev_b32_e32 v82, 16, v83
	v_cndmask_b32_e64 v115, v115, v118, s[0:1]
	v_cmp_lt_f32_e64 s[0:1], 0, v121
	v_and_b32_e32 v83, 0xffff0000, v83
	s_waitcnt vmcnt(0)
	v_lshlrev_b32_e32 v94, 16, v84
	v_cndmask_b32_e64 v115, v115, v119, s[0:1]
	v_mul_f32_e32 v118, 0x37800000, v115
	v_cndmask_b32_e32 v115, v115, v118, vcc
	v_cmp_class_f32_e32 vcc, v113, v114
	v_and_b32_e32 v95, 0xffff0000, v84
	v_lshlrev_b32_e32 v84, 16, v85
	v_cndmask_b32_e32 v113, v115, v113, vcc
	v_div_scale_f32 v114, s[0:1], v113, v113, 1.0
	v_rcp_f32_e32 v115, v114
	v_div_scale_f32 v118, vcc, 1.0, v113, 1.0
	v_and_b32_e32 v85, 0xffff0000, v85
	v_fma_f32 v119, -v114, v115, 1.0
	v_fmac_f32_e32 v115, v119, v115
	v_mul_f32_e32 v119, v118, v115
	v_fma_f32 v120, -v114, v119, v118
	v_fmac_f32_e32 v119, v120, v115
	v_fma_f32 v114, -v114, v119, v118
	v_div_fmas_f32 v114, v114, v115, v119
	v_div_fixup_f32 v114, v114, v113, 1.0
	v_lshlrev_b32_e32 v116, 16, v86
	v_and_b32_e32 v117, 0xffff0000, v86
	v_lshlrev_b32_e32 v86, 16, v87
	v_and_b32_e32 v87, 0xffff0000, v87
	v_pk_mul_f32 v[76:77], v[76:77], v[114:115] op_sel_hi:[1,0]
	v_pk_mul_f32 v[78:79], v[78:79], v[114:115] op_sel_hi:[1,0]
	v_pk_mul_f32 v[72:73], v[72:73], v[114:115] op_sel_hi:[1,0]
	v_pk_mul_f32 v[74:75], v[74:75], v[114:115] op_sel_hi:[1,0]
	v_pk_mul_f32 v[68:69], v[68:69], v[114:115] op_sel_hi:[1,0]
	v_pk_mul_f32 v[70:71], v[70:71], v[114:115] op_sel_hi:[1,0]
	v_pk_mul_f32 v[64:65], v[64:65], v[114:115] op_sel_hi:[1,0]
	v_pk_mul_f32 v[66:67], v[66:67], v[114:115] op_sel_hi:[1,0]
	v_pk_fma_f32 v[78:79], v[106:107], v[78:79], v[80:81]
	v_pk_fma_f32 v[76:77], v[104:105], v[76:77], v[90:91]
	v_pk_fma_f32 v[74:75], v[102:103], v[74:75], v[82:83]
	v_pk_fma_f32 v[72:73], v[100:101], v[72:73], v[92:93]
	v_pk_fma_f32 v[70:71], v[110:111], v[70:71], v[84:85]
	v_pk_fma_f32 v[68:69], v[108:109], v[68:69], v[94:95]
	v_pk_fma_f32 v[80:81], v[98:99], v[66:67], v[86:87]
	v_pk_fma_f32 v[82:83], v[96:97], v[64:65], v[116:117]
	v_cvt_pk_bf16_f32 v64, v76, v77
	v_cvt_pk_bf16_f32 v65, v78, v79
	v_mul_f32_e32 v66, v77, v77
	v_mul_f32_e32 v67, v79, v79
	v_mul_f32_e32 v77, v73, v73
	v_mul_f32_e32 v79, v75, v75
	v_mul_f32_e32 v84, v69, v69
	v_mul_f32_e32 v85, v71, v71
	v_mul_f32_e32 v86, v83, v83
	v_mul_f32_e32 v87, v81, v81
	v_fmac_f32_e32 v66, v76, v76
	v_fmac_f32_e32 v67, v78, v78
	v_fmac_f32_e32 v77, v72, v72
	v_fmac_f32_e32 v79, v74, v74
	v_fmac_f32_e32 v84, v68, v68
	v_fmac_f32_e32 v85, v70, v70
	v_fmac_f32_e32 v86, v82, v82
	v_fmac_f32_e32 v87, v80, v80
	v_add_f32_e32 v66, v66, v67
	v_add_f32_e32 v67, v77, v79
	v_add_f32_e32 v76, v84, v85
	v_add_f32_e32 v77, v86, v87
	v_add_f32_e32 v66, v66, v67
	v_add_f32_e32 v67, v76, v77
	v_add_f32_e32 v76, v66, v67
	v_mov_b32_e32 v77, v76
	s_nop 1
	v_permlane16_swap_b32 v77, v76
	s_nop 0
	v_cvt_pk_bf16_f32 v66, v72, v73
	v_cvt_pk_bf16_f32 v67, v74, v75
	global_store_dwordx4 v[88:89], v[64:67], off
	s_waitcnt lgkmcnt(0)
	s_nop 0
	v_add_f32_e32 v64, v76, v77
	v_mov_b32_e32 v65, v64
	s_nop 1
	v_permlane32_swap_b32 v65, v64
	s_nop 0
	v_cvt_pk_bf16_f32 v66, v68, v69
	v_cvt_pk_bf16_f32 v67, v70, v71
	v_cvt_pk_bf16_f32 v68, v82, v83
	v_cvt_pk_bf16_f32 v69, v80, v81
	global_store_dwordx4 v[88:89], v[66:69], off offset:256
	s_and_saveexec_b64 s[0:1], s[4:5]
	s_cbranch_execz .LBB0_1155
	v_lshl_add_u32 v66, v112, 4, s22
	s_waitcnt lgkmcnt(0)
	v_add_f32_e32 v64, v64, v65
	ds_write_b32 v66, v64
; DI unsigned pk_bf16(float lo, float hi) { f32x2 v = {lo, hi}; bf16x2_t b = __builtin_convertvector(v, bf16x2_t); return __builtin_bit_cast(unsigned, b); }
; DI float bflo(unsigned w) { return __uint_as_float(w << 16); }
; DI float bfhi(unsigned w) { return __uint_as_float(w & 0xffff0000u); }
;     __device__ __forceinline__ void fused(f32x4 (&acc)[2][2][4][2], const pg8::Unit& u, int wr, int wc, int fr, int fq, PG8_LAS unsigned char* lds, int wid, int lane) const {
;     ...
;                 const int rl = ai * 128 + wr * 64 + m * 16 + fr; const size_t row = (size_t)u.pm * 256 + rl;
;                 const float rm = 1.f / sqrtf(__hip_atomic_load(ssqm + row, __ATOMIC_RELAXED, __HIP_MEMORY_SCOPE_AGENT) * (1.f / DM) + RMS_EPS);
;                 float sh = 0.f;
; #pragma unroll
;                 for (int bj = 0; bj < 2; ++bj) {
;                     const size_t off = row * DM + colb + bj * 128;
;                     f32x4 h0, h1;
;                     if (IN16) { const u32x4 hw = *(const u32x4*)((const bf16_t*)hin + off); h0 = (f32x4){bflo(hw.x), bfhi(hw.x), bflo(hw.y), bfhi(hw.y)}; h1 = (f32x4){bflo(hw.z), bfhi(hw.z), bflo(hw.w), bfhi(hw.w)}; }
;                     else { h0 = *(const f32x4*)((const float*)hin + off); h1 = *(const f32x4*)((const float*)hin + off + 4); }
;                     h0 = h0 + acc[ai][bj][m][0] * rm * gv[bj][0]; h1 = h1 + acc[ai][bj][m][1] * rm * gv[bj][1];
;                     sh += ((h0[0] * h0[0] + h0[1] * h0[1]) + (h0[2] * h0[2] + h0[3] * h0[3])) + ((h1[0] * h1[0] + h1[1] * h1[1]) + (h1[2] * h1[2] + h1[3] * h1[3]));
;                     if (OUT16) { u32x4 w; w.x = pk_bf16(h0[0], h0[1]); w.y = pk_bf16(h0[2], h0[3]); w.z = pk_bf16(h1[0], h1[1]); w.w = pk_bf16(h1[2], h1[3]); *(u32x4*)((bf16_t*)hout + off) = w; }
;                     else { *(f32x4*)((float*)hout + off) = h0; *(f32x4*)((float*)hout + off + 4) = h1; }
;                 }
;                 if (ssqh) { sh += __shfl_xor(sh, 16); sh += __shfl_xor(sh, 32); if (fq == 0) red[rl * 4 + wc] = sh; }
.LBB0_1155:
	s_or_b64 exec, exec, s[0:1]
	v_add_u32_e32 v64, 0x80, v152
	s_waitcnt lgkmcnt(0)
	v_mov_b32_e32 v65, 0
	v_lshl_add_u64 v[66:67], s[18:19], 0, v[64:65]
	v_lshl_add_u64 v[68:69], v[66:67], 2, s[12:13]
	global_load_dword v78, v[68:69], off sc1
	v_lshlrev_b64 v[66:67], 11, v[66:67]
	v_lshl_add_u64 v[66:67], s[10:11], 0, v[66:67]
	v_lshl_add_u64 v[76:77], v[156:157], 1, v[66:67]
	global_load_dwordx4 v[68:71], v[76:77], off
	global_load_dwordx4 v[72:75], v[76:77], off offset:256
	v_mov_b32_e32 v67, 0x358637bd
	v_mov_b32_e32 v66, 0x260
	s_waitcnt vmcnt(2)
	v_fmamk_f32 v78, v78, 0x3a800000, v67
	v_mul_f32_e32 v79, 0x4f800000, v78
	v_cmp_gt_f32_e32 vcc, s2, v78
	s_waitcnt vmcnt(1)
	v_lshlrev_b32_e32 v80, 16, v70
	v_and_b32_e32 v81, 0xffff0000, v70
	v_cndmask_b32_e32 v86, v78, v79, vcc
	v_sqrt_f32_e32 v87, v86
	v_lshlrev_b32_e32 v78, 16, v68
	v_and_b32_e32 v79, 0xffff0000, v68
	v_lshlrev_b32_e32 v68, 16, v69
	v_add_u32_e32 v88, -1, v87
	v_add_u32_e32 v89, 1, v87
	v_fma_f32 v90, -v88, v87, v86
	v_fma_f32 v91, -v89, v87, v86
	v_cmp_ge_f32_e64 s[0:1], 0, v90
	v_and_b32_e32 v69, 0xffff0000, v69
	v_lshlrev_b32_e32 v70, 16, v71
	v_cndmask_b32_e64 v87, v87, v88, s[0:1]
	v_cmp_lt_f32_e64 s[0:1], 0, v91
	v_and_b32_e32 v71, 0xffff0000, v71
	s_waitcnt vmcnt(0)
	v_lshlrev_b32_e32 v82, 16, v72
	v_cndmask_b32_e64 v87, v87, v89, s[0:1]
	v_mul_f32_e32 v88, 0x37800000, v87
	v_cndmask_b32_e32 v87, v87, v88, vcc
	v_cmp_class_f32_e32 vcc, v86, v66
	v_and_b32_e32 v83, 0xffff0000, v72
	v_lshlrev_b32_e32 v72, 16, v73
	v_cndmask_b32_e32 v86, v87, v86, vcc
	v_div_scale_f32 v87, s[0:1], v86, v86, 1.0
	v_rcp_f32_e32 v88, v87
	v_div_scale_f32 v89, vcc, 1.0, v86, 1.0
	v_and_b32_e32 v73, 0xffff0000, v73
	v_fma_f32 v90, -v87, v88, 1.0
	v_fmac_f32_e32 v88, v90, v88
	v_mul_f32_e32 v90, v89, v88
	v_fma_f32 v91, -v87, v90, v89
	v_fmac_f32_e32 v90, v91, v88
	v_fma_f32 v87, -v87, v90, v89
	v_div_fmas_f32 v87, v87, v88, v90
	v_div_fixup_f32 v86, v87, v86, 1.0
	v_lshlrev_b32_e32 v84, 16, v74
	v_and_b32_e32 v85, 0xffff0000, v74
	v_lshlrev_b32_e32 v74, 16, v75
	v_and_b32_e32 v75, 0xffff0000, v75
	v_pk_mul_f32 v[60:61], v[60:61], v[86:87] op_sel_hi:[1,0]
	v_pk_mul_f32 v[62:63], v[62:63], v[86:87] op_sel_hi:[1,0]
	v_pk_mul_f32 v[56:57], v[56:57], v[86:87] op_sel_hi:[1,0]
	v_pk_mul_f32 v[58:59], v[58:59], v[86:87] op_sel_hi:[1,0]
	v_pk_mul_f32 v[52:53], v[52:53], v[86:87] op_sel_hi:[1,0]
	v_pk_mul_f32 v[54:55], v[54:55], v[86:87] op_sel_hi:[1,0]
	v_pk_mul_f32 v[48:49], v[48:49], v[86:87] op_sel_hi:[1,0]
	v_pk_mul_f32 v[50:51], v[50:51], v[86:87] op_sel_hi:[1,0]
	v_pk_fma_f32 v[62:63], v[106:107], v[62:63], v[68:69]
	v_pk_fma_f32 v[60:61], v[104:105], v[60:61], v[78:79]
	v_pk_fma_f32 v[58:59], v[102:103], v[58:59], v[70:71]
	v_pk_fma_f32 v[56:57], v[100:101], v[56:57], v[80:81]
	v_pk_fma_f32 v[54:55], v[110:111], v[54:55], v[72:73]
	v_pk_fma_f32 v[52:53], v[108:109], v[52:53], v[82:83]
	v_pk_fma_f32 v[68:69], v[98:99], v[50:51], v[74:75]
	v_pk_fma_f32 v[70:71], v[96:97], v[48:49], v[84:85]
	v_cvt_pk_bf16_f32 v48, v60, v61
	v_cvt_pk_bf16_f32 v49, v62, v63
	v_mul_f32_e32 v50, v61, v61
	v_mul_f32_e32 v51, v63, v63
	v_mul_f32_e32 v61, v57, v57
	v_mul_f32_e32 v63, v59, v59
	v_mul_f32_e32 v72, v53, v53
	v_mul_f32_e32 v73, v55, v55
	v_mul_f32_e32 v74, v71, v71
	v_mul_f32_e32 v75, v69, v69
	v_fmac_f32_e32 v50, v60, v60
	v_fmac_f32_e32 v51, v62, v62
	v_fmac_f32_e32 v61, v56, v56
	v_fmac_f32_e32 v63, v58, v58
	v_fmac_f32_e32 v72, v52, v52
	v_fmac_f32_e32 v73, v54, v54
	v_fmac_f32_e32 v74, v70, v70
	v_fmac_f32_e32 v75, v68, v68
	v_add_f32_e32 v50, v50, v51
	v_add_f32_e32 v51, v61, v63
	v_add_f32_e32 v60, v72, v73
	v_add_f32_e32 v61, v74, v75
	v_add_f32_e32 v50, v50, v51
	v_add_f32_e32 v51, v60, v61
	v_add_f32_e32 v60, v50, v51
	v_mov_b32_e32 v61, v60
	s_nop 1
	v_permlane16_swap_b32 v61, v60
	s_nop 0
	v_cvt_pk_bf16_f32 v50, v56, v57
	v_cvt_pk_bf16_f32 v51, v58, v59
	global_store_dwordx4 v[76:77], v[48:51], off
	s_waitcnt lgkmcnt(0)
	s_nop 0
	v_add_f32_e32 v48, v60, v61
	v_mov_b32_e32 v49, v48
	s_nop 1
	v_permlane32_swap_b32 v49, v48
	s_nop 0
	v_cvt_pk_bf16_f32 v50, v52, v53
	v_cvt_pk_bf16_f32 v51, v54, v55
	v_cvt_pk_bf16_f32 v52, v70, v71
	v_cvt_pk_bf16_f32 v53, v68, v69
	global_store_dwordx4 v[76:77], v[50:53], off offset:256
	s_and_saveexec_b64 s[0:1], s[4:5]
	s_cbranch_execz .LBB0_1157
	v_lshl_add_u32 v50, v64, 4, s22
	s_waitcnt lgkmcnt(0)
	v_add_f32_e32 v48, v48, v49
	ds_write_b32 v50, v48
; DI unsigned pk_bf16(float lo, float hi) { f32x2 v = {lo, hi}; bf16x2_t b = __builtin_convertvector(v, bf16x2_t); return __builtin_bit_cast(unsigned, b); }
; DI float bflo(unsigned w) { return __uint_as_float(w << 16); }
; DI float bfhi(unsigned w) { return __uint_as_float(w & 0xffff0000u); }
;     __device__ __forceinline__ void fused(f32x4 (&acc)[2][2][4][2], const pg8::Unit& u, int wr, int wc, int fr, int fq, PG8_LAS unsigned char* lds, int wid, int lane) const {
;     ...
;                 const int rl = ai * 128 + wr * 64 + m * 16 + fr; const size_t row = (size_t)u.pm * 256 + rl;
;                 const float rm = 1.f / sqrtf(__hip_atomic_load(ssqm + row, __ATOMIC_RELAXED, __HIP_MEMORY_SCOPE_AGENT) * (1.f / DM) + RMS_EPS);
;                 float sh = 0.f;
; #pragma unroll
;                 for (int bj = 0; bj < 2; ++bj) {
;                     const size_t off = row * DM + colb + bj * 128;
;                     f32x4 h0, h1;
;                     if (IN16) { const u32x4 hw = *(const u32x4*)((const bf16_t*)hin + off); h0 = (f32x4){bflo(hw.x), bfhi(hw.x), bflo(hw.y), bfhi(hw.y)}; h1 = (f32x4){bflo(hw.z), bfhi(hw.z), bflo(hw.w), bfhi(hw.w)}; }
;                     else { h0 = *(const f32x4*)((const float*)hin + off); h1 = *(const f32x4*)((const float*)hin + off + 4); }
;                     h0 = h0 + acc[ai][bj][m][0] * rm * gv[bj][0]; h1 = h1 + acc[ai][bj][m][1] * rm * gv[bj][1];
;                     sh += ((h0[0] * h0[0] + h0[1] * h0[1]) + (h0[2] * h0[2] + h0[3] * h0[3])) + ((h1[0] * h1[0] + h1[1] * h1[1]) + (h1[2] * h1[2] + h1[3] * h1[3]));
;                     if (OUT16) { u32x4 w; w.x = pk_bf16(h0[0], h0[1]); w.y = pk_bf16(h0[2], h0[3]); w.z = pk_bf16(h1[0], h1[1]); w.w = pk_bf16(h1[2], h1[3]); *(u32x4*)((bf16_t*)hout + off) = w; }
;                     else { *(f32x4*)((float*)hout + off) = h0; *(f32x4*)((float*)hout + off + 4) = h1; }
;                 }
;                 if (ssqh) { sh += __shfl_xor(sh, 16); sh += __shfl_xor(sh, 32); if (fq == 0) red[rl * 4 + wc] = sh; }
.LBB0_1157:
	s_or_b64 exec, exec, s[0:1]
	v_add_u32_e32 v64, 0x90, v152
	s_waitcnt lgkmcnt(0)
	v_lshl_add_u64 v[48:49], s[18:19], 0, v[64:65]
	v_lshl_add_u64 v[50:51], v[48:49], 2, s[12:13]
	global_load_dword v58, v[50:51], off sc1
	v_lshlrev_b64 v[48:49], 11, v[48:49]
	v_lshl_add_u64 v[48:49], s[10:11], 0, v[48:49]
	v_lshl_add_u64 v[56:57], v[156:157], 1, v[48:49]
	global_load_dwordx4 v[48:51], v[56:57], off
	global_load_dwordx4 v[52:55], v[56:57], off offset:256
	s_waitcnt vmcnt(2)
	v_fmac_f32_e32 v67, 0x3a800000, v58
	v_mul_f32_e32 v58, 0x4f800000, v67
	v_cmp_gt_f32_e32 vcc, s2, v67
	s_waitcnt vmcnt(1)
	v_and_b32_e32 v59, 0xffff0000, v48
	v_lshlrev_b32_e32 v60, 16, v50
	v_cndmask_b32_e32 v65, v67, v58, vcc
	v_sqrt_f32_e32 v67, v65
	v_lshlrev_b32_e32 v58, 16, v48
	v_lshlrev_b32_e32 v48, 16, v49
	v_and_b32_e32 v49, 0xffff0000, v49
	v_add_u32_e32 v70, -1, v67
	v_add_u32_e32 v71, 1, v67
	v_fma_f32 v72, -v70, v67, v65
	v_fma_f32 v73, -v71, v67, v65
	v_cmp_ge_f32_e64 s[0:1], 0, v72
	v_and_b32_e32 v61, 0xffff0000, v50
	v_lshlrev_b32_e32 v50, 16, v51
	v_cndmask_b32_e64 v67, v67, v70, s[0:1]
	v_cmp_lt_f32_e64 s[0:1], 0, v73
	v_and_b32_e32 v51, 0xffff0000, v51
	s_waitcnt vmcnt(0)
	v_lshlrev_b32_e32 v62, 16, v52
	v_cndmask_b32_e64 v67, v67, v71, s[0:1]
	v_mul_f32_e32 v70, 0x37800000, v67
	v_cndmask_b32_e32 v67, v67, v70, vcc
	v_cmp_class_f32_e32 vcc, v65, v66
	v_and_b32_e32 v63, 0xffff0000, v52
	v_lshlrev_b32_e32 v52, 16, v53
	v_cndmask_b32_e32 v65, v67, v65, vcc
	v_div_scale_f32 v66, s[0:1], v65, v65, 1.0
	v_rcp_f32_e32 v67, v66
	v_div_scale_f32 v70, vcc, 1.0, v65, 1.0
	v_and_b32_e32 v53, 0xffff0000, v53
	v_fma_f32 v71, -v66, v67, 1.0
	v_fmac_f32_e32 v67, v71, v67
	v_mul_f32_e32 v71, v70, v67
	v_fma_f32 v72, -v66, v71, v70
	v_fmac_f32_e32 v71, v72, v67
	v_fma_f32 v66, -v66, v71, v70
	v_div_fmas_f32 v66, v66, v67, v71
	v_div_fixup_f32 v66, v66, v65, 1.0
	v_lshlrev_b32_e32 v68, 16, v54
	v_and_b32_e32 v69, 0xffff0000, v54
	v_lshlrev_b32_e32 v54, 16, v55
	v_and_b32_e32 v55, 0xffff0000, v55
	v_pk_mul_f32 v[44:45], v[44:45], v[66:67] op_sel_hi:[1,0]
	v_pk_mul_f32 v[46:47], v[46:47], v[66:67] op_sel_hi:[1,0]
	v_pk_mul_f32 v[40:41], v[40:41], v[66:67] op_sel_hi:[1,0]
	v_pk_mul_f32 v[42:43], v[42:43], v[66:67] op_sel_hi:[1,0]
	v_pk_mul_f32 v[36:37], v[36:37], v[66:67] op_sel_hi:[1,0]
	v_pk_mul_f32 v[38:39], v[38:39], v[66:67] op_sel_hi:[1,0]
	v_pk_mul_f32 v[32:33], v[32:33], v[66:67] op_sel_hi:[1,0]
	v_pk_mul_f32 v[34:35], v[34:35], v[66:67] op_sel_hi:[1,0]
	v_pk_fma_f32 v[46:47], v[106:107], v[46:47], v[48:49]
	v_pk_fma_f32 v[44:45], v[104:105], v[44:45], v[58:59]
	v_pk_fma_f32 v[42:43], v[102:103], v[42:43], v[50:51]
	v_pk_fma_f32 v[40:41], v[100:101], v[40:41], v[60:61]
	v_pk_fma_f32 v[38:39], v[110:111], v[38:39], v[52:53]
	v_pk_fma_f32 v[36:37], v[108:109], v[36:37], v[62:63]
	v_pk_fma_f32 v[48:49], v[98:99], v[34:35], v[54:55]
	v_pk_fma_f32 v[50:51], v[96:97], v[32:33], v[68:69]
	v_cvt_pk_bf16_f32 v32, v44, v45
	v_cvt_pk_bf16_f32 v33, v46, v47
	v_mul_f32_e32 v34, v45, v45
	v_mul_f32_e32 v35, v47, v47
	v_mul_f32_e32 v45, v41, v41
	v_mul_f32_e32 v47, v43, v43
	v_mul_f32_e32 v52, v37, v37
	v_mul_f32_e32 v53, v39, v39
	v_mul_f32_e32 v54, v51, v51
	v_mul_f32_e32 v55, v49, v49
	v_fmac_f32_e32 v34, v44, v44
	v_fmac_f32_e32 v35, v46, v46
	v_fmac_f32_e32 v45, v40, v40
	v_fmac_f32_e32 v47, v42, v42
	v_fmac_f32_e32 v52, v36, v36
	v_fmac_f32_e32 v53, v38, v38
	v_fmac_f32_e32 v54, v50, v50
	v_fmac_f32_e32 v55, v48, v48
	v_add_f32_e32 v34, v34, v35
	v_add_f32_e32 v35, v45, v47
	v_add_f32_e32 v44, v52, v53
	v_add_f32_e32 v45, v54, v55
	v_add_f32_e32 v34, v34, v35
	v_add_f32_e32 v35, v44, v45
	v_add_f32_e32 v44, v34, v35
	v_mov_b32_e32 v45, v44
	s_nop 1
	v_permlane16_swap_b32 v45, v44
	s_nop 0
	v_cvt_pk_bf16_f32 v34, v40, v41
	v_cvt_pk_bf16_f32 v35, v42, v43
	global_store_dwordx4 v[56:57], v[32:35], off
	s_waitcnt lgkmcnt(0)
	s_nop 0
	v_add_f32_e32 v32, v44, v45
	v_mov_b32_e32 v33, v32
	s_nop 1
	v_permlane32_swap_b32 v33, v32
	s_nop 0
	v_cvt_pk_bf16_f32 v34, v36, v37
	v_cvt_pk_bf16_f32 v35, v38, v39
	v_cvt_pk_bf16_f32 v36, v50, v51
	v_cvt_pk_bf16_f32 v37, v48, v49
	global_store_dwordx4 v[56:57], v[34:37], off offset:256
	s_and_saveexec_b64 s[0:1], s[4:5]
	s_cbranch_execz .LBB0_1159
	v_lshl_add_u32 v34, v64, 4, s22
	s_waitcnt lgkmcnt(0)
	v_add_f32_e32 v32, v32, v33
	ds_write_b32 v34, v32
; DI unsigned pk_bf16(float lo, float hi) { f32x2 v = {lo, hi}; bf16x2_t b = __builtin_convertvector(v, bf16x2_t); return __builtin_bit_cast(unsigned, b); }
; DI float bflo(unsigned w) { return __uint_as_float(w << 16); }
; DI float bfhi(unsigned w) { return __uint_as_float(w & 0xffff0000u); }
;     __device__ __forceinline__ void fused(f32x4 (&acc)[2][2][4][2], const pg8::Unit& u, int wr, int wc, int fr, int fq, PG8_LAS unsigned char* lds, int wid, int lane) const {
;     ...
;                 const int rl = ai * 128 + wr * 64 + m * 16 + fr; const size_t row = (size_t)u.pm * 256 + rl;
;                 const float rm = 1.f / sqrtf(__hip_atomic_load(ssqm + row, __ATOMIC_RELAXED, __HIP_MEMORY_SCOPE_AGENT) * (1.f / DM) + RMS_EPS);
;                 float sh = 0.f;
; #pragma unroll
;                 for (int bj = 0; bj < 2; ++bj) {
;                     const size_t off = row * DM + colb + bj * 128;
;                     f32x4 h0, h1;
;                     if (IN16) { const u32x4 hw = *(const u32x4*)((const bf16_t*)hin + off); h0 = (f32x4){bflo(hw.x), bfhi(hw.x), bflo(hw.y), bfhi(hw.y)}; h1 = (f32x4){bflo(hw.z), bfhi(hw.z), bflo(hw.w), bfhi(hw.w)}; }
;                     else { h0 = *(const f32x4*)((const float*)hin + off); h1 = *(const f32x4*)((const float*)hin + off + 4); }
;                     h0 = h0 + acc[ai][bj][m][0] * rm * gv[bj][0]; h1 = h1 + acc[ai][bj][m][1] * rm * gv[bj][1];
;                     sh += ((h0[0] * h0[0] + h0[1] * h0[1]) + (h0[2] * h0[2] + h0[3] * h0[3])) + ((h1[0] * h1[0] + h1[1] * h1[1]) + (h1[2] * h1[2] + h1[3] * h1[3]));
;                     if (OUT16) { u32x4 w; w.x = pk_bf16(h0[0], h0[1]); w.y = pk_bf16(h0[2], h0[3]); w.z = pk_bf16(h1[0], h1[1]); w.w = pk_bf16(h1[2], h1[3]); *(u32x4*)((bf16_t*)hout + off) = w; }
;                     else { *(f32x4*)((float*)hout + off) = h0; *(f32x4*)((float*)hout + off + 4) = h1; }
;                 }
;                 if (ssqh) { sh += __shfl_xor(sh, 16); sh += __shfl_xor(sh, 32); if (fq == 0) red[rl * 4 + wc] = sh; }
.LBB0_1159:
	s_or_b64 exec, exec, s[0:1]
	v_add_u32_e32 v32, 0xa0, v152
	s_waitcnt lgkmcnt(0)
	v_mov_b32_e32 v33, 0
	v_lshl_add_u64 v[34:35], s[18:19], 0, v[32:33]
	v_lshl_add_u64 v[36:37], v[34:35], 2, s[12:13]
	global_load_dword v46, v[36:37], off sc1
	v_lshlrev_b64 v[34:35], 11, v[34:35]
	v_lshl_add_u64 v[34:35], s[10:11], 0, v[34:35]
	v_lshl_add_u64 v[44:45], v[156:157], 1, v[34:35]
	global_load_dwordx4 v[36:39], v[44:45], off
	global_load_dwordx4 v[40:43], v[44:45], off offset:256
	v_mov_b32_e32 v35, 0x358637bd
	v_mov_b32_e32 v34, 0x260
	s_waitcnt vmcnt(2)
	v_fmamk_f32 v46, v46, 0x3a800000, v35
	v_mul_f32_e32 v47, 0x4f800000, v46
	v_cmp_gt_f32_e32 vcc, s2, v46
	s_waitcnt vmcnt(1)
	v_lshlrev_b32_e32 v48, 16, v38
	v_and_b32_e32 v49, 0xffff0000, v38
	v_cndmask_b32_e32 v54, v46, v47, vcc
	v_sqrt_f32_e32 v55, v54
	v_lshlrev_b32_e32 v46, 16, v36
	v_and_b32_e32 v47, 0xffff0000, v36
	v_lshlrev_b32_e32 v36, 16, v37
	v_add_u32_e32 v56, -1, v55
	v_add_u32_e32 v57, 1, v55
	v_fma_f32 v58, -v56, v55, v54
	v_fma_f32 v59, -v57, v55, v54
	v_cmp_ge_f32_e64 s[0:1], 0, v58
	v_and_b32_e32 v37, 0xffff0000, v37
	v_lshlrev_b32_e32 v38, 16, v39
	v_cndmask_b32_e64 v55, v55, v56, s[0:1]
	v_cmp_lt_f32_e64 s[0:1], 0, v59
	v_and_b32_e32 v39, 0xffff0000, v39
	s_waitcnt vmcnt(0)
	v_lshlrev_b32_e32 v50, 16, v40
	v_cndmask_b32_e64 v55, v55, v57, s[0:1]
	v_mul_f32_e32 v56, 0x37800000, v55
	v_cndmask_b32_e32 v55, v55, v56, vcc
	v_cmp_class_f32_e32 vcc, v54, v34
	v_and_b32_e32 v51, 0xffff0000, v40
	v_lshlrev_b32_e32 v40, 16, v41
	v_cndmask_b32_e32 v54, v55, v54, vcc
	v_div_scale_f32 v55, s[0:1], v54, v54, 1.0
	v_rcp_f32_e32 v56, v55
	v_div_scale_f32 v57, vcc, 1.0, v54, 1.0
	v_and_b32_e32 v41, 0xffff0000, v41
	v_fma_f32 v58, -v55, v56, 1.0
	v_fmac_f32_e32 v56, v58, v56
	v_mul_f32_e32 v58, v57, v56
	v_fma_f32 v59, -v55, v58, v57
	v_fmac_f32_e32 v58, v59, v56
	v_fma_f32 v55, -v55, v58, v57
	v_div_fmas_f32 v55, v55, v56, v58
	v_div_fixup_f32 v54, v55, v54, 1.0
	v_lshlrev_b32_e32 v52, 16, v42
	v_and_b32_e32 v53, 0xffff0000, v42
	v_lshlrev_b32_e32 v42, 16, v43
	v_and_b32_e32 v43, 0xffff0000, v43
	v_pk_mul_f32 v[28:29], v[28:29], v[54:55] op_sel_hi:[1,0]
	v_pk_mul_f32 v[30:31], v[30:31], v[54:55] op_sel_hi:[1,0]
	v_pk_mul_f32 v[24:25], v[24:25], v[54:55] op_sel_hi:[1,0]
	v_pk_mul_f32 v[26:27], v[26:27], v[54:55] op_sel_hi:[1,0]
	v_pk_mul_f32 v[20:21], v[20:21], v[54:55] op_sel_hi:[1,0]
	v_pk_mul_f32 v[22:23], v[22:23], v[54:55] op_sel_hi:[1,0]
	v_pk_mul_f32 v[16:17], v[16:17], v[54:55] op_sel_hi:[1,0]
	v_pk_mul_f32 v[18:19], v[18:19], v[54:55] op_sel_hi:[1,0]
	v_pk_fma_f32 v[30:31], v[106:107], v[30:31], v[36:37]
	v_pk_fma_f32 v[28:29], v[104:105], v[28:29], v[46:47]
	v_pk_fma_f32 v[26:27], v[102:103], v[26:27], v[38:39]
	v_pk_fma_f32 v[24:25], v[100:101], v[24:25], v[48:49]
	v_pk_fma_f32 v[22:23], v[110:111], v[22:23], v[40:41]
	v_pk_fma_f32 v[20:21], v[108:109], v[20:21], v[50:51]
	v_pk_fma_f32 v[36:37], v[98:99], v[18:19], v[42:43]
	v_pk_fma_f32 v[38:39], v[96:97], v[16:17], v[52:53]
	v_cvt_pk_bf16_f32 v16, v28, v29
	v_cvt_pk_bf16_f32 v17, v30, v31
	v_mul_f32_e32 v18, v29, v29
	v_mul_f32_e32 v19, v31, v31
	v_mul_f32_e32 v29, v25, v25
	v_mul_f32_e32 v31, v27, v27
	v_mul_f32_e32 v40, v21, v21
	v_mul_f32_e32 v41, v23, v23
	v_mul_f32_e32 v42, v39, v39
	v_mul_f32_e32 v43, v37, v37
	v_fmac_f32_e32 v18, v28, v28
	v_fmac_f32_e32 v19, v30, v30
	v_fmac_f32_e32 v29, v24, v24
	v_fmac_f32_e32 v31, v26, v26
	v_fmac_f32_e32 v40, v20, v20
	v_fmac_f32_e32 v41, v22, v22
	v_fmac_f32_e32 v42, v38, v38
	v_fmac_f32_e32 v43, v36, v36
	v_add_f32_e32 v18, v18, v19
	v_add_f32_e32 v19, v29, v31
	v_add_f32_e32 v28, v40, v41
	v_add_f32_e32 v29, v42, v43
	v_add_f32_e32 v18, v18, v19
	v_add_f32_e32 v19, v28, v29
	v_add_f32_e32 v28, v18, v19
	v_mov_b32_e32 v29, v28
	s_nop 1
	v_permlane16_swap_b32 v29, v28
	s_nop 0
	v_cvt_pk_bf16_f32 v18, v24, v25
	v_cvt_pk_bf16_f32 v19, v26, v27
	global_store_dwordx4 v[44:45], v[16:19], off
	s_waitcnt lgkmcnt(0)
	s_nop 0
	v_add_f32_e32 v16, v28, v29
	v_mov_b32_e32 v17, v16
	s_nop 1
	v_permlane32_swap_b32 v17, v16
	s_nop 0
	v_cvt_pk_bf16_f32 v18, v20, v21
	v_cvt_pk_bf16_f32 v19, v22, v23
	v_cvt_pk_bf16_f32 v20, v38, v39
	v_cvt_pk_bf16_f32 v21, v36, v37
	global_store_dwordx4 v[44:45], v[18:21], off offset:256
	s_and_saveexec_b64 s[0:1], s[4:5]
	s_cbranch_execz .LBB0_1161
	v_lshl_add_u32 v18, v32, 4, s22
	s_waitcnt lgkmcnt(0)
	v_add_f32_e32 v16, v16, v17
	ds_write_b32 v18, v16
; DI unsigned pk_bf16(float lo, float hi) { f32x2 v = {lo, hi}; bf16x2_t b = __builtin_convertvector(v, bf16x2_t); return __builtin_bit_cast(unsigned, b); }
; DI float bflo(unsigned w) { return __uint_as_float(w << 16); }
; DI float bfhi(unsigned w) { return __uint_as_float(w & 0xffff0000u); }
;     __device__ __forceinline__ void fused(f32x4 (&acc)[2][2][4][2], const pg8::Unit& u, int wr, int wc, int fr, int fq, PG8_LAS unsigned char* lds, int wid, int lane) const {
;     ...
;                 const int rl = ai * 128 + wr * 64 + m * 16 + fr; const size_t row = (size_t)u.pm * 256 + rl;
;                 const float rm = 1.f / sqrtf(__hip_atomic_load(ssqm + row, __ATOMIC_RELAXED, __HIP_MEMORY_SCOPE_AGENT) * (1.f / DM) + RMS_EPS);
;                 float sh = 0.f;
; #pragma unroll
;                 for (int bj = 0; bj < 2; ++bj) {
;                     const size_t off = row * DM + colb + bj * 128;
;                     f32x4 h0, h1;
;                     if (IN16) { const u32x4 hw = *(const u32x4*)((const bf16_t*)hin + off); h0 = (f32x4){bflo(hw.x), bfhi(hw.x), bflo(hw.y), bfhi(hw.y)}; h1 = (f32x4){bflo(hw.z), bfhi(hw.z), bflo(hw.w), bfhi(hw.w)}; }
;                     else { h0 = *(const f32x4*)((const float*)hin + off); h1 = *(const f32x4*)((const float*)hin + off + 4); }
;                     h0 = h0 + acc[ai][bj][m][0] * rm * gv[bj][0]; h1 = h1 + acc[ai][bj][m][1] * rm * gv[bj][1];
;                     sh += ((h0[0] * h0[0] + h0[1] * h0[1]) + (h0[2] * h0[2] + h0[3] * h0[3])) + ((h1[0] * h1[0] + h1[1] * h1[1]) + (h1[2] * h1[2] + h1[3] * h1[3]));
;                     if (OUT16) { u32x4 w; w.x = pk_bf16(h0[0], h0[1]); w.y = pk_bf16(h0[2], h0[3]); w.z = pk_bf16(h1[0], h1[1]); w.w = pk_bf16(h1[2], h1[3]); *(u32x4*)((bf16_t*)hout + off) = w; }
;                     else { *(f32x4*)((float*)hout + off) = h0; *(f32x4*)((float*)hout + off + 4) = h1; }
;                 }
;                 if (ssqh) { sh += __shfl_xor(sh, 16); sh += __shfl_xor(sh, 32); if (fq == 0) red[rl * 4 + wc] = sh; }
;             }
;         if (ssqh) { __syncthreads(); if (tid < 256) atomicAdd(ssqh + u.pm * 256 + tid, (red[tid * 4] + red[tid * 4 + 1]) + (red[tid * 4 + 2] + red[tid * 4 + 3])); }
.LBB0_1161:
	s_or_b64 exec, exec, s[0:1]
	v_add_u32_e32 v32, 0xb0, v152
	s_waitcnt lgkmcnt(0)
	v_lshl_add_u64 v[16:17], s[18:19], 0, v[32:33]
	v_lshl_add_u64 v[18:19], v[16:17], 2, s[12:13]
	global_load_dword v26, v[18:19], off sc1
	v_lshlrev_b64 v[16:17], 11, v[16:17]
	v_lshl_add_u64 v[16:17], s[10:11], 0, v[16:17]
	v_lshl_add_u64 v[24:25], v[156:157], 1, v[16:17]
	global_load_dwordx4 v[16:19], v[24:25], off
	global_load_dwordx4 v[20:23], v[24:25], off offset:256
	s_waitcnt vmcnt(2)
	v_fmac_f32_e32 v35, 0x3a800000, v26
	v_mul_f32_e32 v26, 0x4f800000, v35
	v_cmp_gt_f32_e32 vcc, s2, v35
	s_waitcnt vmcnt(1)
	v_and_b32_e32 v27, 0xffff0000, v16
	v_lshlrev_b32_e32 v28, 16, v18
	v_cndmask_b32_e32 v33, v35, v26, vcc
	v_sqrt_f32_e32 v35, v33
	v_lshlrev_b32_e32 v26, 16, v16
	v_lshlrev_b32_e32 v16, 16, v17
	v_and_b32_e32 v17, 0xffff0000, v17
	v_add_u32_e32 v38, -1, v35
	v_add_u32_e32 v39, 1, v35
	v_fma_f32 v40, -v38, v35, v33
	v_fma_f32 v41, -v39, v35, v33
	v_cmp_ge_f32_e64 s[0:1], 0, v40
	v_and_b32_e32 v29, 0xffff0000, v18
	v_lshlrev_b32_e32 v18, 16, v19
	v_cndmask_b32_e64 v35, v35, v38, s[0:1]
	v_cmp_lt_f32_e64 s[0:1], 0, v41
	v_and_b32_e32 v19, 0xffff0000, v19
	s_waitcnt vmcnt(0)
	v_lshlrev_b32_e32 v30, 16, v20
	v_cndmask_b32_e64 v35, v35, v39, s[0:1]
	v_mul_f32_e32 v38, 0x37800000, v35
	v_cndmask_b32_e32 v35, v35, v38, vcc
	v_cmp_class_f32_e32 vcc, v33, v34
	v_and_b32_e32 v31, 0xffff0000, v20
	v_lshlrev_b32_e32 v20, 16, v21
	v_cndmask_b32_e32 v33, v35, v33, vcc
	v_div_scale_f32 v34, s[0:1], v33, v33, 1.0
	v_rcp_f32_e32 v35, v34
	v_div_scale_f32 v38, vcc, 1.0, v33, 1.0
	v_and_b32_e32 v21, 0xffff0000, v21
	v_fma_f32 v39, -v34, v35, 1.0
	v_fmac_f32_e32 v35, v39, v35
	v_mul_f32_e32 v39, v38, v35
	v_fma_f32 v40, -v34, v39, v38
	v_fmac_f32_e32 v39, v40, v35
	v_fma_f32 v34, -v34, v39, v38
	v_div_fmas_f32 v34, v34, v35, v39
	v_div_fixup_f32 v34, v34, v33, 1.0
	v_lshlrev_b32_e32 v36, 16, v22
	v_and_b32_e32 v37, 0xffff0000, v22
	v_lshlrev_b32_e32 v22, 16, v23
	v_and_b32_e32 v23, 0xffff0000, v23
	v_pk_mul_f32 v[12:13], v[12:13], v[34:35] op_sel_hi:[1,0]
	v_pk_mul_f32 v[14:15], v[14:15], v[34:35] op_sel_hi:[1,0]
	v_pk_mul_f32 v[8:9], v[8:9], v[34:35] op_sel_hi:[1,0]
	v_pk_mul_f32 v[10:11], v[10:11], v[34:35] op_sel_hi:[1,0]
	v_pk_mul_f32 v[4:5], v[4:5], v[34:35] op_sel_hi:[1,0]
	v_pk_mul_f32 v[6:7], v[6:7], v[34:35] op_sel_hi:[1,0]
	v_pk_mul_f32 v[0:1], v[0:1], v[34:35] op_sel_hi:[1,0]
	v_pk_mul_f32 v[2:3], v[2:3], v[34:35] op_sel_hi:[1,0]
	v_pk_fma_f32 v[14:15], v[106:107], v[14:15], v[16:17]
	v_pk_fma_f32 v[12:13], v[104:105], v[12:13], v[26:27]
	v_pk_fma_f32 v[10:11], v[102:103], v[10:11], v[18:19]
	v_pk_fma_f32 v[8:9], v[100:101], v[8:9], v[28:29]
	v_pk_fma_f32 v[6:7], v[110:111], v[6:7], v[20:21]
	v_pk_fma_f32 v[4:5], v[108:109], v[4:5], v[30:31]
	v_pk_fma_f32 v[16:17], v[98:99], v[2:3], v[22:23]
	v_pk_fma_f32 v[18:19], v[96:97], v[0:1], v[36:37]
	v_cvt_pk_bf16_f32 v0, v12, v13
	v_cvt_pk_bf16_f32 v1, v14, v15
	v_mul_f32_e32 v2, v13, v13
	v_mul_f32_e32 v3, v15, v15
	v_mul_f32_e32 v13, v9, v9
	v_mul_f32_e32 v15, v11, v11
	v_mul_f32_e32 v20, v5, v5
	v_mul_f32_e32 v21, v7, v7
	v_mul_f32_e32 v22, v19, v19
	v_mul_f32_e32 v23, v17, v17
	v_fmac_f32_e32 v2, v12, v12
	v_fmac_f32_e32 v3, v14, v14
	v_fmac_f32_e32 v13, v8, v8
	v_fmac_f32_e32 v15, v10, v10
	v_fmac_f32_e32 v20, v4, v4
	v_fmac_f32_e32 v21, v6, v6
	v_fmac_f32_e32 v22, v18, v18
	v_fmac_f32_e32 v23, v16, v16
	v_add_f32_e32 v2, v2, v3
	v_add_f32_e32 v3, v13, v15
	v_add_f32_e32 v12, v20, v21
	v_add_f32_e32 v13, v22, v23
	v_add_f32_e32 v2, v2, v3
	v_add_f32_e32 v3, v12, v13
	v_add_f32_e32 v12, v2, v3
	v_mov_b32_e32 v13, v12
	s_nop 1
	v_permlane16_swap_b32 v13, v12
	s_nop 0
	v_cvt_pk_bf16_f32 v2, v8, v9
	v_cvt_pk_bf16_f32 v3, v10, v11
	global_store_dwordx4 v[24:25], v[0:3], off
	s_waitcnt lgkmcnt(0)
	s_nop 0
	v_add_f32_e32 v0, v12, v13
	v_mov_b32_e32 v1, v0
	s_nop 1
	v_permlane32_swap_b32 v1, v0
	s_nop 0
	v_cvt_pk_bf16_f32 v2, v4, v5
	v_cvt_pk_bf16_f32 v3, v6, v7
	v_cvt_pk_bf16_f32 v4, v18, v19
	v_cvt_pk_bf16_f32 v5, v16, v17
	global_store_dwordx4 v[24:25], v[2:5], off offset:256
	s_and_saveexec_b64 s[0:1], s[4:5]
	s_cbranch_execz .LBB0_1163
	v_lshl_add_u32 v2, v32, 4, s22
	s_waitcnt lgkmcnt(0)
	v_add_f32_e32 v0, v0, v1
	ds_write_b32 v2, v0

;     __device__ __forceinline__ void fused(f32x4 (&acc)[2][2][4][2], const pg8::Unit& u, int wr, int wc, int fr, int fq, PG8_LAS unsigned char* lds, int wid, int lane) const {
;     ...
;         for (int ai = 0; ai < 2; ++ai)
; #pragma unroll
;             for (int m = 0; m < 4; ++m) {
;                 float s = 0.f;
; #pragma unroll
;                 for (int bj = 0; bj < 2; ++bj)
; #pragma unroll
;                     for (int n = 0; n < 2; ++n) { const f32x4 x = acc[ai][bj][m][n]; s += (x[0] * x[0] + x[1] * x[1]) + (x[2] * x[2] + x[3] * x[3]); }
;                 s += __shfl_xor(s, 16); s += __shfl_xor(s, 32);
;                 if (fq == 0) red[(ai * 128 + wr * 64 + m * 16 + fr) * 4 + wc] = s;
;             }
;         __syncthreads();
.LBB0_1179:
	v_mbcnt_lo_u32_b32 v96, -1, 0
	v_mbcnt_hi_u32_b32 v96, -1, v96
	v_and_b32_e32 v98, 64, v96
	v_xor_b32_e32 v97, 16, v96
	v_add_u32_e32 v98, 64, v98
	v_cmp_lt_i32_e32 vcc, v97, v98
	v_mul_f32_e32 v99, v143, v143
	v_fmac_f32_e32 v99, v142, v142
	v_cndmask_b32_e32 v97, v96, v97, vcc
	v_lshlrev_b32_e32 v150, 2, v97
	v_mul_f32_e32 v97, v141, v141
	v_fmac_f32_e32 v97, v140, v140
	v_add_f32_e32 v97, v97, v99
	v_mul_f32_e32 v99, v137, v137
	v_mul_f32_e32 v100, v139, v139
	v_fmac_f32_e32 v99, v136, v136
	v_fmac_f32_e32 v100, v138, v138
	v_add_f32_e32 v99, v99, v100
	v_add_f32_e32 v97, v97, v99
	v_mul_f32_e32 v99, v133, v133
	v_mul_f32_e32 v100, v135, v135
	v_fmac_f32_e32 v99, v132, v132
	v_fmac_f32_e32 v100, v134, v134
	v_add_f32_e32 v99, v99, v100
	v_add_f32_e32 v97, v97, v99
	v_mul_f32_e32 v99, v129, v129
	v_mul_f32_e32 v100, v131, v131
	v_fmac_f32_e32 v99, v128, v128
	v_fmac_f32_e32 v100, v130, v130
	v_add_f32_e32 v99, v99, v100
	v_add_f32_e32 v97, v97, v99
	v_mov_b32_e32 v99, v97
	s_nop 1
	v_permlane16_swap_b32 v99, v97
	s_nop 0
	v_xor_b32_e32 v100, 32, v96
	v_cmp_lt_i32_e32 vcc, v100, v98
	s_lshl_b32 s0, s28, 2
	v_cmp_gt_u32_e64 s[4:5], 16, v192
	v_cndmask_b32_e32 v96, v96, v100, vcc
	v_lshlrev_b32_e32 v151, 2, v96
	s_waitcnt lgkmcnt(0)
	v_add_f32_e32 v96, v97, v99
	v_mov_b32_e32 v97, v96
	s_nop 1
	v_permlane32_swap_b32 v97, v96
	s_nop 0
	s_add_i32 s22, s0, 0
	s_barrier
	s_and_saveexec_b64 s[0:1], s[4:5]
	v_readlane_b32 s44, v251, 15
	v_readlane_b32 s45, v251, 16
	v_readlane_b32 s46, v251, 17
	v_readlane_b32 s47, v251, 18
	s_cbranch_execz .LBB0_1181
	s_lshl_b32 s6, s3, 10
	s_add_i32 s6, s22, s6
	s_waitcnt lgkmcnt(0)
	v_add_f32_e32 v96, v96, v97
	v_lshl_add_u32 v97, v161, 4, s6
	ds_write_b32 v97, v96

; DI unsigned pk_bf16(float lo, float hi) { f32x2 v = {lo, hi}; bf16x2_t b = __builtin_convertvector(v, bf16x2_t); return __builtin_bit_cast(unsigned, b); }
; DI float bflo(unsigned w) { return __uint_as_float(w << 16); }
; DI float bfhi(unsigned w) { return __uint_as_float(w & 0xffff0000u); }
;     __device__ __forceinline__ void fused(f32x4 (&acc)[2][2][4][2], const pg8::Unit& u, int wr, int wc, int fr, int fq, PG8_LAS unsigned char* lds, int wid, int lane) const {
;     ...
;         const int colb = u.pn * 256 + wc * 32 + 8 * fq;
;         f32x4 gv[2][2];
; #pragma unroll
;         for (int bj = 0; bj < 2; ++bj)
; #pragma unroll
;             for (int n = 0; n < 2; ++n) gv[bj][n] = *(const f32x4*)(gA + colb + bj * 128 + 4 * n);
; #pragma unroll
;         for (int ai = 0; ai < 2; ++ai)
; #pragma unroll
;             for (int m = 0; m < 4; ++m) {
;                 const int rl = ai * 128 + wr * 64 + m * 16 + fr; const size_t row = (size_t)u.pm * 256 + rl;
;                 const float rm = 1.f / sqrtf(__hip_atomic_load(ssqm + row, __ATOMIC_RELAXED, __HIP_MEMORY_SCOPE_AGENT) * (1.f / DM) + RMS_EPS);
;                 float sh = 0.f;
; #pragma unroll
;                 for (int bj = 0; bj < 2; ++bj) {
;                     const size_t off = row * DM + colb + bj * 128;
;                     f32x4 h0, h1;
;                     if (IN16) { const u32x4 hw = *(const u32x4*)((const bf16_t*)hin + off); h0 = (f32x4){bflo(hw.x), bfhi(hw.x), bflo(hw.y), bfhi(hw.y)}; h1 = (f32x4){bflo(hw.z), bfhi(hw.z), bflo(hw.w), bfhi(hw.w)}; }
;                     else { h0 = *(const f32x4*)((const float*)hin + off); h1 = *(const f32x4*)((const float*)hin + off + 4); }
;                     h0 = h0 + acc[ai][bj][m][0] * rm * gv[bj][0]; h1 = h1 + acc[ai][bj][m][1] * rm * gv[bj][1];
;                     sh += ((h0[0] * h0[0] + h0[1] * h0[1]) + (h0[2] * h0[2] + h0[3] * h0[3])) + ((h1[0] * h1[0] + h1[1] * h1[1]) + (h1[2] * h1[2] + h1[3] * h1[3]));
;                     if (OUT16) { u32x4 w; w.x = pk_bf16(h0[0], h0[1]); w.y = pk_bf16(h0[2], h0[3]); w.z = pk_bf16(h1[0], h1[1]); w.w = pk_bf16(h1[2], h1[3]); *(u32x4*)((bf16_t*)hout + off) = w; }
;                     else { *(f32x4*)((float*)hout + off) = h0; *(f32x4*)((float*)hout + off + 4) = h1; }
;                 }
;                 if (ssqh) { sh += __shfl_xor(sh, 16); sh += __shfl_xor(sh, 32); if (fq == 0) red[rl * 4 + wc] = sh; }
.LBB0_1202:
	s_or_b64 exec, exec, s[0:1]
	s_lshl_b32 s0, s28, 5
	s_lshl_b32 s1, s33, 8
	s_or_b32 s0, s1, s0
	v_or_b32_e32 v146, s0, v160
	v_ashrrev_i32_e32 v147, 31, v146
	v_mov_b32_e32 v149, 0
	v_lshl_add_u64 v[108:109], v[146:147], 2, s[14:15]
	s_lshl_b64 s[14:15], s[16:17], 8
	v_mov_b32_e32 v153, v149
	v_lshl_add_u64 v[156:157], s[14:15], 0, v[152:153]
	v_lshl_add_u64 v[158:159], v[156:157], 2, s[12:13]
	s_barrier
	global_load_dwordx4 v[100:103], v[108:109], off offset:16
	global_load_dwordx4 v[104:107], v[108:109], off
	global_load_dwordx4 v[96:99], v[108:109], off offset:528
	s_nop 0
	global_load_dwordx4 v[108:111], v[108:109], off offset:512
	v_lshlrev_b64 v[156:157], 11, v[156:157]
	global_load_dword v148, v[158:159], off sc1
	v_lshl_add_u64 v[156:157], s[10:11], 0, v[156:157]
	v_lshl_add_u64 v[164:165], v[146:147], 1, v[156:157]
	global_load_dwordx4 v[156:159], v[164:165], off
	global_load_dwordx4 v[160:163], v[164:165], off offset:256
	v_mov_b32_e32 v155, 0x358637bd
	s_mov_b32 s2, 0xf800000
	v_mov_b32_e32 v153, 0x260
	s_waitcnt vmcnt(2)
	v_fmamk_f32 v148, v148, 0x3a800000, v155
	v_mul_f32_e32 v172, 0x4f800000, v148
	v_cmp_gt_f32_e32 vcc, s2, v148
	s_waitcnt vmcnt(1)
	v_lshlrev_b32_e32 v166, 16, v156
	v_and_b32_e32 v167, 0xffff0000, v156
	v_cndmask_b32_e32 v148, v148, v172, vcc
	v_sqrt_f32_e32 v174, v148
	v_lshlrev_b32_e32 v156, 16, v157
	v_and_b32_e32 v157, 0xffff0000, v157
	v_lshlrev_b32_e32 v168, 16, v158
	v_add_u32_e32 v175, -1, v174
	v_add_u32_e32 v176, 1, v174
	v_fma_f32 v177, -v175, v174, v148
	v_fma_f32 v178, -v176, v174, v148
	v_cmp_ge_f32_e64 s[0:1], 0, v177
	v_and_b32_e32 v169, 0xffff0000, v158
	v_lshlrev_b32_e32 v158, 16, v159
	v_cndmask_b32_e64 v174, v174, v175, s[0:1]
	v_cmp_lt_f32_e64 s[0:1], 0, v178
	v_and_b32_e32 v159, 0xffff0000, v159
	s_waitcnt vmcnt(0)
	v_lshlrev_b32_e32 v170, 16, v160
	v_cndmask_b32_e64 v174, v174, v176, s[0:1]
	v_mul_f32_e32 v175, 0x37800000, v174
	v_cndmask_b32_e32 v174, v174, v175, vcc
	v_cmp_class_f32_e32 vcc, v148, v153
	v_and_b32_e32 v171, 0xffff0000, v160
	v_lshlrev_b32_e32 v160, 16, v161
	v_cndmask_b32_e32 v148, v174, v148, vcc
	v_div_scale_f32 v174, s[0:1], v148, v148, 1.0
	v_rcp_f32_e32 v175, v174
	v_div_scale_f32 v176, vcc, 1.0, v148, 1.0
	v_and_b32_e32 v161, 0xffff0000, v161
	v_fma_f32 v177, -v174, v175, 1.0
	v_fmac_f32_e32 v175, v177, v175
	v_mul_f32_e32 v177, v176, v175
	v_fma_f32 v178, -v174, v177, v176
	v_fmac_f32_e32 v177, v178, v175
	v_fma_f32 v174, -v174, v177, v176
	v_div_fmas_f32 v174, v174, v175, v177
	v_div_fixup_f32 v148, v174, v148, 1.0
	v_lshlrev_b32_e32 v172, 16, v162
	v_and_b32_e32 v173, 0xffff0000, v162
	v_lshlrev_b32_e32 v162, 16, v163
	v_and_b32_e32 v163, 0xffff0000, v163
	v_pk_mul_f32 v[140:141], v[140:141], v[148:149] op_sel_hi:[1,0]
	v_pk_mul_f32 v[142:143], v[142:143], v[148:149] op_sel_hi:[1,0]
	v_pk_mul_f32 v[136:137], v[136:137], v[148:149] op_sel_hi:[1,0]
	v_pk_mul_f32 v[138:139], v[138:139], v[148:149] op_sel_hi:[1,0]
	v_pk_mul_f32 v[132:133], v[132:133], v[148:149] op_sel_hi:[1,0]
	v_pk_mul_f32 v[134:135], v[134:135], v[148:149] op_sel_hi:[1,0]
	v_pk_mul_f32 v[128:129], v[128:129], v[148:149] op_sel_hi:[1,0]
	v_pk_mul_f32 v[130:131], v[130:131], v[148:149] op_sel_hi:[1,0]
	v_pk_fma_f32 v[142:143], v[106:107], v[142:143], v[156:157]
	v_pk_fma_f32 v[140:141], v[104:105], v[140:141], v[166:167]
	v_pk_fma_f32 v[138:139], v[102:103], v[138:139], v[158:159]
	v_pk_fma_f32 v[136:137], v[100:101], v[136:137], v[168:169]
	v_pk_fma_f32 v[134:135], v[110:111], v[134:135], v[160:161]
	v_pk_fma_f32 v[132:133], v[108:109], v[132:133], v[170:171]
	v_pk_fma_f32 v[156:157], v[98:99], v[130:131], v[162:163]
	v_pk_fma_f32 v[158:159], v[96:97], v[128:129], v[172:173]
	v_cvt_pk_bf16_f32 v128, v140, v141
	v_cvt_pk_bf16_f32 v129, v142, v143
	v_mul_f32_e32 v130, v141, v141
	v_mul_f32_e32 v131, v143, v143
	v_mul_f32_e32 v141, v137, v137
	v_mul_f32_e32 v143, v139, v139
	v_mul_f32_e32 v148, v133, v133
	v_mul_f32_e32 v160, v135, v135
	v_mul_f32_e32 v161, v159, v159
	v_mul_f32_e32 v162, v157, v157
	v_fmac_f32_e32 v130, v140, v140
	v_fmac_f32_e32 v131, v142, v142
	v_fmac_f32_e32 v141, v136, v136
	v_fmac_f32_e32 v143, v138, v138
	v_fmac_f32_e32 v148, v132, v132
	v_fmac_f32_e32 v160, v134, v134
	v_fmac_f32_e32 v161, v158, v158
	v_fmac_f32_e32 v162, v156, v156
	v_add_f32_e32 v130, v130, v131
	v_add_f32_e32 v131, v141, v143
	v_add_f32_e32 v140, v148, v160
	v_add_f32_e32 v141, v161, v162
	v_add_f32_e32 v130, v130, v131
	v_add_f32_e32 v131, v140, v141
	v_add_f32_e32 v140, v130, v131
	v_mov_b32_e32 v141, v140
	s_nop 1
	v_permlane16_swap_b32 v141, v140
	s_nop 0
	v_cvt_pk_bf16_f32 v130, v136, v137
	v_cvt_pk_bf16_f32 v131, v138, v139
	global_store_dwordx4 v[164:165], v[128:131], off
	s_waitcnt lgkmcnt(0)
	s_nop 0
	v_add_f32_e32 v128, v140, v141
	v_mov_b32_e32 v129, v128
	s_nop 1
	v_permlane32_swap_b32 v129, v128
	s_nop 0
	v_cvt_pk_bf16_f32 v130, v132, v133
	v_cvt_pk_bf16_f32 v131, v134, v135
	v_cvt_pk_bf16_f32 v132, v158, v159
	v_cvt_pk_bf16_f32 v133, v156, v157
	global_store_dwordx4 v[164:165], v[130:133], off offset:256
	s_and_saveexec_b64 s[0:1], s[4:5]
	s_cbranch_execz .LBB0_1204
	v_lshl_add_u32 v130, v152, 4, s22
	s_waitcnt lgkmcnt(0)
	v_add_f32_e32 v128, v128, v129
	ds_write_b32 v130, v128
; DI unsigned pk_bf16(float lo, float hi) { f32x2 v = {lo, hi}; bf16x2_t b = __builtin_convertvector(v, bf16x2_t); return __builtin_bit_cast(unsigned, b); }
; DI float bflo(unsigned w) { return __uint_as_float(w << 16); }
; DI float bfhi(unsigned w) { return __uint_as_float(w & 0xffff0000u); }
;     __device__ __forceinline__ void fused(f32x4 (&acc)[2][2][4][2], const pg8::Unit& u, int wr, int wc, int fr, int fq, PG8_LAS unsigned char* lds, int wid, int lane) const {
;     ...
;                 const int rl = ai * 128 + wr * 64 + m * 16 + fr; const size_t row = (size_t)u.pm * 256 + rl;
;                 const float rm = 1.f / sqrtf(__hip_atomic_load(ssqm + row, __ATOMIC_RELAXED, __HIP_MEMORY_SCOPE_AGENT) * (1.f / DM) + RMS_EPS);
;                 float sh = 0.f;
; #pragma unroll
;                 for (int bj = 0; bj < 2; ++bj) {
;                     const size_t off = row * DM + colb + bj * 128;
;                     f32x4 h0, h1;
;                     if (IN16) { const u32x4 hw = *(const u32x4*)((const bf16_t*)hin + off); h0 = (f32x4){bflo(hw.x), bfhi(hw.x), bflo(hw.y), bfhi(hw.y)}; h1 = (f32x4){bflo(hw.z), bfhi(hw.z), bflo(hw.w), bfhi(hw.w)}; }
;                     else { h0 = *(const f32x4*)((const float*)hin + off); h1 = *(const f32x4*)((const float*)hin + off + 4); }
;                     h0 = h0 + acc[ai][bj][m][0] * rm * gv[bj][0]; h1 = h1 + acc[ai][bj][m][1] * rm * gv[bj][1];
;                     sh += ((h0[0] * h0[0] + h0[1] * h0[1]) + (h0[2] * h0[2] + h0[3] * h0[3])) + ((h1[0] * h1[0] + h1[1] * h1[1]) + (h1[2] * h1[2] + h1[3] * h1[3]));
;                     if (OUT16) { u32x4 w; w.x = pk_bf16(h0[0], h0[1]); w.y = pk_bf16(h0[2], h0[3]); w.z = pk_bf16(h1[0], h1[1]); w.w = pk_bf16(h1[2], h1[3]); *(u32x4*)((bf16_t*)hout + off) = w; }
;                     else { *(f32x4*)((float*)hout + off) = h0; *(f32x4*)((float*)hout + off + 4) = h1; }
;                 }
;                 if (ssqh) { sh += __shfl_xor(sh, 16); sh += __shfl_xor(sh, 32); if (fq == 0) red[rl * 4 + wc] = sh; }
.LBB0_1204:
	s_or_b64 exec, exec, s[0:1]
	v_or_b32_e32 v148, 16, v152
	s_waitcnt lgkmcnt(0)
	v_lshl_add_u64 v[128:129], s[14:15], 0, v[148:149]
	v_lshl_add_u64 v[130:131], v[128:129], 2, s[12:13]
	global_load_dword v138, v[130:131], off sc1
	v_lshlrev_b64 v[128:129], 11, v[128:129]
	v_lshl_add_u64 v[128:129], s[10:11], 0, v[128:129]
	v_lshl_add_u64 v[136:137], v[146:147], 1, v[128:129]
	global_load_dwordx4 v[128:131], v[136:137], off
	global_load_dwordx4 v[132:135], v[136:137], off offset:256
	s_waitcnt vmcnt(2)
	v_fmac_f32_e32 v155, 0x3a800000, v138
	v_mul_f32_e32 v138, 0x4f800000, v155
	v_cmp_gt_f32_e32 vcc, s2, v155
	s_waitcnt vmcnt(1)
	v_and_b32_e32 v139, 0xffff0000, v128
	v_lshlrev_b32_e32 v140, 16, v130
	v_cndmask_b32_e32 v149, v155, v138, vcc
	v_sqrt_f32_e32 v155, v149
	v_lshlrev_b32_e32 v138, 16, v128
	v_lshlrev_b32_e32 v128, 16, v129
	v_and_b32_e32 v129, 0xffff0000, v129
	v_add_u32_e32 v158, -1, v155
	v_add_u32_e32 v159, 1, v155
	v_fma_f32 v160, -v158, v155, v149
	v_fma_f32 v161, -v159, v155, v149
	v_cmp_ge_f32_e64 s[0:1], 0, v160
	v_and_b32_e32 v141, 0xffff0000, v130
	v_lshlrev_b32_e32 v130, 16, v131
	v_cndmask_b32_e64 v155, v155, v158, s[0:1]
	v_cmp_lt_f32_e64 s[0:1], 0, v161
	v_and_b32_e32 v131, 0xffff0000, v131
	s_waitcnt vmcnt(0)
	v_lshlrev_b32_e32 v142, 16, v132
	v_cndmask_b32_e64 v155, v155, v159, s[0:1]
	v_mul_f32_e32 v158, 0x37800000, v155
	v_cndmask_b32_e32 v155, v155, v158, vcc
	v_cmp_class_f32_e32 vcc, v149, v153
	v_and_b32_e32 v143, 0xffff0000, v132
	v_lshlrev_b32_e32 v132, 16, v133
	v_cndmask_b32_e32 v149, v155, v149, vcc
	v_div_scale_f32 v153, s[0:1], v149, v149, 1.0
	v_rcp_f32_e32 v155, v153
	v_div_scale_f32 v158, vcc, 1.0, v149, 1.0
	v_and_b32_e32 v133, 0xffff0000, v133
	v_fma_f32 v159, -v153, v155, 1.0
	v_fmac_f32_e32 v155, v159, v155
	v_mul_f32_e32 v159, v158, v155
	v_fma_f32 v160, -v153, v159, v158
	v_fmac_f32_e32 v159, v160, v155
	v_fma_f32 v153, -v153, v159, v158
	v_div_fmas_f32 v153, v153, v155, v159
	v_div_fixup_f32 v158, v153, v149, 1.0
	v_lshlrev_b32_e32 v156, 16, v134
	v_and_b32_e32 v157, 0xffff0000, v134
	v_lshlrev_b32_e32 v134, 16, v135
	v_and_b32_e32 v135, 0xffff0000, v135
	v_pk_mul_f32 v[124:125], v[124:125], v[158:159] op_sel_hi:[1,0]
	v_pk_mul_f32 v[126:127], v[126:127], v[158:159] op_sel_hi:[1,0]
	v_pk_mul_f32 v[120:121], v[120:121], v[158:159] op_sel_hi:[1,0]
	v_pk_mul_f32 v[122:123], v[122:123], v[158:159] op_sel_hi:[1,0]
	v_pk_mul_f32 v[116:117], v[116:117], v[158:159] op_sel_hi:[1,0]
	v_pk_mul_f32 v[118:119], v[118:119], v[158:159] op_sel_hi:[1,0]
	v_pk_mul_f32 v[112:113], v[112:113], v[158:159] op_sel_hi:[1,0]
	v_pk_mul_f32 v[114:115], v[114:115], v[158:159] op_sel_hi:[1,0]
	v_pk_fma_f32 v[126:127], v[106:107], v[126:127], v[128:129]
	v_pk_fma_f32 v[124:125], v[104:105], v[124:125], v[138:139]
	v_pk_fma_f32 v[122:123], v[102:103], v[122:123], v[130:131]
	v_pk_fma_f32 v[120:121], v[100:101], v[120:121], v[140:141]
	v_pk_fma_f32 v[118:119], v[110:111], v[118:119], v[132:133]
	v_pk_fma_f32 v[116:117], v[108:109], v[116:117], v[142:143]
	v_pk_fma_f32 v[128:129], v[98:99], v[114:115], v[134:135]
	v_pk_fma_f32 v[130:131], v[96:97], v[112:113], v[156:157]
	v_cvt_pk_bf16_f32 v112, v124, v125
	v_cvt_pk_bf16_f32 v113, v126, v127
	v_mul_f32_e32 v114, v125, v125
	v_mul_f32_e32 v115, v127, v127
	v_mul_f32_e32 v125, v121, v121
	v_mul_f32_e32 v127, v123, v123
	v_mul_f32_e32 v132, v117, v117
	v_mul_f32_e32 v133, v119, v119
	v_mul_f32_e32 v134, v131, v131
	v_mul_f32_e32 v135, v129, v129
	v_fmac_f32_e32 v114, v124, v124
	v_fmac_f32_e32 v115, v126, v126
	v_fmac_f32_e32 v125, v120, v120
	v_fmac_f32_e32 v127, v122, v122
	v_fmac_f32_e32 v132, v116, v116
	v_fmac_f32_e32 v133, v118, v118
	v_fmac_f32_e32 v134, v130, v130
	v_fmac_f32_e32 v135, v128, v128
	v_add_f32_e32 v114, v114, v115
	v_add_f32_e32 v115, v125, v127
	v_add_f32_e32 v124, v132, v133
	v_add_f32_e32 v125, v134, v135
	v_add_f32_e32 v114, v114, v115
	v_add_f32_e32 v115, v124, v125
	v_add_f32_e32 v124, v114, v115
	v_mov_b32_e32 v125, v124
	s_nop 1
	v_permlane16_swap_b32 v125, v124
	s_nop 0
	v_cvt_pk_bf16_f32 v114, v120, v121
	v_cvt_pk_bf16_f32 v115, v122, v123
	global_store_dwordx4 v[136:137], v[112:115], off
	s_waitcnt lgkmcnt(0)
	s_nop 0
	v_add_f32_e32 v112, v124, v125
	v_mov_b32_e32 v113, v112
	s_nop 1
	v_permlane32_swap_b32 v113, v112
	s_nop 0
	v_cvt_pk_bf16_f32 v114, v116, v117
	v_cvt_pk_bf16_f32 v115, v118, v119
	v_cvt_pk_bf16_f32 v116, v130, v131
	v_cvt_pk_bf16_f32 v117, v128, v129
	global_store_dwordx4 v[136:137], v[114:117], off offset:256
	s_and_saveexec_b64 s[0:1], s[4:5]
	s_cbranch_execz .LBB0_1206
	v_lshl_add_u32 v114, v148, 4, s22
	s_waitcnt lgkmcnt(0)
	v_add_f32_e32 v112, v112, v113
	ds_write_b32 v114, v112
; DI unsigned pk_bf16(float lo, float hi) { f32x2 v = {lo, hi}; bf16x2_t b = __builtin_convertvector(v, bf16x2_t); return __builtin_bit_cast(unsigned, b); }
; DI float bflo(unsigned w) { return __uint_as_float(w << 16); }
; DI float bfhi(unsigned w) { return __uint_as_float(w & 0xffff0000u); }
;     __device__ __forceinline__ void fused(f32x4 (&acc)[2][2][4][2], const pg8::Unit& u, int wr, int wc, int fr, int fq, PG8_LAS unsigned char* lds, int wid, int lane) const {
;     ...
;                 const int rl = ai * 128 + wr * 64 + m * 16 + fr; const size_t row = (size_t)u.pm * 256 + rl;
;                 const float rm = 1.f / sqrtf(__hip_atomic_load(ssqm + row, __ATOMIC_RELAXED, __HIP_MEMORY_SCOPE_AGENT) * (1.f / DM) + RMS_EPS);
;                 float sh = 0.f;
; #pragma unroll
;                 for (int bj = 0; bj < 2; ++bj) {
;                     const size_t off = row * DM + colb + bj * 128;
;                     f32x4 h0, h1;
;                     if (IN16) { const u32x4 hw = *(const u32x4*)((const bf16_t*)hin + off); h0 = (f32x4){bflo(hw.x), bfhi(hw.x), bflo(hw.y), bfhi(hw.y)}; h1 = (f32x4){bflo(hw.z), bfhi(hw.z), bflo(hw.w), bfhi(hw.w)}; }
;                     else { h0 = *(const f32x4*)((const float*)hin + off); h1 = *(const f32x4*)((const float*)hin + off + 4); }
;                     h0 = h0 + acc[ai][bj][m][0] * rm * gv[bj][0]; h1 = h1 + acc[ai][bj][m][1] * rm * gv[bj][1];
;                     sh += ((h0[0] * h0[0] + h0[1] * h0[1]) + (h0[2] * h0[2] + h0[3] * h0[3])) + ((h1[0] * h1[0] + h1[1] * h1[1]) + (h1[2] * h1[2] + h1[3] * h1[3]));
;                     if (OUT16) { u32x4 w; w.x = pk_bf16(h0[0], h0[1]); w.y = pk_bf16(h0[2], h0[3]); w.z = pk_bf16(h1[0], h1[1]); w.w = pk_bf16(h1[2], h1[3]); *(u32x4*)((bf16_t*)hout + off) = w; }
;                     else { *(f32x4*)((float*)hout + off) = h0; *(f32x4*)((float*)hout + off + 4) = h1; }
;                 }
;                 if (ssqh) { sh += __shfl_xor(sh, 16); sh += __shfl_xor(sh, 32); if (fq == 0) red[rl * 4 + wc] = sh; }
.LBB0_1206:
	s_or_b64 exec, exec, s[0:1]
	v_or_b32_e32 v112, 32, v152
	s_waitcnt lgkmcnt(0)
	v_mov_b32_e32 v113, 0
	v_lshl_add_u64 v[114:115], s[14:15], 0, v[112:113]
	v_lshl_add_u64 v[116:117], v[114:115], 2, s[12:13]
	global_load_dword v126, v[116:117], off sc1
	v_lshlrev_b64 v[114:115], 11, v[114:115]
	v_lshl_add_u64 v[114:115], s[10:11], 0, v[114:115]
	v_lshl_add_u64 v[124:125], v[146:147], 1, v[114:115]
	global_load_dwordx4 v[116:119], v[124:125], off
	global_load_dwordx4 v[120:123], v[124:125], off offset:256
	v_mov_b32_e32 v115, 0x358637bd
	v_mov_b32_e32 v114, 0x260
	s_waitcnt vmcnt(2)
	v_fmamk_f32 v126, v126, 0x3a800000, v115
	v_mul_f32_e32 v127, 0x4f800000, v126
	v_cmp_gt_f32_e32 vcc, s2, v126
	s_waitcnt vmcnt(1)
	v_lshlrev_b32_e32 v128, 16, v118
	v_and_b32_e32 v129, 0xffff0000, v118
	v_cndmask_b32_e32 v134, v126, v127, vcc
	v_sqrt_f32_e32 v135, v134
	v_lshlrev_b32_e32 v126, 16, v116
	v_and_b32_e32 v127, 0xffff0000, v116
	v_lshlrev_b32_e32 v116, 16, v117
	v_add_u32_e32 v136, -1, v135
	v_add_u32_e32 v137, 1, v135
	v_fma_f32 v138, -v136, v135, v134
	v_fma_f32 v139, -v137, v135, v134
	v_cmp_ge_f32_e64 s[0:1], 0, v138
	v_and_b32_e32 v117, 0xffff0000, v117
	v_lshlrev_b32_e32 v118, 16, v119
	v_cndmask_b32_e64 v135, v135, v136, s[0:1]
	v_cmp_lt_f32_e64 s[0:1], 0, v139
	v_and_b32_e32 v119, 0xffff0000, v119
	s_waitcnt vmcnt(0)
	v_lshlrev_b32_e32 v130, 16, v120
	v_cndmask_b32_e64 v135, v135, v137, s[0:1]
	v_mul_f32_e32 v136, 0x37800000, v135
	v_cndmask_b32_e32 v135, v135, v136, vcc
	v_cmp_class_f32_e32 vcc, v134, v114
	v_and_b32_e32 v131, 0xffff0000, v120
	v_lshlrev_b32_e32 v120, 16, v121
	v_cndmask_b32_e32 v134, v135, v134, vcc
	v_div_scale_f32 v135, s[0:1], v134, v134, 1.0
	v_rcp_f32_e32 v136, v135
	v_div_scale_f32 v137, vcc, 1.0, v134, 1.0
	v_and_b32_e32 v121, 0xffff0000, v121
	v_fma_f32 v138, -v135, v136, 1.0
	v_fmac_f32_e32 v136, v138, v136
	v_mul_f32_e32 v138, v137, v136
	v_fma_f32 v139, -v135, v138, v137
	v_fmac_f32_e32 v138, v139, v136
	v_fma_f32 v135, -v135, v138, v137
	v_div_fmas_f32 v135, v135, v136, v138
	v_div_fixup_f32 v134, v135, v134, 1.0
	v_lshlrev_b32_e32 v132, 16, v122
	v_and_b32_e32 v133, 0xffff0000, v122
	v_lshlrev_b32_e32 v122, 16, v123
	v_and_b32_e32 v123, 0xffff0000, v123
	v_pk_mul_f32 v[92:93], v[92:93], v[134:135] op_sel_hi:[1,0]
	v_pk_mul_f32 v[94:95], v[94:95], v[134:135] op_sel_hi:[1,0]
	v_pk_mul_f32 v[88:89], v[88:89], v[134:135] op_sel_hi:[1,0]
	v_pk_mul_f32 v[90:91], v[90:91], v[134:135] op_sel_hi:[1,0]
	v_pk_mul_f32 v[84:85], v[84:85], v[134:135] op_sel_hi:[1,0]
	v_pk_mul_f32 v[86:87], v[86:87], v[134:135] op_sel_hi:[1,0]
	v_pk_mul_f32 v[80:81], v[80:81], v[134:135] op_sel_hi:[1,0]
	v_pk_mul_f32 v[82:83], v[82:83], v[134:135] op_sel_hi:[1,0]
	v_pk_fma_f32 v[94:95], v[106:107], v[94:95], v[116:117]
	v_pk_fma_f32 v[92:93], v[104:105], v[92:93], v[126:127]
	v_pk_fma_f32 v[90:91], v[102:103], v[90:91], v[118:119]
	v_pk_fma_f32 v[88:89], v[100:101], v[88:89], v[128:129]
	v_pk_fma_f32 v[86:87], v[110:111], v[86:87], v[120:121]
	v_pk_fma_f32 v[84:85], v[108:109], v[84:85], v[130:131]
	v_pk_fma_f32 v[116:117], v[98:99], v[82:83], v[122:123]
	v_pk_fma_f32 v[118:119], v[96:97], v[80:81], v[132:133]
	v_cvt_pk_bf16_f32 v80, v92, v93
	v_cvt_pk_bf16_f32 v81, v94, v95
	v_mul_f32_e32 v82, v93, v93
	v_mul_f32_e32 v83, v95, v95
	v_mul_f32_e32 v93, v89, v89
	v_mul_f32_e32 v95, v91, v91
	v_mul_f32_e32 v120, v85, v85
	v_mul_f32_e32 v121, v87, v87
	v_mul_f32_e32 v122, v119, v119
	v_mul_f32_e32 v123, v117, v117
	v_fmac_f32_e32 v82, v92, v92
	v_fmac_f32_e32 v83, v94, v94
	v_fmac_f32_e32 v93, v88, v88
	v_fmac_f32_e32 v95, v90, v90
	v_fmac_f32_e32 v120, v84, v84
	v_fmac_f32_e32 v121, v86, v86
	v_fmac_f32_e32 v122, v118, v118
	v_fmac_f32_e32 v123, v116, v116
	v_add_f32_e32 v82, v82, v83
	v_add_f32_e32 v83, v93, v95
	v_add_f32_e32 v92, v120, v121
	v_add_f32_e32 v93, v122, v123
	v_add_f32_e32 v82, v82, v83
	v_add_f32_e32 v83, v92, v93
	v_add_f32_e32 v92, v82, v83
	v_mov_b32_e32 v93, v92
	s_nop 1
	v_permlane16_swap_b32 v93, v92
	s_nop 0
	v_cvt_pk_bf16_f32 v82, v88, v89
	v_cvt_pk_bf16_f32 v83, v90, v91
	global_store_dwordx4 v[124:125], v[80:83], off
	s_waitcnt lgkmcnt(0)
	s_nop 0
	v_add_f32_e32 v80, v92, v93
	v_mov_b32_e32 v81, v80
	s_nop 1
	v_permlane32_swap_b32 v81, v80
	s_nop 0
	v_cvt_pk_bf16_f32 v82, v84, v85
	v_cvt_pk_bf16_f32 v83, v86, v87
	v_cvt_pk_bf16_f32 v84, v118, v119
	v_cvt_pk_bf16_f32 v85, v116, v117
	global_store_dwordx4 v[124:125], v[82:85], off offset:256
	s_and_saveexec_b64 s[0:1], s[4:5]
	s_cbranch_execz .LBB0_1208
	v_lshl_add_u32 v82, v112, 4, s22
	s_waitcnt lgkmcnt(0)
	v_add_f32_e32 v80, v80, v81
	ds_write_b32 v82, v80
; DI unsigned pk_bf16(float lo, float hi) { f32x2 v = {lo, hi}; bf16x2_t b = __builtin_convertvector(v, bf16x2_t); return __builtin_bit_cast(unsigned, b); }
; DI float bflo(unsigned w) { return __uint_as_float(w << 16); }
; DI float bfhi(unsigned w) { return __uint_as_float(w & 0xffff0000u); }
;     __device__ __forceinline__ void fused(f32x4 (&acc)[2][2][4][2], const pg8::Unit& u, int wr, int wc, int fr, int fq, PG8_LAS unsigned char* lds, int wid, int lane) const {
;     ...
;                 const int rl = ai * 128 + wr * 64 + m * 16 + fr; const size_t row = (size_t)u.pm * 256 + rl;
;                 const float rm = 1.f / sqrtf(__hip_atomic_load(ssqm + row, __ATOMIC_RELAXED, __HIP_MEMORY_SCOPE_AGENT) * (1.f / DM) + RMS_EPS);
;                 float sh = 0.f;
; #pragma unroll
;                 for (int bj = 0; bj < 2; ++bj) {
;                     const size_t off = row * DM + colb + bj * 128;
;                     f32x4 h0, h1;
;                     if (IN16) { const u32x4 hw = *(const u32x4*)((const bf16_t*)hin + off); h0 = (f32x4){bflo(hw.x), bfhi(hw.x), bflo(hw.y), bfhi(hw.y)}; h1 = (f32x4){bflo(hw.z), bfhi(hw.z), bflo(hw.w), bfhi(hw.w)}; }
;                     else { h0 = *(const f32x4*)((const float*)hin + off); h1 = *(const f32x4*)((const float*)hin + off + 4); }
;                     h0 = h0 + acc[ai][bj][m][0] * rm * gv[bj][0]; h1 = h1 + acc[ai][bj][m][1] * rm * gv[bj][1];
;                     sh += ((h0[0] * h0[0] + h0[1] * h0[1]) + (h0[2] * h0[2] + h0[3] * h0[3])) + ((h1[0] * h1[0] + h1[1] * h1[1]) + (h1[2] * h1[2] + h1[3] * h1[3]));
;                     if (OUT16) { u32x4 w; w.x = pk_bf16(h0[0], h0[1]); w.y = pk_bf16(h0[2], h0[3]); w.z = pk_bf16(h1[0], h1[1]); w.w = pk_bf16(h1[2], h1[3]); *(u32x4*)((bf16_t*)hout + off) = w; }
;                     else { *(f32x4*)((float*)hout + off) = h0; *(f32x4*)((float*)hout + off + 4) = h1; }
;                 }
;                 if (ssqh) { sh += __shfl_xor(sh, 16); sh += __shfl_xor(sh, 32); if (fq == 0) red[rl * 4 + wc] = sh; }
.LBB0_1208:
	s_or_b64 exec, exec, s[0:1]
	v_or_b32_e32 v112, 48, v152
	s_waitcnt lgkmcnt(0)
	v_lshl_add_u64 v[80:81], s[14:15], 0, v[112:113]
	v_lshl_add_u64 v[82:83], v[80:81], 2, s[12:13]
	global_load_dword v90, v[82:83], off sc1
	v_lshlrev_b64 v[80:81], 11, v[80:81]
	v_lshl_add_u64 v[80:81], s[10:11], 0, v[80:81]
	v_lshl_add_u64 v[88:89], v[146:147], 1, v[80:81]
	global_load_dwordx4 v[80:83], v[88:89], off
	global_load_dwordx4 v[84:87], v[88:89], off offset:256
	s_waitcnt vmcnt(2)
	v_fmac_f32_e32 v115, 0x3a800000, v90
	v_mul_f32_e32 v90, 0x4f800000, v115
	v_cmp_gt_f32_e32 vcc, s2, v115
	s_waitcnt vmcnt(1)
	v_and_b32_e32 v91, 0xffff0000, v80
	v_lshlrev_b32_e32 v92, 16, v82
	v_cndmask_b32_e32 v113, v115, v90, vcc
	v_sqrt_f32_e32 v115, v113
	v_lshlrev_b32_e32 v90, 16, v80
	v_lshlrev_b32_e32 v80, 16, v81
	v_and_b32_e32 v81, 0xffff0000, v81
	v_add_u32_e32 v118, -1, v115
	v_add_u32_e32 v119, 1, v115
	v_fma_f32 v120, -v118, v115, v113
	v_fma_f32 v121, -v119, v115, v113
	v_cmp_ge_f32_e64 s[0:1], 0, v120
	v_and_b32_e32 v93, 0xffff0000, v82
	v_lshlrev_b32_e32 v82, 16, v83
	v_cndmask_b32_e64 v115, v115, v118, s[0:1]
	v_cmp_lt_f32_e64 s[0:1], 0, v121
	v_and_b32_e32 v83, 0xffff0000, v83
	s_waitcnt vmcnt(0)
	v_lshlrev_b32_e32 v94, 16, v84
	v_cndmask_b32_e64 v115, v115, v119, s[0:1]
	v_mul_f32_e32 v118, 0x37800000, v115
	v_cndmask_b32_e32 v115, v115, v118, vcc
	v_cmp_class_f32_e32 vcc, v113, v114
	v_and_b32_e32 v95, 0xffff0000, v84
	v_lshlrev_b32_e32 v84, 16, v85
	v_cndmask_b32_e32 v113, v115, v113, vcc
	v_div_scale_f32 v114, s[0:1], v113, v113, 1.0
	v_rcp_f32_e32 v115, v114
	v_div_scale_f32 v118, vcc, 1.0, v113, 1.0
	v_and_b32_e32 v85, 0xffff0000, v85
	v_fma_f32 v119, -v114, v115, 1.0
	v_fmac_f32_e32 v115, v119, v115
	v_mul_f32_e32 v119, v118, v115
	v_fma_f32 v120, -v114, v119, v118
	v_fmac_f32_e32 v119, v120, v115
	v_fma_f32 v114, -v114, v119, v118
	v_div_fmas_f32 v114, v114, v115, v119
	v_div_fixup_f32 v114, v114, v113, 1.0
	v_lshlrev_b32_e32 v116, 16, v86
	v_and_b32_e32 v117, 0xffff0000, v86
	v_lshlrev_b32_e32 v86, 16, v87
	v_and_b32_e32 v87, 0xffff0000, v87
	v_pk_mul_f32 v[76:77], v[76:77], v[114:115] op_sel_hi:[1,0]
	v_pk_mul_f32 v[78:79], v[78:79], v[114:115] op_sel_hi:[1,0]
	v_pk_mul_f32 v[72:73], v[72:73], v[114:115] op_sel_hi:[1,0]
	v_pk_mul_f32 v[74:75], v[74:75], v[114:115] op_sel_hi:[1,0]
	v_pk_mul_f32 v[68:69], v[68:69], v[114:115] op_sel_hi:[1,0]
	v_pk_mul_f32 v[70:71], v[70:71], v[114:115] op_sel_hi:[1,0]
	v_pk_mul_f32 v[64:65], v[64:65], v[114:115] op_sel_hi:[1,0]
	v_pk_mul_f32 v[66:67], v[66:67], v[114:115] op_sel_hi:[1,0]
	v_pk_fma_f32 v[78:79], v[106:107], v[78:79], v[80:81]
	v_pk_fma_f32 v[76:77], v[104:105], v[76:77], v[90:91]
	v_pk_fma_f32 v[74:75], v[102:103], v[74:75], v[82:83]
	v_pk_fma_f32 v[72:73], v[100:101], v[72:73], v[92:93]
	v_pk_fma_f32 v[70:71], v[110:111], v[70:71], v[84:85]
	v_pk_fma_f32 v[68:69], v[108:109], v[68:69], v[94:95]
	v_pk_fma_f32 v[80:81], v[98:99], v[66:67], v[86:87]
	v_pk_fma_f32 v[82:83], v[96:97], v[64:65], v[116:117]
	v_cvt_pk_bf16_f32 v64, v76, v77
	v_cvt_pk_bf16_f32 v65, v78, v79
	v_mul_f32_e32 v66, v77, v77
	v_mul_f32_e32 v67, v79, v79
	v_mul_f32_e32 v77, v73, v73
	v_mul_f32_e32 v79, v75, v75
	v_mul_f32_e32 v84, v69, v69
	v_mul_f32_e32 v85, v71, v71
	v_mul_f32_e32 v86, v83, v83
	v_mul_f32_e32 v87, v81, v81
	v_fmac_f32_e32 v66, v76, v76
	v_fmac_f32_e32 v67, v78, v78
	v_fmac_f32_e32 v77, v72, v72
	v_fmac_f32_e32 v79, v74, v74
	v_fmac_f32_e32 v84, v68, v68
	v_fmac_f32_e32 v85, v70, v70
	v_fmac_f32_e32 v86, v82, v82
	v_fmac_f32_e32 v87, v80, v80
	v_add_f32_e32 v66, v66, v67
	v_add_f32_e32 v67, v77, v79
	v_add_f32_e32 v76, v84, v85
	v_add_f32_e32 v77, v86, v87
	v_add_f32_e32 v66, v66, v67
	v_add_f32_e32 v67, v76, v77
	v_add_f32_e32 v76, v66, v67
	v_mov_b32_e32 v77, v76
	s_nop 1
	v_permlane16_swap_b32 v77, v76
	s_nop 0
	v_cvt_pk_bf16_f32 v66, v72, v73
	v_cvt_pk_bf16_f32 v67, v74, v75
	global_store_dwordx4 v[88:89], v[64:67], off
	s_waitcnt lgkmcnt(0)
	s_nop 0
	v_add_f32_e32 v64, v76, v77
	v_mov_b32_e32 v65, v64
	s_nop 1
	v_permlane32_swap_b32 v65, v64
	s_nop 0
	v_cvt_pk_bf16_f32 v66, v68, v69
	v_cvt_pk_bf16_f32 v67, v70, v71
	v_cvt_pk_bf16_f32 v68, v82, v83
	v_cvt_pk_bf16_f32 v69, v80, v81
	global_store_dwordx4 v[88:89], v[66:69], off offset:256
	s_and_saveexec_b64 s[0:1], s[4:5]
	s_cbranch_execz .LBB0_1210
	v_lshl_add_u32 v66, v112, 4, s22
	s_waitcnt lgkmcnt(0)
	v_add_f32_e32 v64, v64, v65
	ds_write_b32 v66, v64
; DI unsigned pk_bf16(float lo, float hi) { f32x2 v = {lo, hi}; bf16x2_t b = __builtin_convertvector(v, bf16x2_t); return __builtin_bit_cast(unsigned, b); }
; DI float bflo(unsigned w) { return __uint_as_float(w << 16); }
; DI float bfhi(unsigned w) { return __uint_as_float(w & 0xffff0000u); }
;     __device__ __forceinline__ void fused(f32x4 (&acc)[2][2][4][2], const pg8::Unit& u, int wr, int wc, int fr, int fq, PG8_LAS unsigned char* lds, int wid, int lane) const {
;     ...
;                 const int rl = ai * 128 + wr * 64 + m * 16 + fr; const size_t row = (size_t)u.pm * 256 + rl;
;                 const float rm = 1.f / sqrtf(__hip_atomic_load(ssqm + row, __ATOMIC_RELAXED, __HIP_MEMORY_SCOPE_AGENT) * (1.f / DM) + RMS_EPS);
;                 float sh = 0.f;
; #pragma unroll
;                 for (int bj = 0; bj < 2; ++bj) {
;                     const size_t off = row * DM + colb + bj * 128;
;                     f32x4 h0, h1;
;                     if (IN16) { const u32x4 hw = *(const u32x4*)((const bf16_t*)hin + off); h0 = (f32x4){bflo(hw.x), bfhi(hw.x), bflo(hw.y), bfhi(hw.y)}; h1 = (f32x4){bflo(hw.z), bfhi(hw.z), bflo(hw.w), bfhi(hw.w)}; }
;                     else { h0 = *(const f32x4*)((const float*)hin + off); h1 = *(const f32x4*)((const float*)hin + off + 4); }
;                     h0 = h0 + acc[ai][bj][m][0] * rm * gv[bj][0]; h1 = h1 + acc[ai][bj][m][1] * rm * gv[bj][1];
;                     sh += ((h0[0] * h0[0] + h0[1] * h0[1]) + (h0[2] * h0[2] + h0[3] * h0[3])) + ((h1[0] * h1[0] + h1[1] * h1[1]) + (h1[2] * h1[2] + h1[3] * h1[3]));
;                     if (OUT16) { u32x4 w; w.x = pk_bf16(h0[0], h0[1]); w.y = pk_bf16(h0[2], h0[3]); w.z = pk_bf16(h1[0], h1[1]); w.w = pk_bf16(h1[2], h1[3]); *(u32x4*)((bf16_t*)hout + off) = w; }
;                     else { *(f32x4*)((float*)hout + off) = h0; *(f32x4*)((float*)hout + off + 4) = h1; }
;                 }
;                 if (ssqh) { sh += __shfl_xor(sh, 16); sh += __shfl_xor(sh, 32); if (fq == 0) red[rl * 4 + wc] = sh; }
.LBB0_1210:
	s_or_b64 exec, exec, s[0:1]
	v_add_u32_e32 v64, 0x80, v152
	s_waitcnt lgkmcnt(0)
	v_mov_b32_e32 v65, 0
	v_lshl_add_u64 v[66:67], s[14:15], 0, v[64:65]
	v_lshl_add_u64 v[68:69], v[66:67], 2, s[12:13]
	global_load_dword v78, v[68:69], off sc1
	v_lshlrev_b64 v[66:67], 11, v[66:67]
	v_lshl_add_u64 v[66:67], s[10:11], 0, v[66:67]
	v_lshl_add_u64 v[76:77], v[146:147], 1, v[66:67]
	global_load_dwordx4 v[68:71], v[76:77], off
	global_load_dwordx4 v[72:75], v[76:77], off offset:256
	v_mov_b32_e32 v67, 0x358637bd
	v_mov_b32_e32 v66, 0x260
	s_waitcnt vmcnt(2)
	v_fmamk_f32 v78, v78, 0x3a800000, v67
	v_mul_f32_e32 v79, 0x4f800000, v78
	v_cmp_gt_f32_e32 vcc, s2, v78
	s_waitcnt vmcnt(1)
	v_lshlrev_b32_e32 v80, 16, v70
	v_and_b32_e32 v81, 0xffff0000, v70
	v_cndmask_b32_e32 v86, v78, v79, vcc
	v_sqrt_f32_e32 v87, v86
	v_lshlrev_b32_e32 v78, 16, v68
	v_and_b32_e32 v79, 0xffff0000, v68
	v_lshlrev_b32_e32 v68, 16, v69
	v_add_u32_e32 v88, -1, v87
	v_add_u32_e32 v89, 1, v87
	v_fma_f32 v90, -v88, v87, v86
	v_fma_f32 v91, -v89, v87, v86
	v_cmp_ge_f32_e64 s[0:1], 0, v90
	v_and_b32_e32 v69, 0xffff0000, v69
	v_lshlrev_b32_e32 v70, 16, v71
	v_cndmask_b32_e64 v87, v87, v88, s[0:1]
	v_cmp_lt_f32_e64 s[0:1], 0, v91
	v_and_b32_e32 v71, 0xffff0000, v71
	s_waitcnt vmcnt(0)
	v_lshlrev_b32_e32 v82, 16, v72
	v_cndmask_b32_e64 v87, v87, v89, s[0:1]
	v_mul_f32_e32 v88, 0x37800000, v87
	v_cndmask_b32_e32 v87, v87, v88, vcc
	v_cmp_class_f32_e32 vcc, v86, v66
	v_and_b32_e32 v83, 0xffff0000, v72
	v_lshlrev_b32_e32 v72, 16, v73
	v_cndmask_b32_e32 v86, v87, v86, vcc
	v_div_scale_f32 v87, s[0:1], v86, v86, 1.0
	v_rcp_f32_e32 v88, v87
	v_div_scale_f32 v89, vcc, 1.0, v86, 1.0
	v_and_b32_e32 v73, 0xffff0000, v73
	v_fma_f32 v90, -v87, v88, 1.0
	v_fmac_f32_e32 v88, v90, v88
	v_mul_f32_e32 v90, v89, v88
	v_fma_f32 v91, -v87, v90, v89
	v_fmac_f32_e32 v90, v91, v88
	v_fma_f32 v87, -v87, v90, v89
	v_div_fmas_f32 v87, v87, v88, v90
	v_div_fixup_f32 v86, v87, v86, 1.0
	v_lshlrev_b32_e32 v84, 16, v74
	v_and_b32_e32 v85, 0xffff0000, v74
	v_lshlrev_b32_e32 v74, 16, v75
	v_and_b32_e32 v75, 0xffff0000, v75
	v_pk_mul_f32 v[60:61], v[60:61], v[86:87] op_sel_hi:[1,0]
	v_pk_mul_f32 v[62:63], v[62:63], v[86:87] op_sel_hi:[1,0]
	v_pk_mul_f32 v[56:57], v[56:57], v[86:87] op_sel_hi:[1,0]
	v_pk_mul_f32 v[58:59], v[58:59], v[86:87] op_sel_hi:[1,0]
	v_pk_mul_f32 v[52:53], v[52:53], v[86:87] op_sel_hi:[1,0]
	v_pk_mul_f32 v[54:55], v[54:55], v[86:87] op_sel_hi:[1,0]
	v_pk_mul_f32 v[48:49], v[48:49], v[86:87] op_sel_hi:[1,0]
	v_pk_mul_f32 v[50:51], v[50:51], v[86:87] op_sel_hi:[1,0]
	v_pk_fma_f32 v[62:63], v[106:107], v[62:63], v[68:69]
	v_pk_fma_f32 v[60:61], v[104:105], v[60:61], v[78:79]
	v_pk_fma_f32 v[58:59], v[102:103], v[58:59], v[70:71]
	v_pk_fma_f32 v[56:57], v[100:101], v[56:57], v[80:81]
	v_pk_fma_f32 v[54:55], v[110:111], v[54:55], v[72:73]
	v_pk_fma_f32 v[52:53], v[108:109], v[52:53], v[82:83]
	v_pk_fma_f32 v[68:69], v[98:99], v[50:51], v[74:75]
	v_pk_fma_f32 v[70:71], v[96:97], v[48:49], v[84:85]
	v_cvt_pk_bf16_f32 v48, v60, v61
	v_cvt_pk_bf16_f32 v49, v62, v63
	v_mul_f32_e32 v50, v61, v61
	v_mul_f32_e32 v51, v63, v63
	v_mul_f32_e32 v61, v57, v57
	v_mul_f32_e32 v63, v59, v59
	v_mul_f32_e32 v72, v53, v53
	v_mul_f32_e32 v73, v55, v55
	v_mul_f32_e32 v74, v71, v71
	v_mul_f32_e32 v75, v69, v69
	v_fmac_f32_e32 v50, v60, v60
	v_fmac_f32_e32 v51, v62, v62
	v_fmac_f32_e32 v61, v56, v56
	v_fmac_f32_e32 v63, v58, v58
	v_fmac_f32_e32 v72, v52, v52
	v_fmac_f32_e32 v73, v54, v54
	v_fmac_f32_e32 v74, v70, v70
	v_fmac_f32_e32 v75, v68, v68
	v_add_f32_e32 v50, v50, v51
	v_add_f32_e32 v51, v61, v63
	v_add_f32_e32 v60, v72, v73
	v_add_f32_e32 v61, v74, v75
	v_add_f32_e32 v50, v50, v51
	v_add_f32_e32 v51, v60, v61
	v_add_f32_e32 v60, v50, v51
	v_mov_b32_e32 v61, v60
	s_nop 1
	v_permlane16_swap_b32 v61, v60
	s_nop 0
	v_cvt_pk_bf16_f32 v50, v56, v57
	v_cvt_pk_bf16_f32 v51, v58, v59
	global_store_dwordx4 v[76:77], v[48:51], off
	s_waitcnt lgkmcnt(0)
	s_nop 0
	v_add_f32_e32 v48, v60, v61
	v_mov_b32_e32 v49, v48
	s_nop 1
	v_permlane32_swap_b32 v49, v48
	s_nop 0
	v_cvt_pk_bf16_f32 v50, v52, v53
	v_cvt_pk_bf16_f32 v51, v54, v55
	v_cvt_pk_bf16_f32 v52, v70, v71
	v_cvt_pk_bf16_f32 v53, v68, v69
	global_store_dwordx4 v[76:77], v[50:53], off offset:256
	s_and_saveexec_b64 s[0:1], s[4:5]
	s_cbranch_execz .LBB0_1212
	v_lshl_add_u32 v50, v64, 4, s22
	s_waitcnt lgkmcnt(0)
	v_add_f32_e32 v48, v48, v49
	ds_write_b32 v50, v48
; DI unsigned pk_bf16(float lo, float hi) { f32x2 v = {lo, hi}; bf16x2_t b = __builtin_convertvector(v, bf16x2_t); return __builtin_bit_cast(unsigned, b); }
; DI float bflo(unsigned w) { return __uint_as_float(w << 16); }
; DI float bfhi(unsigned w) { return __uint_as_float(w & 0xffff0000u); }
;     __device__ __forceinline__ void fused(f32x4 (&acc)[2][2][4][2], const pg8::Unit& u, int wr, int wc, int fr, int fq, PG8_LAS unsigned char* lds, int wid, int lane) const {
;     ...
;                 const int rl = ai * 128 + wr * 64 + m * 16 + fr; const size_t row = (size_t)u.pm * 256 + rl;
;                 const float rm = 1.f / sqrtf(__hip_atomic_load(ssqm + row, __ATOMIC_RELAXED, __HIP_MEMORY_SCOPE_AGENT) * (1.f / DM) + RMS_EPS);
;                 float sh = 0.f;
; #pragma unroll
;                 for (int bj = 0; bj < 2; ++bj) {
;                     const size_t off = row * DM + colb + bj * 128;
;                     f32x4 h0, h1;
;                     if (IN16) { const u32x4 hw = *(const u32x4*)((const bf16_t*)hin + off); h0 = (f32x4){bflo(hw.x), bfhi(hw.x), bflo(hw.y), bfhi(hw.y)}; h1 = (f32x4){bflo(hw.z), bfhi(hw.z), bflo(hw.w), bfhi(hw.w)}; }
;                     else { h0 = *(const f32x4*)((const float*)hin + off); h1 = *(const f32x4*)((const float*)hin + off + 4); }
;                     h0 = h0 + acc[ai][bj][m][0] * rm * gv[bj][0]; h1 = h1 + acc[ai][bj][m][1] * rm * gv[bj][1];
;                     sh += ((h0[0] * h0[0] + h0[1] * h0[1]) + (h0[2] * h0[2] + h0[3] * h0[3])) + ((h1[0] * h1[0] + h1[1] * h1[1]) + (h1[2] * h1[2] + h1[3] * h1[3]));
;                     if (OUT16) { u32x4 w; w.x = pk_bf16(h0[0], h0[1]); w.y = pk_bf16(h0[2], h0[3]); w.z = pk_bf16(h1[0], h1[1]); w.w = pk_bf16(h1[2], h1[3]); *(u32x4*)((bf16_t*)hout + off) = w; }
;                     else { *(f32x4*)((float*)hout + off) = h0; *(f32x4*)((float*)hout + off + 4) = h1; }
;                 }
;                 if (ssqh) { sh += __shfl_xor(sh, 16); sh += __shfl_xor(sh, 32); if (fq == 0) red[rl * 4 + wc] = sh; }
.LBB0_1212:
	s_or_b64 exec, exec, s[0:1]
	v_add_u32_e32 v64, 0x90, v152
	s_waitcnt lgkmcnt(0)
	v_lshl_add_u64 v[48:49], s[14:15], 0, v[64:65]
	v_lshl_add_u64 v[50:51], v[48:49], 2, s[12:13]
	global_load_dword v58, v[50:51], off sc1
	v_lshlrev_b64 v[48:49], 11, v[48:49]
	v_lshl_add_u64 v[48:49], s[10:11], 0, v[48:49]
	v_lshl_add_u64 v[56:57], v[146:147], 1, v[48:49]
	global_load_dwordx4 v[48:51], v[56:57], off
	global_load_dwordx4 v[52:55], v[56:57], off offset:256
	s_waitcnt vmcnt(2)
	v_fmac_f32_e32 v67, 0x3a800000, v58
	v_mul_f32_e32 v58, 0x4f800000, v67
	v_cmp_gt_f32_e32 vcc, s2, v67
	s_waitcnt vmcnt(1)
	v_and_b32_e32 v59, 0xffff0000, v48
	v_lshlrev_b32_e32 v60, 16, v50
	v_cndmask_b32_e32 v65, v67, v58, vcc
	v_sqrt_f32_e32 v67, v65
	v_lshlrev_b32_e32 v58, 16, v48
	v_lshlrev_b32_e32 v48, 16, v49
	v_and_b32_e32 v49, 0xffff0000, v49
	v_add_u32_e32 v70, -1, v67
	v_add_u32_e32 v71, 1, v67
	v_fma_f32 v72, -v70, v67, v65
	v_fma_f32 v73, -v71, v67, v65
	v_cmp_ge_f32_e64 s[0:1], 0, v72
	v_and_b32_e32 v61, 0xffff0000, v50
	v_lshlrev_b32_e32 v50, 16, v51
	v_cndmask_b32_e64 v67, v67, v70, s[0:1]
	v_cmp_lt_f32_e64 s[0:1], 0, v73
	v_and_b32_e32 v51, 0xffff0000, v51
	s_waitcnt vmcnt(0)
	v_lshlrev_b32_e32 v62, 16, v52
	v_cndmask_b32_e64 v67, v67, v71, s[0:1]
	v_mul_f32_e32 v70, 0x37800000, v67
	v_cndmask_b32_e32 v67, v67, v70, vcc
	v_cmp_class_f32_e32 vcc, v65, v66
	v_and_b32_e32 v63, 0xffff0000, v52
	v_lshlrev_b32_e32 v52, 16, v53
	v_cndmask_b32_e32 v65, v67, v65, vcc
	v_div_scale_f32 v66, s[0:1], v65, v65, 1.0
	v_rcp_f32_e32 v67, v66
	v_div_scale_f32 v70, vcc, 1.0, v65, 1.0
	v_and_b32_e32 v53, 0xffff0000, v53
	v_fma_f32 v71, -v66, v67, 1.0
	v_fmac_f32_e32 v67, v71, v67
	v_mul_f32_e32 v71, v70, v67
	v_fma_f32 v72, -v66, v71, v70
	v_fmac_f32_e32 v71, v72, v67
	v_fma_f32 v66, -v66, v71, v70
	v_div_fmas_f32 v66, v66, v67, v71
	v_div_fixup_f32 v66, v66, v65, 1.0
	v_lshlrev_b32_e32 v68, 16, v54
	v_and_b32_e32 v69, 0xffff0000, v54
	v_lshlrev_b32_e32 v54, 16, v55
	v_and_b32_e32 v55, 0xffff0000, v55
	v_pk_mul_f32 v[44:45], v[44:45], v[66:67] op_sel_hi:[1,0]
	v_pk_mul_f32 v[46:47], v[46:47], v[66:67] op_sel_hi:[1,0]
	v_pk_mul_f32 v[40:41], v[40:41], v[66:67] op_sel_hi:[1,0]
	v_pk_mul_f32 v[42:43], v[42:43], v[66:67] op_sel_hi:[1,0]
	v_pk_mul_f32 v[36:37], v[36:37], v[66:67] op_sel_hi:[1,0]
	v_pk_mul_f32 v[38:39], v[38:39], v[66:67] op_sel_hi:[1,0]
	v_pk_mul_f32 v[32:33], v[32:33], v[66:67] op_sel_hi:[1,0]
	v_pk_mul_f32 v[34:35], v[34:35], v[66:67] op_sel_hi:[1,0]
	v_pk_fma_f32 v[46:47], v[106:107], v[46:47], v[48:49]
	v_pk_fma_f32 v[44:45], v[104:105], v[44:45], v[58:59]
	v_pk_fma_f32 v[42:43], v[102:103], v[42:43], v[50:51]
	v_pk_fma_f32 v[40:41], v[100:101], v[40:41], v[60:61]
	v_pk_fma_f32 v[38:39], v[110:111], v[38:39], v[52:53]
	v_pk_fma_f32 v[36:37], v[108:109], v[36:37], v[62:63]
	v_pk_fma_f32 v[48:49], v[98:99], v[34:35], v[54:55]
	v_pk_fma_f32 v[50:51], v[96:97], v[32:33], v[68:69]
	v_cvt_pk_bf16_f32 v32, v44, v45
	v_cvt_pk_bf16_f32 v33, v46, v47
	v_mul_f32_e32 v34, v45, v45
	v_mul_f32_e32 v35, v47, v47
	v_mul_f32_e32 v45, v41, v41
	v_mul_f32_e32 v47, v43, v43
	v_mul_f32_e32 v52, v37, v37
	v_mul_f32_e32 v53, v39, v39
	v_mul_f32_e32 v54, v51, v51
	v_mul_f32_e32 v55, v49, v49
	v_fmac_f32_e32 v34, v44, v44
	v_fmac_f32_e32 v35, v46, v46
	v_fmac_f32_e32 v45, v40, v40
	v_fmac_f32_e32 v47, v42, v42
	v_fmac_f32_e32 v52, v36, v36
	v_fmac_f32_e32 v53, v38, v38
	v_fmac_f32_e32 v54, v50, v50
	v_fmac_f32_e32 v55, v48, v48
	v_add_f32_e32 v34, v34, v35
	v_add_f32_e32 v35, v45, v47
	v_add_f32_e32 v44, v52, v53
	v_add_f32_e32 v45, v54, v55
	v_add_f32_e32 v34, v34, v35
	v_add_f32_e32 v35, v44, v45
	v_add_f32_e32 v44, v34, v35
	v_mov_b32_e32 v45, v44
	s_nop 1
	v_permlane16_swap_b32 v45, v44
	s_nop 0
	v_cvt_pk_bf16_f32 v34, v40, v41
	v_cvt_pk_bf16_f32 v35, v42, v43
	global_store_dwordx4 v[56:57], v[32:35], off
	s_waitcnt lgkmcnt(0)
	s_nop 0
	v_add_f32_e32 v32, v44, v45
	v_mov_b32_e32 v33, v32
	s_nop 1
	v_permlane32_swap_b32 v33, v32
	s_nop 0
	v_cvt_pk_bf16_f32 v34, v36, v37
	v_cvt_pk_bf16_f32 v35, v38, v39
	v_cvt_pk_bf16_f32 v36, v50, v51
	v_cvt_pk_bf16_f32 v37, v48, v49
	global_store_dwordx4 v[56:57], v[34:37], off offset:256
	s_and_saveexec_b64 s[0:1], s[4:5]
	s_cbranch_execz .LBB0_1214
	v_lshl_add_u32 v34, v64, 4, s22
	s_waitcnt lgkmcnt(0)
	v_add_f32_e32 v32, v32, v33
	ds_write_b32 v34, v32
; DI unsigned pk_bf16(float lo, float hi) { f32x2 v = {lo, hi}; bf16x2_t b = __builtin_convertvector(v, bf16x2_t); return __builtin_bit_cast(unsigned, b); }
; DI float bflo(unsigned w) { return __uint_as_float(w << 16); }
; DI float bfhi(unsigned w) { return __uint_as_float(w & 0xffff0000u); }
;     __device__ __forceinline__ void fused(f32x4 (&acc)[2][2][4][2], const pg8::Unit& u, int wr, int wc, int fr, int fq, PG8_LAS unsigned char* lds, int wid, int lane) const {
;     ...
;                 const int rl = ai * 128 + wr * 64 + m * 16 + fr; const size_t row = (size_t)u.pm * 256 + rl;
;                 const float rm = 1.f / sqrtf(__hip_atomic_load(ssqm + row, __ATOMIC_RELAXED, __HIP_MEMORY_SCOPE_AGENT) * (1.f / DM) + RMS_EPS);
;                 float sh = 0.f;
; #pragma unroll
;                 for (int bj = 0; bj < 2; ++bj) {
;                     const size_t off = row * DM + colb + bj * 128;
;                     f32x4 h0, h1;
;                     if (IN16) { const u32x4 hw = *(const u32x4*)((const bf16_t*)hin + off); h0 = (f32x4){bflo(hw.x), bfhi(hw.x), bflo(hw.y), bfhi(hw.y)}; h1 = (f32x4){bflo(hw.z), bfhi(hw.z), bflo(hw.w), bfhi(hw.w)}; }
;                     else { h0 = *(const f32x4*)((const float*)hin + off); h1 = *(const f32x4*)((const float*)hin + off + 4); }
;                     h0 = h0 + acc[ai][bj][m][0] * rm * gv[bj][0]; h1 = h1 + acc[ai][bj][m][1] * rm * gv[bj][1];
;                     sh += ((h0[0] * h0[0] + h0[1] * h0[1]) + (h0[2] * h0[2] + h0[3] * h0[3])) + ((h1[0] * h1[0] + h1[1] * h1[1]) + (h1[2] * h1[2] + h1[3] * h1[3]));
;                     if (OUT16) { u32x4 w; w.x = pk_bf16(h0[0], h0[1]); w.y = pk_bf16(h0[2], h0[3]); w.z = pk_bf16(h1[0], h1[1]); w.w = pk_bf16(h1[2], h1[3]); *(u32x4*)((bf16_t*)hout + off) = w; }
;                     else { *(f32x4*)((float*)hout + off) = h0; *(f32x4*)((float*)hout + off + 4) = h1; }
;                 }
;                 if (ssqh) { sh += __shfl_xor(sh, 16); sh += __shfl_xor(sh, 32); if (fq == 0) red[rl * 4 + wc] = sh; }
.LBB0_1214:
	s_or_b64 exec, exec, s[0:1]
	v_add_u32_e32 v32, 0xa0, v152
	s_waitcnt lgkmcnt(0)
	v_mov_b32_e32 v33, 0
	v_lshl_add_u64 v[34:35], s[14:15], 0, v[32:33]
	v_lshl_add_u64 v[36:37], v[34:35], 2, s[12:13]
	global_load_dword v46, v[36:37], off sc1
	v_lshlrev_b64 v[34:35], 11, v[34:35]
	v_lshl_add_u64 v[34:35], s[10:11], 0, v[34:35]
	v_lshl_add_u64 v[44:45], v[146:147], 1, v[34:35]
	global_load_dwordx4 v[36:39], v[44:45], off
	global_load_dwordx4 v[40:43], v[44:45], off offset:256
	v_mov_b32_e32 v35, 0x358637bd
	v_mov_b32_e32 v34, 0x260
	s_waitcnt vmcnt(2)
	v_fmamk_f32 v46, v46, 0x3a800000, v35
	v_mul_f32_e32 v47, 0x4f800000, v46
	v_cmp_gt_f32_e32 vcc, s2, v46
	s_waitcnt vmcnt(1)
	v_lshlrev_b32_e32 v48, 16, v38
	v_and_b32_e32 v49, 0xffff0000, v38
	v_cndmask_b32_e32 v54, v46, v47, vcc
	v_sqrt_f32_e32 v55, v54
	v_lshlrev_b32_e32 v46, 16, v36
	v_and_b32_e32 v47, 0xffff0000, v36
	v_lshlrev_b32_e32 v36, 16, v37
	v_add_u32_e32 v56, -1, v55
	v_add_u32_e32 v57, 1, v55
	v_fma_f32 v58, -v56, v55, v54
	v_fma_f32 v59, -v57, v55, v54
	v_cmp_ge_f32_e64 s[0:1], 0, v58
	v_and_b32_e32 v37, 0xffff0000, v37
	v_lshlrev_b32_e32 v38, 16, v39
	v_cndmask_b32_e64 v55, v55, v56, s[0:1]
	v_cmp_lt_f32_e64 s[0:1], 0, v59
	v_and_b32_e32 v39, 0xffff0000, v39
	s_waitcnt vmcnt(0)
	v_lshlrev_b32_e32 v50, 16, v40
	v_cndmask_b32_e64 v55, v55, v57, s[0:1]
	v_mul_f32_e32 v56, 0x37800000, v55
	v_cndmask_b32_e32 v55, v55, v56, vcc
	v_cmp_class_f32_e32 vcc, v54, v34
	v_and_b32_e32 v51, 0xffff0000, v40
	v_lshlrev_b32_e32 v40, 16, v41
	v_cndmask_b32_e32 v54, v55, v54, vcc
	v_div_scale_f32 v55, s[0:1], v54, v54, 1.0
	v_rcp_f32_e32 v56, v55
	v_div_scale_f32 v57, vcc, 1.0, v54, 1.0
	v_and_b32_e32 v41, 0xffff0000, v41
	v_fma_f32 v58, -v55, v56, 1.0
	v_fmac_f32_e32 v56, v58, v56
	v_mul_f32_e32 v58, v57, v56
	v_fma_f32 v59, -v55, v58, v57
	v_fmac_f32_e32 v58, v59, v56
	v_fma_f32 v55, -v55, v58, v57
	v_div_fmas_f32 v55, v55, v56, v58
	v_div_fixup_f32 v54, v55, v54, 1.0
	v_lshlrev_b32_e32 v52, 16, v42
	v_and_b32_e32 v53, 0xffff0000, v42
	v_lshlrev_b32_e32 v42, 16, v43
	v_and_b32_e32 v43, 0xffff0000, v43
	v_pk_mul_f32 v[28:29], v[28:29], v[54:55] op_sel_hi:[1,0]
	v_pk_mul_f32 v[30:31], v[30:31], v[54:55] op_sel_hi:[1,0]
	v_pk_mul_f32 v[24:25], v[24:25], v[54:55] op_sel_hi:[1,0]
	v_pk_mul_f32 v[26:27], v[26:27], v[54:55] op_sel_hi:[1,0]
	v_pk_mul_f32 v[20:21], v[20:21], v[54:55] op_sel_hi:[1,0]
	v_pk_mul_f32 v[22:23], v[22:23], v[54:55] op_sel_hi:[1,0]
	v_pk_mul_f32 v[16:17], v[16:17], v[54:55] op_sel_hi:[1,0]
	v_pk_mul_f32 v[18:19], v[18:19], v[54:55] op_sel_hi:[1,0]
	v_pk_fma_f32 v[30:31], v[106:107], v[30:31], v[36:37]
	v_pk_fma_f32 v[28:29], v[104:105], v[28:29], v[46:47]
	v_pk_fma_f32 v[26:27], v[102:103], v[26:27], v[38:39]
	v_pk_fma_f32 v[24:25], v[100:101], v[24:25], v[48:49]
	v_pk_fma_f32 v[22:23], v[110:111], v[22:23], v[40:41]
	v_pk_fma_f32 v[20:21], v[108:109], v[20:21], v[50:51]
	v_pk_fma_f32 v[36:37], v[98:99], v[18:19], v[42:43]
	v_pk_fma_f32 v[38:39], v[96:97], v[16:17], v[52:53]
	v_cvt_pk_bf16_f32 v16, v28, v29
	v_cvt_pk_bf16_f32 v17, v30, v31
	v_mul_f32_e32 v18, v29, v29
	v_mul_f32_e32 v19, v31, v31
	v_mul_f32_e32 v29, v25, v25
	v_mul_f32_e32 v31, v27, v27
	v_mul_f32_e32 v40, v21, v21
	v_mul_f32_e32 v41, v23, v23
	v_mul_f32_e32 v42, v39, v39
	v_mul_f32_e32 v43, v37, v37
	v_fmac_f32_e32 v18, v28, v28
	v_fmac_f32_e32 v19, v30, v30
	v_fmac_f32_e32 v29, v24, v24
	v_fmac_f32_e32 v31, v26, v26
	v_fmac_f32_e32 v40, v20, v20
	v_fmac_f32_e32 v41, v22, v22
	v_fmac_f32_e32 v42, v38, v38
	v_fmac_f32_e32 v43, v36, v36
	v_add_f32_e32 v18, v18, v19
	v_add_f32_e32 v19, v29, v31
	v_add_f32_e32 v28, v40, v41
	v_add_f32_e32 v29, v42, v43
	v_add_f32_e32 v18, v18, v19
	v_add_f32_e32 v19, v28, v29
	v_add_f32_e32 v28, v18, v19
	v_mov_b32_e32 v29, v28
	s_nop 1
	v_permlane16_swap_b32 v29, v28
	s_nop 0
	v_cvt_pk_bf16_f32 v18, v24, v25
	v_cvt_pk_bf16_f32 v19, v26, v27
	global_store_dwordx4 v[44:45], v[16:19], off
	s_waitcnt lgkmcnt(0)
	s_nop 0
	v_add_f32_e32 v16, v28, v29
	v_mov_b32_e32 v17, v16
	s_nop 1
	v_permlane32_swap_b32 v17, v16
	s_nop 0
	v_cvt_pk_bf16_f32 v18, v20, v21
	v_cvt_pk_bf16_f32 v19, v22, v23
	v_cvt_pk_bf16_f32 v20, v38, v39
	v_cvt_pk_bf16_f32 v21, v36, v37
	global_store_dwordx4 v[44:45], v[18:21], off offset:256
	s_and_saveexec_b64 s[0:1], s[4:5]
	s_cbranch_execz .LBB0_1216
	v_lshl_add_u32 v18, v32, 4, s22
	s_waitcnt lgkmcnt(0)
	v_add_f32_e32 v16, v16, v17
	ds_write_b32 v18, v16
; DI unsigned pk_bf16(float lo, float hi) { f32x2 v = {lo, hi}; bf16x2_t b = __builtin_convertvector(v, bf16x2_t); return __builtin_bit_cast(unsigned, b); }
; DI float bflo(unsigned w) { return __uint_as_float(w << 16); }
; DI float bfhi(unsigned w) { return __uint_as_float(w & 0xffff0000u); }
;     __device__ __forceinline__ void fused(f32x4 (&acc)[2][2][4][2], const pg8::Unit& u, int wr, int wc, int fr, int fq, PG8_LAS unsigned char* lds, int wid, int lane) const {
;     ...
;                 const int rl = ai * 128 + wr * 64 + m * 16 + fr; const size_t row = (size_t)u.pm * 256 + rl;
;                 const float rm = 1.f / sqrtf(__hip_atomic_load(ssqm + row, __ATOMIC_RELAXED, __HIP_MEMORY_SCOPE_AGENT) * (1.f / DM) + RMS_EPS);
;                 float sh = 0.f;
; #pragma unroll
;                 for (int bj = 0; bj < 2; ++bj) {
;                     const size_t off = row * DM + colb + bj * 128;
;                     f32x4 h0, h1;
;                     if (IN16) { const u32x4 hw = *(const u32x4*)((const bf16_t*)hin + off); h0 = (f32x4){bflo(hw.x), bfhi(hw.x), bflo(hw.y), bfhi(hw.y)}; h1 = (f32x4){bflo(hw.z), bfhi(hw.z), bflo(hw.w), bfhi(hw.w)}; }
;                     else { h0 = *(const f32x4*)((const float*)hin + off); h1 = *(const f32x4*)((const float*)hin + off + 4); }
;                     h0 = h0 + acc[ai][bj][m][0] * rm * gv[bj][0]; h1 = h1 + acc[ai][bj][m][1] * rm * gv[bj][1];
;                     sh += ((h0[0] * h0[0] + h0[1] * h0[1]) + (h0[2] * h0[2] + h0[3] * h0[3])) + ((h1[0] * h1[0] + h1[1] * h1[1]) + (h1[2] * h1[2] + h1[3] * h1[3]));
;                     if (OUT16) { u32x4 w; w.x = pk_bf16(h0[0], h0[1]); w.y = pk_bf16(h0[2], h0[3]); w.z = pk_bf16(h1[0], h1[1]); w.w = pk_bf16(h1[2], h1[3]); *(u32x4*)((bf16_t*)hout + off) = w; }
;                     else { *(f32x4*)((float*)hout + off) = h0; *(f32x4*)((float*)hout + off + 4) = h1; }
;                 }
;                 if (ssqh) { sh += __shfl_xor(sh, 16); sh += __shfl_xor(sh, 32); if (fq == 0) red[rl * 4 + wc] = sh; }
.LBB0_1216:
	s_or_b64 exec, exec, s[0:1]
	v_add_u32_e32 v32, 0xb0, v152
	s_waitcnt lgkmcnt(0)
	v_lshl_add_u64 v[16:17], s[14:15], 0, v[32:33]
	v_lshl_add_u64 v[18:19], v[16:17], 2, s[12:13]
	global_load_dword v26, v[18:19], off sc1
	v_lshlrev_b64 v[16:17], 11, v[16:17]
	v_lshl_add_u64 v[16:17], s[10:11], 0, v[16:17]
	v_lshl_add_u64 v[24:25], v[146:147], 1, v[16:17]
	global_load_dwordx4 v[16:19], v[24:25], off
	global_load_dwordx4 v[20:23], v[24:25], off offset:256
	s_waitcnt vmcnt(2)
	v_fmac_f32_e32 v35, 0x3a800000, v26
	v_mul_f32_e32 v26, 0x4f800000, v35
	v_cmp_gt_f32_e32 vcc, s2, v35
	s_waitcnt vmcnt(1)
	v_and_b32_e32 v27, 0xffff0000, v16
	v_lshlrev_b32_e32 v28, 16, v18
	v_cndmask_b32_e32 v33, v35, v26, vcc
	v_sqrt_f32_e32 v35, v33
	v_lshlrev_b32_e32 v26, 16, v16
	v_lshlrev_b32_e32 v16, 16, v17
	v_and_b32_e32 v17, 0xffff0000, v17
	v_add_u32_e32 v38, -1, v35
	v_add_u32_e32 v39, 1, v35
	v_fma_f32 v40, -v38, v35, v33
	v_fma_f32 v41, -v39, v35, v33
	v_cmp_ge_f32_e64 s[0:1], 0, v40
	v_and_b32_e32 v29, 0xffff0000, v18
	v_lshlrev_b32_e32 v18, 16, v19
	v_cndmask_b32_e64 v35, v35, v38, s[0:1]
	v_cmp_lt_f32_e64 s[0:1], 0, v41
	v_and_b32_e32 v19, 0xffff0000, v19
	s_waitcnt vmcnt(0)
	v_lshlrev_b32_e32 v30, 16, v20
	v_cndmask_b32_e64 v35, v35, v39, s[0:1]
	v_mul_f32_e32 v38, 0x37800000, v35
	v_cndmask_b32_e32 v35, v35, v38, vcc
	v_cmp_class_f32_e32 vcc, v33, v34
	v_and_b32_e32 v31, 0xffff0000, v20
	v_lshlrev_b32_e32 v20, 16, v21
	v_cndmask_b32_e32 v33, v35, v33, vcc
	v_div_scale_f32 v34, s[0:1], v33, v33, 1.0
	v_rcp_f32_e32 v35, v34
	v_div_scale_f32 v38, vcc, 1.0, v33, 1.0
	v_and_b32_e32 v21, 0xffff0000, v21
	v_fma_f32 v39, -v34, v35, 1.0
	v_fmac_f32_e32 v35, v39, v35
	v_mul_f32_e32 v39, v38, v35
	v_fma_f32 v40, -v34, v39, v38
	v_fmac_f32_e32 v39, v40, v35
	v_fma_f32 v34, -v34, v39, v38
	v_div_fmas_f32 v34, v34, v35, v39
	v_div_fixup_f32 v34, v34, v33, 1.0
	v_lshlrev_b32_e32 v36, 16, v22
	v_and_b32_e32 v37, 0xffff0000, v22
	v_lshlrev_b32_e32 v22, 16, v23
	v_and_b32_e32 v23, 0xffff0000, v23
	v_pk_mul_f32 v[12:13], v[12:13], v[34:35] op_sel_hi:[1,0]
	v_pk_mul_f32 v[14:15], v[14:15], v[34:35] op_sel_hi:[1,0]
	v_pk_mul_f32 v[8:9], v[8:9], v[34:35] op_sel_hi:[1,0]
	v_pk_mul_f32 v[10:11], v[10:11], v[34:35] op_sel_hi:[1,0]
	v_pk_mul_f32 v[4:5], v[4:5], v[34:35] op_sel_hi:[1,0]
	v_pk_mul_f32 v[6:7], v[6:7], v[34:35] op_sel_hi:[1,0]
	v_pk_mul_f32 v[0:1], v[0:1], v[34:35] op_sel_hi:[1,0]
	v_pk_mul_f32 v[2:3], v[2:3], v[34:35] op_sel_hi:[1,0]
	v_pk_fma_f32 v[14:15], v[106:107], v[14:15], v[16:17]
	v_pk_fma_f32 v[12:13], v[104:105], v[12:13], v[26:27]
	v_pk_fma_f32 v[10:11], v[102:103], v[10:11], v[18:19]
	v_pk_fma_f32 v[8:9], v[100:101], v[8:9], v[28:29]
	v_pk_fma_f32 v[6:7], v[110:111], v[6:7], v[20:21]
	v_pk_fma_f32 v[4:5], v[108:109], v[4:5], v[30:31]
	v_pk_fma_f32 v[16:17], v[98:99], v[2:3], v[22:23]
	v_pk_fma_f32 v[18:19], v[96:97], v[0:1], v[36:37]
	v_cvt_pk_bf16_f32 v0, v12, v13
	v_cvt_pk_bf16_f32 v1, v14, v15
	v_mul_f32_e32 v2, v13, v13
	v_mul_f32_e32 v3, v15, v15
	v_mul_f32_e32 v13, v9, v9
	v_mul_f32_e32 v15, v11, v11
	v_mul_f32_e32 v20, v5, v5
	v_mul_f32_e32 v21, v7, v7
	v_mul_f32_e32 v22, v19, v19
	v_mul_f32_e32 v23, v17, v17
	v_fmac_f32_e32 v2, v12, v12
	v_fmac_f32_e32 v3, v14, v14
	v_fmac_f32_e32 v13, v8, v8
	v_fmac_f32_e32 v15, v10, v10
	v_fmac_f32_e32 v20, v4, v4
	v_fmac_f32_e32 v21, v6, v6
	v_fmac_f32_e32 v22, v18, v18
	v_fmac_f32_e32 v23, v16, v16
	v_add_f32_e32 v2, v2, v3
	v_add_f32_e32 v3, v13, v15
	v_add_f32_e32 v12, v20, v21
	v_add_f32_e32 v13, v22, v23
	v_add_f32_e32 v2, v2, v3
	v_add_f32_e32 v3, v12, v13
	v_add_f32_e32 v12, v2, v3
	v_mov_b32_e32 v13, v12
	s_nop 1
	v_permlane16_swap_b32 v13, v12
	s_nop 0
	v_cvt_pk_bf16_f32 v2, v8, v9
	v_cvt_pk_bf16_f32 v3, v10, v11
	global_store_dwordx4 v[24:25], v[0:3], off
	s_waitcnt lgkmcnt(0)
	s_nop 0
	v_add_f32_e32 v0, v12, v13
	v_mov_b32_e32 v1, v0
	s_nop 1
	v_permlane32_swap_b32 v1, v0
	s_nop 0
	v_cvt_pk_bf16_f32 v2, v4, v5
	v_cvt_pk_bf16_f32 v3, v6, v7
	v_cvt_pk_bf16_f32 v4, v18, v19
	v_cvt_pk_bf16_f32 v5, v16, v17
	global_store_dwordx4 v[24:25], v[2:5], off offset:256
	s_and_saveexec_b64 s[0:1], s[4:5]
	s_cbranch_execz .LBB0_1218
	v_lshl_add_u32 v2, v32, 4, s22
	s_waitcnt lgkmcnt(0)
	v_add_f32_e32 v0, v0, v1
	ds_write_b32 v2, v0

;     __device__ __forceinline__ void fused(f32x4 (&acc)[2][2][4][2], const pg8::Unit& u, int wr, int wc, int fr, int fq, PG8_LAS unsigned char* lds, int wid, int lane) const {
;     ...
;         for (int ai = 0; ai < 2; ++ai)
; #pragma unroll
;             for (int m = 0; m < 4; ++m) {
;                 float s = 0.f;
; #pragma unroll
;                 for (int bj = 0; bj < 2; ++bj)
; #pragma unroll
;                     for (int n = 0; n < 2; ++n) { const f32x4 x = acc[ai][bj][m][n]; s += (x[0] * x[0] + x[1] * x[1]) + (x[2] * x[2] + x[3] * x[3]); }
;                 s += __shfl_xor(s, 16); s += __shfl_xor(s, 32);
;                 if (fq == 0) red[(ai * 128 + wr * 64 + m * 16 + fr) * 4 + wc] = s;
;             }
.LBB0_1370:
	v_mbcnt_lo_u32_b32 v96, -1, 0
	v_mbcnt_hi_u32_b32 v96, -1, v96
	v_and_b32_e32 v98, 64, v96
	v_xor_b32_e32 v97, 16, v96
	v_add_u32_e32 v98, 64, v98
	v_cmp_lt_i32_e32 vcc, v97, v98
	v_mul_f32_e32 v99, v143, v143
	v_fmac_f32_e32 v99, v142, v142
	v_cndmask_b32_e32 v97, v96, v97, vcc
	v_lshlrev_b32_e32 v145, 2, v97
	v_mul_f32_e32 v97, v141, v141
	v_fmac_f32_e32 v97, v140, v140
	v_add_f32_e32 v97, v97, v99
	v_mul_f32_e32 v99, v137, v137
	v_mul_f32_e32 v100, v139, v139
	v_fmac_f32_e32 v99, v136, v136
	v_fmac_f32_e32 v100, v138, v138
	v_add_f32_e32 v99, v99, v100
	v_add_f32_e32 v97, v97, v99
	v_mul_f32_e32 v99, v133, v133
	v_mul_f32_e32 v100, v135, v135
	v_fmac_f32_e32 v99, v132, v132
	v_fmac_f32_e32 v100, v134, v134
	v_add_f32_e32 v99, v99, v100
	v_add_f32_e32 v97, v97, v99
	v_mul_f32_e32 v99, v129, v129
	v_mul_f32_e32 v100, v131, v131
	v_fmac_f32_e32 v99, v128, v128
	v_fmac_f32_e32 v100, v130, v130
	v_add_f32_e32 v99, v99, v100
	v_add_f32_e32 v97, v97, v99
	v_mov_b32_e32 v99, v97
	s_nop 1
	v_permlane16_swap_b32 v99, v97
	s_nop 0
	v_xor_b32_e32 v100, 32, v96
	v_cmp_lt_i32_e32 vcc, v100, v98
	s_lshl_b32 s2, s1, 2
	v_cmp_gt_u32_e64 s[4:5], 16, v192
	v_cndmask_b32_e32 v96, v96, v100, vcc
	v_lshlrev_b32_e32 v147, 2, v96
	s_waitcnt lgkmcnt(0)
	v_add_f32_e32 v96, v97, v99
	v_mov_b32_e32 v97, v96
	s_nop 1
	v_permlane32_swap_b32 v97, v96
	s_nop 0
	s_add_i32 s24, s2, 0
	s_barrier
	s_and_saveexec_b64 s[2:3], s[4:5]
	v_readlane_b32 s44, v251, 15
	v_readlane_b32 s45, v251, 16
	v_readlane_b32 s46, v251, 17
	v_readlane_b32 s47, v251, 18
	s_cbranch_execz .LBB0_1372
	s_lshl_b32 s6, s42, 10
	s_add_i32 s6, s24, s6
	s_waitcnt lgkmcnt(0)
	v_add_f32_e32 v96, v96, v97
	v_lshl_add_u32 v97, v161, 4, s6
	ds_write_b32 v97, v96
.LBB0_1372:
	s_or_b64 exec, exec, s[2:3]
	v_mul_f32_e32 v96, v125, v125
	s_waitcnt lgkmcnt(0)
	v_mul_f32_e32 v97, v127, v127
	v_fmac_f32_e32 v96, v124, v124
	v_fmac_f32_e32 v97, v126, v126
	v_add_f32_e32 v96, v96, v97
	v_mul_f32_e32 v97, v121, v121
	v_mul_f32_e32 v98, v123, v123
	v_fmac_f32_e32 v97, v120, v120
	v_fmac_f32_e32 v98, v122, v122
	v_add_f32_e32 v97, v97, v98
	v_add_f32_e32 v96, v96, v97
	v_mul_f32_e32 v97, v117, v117
	v_mul_f32_e32 v98, v119, v119
	v_fmac_f32_e32 v97, v116, v116
	v_fmac_f32_e32 v98, v118, v118
	v_add_f32_e32 v97, v97, v98
	v_add_f32_e32 v96, v96, v97
	v_mul_f32_e32 v97, v113, v113
	v_mul_f32_e32 v98, v115, v115
	v_fmac_f32_e32 v97, v112, v112
	v_fmac_f32_e32 v98, v114, v114
	v_add_f32_e32 v97, v97, v98
	v_add_f32_e32 v96, v96, v97
	v_mov_b32_e32 v97, v96
	s_nop 1
	v_permlane16_swap_b32 v97, v96
	s_nop 0
	s_waitcnt lgkmcnt(0)
	v_add_f32_e32 v96, v96, v97
	v_mov_b32_e32 v97, v96
	s_nop 1
	v_permlane32_swap_b32 v97, v96
	s_nop 0
	s_and_saveexec_b64 s[2:3], s[4:5]
	s_cbranch_execz .LBB0_1374
	s_lshl_b32 s6, s42, 10
	s_add_i32 s6, s24, s6
	s_waitcnt lgkmcnt(0)
	v_add_f32_e32 v96, v96, v97
	v_lshl_add_u32 v97, v161, 4, s6
	ds_write_b32 v97, v96 offset:256
.LBB0_1374:
	s_or_b64 exec, exec, s[2:3]
	v_mul_f32_e32 v96, v93, v93
	s_waitcnt lgkmcnt(0)
	v_mul_f32_e32 v97, v95, v95
	v_fmac_f32_e32 v96, v92, v92
	v_fmac_f32_e32 v97, v94, v94
	v_add_f32_e32 v96, v96, v97
	v_mul_f32_e32 v97, v89, v89
	v_mul_f32_e32 v98, v91, v91
	v_fmac_f32_e32 v97, v88, v88
	v_fmac_f32_e32 v98, v90, v90
	v_add_f32_e32 v97, v97, v98
	v_add_f32_e32 v96, v96, v97
	v_mul_f32_e32 v97, v85, v85
	v_mul_f32_e32 v98, v87, v87
	v_fmac_f32_e32 v97, v84, v84
	v_fmac_f32_e32 v98, v86, v86
	v_add_f32_e32 v97, v97, v98
	v_add_f32_e32 v96, v96, v97
	v_mul_f32_e32 v97, v81, v81
	v_mul_f32_e32 v98, v83, v83
	v_fmac_f32_e32 v97, v80, v80
	v_fmac_f32_e32 v98, v82, v82
	v_add_f32_e32 v97, v97, v98
	v_add_f32_e32 v96, v96, v97
	v_mov_b32_e32 v97, v96
	s_nop 1
	v_permlane16_swap_b32 v97, v96
	s_nop 0
	s_waitcnt lgkmcnt(0)
	v_add_f32_e32 v96, v96, v97
	v_mov_b32_e32 v97, v96
	s_nop 1
	v_permlane32_swap_b32 v97, v96
	s_nop 0
	s_and_saveexec_b64 s[2:3], s[4:5]
	s_cbranch_execz .LBB0_1376
	s_lshl_b32 s6, s42, 10
	s_add_i32 s6, s24, s6
	s_waitcnt lgkmcnt(0)
	v_add_f32_e32 v96, v96, v97
	v_lshl_add_u32 v97, v161, 4, s6
	ds_write_b32 v97, v96 offset:512
.LBB0_1376:
	s_or_b64 exec, exec, s[2:3]
	v_mul_f32_e32 v96, v77, v77
	s_waitcnt lgkmcnt(0)
	v_mul_f32_e32 v97, v79, v79
	v_fmac_f32_e32 v96, v76, v76
	v_fmac_f32_e32 v97, v78, v78
	v_add_f32_e32 v96, v96, v97
	v_mul_f32_e32 v97, v73, v73
	v_mul_f32_e32 v98, v75, v75
	v_fmac_f32_e32 v97, v72, v72
	v_fmac_f32_e32 v98, v74, v74
	v_add_f32_e32 v97, v97, v98
	v_add_f32_e32 v96, v96, v97
	v_mul_f32_e32 v97, v69, v69
	v_mul_f32_e32 v98, v71, v71
	v_fmac_f32_e32 v97, v68, v68
	v_fmac_f32_e32 v98, v70, v70
	v_add_f32_e32 v97, v97, v98
	v_add_f32_e32 v96, v96, v97
	v_mul_f32_e32 v97, v65, v65
	v_mul_f32_e32 v98, v67, v67
	v_fmac_f32_e32 v97, v64, v64
	v_fmac_f32_e32 v98, v66, v66
	v_add_f32_e32 v97, v97, v98
	v_add_f32_e32 v96, v96, v97
	v_mov_b32_e32 v97, v96
	s_nop 1
	v_permlane16_swap_b32 v97, v96
	s_nop 0
	s_waitcnt lgkmcnt(0)
	v_add_f32_e32 v96, v96, v97
	v_mov_b32_e32 v97, v96
	s_nop 1
	v_permlane32_swap_b32 v97, v96
	s_nop 0
	s_and_saveexec_b64 s[2:3], s[4:5]
	s_cbranch_execz .LBB0_1378
	s_lshl_b32 s6, s42, 10
	s_add_i32 s6, s24, s6
	s_waitcnt lgkmcnt(0)
	v_add_f32_e32 v96, v96, v97
	v_lshl_add_u32 v97, v161, 4, s6
	ds_write_b32 v97, v96 offset:768
;     __device__ __forceinline__ void fused(f32x4 (&acc)[2][2][4][2], const pg8::Unit& u, int wr, int wc, int fr, int fq, PG8_LAS unsigned char* lds, int wid, int lane) const {
;     ...
;         for (int ai = 0; ai < 2; ++ai)
; #pragma unroll
;             for (int m = 0; m < 4; ++m) {
;                 float s = 0.f;
; #pragma unroll
;                 for (int bj = 0; bj < 2; ++bj)
; #pragma unroll
;                     for (int n = 0; n < 2; ++n) { const f32x4 x = acc[ai][bj][m][n]; s += (x[0] * x[0] + x[1] * x[1]) + (x[2] * x[2] + x[3] * x[3]); }
;                 s += __shfl_xor(s, 16); s += __shfl_xor(s, 32);
;                 if (fq == 0) red[(ai * 128 + wr * 64 + m * 16 + fr) * 4 + wc] = s;
;             }
.LBB0_1378:
	s_or_b64 exec, exec, s[2:3]
	v_mul_f32_e32 v96, v61, v61
	s_waitcnt lgkmcnt(0)
	v_mul_f32_e32 v97, v63, v63
	v_fmac_f32_e32 v96, v60, v60
	v_fmac_f32_e32 v97, v62, v62
	v_add_f32_e32 v96, v96, v97
	v_mul_f32_e32 v97, v57, v57
	v_mul_f32_e32 v98, v59, v59
	v_fmac_f32_e32 v97, v56, v56
	v_fmac_f32_e32 v98, v58, v58
	v_add_f32_e32 v97, v97, v98
	v_add_f32_e32 v96, v96, v97
	v_mul_f32_e32 v97, v53, v53
	v_mul_f32_e32 v98, v55, v55
	v_fmac_f32_e32 v97, v52, v52
	v_fmac_f32_e32 v98, v54, v54
	v_add_f32_e32 v97, v97, v98
	v_add_f32_e32 v96, v96, v97
	v_mul_f32_e32 v97, v49, v49
	v_mul_f32_e32 v98, v51, v51
	v_fmac_f32_e32 v97, v48, v48
	v_fmac_f32_e32 v98, v50, v50
	v_add_f32_e32 v97, v97, v98
	v_add_f32_e32 v96, v96, v97
	v_mov_b32_e32 v97, v96
	s_nop 1
	v_permlane16_swap_b32 v97, v96
	s_nop 0
	s_waitcnt lgkmcnt(0)
	v_add_f32_e32 v96, v96, v97
	v_mov_b32_e32 v97, v96
	s_nop 1
	v_permlane32_swap_b32 v97, v96
	s_nop 0
	s_and_saveexec_b64 s[2:3], s[4:5]
	s_cbranch_execz .LBB0_1380
	s_lshl_b32 s6, s42, 10
	s_add_i32 s6, s24, s6
	s_waitcnt lgkmcnt(0)
	v_add_f32_e32 v96, v96, v97
	v_lshl_add_u32 v97, v161, 4, s6
	ds_write_b32 v97, v96 offset:2048
.LBB0_1380:
	s_or_b64 exec, exec, s[2:3]
	v_mul_f32_e32 v96, v45, v45
	s_waitcnt lgkmcnt(0)
	v_mul_f32_e32 v97, v47, v47
	v_fmac_f32_e32 v96, v44, v44
	v_fmac_f32_e32 v97, v46, v46
	v_add_f32_e32 v96, v96, v97
	v_mul_f32_e32 v97, v41, v41
	v_mul_f32_e32 v98, v43, v43
	v_fmac_f32_e32 v97, v40, v40
	v_fmac_f32_e32 v98, v42, v42
	v_add_f32_e32 v97, v97, v98
	v_add_f32_e32 v96, v96, v97
	v_mul_f32_e32 v97, v37, v37
	v_mul_f32_e32 v98, v39, v39
	v_fmac_f32_e32 v97, v36, v36
	v_fmac_f32_e32 v98, v38, v38
	v_add_f32_e32 v97, v97, v98
	v_add_f32_e32 v96, v96, v97
	v_mul_f32_e32 v97, v33, v33
	v_mul_f32_e32 v98, v35, v35
	v_fmac_f32_e32 v97, v32, v32
	v_fmac_f32_e32 v98, v34, v34
	v_add_f32_e32 v97, v97, v98
	v_add_f32_e32 v96, v96, v97
	v_mov_b32_e32 v97, v96
	s_nop 1
	v_permlane16_swap_b32 v97, v96
	s_nop 0
	s_waitcnt lgkmcnt(0)
	v_add_f32_e32 v96, v96, v97
	v_mov_b32_e32 v97, v96
	s_nop 1
	v_permlane32_swap_b32 v97, v96
	s_nop 0
	s_and_saveexec_b64 s[2:3], s[4:5]
	s_cbranch_execz .LBB0_1382
	s_lshl_b32 s6, s42, 10
	s_add_i32 s6, s24, s6
	s_waitcnt lgkmcnt(0)
	v_add_f32_e32 v96, v96, v97
	v_lshl_add_u32 v97, v161, 4, s6
	ds_write_b32 v97, v96 offset:2304
.LBB0_1382:
	s_or_b64 exec, exec, s[2:3]
	v_mul_f32_e32 v96, v29, v29
	s_waitcnt lgkmcnt(0)
	v_mul_f32_e32 v97, v31, v31
	v_fmac_f32_e32 v96, v28, v28
	v_fmac_f32_e32 v97, v30, v30
	v_add_f32_e32 v96, v96, v97
	v_mul_f32_e32 v97, v25, v25
	v_mul_f32_e32 v98, v27, v27
	v_fmac_f32_e32 v97, v24, v24
	v_fmac_f32_e32 v98, v26, v26
	v_add_f32_e32 v97, v97, v98
	v_add_f32_e32 v96, v96, v97
	v_mul_f32_e32 v97, v21, v21
	v_mul_f32_e32 v98, v23, v23
	v_fmac_f32_e32 v97, v20, v20
	v_fmac_f32_e32 v98, v22, v22
	v_add_f32_e32 v97, v97, v98
	v_add_f32_e32 v96, v96, v97
	v_mul_f32_e32 v97, v17, v17
	v_mul_f32_e32 v98, v19, v19
	v_fmac_f32_e32 v97, v16, v16
	v_fmac_f32_e32 v98, v18, v18
	v_add_f32_e32 v97, v97, v98
	v_add_f32_e32 v96, v96, v97
	v_mov_b32_e32 v97, v96
	s_nop 1
	v_permlane16_swap_b32 v97, v96
	s_nop 0
	s_waitcnt lgkmcnt(0)
	v_add_f32_e32 v96, v96, v97
	v_mov_b32_e32 v97, v96
	s_nop 1
	v_permlane32_swap_b32 v97, v96
	s_nop 0
	s_and_saveexec_b64 s[2:3], s[4:5]
	s_cbranch_execz .LBB0_1384
	s_lshl_b32 s6, s42, 10
	s_add_i32 s6, s24, s6
	s_waitcnt lgkmcnt(0)
	v_add_f32_e32 v96, v96, v97
	v_lshl_add_u32 v97, v161, 4, s6
	ds_write_b32 v97, v96 offset:2560
.LBB0_1384:
	s_or_b64 exec, exec, s[2:3]
	v_mul_f32_e32 v96, v13, v13
	s_waitcnt lgkmcnt(0)
	v_mul_f32_e32 v97, v15, v15
	v_fmac_f32_e32 v96, v12, v12
	v_fmac_f32_e32 v97, v14, v14
	v_add_f32_e32 v96, v96, v97
	v_mul_f32_e32 v97, v9, v9
	v_mul_f32_e32 v98, v11, v11
	v_fmac_f32_e32 v97, v8, v8
	v_fmac_f32_e32 v98, v10, v10
	v_add_f32_e32 v97, v97, v98
	v_add_f32_e32 v96, v96, v97
	v_mul_f32_e32 v97, v5, v5
	v_mul_f32_e32 v98, v7, v7
	v_fmac_f32_e32 v97, v4, v4
	v_fmac_f32_e32 v98, v6, v6
	v_add_f32_e32 v97, v97, v98
	v_add_f32_e32 v96, v96, v97
	v_mul_f32_e32 v97, v1, v1
	v_mul_f32_e32 v98, v3, v3
	v_fmac_f32_e32 v97, v0, v0
	v_fmac_f32_e32 v98, v2, v2
	v_add_f32_e32 v97, v97, v98
	v_add_f32_e32 v96, v96, v97
	v_mov_b32_e32 v97, v96
	s_nop 1
	v_permlane16_swap_b32 v97, v96
	s_nop 0
	s_waitcnt lgkmcnt(0)
	v_add_f32_e32 v96, v96, v97
	v_mov_b32_e32 v97, v96
	s_nop 1
	v_permlane32_swap_b32 v97, v96
	s_nop 0
	s_and_saveexec_b64 s[2:3], s[4:5]
	s_cbranch_execz .LBB0_1386
	s_lshl_b32 s6, s42, 10
	s_add_i32 s6, s24, s6
	s_waitcnt lgkmcnt(0)
	v_add_f32_e32 v96, v96, v97
	v_lshl_add_u32 v97, v161, 4, s6
	ds_write_b32 v97, v96 offset:2816

; DI unsigned pk_bf16(float lo, float hi) { f32x2 v = {lo, hi}; bf16x2_t b = __builtin_convertvector(v, bf16x2_t); return __builtin_bit_cast(unsigned, b); }
; DI float bflo(unsigned w) { return __uint_as_float(w << 16); }
; DI float bfhi(unsigned w) { return __uint_as_float(w & 0xffff0000u); }
;     __device__ __forceinline__ void fused(f32x4 (&acc)[2][2][4][2], const pg8::Unit& u, int wr, int wc, int fr, int fq, PG8_LAS unsigned char* lds, int wid, int lane) const {
;     ...
;         const int colb = u.pn * 256 + wc * 32 + 8 * fq;
;         f32x4 gv[2][2];
; #pragma unroll
;         for (int bj = 0; bj < 2; ++bj)
; #pragma unroll
;             for (int n = 0; n < 2; ++n) gv[bj][n] = *(const f32x4*)(gA + colb + bj * 128 + 4 * n);
; #pragma unroll
;         for (int ai = 0; ai < 2; ++ai)
; #pragma unroll
;             for (int m = 0; m < 4; ++m) {
;                 const int rl = ai * 128 + wr * 64 + m * 16 + fr; const size_t row = (size_t)u.pm * 256 + rl;
;                 const float rm = 1.f / sqrtf(__hip_atomic_load(ssqm + row, __ATOMIC_RELAXED, __HIP_MEMORY_SCOPE_AGENT) * (1.f / DM) + RMS_EPS);
;                 float sh = 0.f;
; #pragma unroll
;                 for (int bj = 0; bj < 2; ++bj) {
;                     const size_t off = row * DM + colb + bj * 128;
;                     f32x4 h0, h1;
;                     if (IN16) { const u32x4 hw = *(const u32x4*)((const bf16_t*)hin + off); h0 = (f32x4){bflo(hw.x), bfhi(hw.x), bflo(hw.y), bfhi(hw.y)}; h1 = (f32x4){bflo(hw.z), bfhi(hw.z), bflo(hw.w), bfhi(hw.w)}; }
;                     else { h0 = *(const f32x4*)((const float*)hin + off); h1 = *(const f32x4*)((const float*)hin + off + 4); }
;                     h0 = h0 + acc[ai][bj][m][0] * rm * gv[bj][0]; h1 = h1 + acc[ai][bj][m][1] * rm * gv[bj][1];
;                     sh += ((h0[0] * h0[0] + h0[1] * h0[1]) + (h0[2] * h0[2] + h0[3] * h0[3])) + ((h1[0] * h1[0] + h1[1] * h1[1]) + (h1[2] * h1[2] + h1[3] * h1[3]));
;                     if (OUT16) { u32x4 w; w.x = pk_bf16(h0[0], h0[1]); w.y = pk_bf16(h0[2], h0[3]); w.z = pk_bf16(h1[0], h1[1]); w.w = pk_bf16(h1[2], h1[3]); *(u32x4*)((bf16_t*)hout + off) = w; }
;                     else { *(f32x4*)((float*)hout + off) = h0; *(f32x4*)((float*)hout + off + 4) = h1; }
;                 }
;                 if (ssqh) { sh += __shfl_xor(sh, 16); sh += __shfl_xor(sh, 32); if (fq == 0) red[rl * 4 + wc] = sh; }
.LBB0_1393:
	s_or_b64 exec, exec, s[2:3]
	s_lshl_b32 s1, s1, 5
	s_lshl_b32 s0, s0, 8
	s_or_b32 s0, s0, s1
	v_mov_b32_e32 v159, 0
	v_or_b32_e32 v156, s0, v160
	s_lshl_b64 s[18:19], s[16:17], 8
	v_mov_b32_e32 v153, v159
	v_ashrrev_i32_e32 v157, 31, v156
	v_lshl_add_u64 v[164:165], s[18:19], 0, v[152:153]
	v_lshl_add_u64 v[108:109], v[156:157], 2, s[14:15]
	v_lshl_add_u64 v[166:167], v[164:165], 2, s[12:13]
	s_barrier
	global_load_dwordx4 v[100:103], v[108:109], off offset:16
	global_load_dwordx4 v[104:107], v[108:109], off
	global_load_dwordx4 v[96:99], v[108:109], off offset:528
	s_nop 0
	global_load_dwordx4 v[108:111], v[108:109], off offset:512
	v_lshlrev_b64 v[164:165], 11, v[164:165]
	global_load_dword v158, v[166:167], off sc1
	v_lshl_add_u64 v[164:165], s[10:11], 0, v[164:165]
	v_lshl_add_u64 v[172:173], v[156:157], 1, v[164:165]
	global_load_dwordx4 v[164:167], v[172:173], off
	global_load_dwordx4 v[168:171], v[172:173], off offset:256
	v_mov_b32_e32 v153, 0x358637bd
	s_mov_b32 s2, 0xf800000
	v_mov_b32_e32 v151, 0x260
	s_waitcnt vmcnt(2)
	v_fmamk_f32 v158, v158, 0x3a800000, v153
	v_mul_f32_e32 v180, 0x4f800000, v158
	v_cmp_gt_f32_e32 vcc, s2, v158
	s_waitcnt vmcnt(1)
	v_lshlrev_b32_e32 v174, 16, v164
	v_and_b32_e32 v175, 0xffff0000, v164
	v_cndmask_b32_e32 v158, v158, v180, vcc
	v_sqrt_f32_e32 v182, v158
	v_lshlrev_b32_e32 v164, 16, v165
	v_and_b32_e32 v165, 0xffff0000, v165
	v_lshlrev_b32_e32 v176, 16, v166
	v_add_u32_e32 v183, -1, v182
	v_add_u32_e32 v184, 1, v182
	v_fma_f32 v185, -v183, v182, v158
	v_fma_f32 v186, -v184, v182, v158
	v_cmp_ge_f32_e64 s[0:1], 0, v185
	v_and_b32_e32 v177, 0xffff0000, v166
	v_lshlrev_b32_e32 v166, 16, v167
	v_cndmask_b32_e64 v182, v182, v183, s[0:1]
	v_cmp_lt_f32_e64 s[0:1], 0, v186
	v_and_b32_e32 v167, 0xffff0000, v167
	s_waitcnt vmcnt(0)
	v_lshlrev_b32_e32 v178, 16, v168
	v_cndmask_b32_e64 v182, v182, v184, s[0:1]
	v_mul_f32_e32 v183, 0x37800000, v182
	v_cndmask_b32_e32 v182, v182, v183, vcc
	v_cmp_class_f32_e32 vcc, v158, v151
	v_and_b32_e32 v179, 0xffff0000, v168
	v_lshlrev_b32_e32 v168, 16, v169
	v_cndmask_b32_e32 v158, v182, v158, vcc
	v_div_scale_f32 v182, s[0:1], v158, v158, 1.0
	v_rcp_f32_e32 v183, v182
	v_div_scale_f32 v184, vcc, 1.0, v158, 1.0
	v_and_b32_e32 v169, 0xffff0000, v169
	v_fma_f32 v185, -v182, v183, 1.0
	v_fmac_f32_e32 v183, v185, v183
	v_mul_f32_e32 v185, v184, v183
	v_fma_f32 v186, -v182, v185, v184
	v_fmac_f32_e32 v185, v186, v183
	v_fma_f32 v182, -v182, v185, v184
	v_div_fmas_f32 v182, v182, v183, v185
	v_div_fixup_f32 v158, v182, v158, 1.0
	v_lshlrev_b32_e32 v180, 16, v170
	v_and_b32_e32 v181, 0xffff0000, v170
	v_lshlrev_b32_e32 v170, 16, v171
	v_and_b32_e32 v171, 0xffff0000, v171
	v_pk_mul_f32 v[140:141], v[140:141], v[158:159] op_sel_hi:[1,0]
	v_pk_mul_f32 v[142:143], v[142:143], v[158:159] op_sel_hi:[1,0]
	v_pk_mul_f32 v[136:137], v[136:137], v[158:159] op_sel_hi:[1,0]
	v_pk_mul_f32 v[138:139], v[138:139], v[158:159] op_sel_hi:[1,0]
	v_pk_mul_f32 v[132:133], v[132:133], v[158:159] op_sel_hi:[1,0]
	v_pk_mul_f32 v[134:135], v[134:135], v[158:159] op_sel_hi:[1,0]
	v_pk_mul_f32 v[128:129], v[128:129], v[158:159] op_sel_hi:[1,0]
	v_pk_mul_f32 v[130:131], v[130:131], v[158:159] op_sel_hi:[1,0]
	v_pk_fma_f32 v[142:143], v[106:107], v[142:143], v[164:165]
	v_pk_fma_f32 v[140:141], v[104:105], v[140:141], v[174:175]
	v_pk_fma_f32 v[138:139], v[102:103], v[138:139], v[166:167]
	v_pk_fma_f32 v[136:137], v[100:101], v[136:137], v[176:177]
	v_pk_fma_f32 v[134:135], v[110:111], v[134:135], v[168:169]
	v_pk_fma_f32 v[132:133], v[108:109], v[132:133], v[178:179]
	v_pk_fma_f32 v[164:165], v[98:99], v[130:131], v[170:171]
	v_pk_fma_f32 v[166:167], v[96:97], v[128:129], v[180:181]
	v_cvt_pk_bf16_f32 v128, v140, v141
	v_cvt_pk_bf16_f32 v129, v142, v143
	v_mul_f32_e32 v130, v141, v141
	v_mul_f32_e32 v131, v143, v143
	v_mul_f32_e32 v141, v137, v137
	v_mul_f32_e32 v143, v139, v139
	v_mul_f32_e32 v158, v133, v133
	v_mul_f32_e32 v168, v135, v135
	v_mul_f32_e32 v169, v167, v167
	v_mul_f32_e32 v170, v165, v165
	v_fmac_f32_e32 v130, v140, v140
	v_fmac_f32_e32 v131, v142, v142
	v_fmac_f32_e32 v141, v136, v136
	v_fmac_f32_e32 v143, v138, v138
	v_fmac_f32_e32 v158, v132, v132
	v_fmac_f32_e32 v168, v134, v134
	v_fmac_f32_e32 v169, v166, v166
	v_fmac_f32_e32 v170, v164, v164
	v_add_f32_e32 v130, v130, v131
	v_add_f32_e32 v131, v141, v143
	v_add_f32_e32 v140, v158, v168
	v_add_f32_e32 v141, v169, v170
	v_add_f32_e32 v130, v130, v131
	v_add_f32_e32 v131, v140, v141
	v_add_f32_e32 v140, v130, v131
	v_mov_b32_e32 v141, v140
	s_nop 1
	v_permlane16_swap_b32 v141, v140
	s_nop 0
	v_cvt_pk_bf16_f32 v130, v136, v137
	v_cvt_pk_bf16_f32 v131, v138, v139
	global_store_dwordx4 v[172:173], v[128:131], off
	s_waitcnt lgkmcnt(0)
	s_nop 0
	v_add_f32_e32 v128, v140, v141
	v_mov_b32_e32 v129, v128
	s_nop 1
	v_permlane32_swap_b32 v129, v128
	s_nop 0
	v_cvt_pk_bf16_f32 v130, v132, v133
	v_cvt_pk_bf16_f32 v131, v134, v135
	v_cvt_pk_bf16_f32 v132, v166, v167
	v_cvt_pk_bf16_f32 v133, v164, v165
	global_store_dwordx4 v[172:173], v[130:133], off offset:256
	s_and_saveexec_b64 s[0:1], s[4:5]
	s_cbranch_execz .LBB0_1395
	v_lshl_add_u32 v130, v152, 4, s24
	s_waitcnt lgkmcnt(0)
	v_add_f32_e32 v128, v128, v129
	ds_write_b32 v130, v128
; DI unsigned pk_bf16(float lo, float hi) { f32x2 v = {lo, hi}; bf16x2_t b = __builtin_convertvector(v, bf16x2_t); return __builtin_bit_cast(unsigned, b); }
; DI float bflo(unsigned w) { return __uint_as_float(w << 16); }
; DI float bfhi(unsigned w) { return __uint_as_float(w & 0xffff0000u); }
;     __device__ __forceinline__ void fused(f32x4 (&acc)[2][2][4][2], const pg8::Unit& u, int wr, int wc, int fr, int fq, PG8_LAS unsigned char* lds, int wid, int lane) const {
;     ...
;                 const int rl = ai * 128 + wr * 64 + m * 16 + fr; const size_t row = (size_t)u.pm * 256 + rl;
;                 const float rm = 1.f / sqrtf(__hip_atomic_load(ssqm + row, __ATOMIC_RELAXED, __HIP_MEMORY_SCOPE_AGENT) * (1.f / DM) + RMS_EPS);
;                 float sh = 0.f;
; #pragma unroll
;                 for (int bj = 0; bj < 2; ++bj) {
;                     const size_t off = row * DM + colb + bj * 128;
;                     f32x4 h0, h1;
;                     if (IN16) { const u32x4 hw = *(const u32x4*)((const bf16_t*)hin + off); h0 = (f32x4){bflo(hw.x), bfhi(hw.x), bflo(hw.y), bfhi(hw.y)}; h1 = (f32x4){bflo(hw.z), bfhi(hw.z), bflo(hw.w), bfhi(hw.w)}; }
;                     else { h0 = *(const f32x4*)((const float*)hin + off); h1 = *(const f32x4*)((const float*)hin + off + 4); }
;                     h0 = h0 + acc[ai][bj][m][0] * rm * gv[bj][0]; h1 = h1 + acc[ai][bj][m][1] * rm * gv[bj][1];
;                     sh += ((h0[0] * h0[0] + h0[1] * h0[1]) + (h0[2] * h0[2] + h0[3] * h0[3])) + ((h1[0] * h1[0] + h1[1] * h1[1]) + (h1[2] * h1[2] + h1[3] * h1[3]));
;                     if (OUT16) { u32x4 w; w.x = pk_bf16(h0[0], h0[1]); w.y = pk_bf16(h0[2], h0[3]); w.z = pk_bf16(h1[0], h1[1]); w.w = pk_bf16(h1[2], h1[3]); *(u32x4*)((bf16_t*)hout + off) = w; }
;                     else { *(f32x4*)((float*)hout + off) = h0; *(f32x4*)((float*)hout + off + 4) = h1; }
;                 }
;                 if (ssqh) { sh += __shfl_xor(sh, 16); sh += __shfl_xor(sh, 32); if (fq == 0) red[rl * 4 + wc] = sh; }
.LBB0_1395:
	s_or_b64 exec, exec, s[0:1]
	v_or_b32_e32 v158, 16, v152
	s_waitcnt lgkmcnt(0)
	v_lshl_add_u64 v[128:129], s[18:19], 0, v[158:159]
	v_lshl_add_u64 v[130:131], v[128:129], 2, s[12:13]
	global_load_dword v138, v[130:131], off sc1
	v_lshlrev_b64 v[128:129], 11, v[128:129]
	v_lshl_add_u64 v[128:129], s[10:11], 0, v[128:129]
	v_lshl_add_u64 v[136:137], v[156:157], 1, v[128:129]
	global_load_dwordx4 v[128:131], v[136:137], off
	global_load_dwordx4 v[132:135], v[136:137], off offset:256
	s_waitcnt vmcnt(2)
	v_fmac_f32_e32 v153, 0x3a800000, v138
	v_mul_f32_e32 v138, 0x4f800000, v153
	v_cmp_gt_f32_e32 vcc, s2, v153
	s_waitcnt vmcnt(1)
	v_and_b32_e32 v139, 0xffff0000, v128
	v_lshlrev_b32_e32 v140, 16, v130
	v_cndmask_b32_e32 v153, v153, v138, vcc
	v_sqrt_f32_e32 v159, v153
	v_lshlrev_b32_e32 v138, 16, v128
	v_lshlrev_b32_e32 v128, 16, v129
	v_and_b32_e32 v129, 0xffff0000, v129
	v_add_u32_e32 v166, -1, v159
	v_add_u32_e32 v167, 1, v159
	v_fma_f32 v168, -v166, v159, v153
	v_fma_f32 v169, -v167, v159, v153
	v_cmp_ge_f32_e64 s[0:1], 0, v168
	v_and_b32_e32 v141, 0xffff0000, v130
	v_lshlrev_b32_e32 v130, 16, v131
	v_cndmask_b32_e64 v159, v159, v166, s[0:1]
	v_cmp_lt_f32_e64 s[0:1], 0, v169
	v_and_b32_e32 v131, 0xffff0000, v131
	s_waitcnt vmcnt(0)
	v_lshlrev_b32_e32 v142, 16, v132
	v_cndmask_b32_e64 v159, v159, v167, s[0:1]
	v_mul_f32_e32 v166, 0x37800000, v159
	v_cndmask_b32_e32 v159, v159, v166, vcc
	v_cmp_class_f32_e32 vcc, v153, v151
	v_and_b32_e32 v143, 0xffff0000, v132
	v_lshlrev_b32_e32 v132, 16, v133
	v_cndmask_b32_e32 v151, v159, v153, vcc
	v_div_scale_f32 v153, s[0:1], v151, v151, 1.0
	v_rcp_f32_e32 v159, v153
	v_div_scale_f32 v166, vcc, 1.0, v151, 1.0
	v_and_b32_e32 v133, 0xffff0000, v133
	v_fma_f32 v167, -v153, v159, 1.0
	v_fmac_f32_e32 v159, v167, v159
	v_mul_f32_e32 v167, v166, v159
	v_fma_f32 v168, -v153, v167, v166
	v_fmac_f32_e32 v167, v168, v159
	v_fma_f32 v153, -v153, v167, v166
	v_div_fmas_f32 v153, v153, v159, v167
	v_div_fixup_f32 v166, v153, v151, 1.0
	v_lshlrev_b32_e32 v164, 16, v134
	v_and_b32_e32 v165, 0xffff0000, v134
	v_lshlrev_b32_e32 v134, 16, v135
	v_and_b32_e32 v135, 0xffff0000, v135
	v_pk_mul_f32 v[124:125], v[124:125], v[166:167] op_sel_hi:[1,0]
	v_pk_mul_f32 v[126:127], v[126:127], v[166:167] op_sel_hi:[1,0]
	v_pk_mul_f32 v[120:121], v[120:121], v[166:167] op_sel_hi:[1,0]
	v_pk_mul_f32 v[122:123], v[122:123], v[166:167] op_sel_hi:[1,0]
	v_pk_mul_f32 v[116:117], v[116:117], v[166:167] op_sel_hi:[1,0]
	v_pk_mul_f32 v[118:119], v[118:119], v[166:167] op_sel_hi:[1,0]
	v_pk_mul_f32 v[112:113], v[112:113], v[166:167] op_sel_hi:[1,0]
	v_pk_mul_f32 v[114:115], v[114:115], v[166:167] op_sel_hi:[1,0]
	v_pk_fma_f32 v[126:127], v[106:107], v[126:127], v[128:129]
	v_pk_fma_f32 v[124:125], v[104:105], v[124:125], v[138:139]
	v_pk_fma_f32 v[122:123], v[102:103], v[122:123], v[130:131]
	v_pk_fma_f32 v[120:121], v[100:101], v[120:121], v[140:141]
	v_pk_fma_f32 v[118:119], v[110:111], v[118:119], v[132:133]
	v_pk_fma_f32 v[116:117], v[108:109], v[116:117], v[142:143]
	v_pk_fma_f32 v[128:129], v[98:99], v[114:115], v[134:135]
	v_pk_fma_f32 v[130:131], v[96:97], v[112:113], v[164:165]
	v_cvt_pk_bf16_f32 v112, v124, v125
	v_cvt_pk_bf16_f32 v113, v126, v127
	v_mul_f32_e32 v114, v125, v125
	v_mul_f32_e32 v115, v127, v127
	v_mul_f32_e32 v125, v121, v121
	v_mul_f32_e32 v127, v123, v123
	v_mul_f32_e32 v132, v117, v117
	v_mul_f32_e32 v133, v119, v119
	v_mul_f32_e32 v134, v131, v131
	v_mul_f32_e32 v135, v129, v129
	v_fmac_f32_e32 v114, v124, v124
	v_fmac_f32_e32 v115, v126, v126
	v_fmac_f32_e32 v125, v120, v120
	v_fmac_f32_e32 v127, v122, v122
	v_fmac_f32_e32 v132, v116, v116
	v_fmac_f32_e32 v133, v118, v118
	v_fmac_f32_e32 v134, v130, v130
	v_fmac_f32_e32 v135, v128, v128
	v_add_f32_e32 v114, v114, v115
	v_add_f32_e32 v115, v125, v127
	v_add_f32_e32 v124, v132, v133
	v_add_f32_e32 v125, v134, v135
	v_add_f32_e32 v114, v114, v115
	v_add_f32_e32 v115, v124, v125
	v_add_f32_e32 v124, v114, v115
	v_mov_b32_e32 v125, v124
	s_nop 1
	v_permlane16_swap_b32 v125, v124
	s_nop 0
	v_cvt_pk_bf16_f32 v114, v120, v121
	v_cvt_pk_bf16_f32 v115, v122, v123
	global_store_dwordx4 v[136:137], v[112:115], off
	s_waitcnt lgkmcnt(0)
	s_nop 0
	v_add_f32_e32 v112, v124, v125
	v_mov_b32_e32 v113, v112
	s_nop 1
	v_permlane32_swap_b32 v113, v112
	s_nop 0
	v_cvt_pk_bf16_f32 v114, v116, v117
	v_cvt_pk_bf16_f32 v115, v118, v119
	v_cvt_pk_bf16_f32 v116, v130, v131
	v_cvt_pk_bf16_f32 v117, v128, v129
	global_store_dwordx4 v[136:137], v[114:117], off offset:256
	s_and_saveexec_b64 s[0:1], s[4:5]
	s_cbranch_execz .LBB0_1397
	v_lshl_add_u32 v114, v158, 4, s24
	s_waitcnt lgkmcnt(0)
	v_add_f32_e32 v112, v112, v113
	ds_write_b32 v114, v112
; DI unsigned pk_bf16(float lo, float hi) { f32x2 v = {lo, hi}; bf16x2_t b = __builtin_convertvector(v, bf16x2_t); return __builtin_bit_cast(unsigned, b); }
; DI float bflo(unsigned w) { return __uint_as_float(w << 16); }
; DI float bfhi(unsigned w) { return __uint_as_float(w & 0xffff0000u); }
;     __device__ __forceinline__ void fused(f32x4 (&acc)[2][2][4][2], const pg8::Unit& u, int wr, int wc, int fr, int fq, PG8_LAS unsigned char* lds, int wid, int lane) const {
;     ...
;                 const int rl = ai * 128 + wr * 64 + m * 16 + fr; const size_t row = (size_t)u.pm * 256 + rl;
;                 const float rm = 1.f / sqrtf(__hip_atomic_load(ssqm + row, __ATOMIC_RELAXED, __HIP_MEMORY_SCOPE_AGENT) * (1.f / DM) + RMS_EPS);
;                 float sh = 0.f;
; #pragma unroll
;                 for (int bj = 0; bj < 2; ++bj) {
;                     const size_t off = row * DM + colb + bj * 128;
;                     f32x4 h0, h1;
;                     if (IN16) { const u32x4 hw = *(const u32x4*)((const bf16_t*)hin + off); h0 = (f32x4){bflo(hw.x), bfhi(hw.x), bflo(hw.y), bfhi(hw.y)}; h1 = (f32x4){bflo(hw.z), bfhi(hw.z), bflo(hw.w), bfhi(hw.w)}; }
;                     else { h0 = *(const f32x4*)((const float*)hin + off); h1 = *(const f32x4*)((const float*)hin + off + 4); }
;                     h0 = h0 + acc[ai][bj][m][0] * rm * gv[bj][0]; h1 = h1 + acc[ai][bj][m][1] * rm * gv[bj][1];
;                     sh += ((h0[0] * h0[0] + h0[1] * h0[1]) + (h0[2] * h0[2] + h0[3] * h0[3])) + ((h1[0] * h1[0] + h1[1] * h1[1]) + (h1[2] * h1[2] + h1[3] * h1[3]));
;                     if (OUT16) { u32x4 w; w.x = pk_bf16(h0[0], h0[1]); w.y = pk_bf16(h0[2], h0[3]); w.z = pk_bf16(h1[0], h1[1]); w.w = pk_bf16(h1[2], h1[3]); *(u32x4*)((bf16_t*)hout + off) = w; }
;                     else { *(f32x4*)((float*)hout + off) = h0; *(f32x4*)((float*)hout + off + 4) = h1; }
;                 }
;                 if (ssqh) { sh += __shfl_xor(sh, 16); sh += __shfl_xor(sh, 32); if (fq == 0) red[rl * 4 + wc] = sh; }
.LBB0_1397:
	s_or_b64 exec, exec, s[0:1]
	v_or_b32_e32 v112, 32, v152
	s_waitcnt lgkmcnt(0)
	v_mov_b32_e32 v113, 0
	v_lshl_add_u64 v[114:115], s[18:19], 0, v[112:113]
	v_lshl_add_u64 v[116:117], v[114:115], 2, s[12:13]
	global_load_dword v126, v[116:117], off sc1
	v_lshlrev_b64 v[114:115], 11, v[114:115]
	v_lshl_add_u64 v[114:115], s[10:11], 0, v[114:115]
	v_lshl_add_u64 v[124:125], v[156:157], 1, v[114:115]
	global_load_dwordx4 v[116:119], v[124:125], off
	global_load_dwordx4 v[120:123], v[124:125], off offset:256
	v_mov_b32_e32 v115, 0x358637bd
	v_mov_b32_e32 v114, 0x260
	s_waitcnt vmcnt(2)
	v_fmamk_f32 v126, v126, 0x3a800000, v115
	v_mul_f32_e32 v127, 0x4f800000, v126
	v_cmp_gt_f32_e32 vcc, s2, v126
	s_waitcnt vmcnt(1)
	v_lshlrev_b32_e32 v128, 16, v118
	v_and_b32_e32 v129, 0xffff0000, v118
	v_cndmask_b32_e32 v134, v126, v127, vcc
	v_sqrt_f32_e32 v135, v134
	v_lshlrev_b32_e32 v126, 16, v116
	v_and_b32_e32 v127, 0xffff0000, v116
	v_lshlrev_b32_e32 v116, 16, v117
	v_add_u32_e32 v136, -1, v135
	v_add_u32_e32 v137, 1, v135
	v_fma_f32 v138, -v136, v135, v134
	v_fma_f32 v139, -v137, v135, v134
	v_cmp_ge_f32_e64 s[0:1], 0, v138
	v_and_b32_e32 v117, 0xffff0000, v117
	v_lshlrev_b32_e32 v118, 16, v119
	v_cndmask_b32_e64 v135, v135, v136, s[0:1]
	v_cmp_lt_f32_e64 s[0:1], 0, v139
	v_and_b32_e32 v119, 0xffff0000, v119
	s_waitcnt vmcnt(0)
	v_lshlrev_b32_e32 v130, 16, v120
	v_cndmask_b32_e64 v135, v135, v137, s[0:1]
	v_mul_f32_e32 v136, 0x37800000, v135
	v_cndmask_b32_e32 v135, v135, v136, vcc
	v_cmp_class_f32_e32 vcc, v134, v114
	v_and_b32_e32 v131, 0xffff0000, v120
	v_lshlrev_b32_e32 v120, 16, v121
	v_cndmask_b32_e32 v134, v135, v134, vcc
	v_div_scale_f32 v135, s[0:1], v134, v134, 1.0
	v_rcp_f32_e32 v136, v135
	v_div_scale_f32 v137, vcc, 1.0, v134, 1.0
	v_and_b32_e32 v121, 0xffff0000, v121
	v_fma_f32 v138, -v135, v136, 1.0
	v_fmac_f32_e32 v136, v138, v136
	v_mul_f32_e32 v138, v137, v136
	v_fma_f32 v139, -v135, v138, v137
	v_fmac_f32_e32 v138, v139, v136
	v_fma_f32 v135, -v135, v138, v137
	v_div_fmas_f32 v135, v135, v136, v138
	v_div_fixup_f32 v134, v135, v134, 1.0
	v_lshlrev_b32_e32 v132, 16, v122
	v_and_b32_e32 v133, 0xffff0000, v122
	v_lshlrev_b32_e32 v122, 16, v123
	v_and_b32_e32 v123, 0xffff0000, v123
	v_pk_mul_f32 v[92:93], v[92:93], v[134:135] op_sel_hi:[1,0]
	v_pk_mul_f32 v[94:95], v[94:95], v[134:135] op_sel_hi:[1,0]
	v_pk_mul_f32 v[88:89], v[88:89], v[134:135] op_sel_hi:[1,0]
	v_pk_mul_f32 v[90:91], v[90:91], v[134:135] op_sel_hi:[1,0]
	v_pk_mul_f32 v[84:85], v[84:85], v[134:135] op_sel_hi:[1,0]
	v_pk_mul_f32 v[86:87], v[86:87], v[134:135] op_sel_hi:[1,0]
	v_pk_mul_f32 v[80:81], v[80:81], v[134:135] op_sel_hi:[1,0]
	v_pk_mul_f32 v[82:83], v[82:83], v[134:135] op_sel_hi:[1,0]
	v_pk_fma_f32 v[94:95], v[106:107], v[94:95], v[116:117]
	v_pk_fma_f32 v[92:93], v[104:105], v[92:93], v[126:127]
	v_pk_fma_f32 v[90:91], v[102:103], v[90:91], v[118:119]
	v_pk_fma_f32 v[88:89], v[100:101], v[88:89], v[128:129]
	v_pk_fma_f32 v[86:87], v[110:111], v[86:87], v[120:121]
	v_pk_fma_f32 v[84:85], v[108:109], v[84:85], v[130:131]
	v_pk_fma_f32 v[116:117], v[98:99], v[82:83], v[122:123]
	v_pk_fma_f32 v[118:119], v[96:97], v[80:81], v[132:133]
	v_cvt_pk_bf16_f32 v80, v92, v93
	v_cvt_pk_bf16_f32 v81, v94, v95
	v_mul_f32_e32 v82, v93, v93
	v_mul_f32_e32 v83, v95, v95
	v_mul_f32_e32 v93, v89, v89
	v_mul_f32_e32 v95, v91, v91
	v_mul_f32_e32 v120, v85, v85
	v_mul_f32_e32 v121, v87, v87
	v_mul_f32_e32 v122, v119, v119
	v_mul_f32_e32 v123, v117, v117
	v_fmac_f32_e32 v82, v92, v92
	v_fmac_f32_e32 v83, v94, v94
	v_fmac_f32_e32 v93, v88, v88
	v_fmac_f32_e32 v95, v90, v90
	v_fmac_f32_e32 v120, v84, v84
	v_fmac_f32_e32 v121, v86, v86
	v_fmac_f32_e32 v122, v118, v118
	v_fmac_f32_e32 v123, v116, v116
	v_add_f32_e32 v82, v82, v83
	v_add_f32_e32 v83, v93, v95
	v_add_f32_e32 v92, v120, v121
	v_add_f32_e32 v93, v122, v123
	v_add_f32_e32 v82, v82, v83
	v_add_f32_e32 v83, v92, v93
	v_add_f32_e32 v92, v82, v83
	v_mov_b32_e32 v93, v92
	s_nop 1
	v_permlane16_swap_b32 v93, v92
	s_nop 0
	v_cvt_pk_bf16_f32 v82, v88, v89
	v_cvt_pk_bf16_f32 v83, v90, v91
	global_store_dwordx4 v[124:125], v[80:83], off
	s_waitcnt lgkmcnt(0)
	s_nop 0
	v_add_f32_e32 v80, v92, v93
	v_mov_b32_e32 v81, v80
	s_nop 1
	v_permlane32_swap_b32 v81, v80
	s_nop 0
	v_cvt_pk_bf16_f32 v82, v84, v85
	v_cvt_pk_bf16_f32 v83, v86, v87
	v_cvt_pk_bf16_f32 v84, v118, v119
	v_cvt_pk_bf16_f32 v85, v116, v117
	global_store_dwordx4 v[124:125], v[82:85], off offset:256
	s_and_saveexec_b64 s[0:1], s[4:5]
	s_cbranch_execz .LBB0_1399
	v_lshl_add_u32 v82, v112, 4, s24
	s_waitcnt lgkmcnt(0)
	v_add_f32_e32 v80, v80, v81
	ds_write_b32 v82, v80
; DI unsigned pk_bf16(float lo, float hi) { f32x2 v = {lo, hi}; bf16x2_t b = __builtin_convertvector(v, bf16x2_t); return __builtin_bit_cast(unsigned, b); }
; DI float bflo(unsigned w) { return __uint_as_float(w << 16); }
; DI float bfhi(unsigned w) { return __uint_as_float(w & 0xffff0000u); }
;     __device__ __forceinline__ void fused(f32x4 (&acc)[2][2][4][2], const pg8::Unit& u, int wr, int wc, int fr, int fq, PG8_LAS unsigned char* lds, int wid, int lane) const {
;     ...
;                 const int rl = ai * 128 + wr * 64 + m * 16 + fr; const size_t row = (size_t)u.pm * 256 + rl;
;                 const float rm = 1.f / sqrtf(__hip_atomic_load(ssqm + row, __ATOMIC_RELAXED, __HIP_MEMORY_SCOPE_AGENT) * (1.f / DM) + RMS_EPS);
;                 float sh = 0.f;
; #pragma unroll
;                 for (int bj = 0; bj < 2; ++bj) {
;                     const size_t off = row * DM + colb + bj * 128;
;                     f32x4 h0, h1;
;                     if (IN16) { const u32x4 hw = *(const u32x4*)((const bf16_t*)hin + off); h0 = (f32x4){bflo(hw.x), bfhi(hw.x), bflo(hw.y), bfhi(hw.y)}; h1 = (f32x4){bflo(hw.z), bfhi(hw.z), bflo(hw.w), bfhi(hw.w)}; }
;                     else { h0 = *(const f32x4*)((const float*)hin + off); h1 = *(const f32x4*)((const float*)hin + off + 4); }
;                     h0 = h0 + acc[ai][bj][m][0] * rm * gv[bj][0]; h1 = h1 + acc[ai][bj][m][1] * rm * gv[bj][1];
;                     sh += ((h0[0] * h0[0] + h0[1] * h0[1]) + (h0[2] * h0[2] + h0[3] * h0[3])) + ((h1[0] * h1[0] + h1[1] * h1[1]) + (h1[2] * h1[2] + h1[3] * h1[3]));
;                     if (OUT16) { u32x4 w; w.x = pk_bf16(h0[0], h0[1]); w.y = pk_bf16(h0[2], h0[3]); w.z = pk_bf16(h1[0], h1[1]); w.w = pk_bf16(h1[2], h1[3]); *(u32x4*)((bf16_t*)hout + off) = w; }
;                     else { *(f32x4*)((float*)hout + off) = h0; *(f32x4*)((float*)hout + off + 4) = h1; }
;                 }
;                 if (ssqh) { sh += __shfl_xor(sh, 16); sh += __shfl_xor(sh, 32); if (fq == 0) red[rl * 4 + wc] = sh; }
.LBB0_1399:
	s_or_b64 exec, exec, s[0:1]
	v_or_b32_e32 v112, 48, v152
	s_waitcnt lgkmcnt(0)
	v_lshl_add_u64 v[80:81], s[18:19], 0, v[112:113]
	v_lshl_add_u64 v[82:83], v[80:81], 2, s[12:13]
	global_load_dword v90, v[82:83], off sc1
	v_lshlrev_b64 v[80:81], 11, v[80:81]
	v_lshl_add_u64 v[80:81], s[10:11], 0, v[80:81]
	v_lshl_add_u64 v[88:89], v[156:157], 1, v[80:81]
	global_load_dwordx4 v[80:83], v[88:89], off
	global_load_dwordx4 v[84:87], v[88:89], off offset:256
	s_waitcnt vmcnt(2)
	v_fmac_f32_e32 v115, 0x3a800000, v90
	v_mul_f32_e32 v90, 0x4f800000, v115
	v_cmp_gt_f32_e32 vcc, s2, v115
	s_waitcnt vmcnt(1)
	v_and_b32_e32 v91, 0xffff0000, v80
	v_lshlrev_b32_e32 v92, 16, v82
	v_cndmask_b32_e32 v113, v115, v90, vcc
	v_sqrt_f32_e32 v115, v113
	v_lshlrev_b32_e32 v90, 16, v80
	v_lshlrev_b32_e32 v80, 16, v81
	v_and_b32_e32 v81, 0xffff0000, v81
	v_add_u32_e32 v118, -1, v115
	v_add_u32_e32 v119, 1, v115
	v_fma_f32 v120, -v118, v115, v113
	v_fma_f32 v121, -v119, v115, v113
	v_cmp_ge_f32_e64 s[0:1], 0, v120
	v_and_b32_e32 v93, 0xffff0000, v82
	v_lshlrev_b32_e32 v82, 16, v83
	v_cndmask_b32_e64 v115, v115, v118, s[0:1]
	v_cmp_lt_f32_e64 s[0:1], 0, v121
	v_and_b32_e32 v83, 0xffff0000, v83
	s_waitcnt vmcnt(0)
	v_lshlrev_b32_e32 v94, 16, v84
	v_cndmask_b32_e64 v115, v115, v119, s[0:1]
	v_mul_f32_e32 v118, 0x37800000, v115
	v_cndmask_b32_e32 v115, v115, v118, vcc
	v_cmp_class_f32_e32 vcc, v113, v114
	v_and_b32_e32 v95, 0xffff0000, v84
	v_lshlrev_b32_e32 v84, 16, v85
	v_cndmask_b32_e32 v113, v115, v113, vcc
	v_div_scale_f32 v114, s[0:1], v113, v113, 1.0
	v_rcp_f32_e32 v115, v114
	v_div_scale_f32 v118, vcc, 1.0, v113, 1.0
	v_and_b32_e32 v85, 0xffff0000, v85
	v_fma_f32 v119, -v114, v115, 1.0
	v_fmac_f32_e32 v115, v119, v115
	v_mul_f32_e32 v119, v118, v115
	v_fma_f32 v120, -v114, v119, v118
	v_fmac_f32_e32 v119, v120, v115
	v_fma_f32 v114, -v114, v119, v118
	v_div_fmas_f32 v114, v114, v115, v119
	v_div_fixup_f32 v114, v114, v113, 1.0
	v_lshlrev_b32_e32 v116, 16, v86
	v_and_b32_e32 v117, 0xffff0000, v86
	v_lshlrev_b32_e32 v86, 16, v87
	v_and_b32_e32 v87, 0xffff0000, v87
	v_pk_mul_f32 v[76:77], v[76:77], v[114:115] op_sel_hi:[1,0]
	v_pk_mul_f32 v[78:79], v[78:79], v[114:115] op_sel_hi:[1,0]
	v_pk_mul_f32 v[72:73], v[72:73], v[114:115] op_sel_hi:[1,0]
	v_pk_mul_f32 v[74:75], v[74:75], v[114:115] op_sel_hi:[1,0]
	v_pk_mul_f32 v[68:69], v[68:69], v[114:115] op_sel_hi:[1,0]
	v_pk_mul_f32 v[70:71], v[70:71], v[114:115] op_sel_hi:[1,0]
	v_pk_mul_f32 v[64:65], v[64:65], v[114:115] op_sel_hi:[1,0]
	v_pk_mul_f32 v[66:67], v[66:67], v[114:115] op_sel_hi:[1,0]
	v_pk_fma_f32 v[78:79], v[106:107], v[78:79], v[80:81]
	v_pk_fma_f32 v[76:77], v[104:105], v[76:77], v[90:91]
	v_pk_fma_f32 v[74:75], v[102:103], v[74:75], v[82:83]
	v_pk_fma_f32 v[72:73], v[100:101], v[72:73], v[92:93]
	v_pk_fma_f32 v[70:71], v[110:111], v[70:71], v[84:85]
	v_pk_fma_f32 v[68:69], v[108:109], v[68:69], v[94:95]
	v_pk_fma_f32 v[80:81], v[98:99], v[66:67], v[86:87]
	v_pk_fma_f32 v[82:83], v[96:97], v[64:65], v[116:117]
	v_cvt_pk_bf16_f32 v64, v76, v77
	v_cvt_pk_bf16_f32 v65, v78, v79
	v_mul_f32_e32 v66, v77, v77
	v_mul_f32_e32 v67, v79, v79
	v_mul_f32_e32 v77, v73, v73
	v_mul_f32_e32 v79, v75, v75
	v_mul_f32_e32 v84, v69, v69
	v_mul_f32_e32 v85, v71, v71
	v_mul_f32_e32 v86, v83, v83
	v_mul_f32_e32 v87, v81, v81
	v_fmac_f32_e32 v66, v76, v76
	v_fmac_f32_e32 v67, v78, v78
	v_fmac_f32_e32 v77, v72, v72
	v_fmac_f32_e32 v79, v74, v74
	v_fmac_f32_e32 v84, v68, v68
	v_fmac_f32_e32 v85, v70, v70
	v_fmac_f32_e32 v86, v82, v82
	v_fmac_f32_e32 v87, v80, v80
	v_add_f32_e32 v66, v66, v67
	v_add_f32_e32 v67, v77, v79
	v_add_f32_e32 v76, v84, v85
	v_add_f32_e32 v77, v86, v87
	v_add_f32_e32 v66, v66, v67
	v_add_f32_e32 v67, v76, v77
	v_add_f32_e32 v76, v66, v67
	v_mov_b32_e32 v77, v76
	s_nop 1
	v_permlane16_swap_b32 v77, v76
	s_nop 0
	v_cvt_pk_bf16_f32 v66, v72, v73
	v_cvt_pk_bf16_f32 v67, v74, v75
	global_store_dwordx4 v[88:89], v[64:67], off
	s_waitcnt lgkmcnt(0)
	s_nop 0
	v_add_f32_e32 v64, v76, v77
	v_mov_b32_e32 v65, v64
	s_nop 1
	v_permlane32_swap_b32 v65, v64
	s_nop 0
	v_cvt_pk_bf16_f32 v66, v68, v69
	v_cvt_pk_bf16_f32 v67, v70, v71
	v_cvt_pk_bf16_f32 v68, v82, v83
	v_cvt_pk_bf16_f32 v69, v80, v81
	global_store_dwordx4 v[88:89], v[66:69], off offset:256
	s_and_saveexec_b64 s[0:1], s[4:5]
	s_cbranch_execz .LBB0_1401
	v_lshl_add_u32 v66, v112, 4, s24
	s_waitcnt lgkmcnt(0)
	v_add_f32_e32 v64, v64, v65
	ds_write_b32 v66, v64
; DI unsigned pk_bf16(float lo, float hi) { f32x2 v = {lo, hi}; bf16x2_t b = __builtin_convertvector(v, bf16x2_t); return __builtin_bit_cast(unsigned, b); }
; DI float bflo(unsigned w) { return __uint_as_float(w << 16); }
; DI float bfhi(unsigned w) { return __uint_as_float(w & 0xffff0000u); }
;     __device__ __forceinline__ void fused(f32x4 (&acc)[2][2][4][2], const pg8::Unit& u, int wr, int wc, int fr, int fq, PG8_LAS unsigned char* lds, int wid, int lane) const {
;     ...
;                 const int rl = ai * 128 + wr * 64 + m * 16 + fr; const size_t row = (size_t)u.pm * 256 + rl;
;                 const float rm = 1.f / sqrtf(__hip_atomic_load(ssqm + row, __ATOMIC_RELAXED, __HIP_MEMORY_SCOPE_AGENT) * (1.f / DM) + RMS_EPS);
;                 float sh = 0.f;
; #pragma unroll
;                 for (int bj = 0; bj < 2; ++bj) {
;                     const size_t off = row * DM + colb + bj * 128;
;                     f32x4 h0, h1;
;                     if (IN16) { const u32x4 hw = *(const u32x4*)((const bf16_t*)hin + off); h0 = (f32x4){bflo(hw.x), bfhi(hw.x), bflo(hw.y), bfhi(hw.y)}; h1 = (f32x4){bflo(hw.z), bfhi(hw.z), bflo(hw.w), bfhi(hw.w)}; }
;                     else { h0 = *(const f32x4*)((const float*)hin + off); h1 = *(const f32x4*)((const float*)hin + off + 4); }
;                     h0 = h0 + acc[ai][bj][m][0] * rm * gv[bj][0]; h1 = h1 + acc[ai][bj][m][1] * rm * gv[bj][1];
;                     sh += ((h0[0] * h0[0] + h0[1] * h0[1]) + (h0[2] * h0[2] + h0[3] * h0[3])) + ((h1[0] * h1[0] + h1[1] * h1[1]) + (h1[2] * h1[2] + h1[3] * h1[3]));
;                     if (OUT16) { u32x4 w; w.x = pk_bf16(h0[0], h0[1]); w.y = pk_bf16(h0[2], h0[3]); w.z = pk_bf16(h1[0], h1[1]); w.w = pk_bf16(h1[2], h1[3]); *(u32x4*)((bf16_t*)hout + off) = w; }
;                     else { *(f32x4*)((float*)hout + off) = h0; *(f32x4*)((float*)hout + off + 4) = h1; }
;                 }
;                 if (ssqh) { sh += __shfl_xor(sh, 16); sh += __shfl_xor(sh, 32); if (fq == 0) red[rl * 4 + wc] = sh; }
.LBB0_1401:
	s_or_b64 exec, exec, s[0:1]
	v_add_u32_e32 v64, 0x80, v152
	s_waitcnt lgkmcnt(0)
	v_mov_b32_e32 v65, 0
	v_lshl_add_u64 v[66:67], s[18:19], 0, v[64:65]
	v_lshl_add_u64 v[68:69], v[66:67], 2, s[12:13]
	global_load_dword v78, v[68:69], off sc1
	v_lshlrev_b64 v[66:67], 11, v[66:67]
	v_lshl_add_u64 v[66:67], s[10:11], 0, v[66:67]
	v_lshl_add_u64 v[76:77], v[156:157], 1, v[66:67]
	global_load_dwordx4 v[68:71], v[76:77], off
	global_load_dwordx4 v[72:75], v[76:77], off offset:256
	v_mov_b32_e32 v67, 0x358637bd
	v_mov_b32_e32 v66, 0x260
	s_waitcnt vmcnt(2)
	v_fmamk_f32 v78, v78, 0x3a800000, v67
	v_mul_f32_e32 v79, 0x4f800000, v78
	v_cmp_gt_f32_e32 vcc, s2, v78
	s_waitcnt vmcnt(1)
	v_lshlrev_b32_e32 v80, 16, v70
	v_and_b32_e32 v81, 0xffff0000, v70
	v_cndmask_b32_e32 v86, v78, v79, vcc
	v_sqrt_f32_e32 v87, v86
	v_lshlrev_b32_e32 v78, 16, v68
	v_and_b32_e32 v79, 0xffff0000, v68
	v_lshlrev_b32_e32 v68, 16, v69
	v_add_u32_e32 v88, -1, v87
	v_add_u32_e32 v89, 1, v87
	v_fma_f32 v90, -v88, v87, v86
	v_fma_f32 v91, -v89, v87, v86
	v_cmp_ge_f32_e64 s[0:1], 0, v90
	v_and_b32_e32 v69, 0xffff0000, v69
	v_lshlrev_b32_e32 v70, 16, v71
	v_cndmask_b32_e64 v87, v87, v88, s[0:1]
	v_cmp_lt_f32_e64 s[0:1], 0, v91
	v_and_b32_e32 v71, 0xffff0000, v71
	s_waitcnt vmcnt(0)
	v_lshlrev_b32_e32 v82, 16, v72
	v_cndmask_b32_e64 v87, v87, v89, s[0:1]
	v_mul_f32_e32 v88, 0x37800000, v87
	v_cndmask_b32_e32 v87, v87, v88, vcc
	v_cmp_class_f32_e32 vcc, v86, v66
	v_and_b32_e32 v83, 0xffff0000, v72
	v_lshlrev_b32_e32 v72, 16, v73
	v_cndmask_b32_e32 v86, v87, v86, vcc
	v_div_scale_f32 v87, s[0:1], v86, v86, 1.0
	v_rcp_f32_e32 v88, v87
	v_div_scale_f32 v89, vcc, 1.0, v86, 1.0
	v_and_b32_e32 v73, 0xffff0000, v73
	v_fma_f32 v90, -v87, v88, 1.0
	v_fmac_f32_e32 v88, v90, v88
	v_mul_f32_e32 v90, v89, v88
	v_fma_f32 v91, -v87, v90, v89
	v_fmac_f32_e32 v90, v91, v88
	v_fma_f32 v87, -v87, v90, v89
	v_div_fmas_f32 v87, v87, v88, v90
	v_div_fixup_f32 v86, v87, v86, 1.0
	v_lshlrev_b32_e32 v84, 16, v74
	v_and_b32_e32 v85, 0xffff0000, v74
	v_lshlrev_b32_e32 v74, 16, v75
	v_and_b32_e32 v75, 0xffff0000, v75
	v_pk_mul_f32 v[60:61], v[60:61], v[86:87] op_sel_hi:[1,0]
	v_pk_mul_f32 v[62:63], v[62:63], v[86:87] op_sel_hi:[1,0]
	v_pk_mul_f32 v[56:57], v[56:57], v[86:87] op_sel_hi:[1,0]
	v_pk_mul_f32 v[58:59], v[58:59], v[86:87] op_sel_hi:[1,0]
	v_pk_mul_f32 v[52:53], v[52:53], v[86:87] op_sel_hi:[1,0]
	v_pk_mul_f32 v[54:55], v[54:55], v[86:87] op_sel_hi:[1,0]
	v_pk_mul_f32 v[48:49], v[48:49], v[86:87] op_sel_hi:[1,0]
	v_pk_mul_f32 v[50:51], v[50:51], v[86:87] op_sel_hi:[1,0]
	v_pk_fma_f32 v[62:63], v[106:107], v[62:63], v[68:69]
	v_pk_fma_f32 v[60:61], v[104:105], v[60:61], v[78:79]
	v_pk_fma_f32 v[58:59], v[102:103], v[58:59], v[70:71]
	v_pk_fma_f32 v[56:57], v[100:101], v[56:57], v[80:81]
	v_pk_fma_f32 v[54:55], v[110:111], v[54:55], v[72:73]
	v_pk_fma_f32 v[52:53], v[108:109], v[52:53], v[82:83]
	v_pk_fma_f32 v[68:69], v[98:99], v[50:51], v[74:75]
	v_pk_fma_f32 v[70:71], v[96:97], v[48:49], v[84:85]
	v_cvt_pk_bf16_f32 v48, v60, v61
	v_cvt_pk_bf16_f32 v49, v62, v63
	v_mul_f32_e32 v50, v61, v61
	v_mul_f32_e32 v51, v63, v63
	v_mul_f32_e32 v61, v57, v57
	v_mul_f32_e32 v63, v59, v59
	v_mul_f32_e32 v72, v53, v53
	v_mul_f32_e32 v73, v55, v55
	v_mul_f32_e32 v74, v71, v71
	v_mul_f32_e32 v75, v69, v69
	v_fmac_f32_e32 v50, v60, v60
	v_fmac_f32_e32 v51, v62, v62
	v_fmac_f32_e32 v61, v56, v56
	v_fmac_f32_e32 v63, v58, v58
	v_fmac_f32_e32 v72, v52, v52
	v_fmac_f32_e32 v73, v54, v54
	v_fmac_f32_e32 v74, v70, v70
	v_fmac_f32_e32 v75, v68, v68
	v_add_f32_e32 v50, v50, v51
	v_add_f32_e32 v51, v61, v63
	v_add_f32_e32 v60, v72, v73
	v_add_f32_e32 v61, v74, v75
	v_add_f32_e32 v50, v50, v51
	v_add_f32_e32 v51, v60, v61
	v_add_f32_e32 v60, v50, v51
	v_mov_b32_e32 v61, v60
	s_nop 1
	v_permlane16_swap_b32 v61, v60
	s_nop 0
	v_cvt_pk_bf16_f32 v50, v56, v57
	v_cvt_pk_bf16_f32 v51, v58, v59
	global_store_dwordx4 v[76:77], v[48:51], off
	s_waitcnt lgkmcnt(0)
	s_nop 0
	v_add_f32_e32 v48, v60, v61
	v_mov_b32_e32 v49, v48
	s_nop 1
	v_permlane32_swap_b32 v49, v48
	s_nop 0
	v_cvt_pk_bf16_f32 v50, v52, v53
	v_cvt_pk_bf16_f32 v51, v54, v55
	v_cvt_pk_bf16_f32 v52, v70, v71
	v_cvt_pk_bf16_f32 v53, v68, v69
	global_store_dwordx4 v[76:77], v[50:53], off offset:256
	s_and_saveexec_b64 s[0:1], s[4:5]
	s_cbranch_execz .LBB0_1403
	v_lshl_add_u32 v50, v64, 4, s24
	s_waitcnt lgkmcnt(0)
	v_add_f32_e32 v48, v48, v49
	ds_write_b32 v50, v48
; DI unsigned pk_bf16(float lo, float hi) { f32x2 v = {lo, hi}; bf16x2_t b = __builtin_convertvector(v, bf16x2_t); return __builtin_bit_cast(unsigned, b); }
; DI float bflo(unsigned w) { return __uint_as_float(w << 16); }
; DI float bfhi(unsigned w) { return __uint_as_float(w & 0xffff0000u); }
;     __device__ __forceinline__ void fused(f32x4 (&acc)[2][2][4][2], const pg8::Unit& u, int wr, int wc, int fr, int fq, PG8_LAS unsigned char* lds, int wid, int lane) const {
;     ...
;                 const int rl = ai * 128 + wr * 64 + m * 16 + fr; const size_t row = (size_t)u.pm * 256 + rl;
;                 const float rm = 1.f / sqrtf(__hip_atomic_load(ssqm + row, __ATOMIC_RELAXED, __HIP_MEMORY_SCOPE_AGENT) * (1.f / DM) + RMS_EPS);
;                 float sh = 0.f;
; #pragma unroll
;                 for (int bj = 0; bj < 2; ++bj) {
;                     const size_t off = row * DM + colb + bj * 128;
;                     f32x4 h0, h1;
;                     if (IN16) { const u32x4 hw = *(const u32x4*)((const bf16_t*)hin + off); h0 = (f32x4){bflo(hw.x), bfhi(hw.x), bflo(hw.y), bfhi(hw.y)}; h1 = (f32x4){bflo(hw.z), bfhi(hw.z), bflo(hw.w), bfhi(hw.w)}; }
;                     else { h0 = *(const f32x4*)((const float*)hin + off); h1 = *(const f32x4*)((const float*)hin + off + 4); }
;                     h0 = h0 + acc[ai][bj][m][0] * rm * gv[bj][0]; h1 = h1 + acc[ai][bj][m][1] * rm * gv[bj][1];
;                     sh += ((h0[0] * h0[0] + h0[1] * h0[1]) + (h0[2] * h0[2] + h0[3] * h0[3])) + ((h1[0] * h1[0] + h1[1] * h1[1]) + (h1[2] * h1[2] + h1[3] * h1[3]));
;                     if (OUT16) { u32x4 w; w.x = pk_bf16(h0[0], h0[1]); w.y = pk_bf16(h0[2], h0[3]); w.z = pk_bf16(h1[0], h1[1]); w.w = pk_bf16(h1[2], h1[3]); *(u32x4*)((bf16_t*)hout + off) = w; }
;                     else { *(f32x4*)((float*)hout + off) = h0; *(f32x4*)((float*)hout + off + 4) = h1; }
;                 }
;                 if (ssqh) { sh += __shfl_xor(sh, 16); sh += __shfl_xor(sh, 32); if (fq == 0) red[rl * 4 + wc] = sh; }
.LBB0_1403:
	s_or_b64 exec, exec, s[0:1]
	v_add_u32_e32 v64, 0x90, v152
	s_waitcnt lgkmcnt(0)
	v_lshl_add_u64 v[48:49], s[18:19], 0, v[64:65]
	v_lshl_add_u64 v[50:51], v[48:49], 2, s[12:13]
	global_load_dword v58, v[50:51], off sc1
	v_lshlrev_b64 v[48:49], 11, v[48:49]
	v_lshl_add_u64 v[48:49], s[10:11], 0, v[48:49]
	v_lshl_add_u64 v[56:57], v[156:157], 1, v[48:49]
	global_load_dwordx4 v[48:51], v[56:57], off
	global_load_dwordx4 v[52:55], v[56:57], off offset:256
	s_waitcnt vmcnt(2)
	v_fmac_f32_e32 v67, 0x3a800000, v58
	v_mul_f32_e32 v58, 0x4f800000, v67
	v_cmp_gt_f32_e32 vcc, s2, v67
	s_waitcnt vmcnt(1)
	v_and_b32_e32 v59, 0xffff0000, v48
	v_lshlrev_b32_e32 v60, 16, v50
	v_cndmask_b32_e32 v65, v67, v58, vcc
	v_sqrt_f32_e32 v67, v65
	v_lshlrev_b32_e32 v58, 16, v48
	v_lshlrev_b32_e32 v48, 16, v49
	v_and_b32_e32 v49, 0xffff0000, v49
	v_add_u32_e32 v70, -1, v67
	v_add_u32_e32 v71, 1, v67
	v_fma_f32 v72, -v70, v67, v65
	v_fma_f32 v73, -v71, v67, v65
	v_cmp_ge_f32_e64 s[0:1], 0, v72
	v_and_b32_e32 v61, 0xffff0000, v50
	v_lshlrev_b32_e32 v50, 16, v51
	v_cndmask_b32_e64 v67, v67, v70, s[0:1]
	v_cmp_lt_f32_e64 s[0:1], 0, v73
	v_and_b32_e32 v51, 0xffff0000, v51
	s_waitcnt vmcnt(0)
	v_lshlrev_b32_e32 v62, 16, v52
	v_cndmask_b32_e64 v67, v67, v71, s[0:1]
	v_mul_f32_e32 v70, 0x37800000, v67
	v_cndmask_b32_e32 v67, v67, v70, vcc
	v_cmp_class_f32_e32 vcc, v65, v66
	v_and_b32_e32 v63, 0xffff0000, v52
	v_lshlrev_b32_e32 v52, 16, v53
	v_cndmask_b32_e32 v65, v67, v65, vcc
	v_div_scale_f32 v66, s[0:1], v65, v65, 1.0
	v_rcp_f32_e32 v67, v66
	v_div_scale_f32 v70, vcc, 1.0, v65, 1.0
	v_and_b32_e32 v53, 0xffff0000, v53
	v_fma_f32 v71, -v66, v67, 1.0
	v_fmac_f32_e32 v67, v71, v67
	v_mul_f32_e32 v71, v70, v67
	v_fma_f32 v72, -v66, v71, v70
	v_fmac_f32_e32 v71, v72, v67
	v_fma_f32 v66, -v66, v71, v70
	v_div_fmas_f32 v66, v66, v67, v71
	v_div_fixup_f32 v66, v66, v65, 1.0
	v_lshlrev_b32_e32 v68, 16, v54
	v_and_b32_e32 v69, 0xffff0000, v54
	v_lshlrev_b32_e32 v54, 16, v55
	v_and_b32_e32 v55, 0xffff0000, v55
	v_pk_mul_f32 v[44:45], v[44:45], v[66:67] op_sel_hi:[1,0]
	v_pk_mul_f32 v[46:47], v[46:47], v[66:67] op_sel_hi:[1,0]
	v_pk_mul_f32 v[40:41], v[40:41], v[66:67] op_sel_hi:[1,0]
	v_pk_mul_f32 v[42:43], v[42:43], v[66:67] op_sel_hi:[1,0]
	v_pk_mul_f32 v[36:37], v[36:37], v[66:67] op_sel_hi:[1,0]
	v_pk_mul_f32 v[38:39], v[38:39], v[66:67] op_sel_hi:[1,0]
	v_pk_mul_f32 v[32:33], v[32:33], v[66:67] op_sel_hi:[1,0]
	v_pk_mul_f32 v[34:35], v[34:35], v[66:67] op_sel_hi:[1,0]
	v_pk_fma_f32 v[46:47], v[106:107], v[46:47], v[48:49]
	v_pk_fma_f32 v[44:45], v[104:105], v[44:45], v[58:59]
	v_pk_fma_f32 v[42:43], v[102:103], v[42:43], v[50:51]
	v_pk_fma_f32 v[40:41], v[100:101], v[40:41], v[60:61]
	v_pk_fma_f32 v[38:39], v[110:111], v[38:39], v[52:53]
	v_pk_fma_f32 v[36:37], v[108:109], v[36:37], v[62:63]
	v_pk_fma_f32 v[48:49], v[98:99], v[34:35], v[54:55]
	v_pk_fma_f32 v[50:51], v[96:97], v[32:33], v[68:69]
	v_cvt_pk_bf16_f32 v32, v44, v45
	v_cvt_pk_bf16_f32 v33, v46, v47
	v_mul_f32_e32 v34, v45, v45
	v_mul_f32_e32 v35, v47, v47
	v_mul_f32_e32 v45, v41, v41
	v_mul_f32_e32 v47, v43, v43
	v_mul_f32_e32 v52, v37, v37
	v_mul_f32_e32 v53, v39, v39
	v_mul_f32_e32 v54, v51, v51
	v_mul_f32_e32 v55, v49, v49
	v_fmac_f32_e32 v34, v44, v44
	v_fmac_f32_e32 v35, v46, v46
	v_fmac_f32_e32 v45, v40, v40
	v_fmac_f32_e32 v47, v42, v42
	v_fmac_f32_e32 v52, v36, v36
	v_fmac_f32_e32 v53, v38, v38
	v_fmac_f32_e32 v54, v50, v50
	v_fmac_f32_e32 v55, v48, v48
	v_add_f32_e32 v34, v34, v35
	v_add_f32_e32 v35, v45, v47
	v_add_f32_e32 v44, v52, v53
	v_add_f32_e32 v45, v54, v55
	v_add_f32_e32 v34, v34, v35
	v_add_f32_e32 v35, v44, v45
	v_add_f32_e32 v44, v34, v35
	v_mov_b32_e32 v45, v44
	s_nop 1
	v_permlane16_swap_b32 v45, v44
	s_nop 0
	v_cvt_pk_bf16_f32 v34, v40, v41
	v_cvt_pk_bf16_f32 v35, v42, v43
	global_store_dwordx4 v[56:57], v[32:35], off
	s_waitcnt lgkmcnt(0)
	s_nop 0
	v_add_f32_e32 v32, v44, v45
	v_mov_b32_e32 v33, v32
	s_nop 1
	v_permlane32_swap_b32 v33, v32
	s_nop 0
	v_cvt_pk_bf16_f32 v34, v36, v37
	v_cvt_pk_bf16_f32 v35, v38, v39
	v_cvt_pk_bf16_f32 v36, v50, v51
	v_cvt_pk_bf16_f32 v37, v48, v49
	global_store_dwordx4 v[56:57], v[34:37], off offset:256
	s_and_saveexec_b64 s[0:1], s[4:5]
	s_cbranch_execz .LBB0_1405
	v_lshl_add_u32 v34, v64, 4, s24
	s_waitcnt lgkmcnt(0)
	v_add_f32_e32 v32, v32, v33
	ds_write_b32 v34, v32
; DI unsigned pk_bf16(float lo, float hi) { f32x2 v = {lo, hi}; bf16x2_t b = __builtin_convertvector(v, bf16x2_t); return __builtin_bit_cast(unsigned, b); }
; DI float bflo(unsigned w) { return __uint_as_float(w << 16); }
; DI float bfhi(unsigned w) { return __uint_as_float(w & 0xffff0000u); }
;     __device__ __forceinline__ void fused(f32x4 (&acc)[2][2][4][2], const pg8::Unit& u, int wr, int wc, int fr, int fq, PG8_LAS unsigned char* lds, int wid, int lane) const {
;     ...
;                 const int rl = ai * 128 + wr * 64 + m * 16 + fr; const size_t row = (size_t)u.pm * 256 + rl;
;                 const float rm = 1.f / sqrtf(__hip_atomic_load(ssqm + row, __ATOMIC_RELAXED, __HIP_MEMORY_SCOPE_AGENT) * (1.f / DM) + RMS_EPS);
;                 float sh = 0.f;
; #pragma unroll
;                 for (int bj = 0; bj < 2; ++bj) {
;                     const size_t off = row * DM + colb + bj * 128;
;                     f32x4 h0, h1;
;                     if (IN16) { const u32x4 hw = *(const u32x4*)((const bf16_t*)hin + off); h0 = (f32x4){bflo(hw.x), bfhi(hw.x), bflo(hw.y), bfhi(hw.y)}; h1 = (f32x4){bflo(hw.z), bfhi(hw.z), bflo(hw.w), bfhi(hw.w)}; }
;                     else { h0 = *(const f32x4*)((const float*)hin + off); h1 = *(const f32x4*)((const float*)hin + off + 4); }
;                     h0 = h0 + acc[ai][bj][m][0] * rm * gv[bj][0]; h1 = h1 + acc[ai][bj][m][1] * rm * gv[bj][1];
;                     sh += ((h0[0] * h0[0] + h0[1] * h0[1]) + (h0[2] * h0[2] + h0[3] * h0[3])) + ((h1[0] * h1[0] + h1[1] * h1[1]) + (h1[2] * h1[2] + h1[3] * h1[3]));
;                     if (OUT16) { u32x4 w; w.x = pk_bf16(h0[0], h0[1]); w.y = pk_bf16(h0[2], h0[3]); w.z = pk_bf16(h1[0], h1[1]); w.w = pk_bf16(h1[2], h1[3]); *(u32x4*)((bf16_t*)hout + off) = w; }
;                     else { *(f32x4*)((float*)hout + off) = h0; *(f32x4*)((float*)hout + off + 4) = h1; }
;                 }
;                 if (ssqh) { sh += __shfl_xor(sh, 16); sh += __shfl_xor(sh, 32); if (fq == 0) red[rl * 4 + wc] = sh; }
.LBB0_1405:
	s_or_b64 exec, exec, s[0:1]
	v_add_u32_e32 v32, 0xa0, v152
	s_waitcnt lgkmcnt(0)
	v_mov_b32_e32 v33, 0
	v_lshl_add_u64 v[34:35], s[18:19], 0, v[32:33]
	v_lshl_add_u64 v[36:37], v[34:35], 2, s[12:13]
	global_load_dword v46, v[36:37], off sc1
	v_lshlrev_b64 v[34:35], 11, v[34:35]
	v_lshl_add_u64 v[34:35], s[10:11], 0, v[34:35]
	v_lshl_add_u64 v[44:45], v[156:157], 1, v[34:35]
	global_load_dwordx4 v[36:39], v[44:45], off
	global_load_dwordx4 v[40:43], v[44:45], off offset:256
	v_mov_b32_e32 v35, 0x358637bd
	v_mov_b32_e32 v34, 0x260
	s_waitcnt vmcnt(2)
	v_fmamk_f32 v46, v46, 0x3a800000, v35
	v_mul_f32_e32 v47, 0x4f800000, v46
	v_cmp_gt_f32_e32 vcc, s2, v46
	s_waitcnt vmcnt(1)
	v_lshlrev_b32_e32 v48, 16, v38
	v_and_b32_e32 v49, 0xffff0000, v38
	v_cndmask_b32_e32 v54, v46, v47, vcc
	v_sqrt_f32_e32 v55, v54
	v_lshlrev_b32_e32 v46, 16, v36
	v_and_b32_e32 v47, 0xffff0000, v36
	v_lshlrev_b32_e32 v36, 16, v37
	v_add_u32_e32 v56, -1, v55
	v_add_u32_e32 v57, 1, v55
	v_fma_f32 v58, -v56, v55, v54
	v_fma_f32 v59, -v57, v55, v54
	v_cmp_ge_f32_e64 s[0:1], 0, v58
	v_and_b32_e32 v37, 0xffff0000, v37
	v_lshlrev_b32_e32 v38, 16, v39
	v_cndmask_b32_e64 v55, v55, v56, s[0:1]
	v_cmp_lt_f32_e64 s[0:1], 0, v59
	v_and_b32_e32 v39, 0xffff0000, v39
	s_waitcnt vmcnt(0)
	v_lshlrev_b32_e32 v50, 16, v40
	v_cndmask_b32_e64 v55, v55, v57, s[0:1]
	v_mul_f32_e32 v56, 0x37800000, v55
	v_cndmask_b32_e32 v55, v55, v56, vcc
	v_cmp_class_f32_e32 vcc, v54, v34
	v_and_b32_e32 v51, 0xffff0000, v40
	v_lshlrev_b32_e32 v40, 16, v41
	v_cndmask_b32_e32 v54, v55, v54, vcc
	v_div_scale_f32 v55, s[0:1], v54, v54, 1.0
	v_rcp_f32_e32 v56, v55
	v_div_scale_f32 v57, vcc, 1.0, v54, 1.0
	v_and_b32_e32 v41, 0xffff0000, v41
	v_fma_f32 v58, -v55, v56, 1.0
	v_fmac_f32_e32 v56, v58, v56
	v_mul_f32_e32 v58, v57, v56
	v_fma_f32 v59, -v55, v58, v57
	v_fmac_f32_e32 v58, v59, v56
	v_fma_f32 v55, -v55, v58, v57
	v_div_fmas_f32 v55, v55, v56, v58
	v_div_fixup_f32 v54, v55, v54, 1.0
	v_lshlrev_b32_e32 v52, 16, v42
	v_and_b32_e32 v53, 0xffff0000, v42
	v_lshlrev_b32_e32 v42, 16, v43
	v_and_b32_e32 v43, 0xffff0000, v43
	v_pk_mul_f32 v[28:29], v[28:29], v[54:55] op_sel_hi:[1,0]
	v_pk_mul_f32 v[30:31], v[30:31], v[54:55] op_sel_hi:[1,0]
	v_pk_mul_f32 v[24:25], v[24:25], v[54:55] op_sel_hi:[1,0]
	v_pk_mul_f32 v[26:27], v[26:27], v[54:55] op_sel_hi:[1,0]
	v_pk_mul_f32 v[20:21], v[20:21], v[54:55] op_sel_hi:[1,0]
	v_pk_mul_f32 v[22:23], v[22:23], v[54:55] op_sel_hi:[1,0]
	v_pk_mul_f32 v[16:17], v[16:17], v[54:55] op_sel_hi:[1,0]
	v_pk_mul_f32 v[18:19], v[18:19], v[54:55] op_sel_hi:[1,0]
	v_pk_fma_f32 v[30:31], v[106:107], v[30:31], v[36:37]
	v_pk_fma_f32 v[28:29], v[104:105], v[28:29], v[46:47]
	v_pk_fma_f32 v[26:27], v[102:103], v[26:27], v[38:39]
	v_pk_fma_f32 v[24:25], v[100:101], v[24:25], v[48:49]
	v_pk_fma_f32 v[22:23], v[110:111], v[22:23], v[40:41]
	v_pk_fma_f32 v[20:21], v[108:109], v[20:21], v[50:51]
	v_pk_fma_f32 v[36:37], v[98:99], v[18:19], v[42:43]
	v_pk_fma_f32 v[38:39], v[96:97], v[16:17], v[52:53]
	v_cvt_pk_bf16_f32 v16, v28, v29
	v_cvt_pk_bf16_f32 v17, v30, v31
	v_mul_f32_e32 v18, v29, v29
	v_mul_f32_e32 v19, v31, v31
	v_mul_f32_e32 v29, v25, v25
	v_mul_f32_e32 v31, v27, v27
	v_mul_f32_e32 v40, v21, v21
	v_mul_f32_e32 v41, v23, v23
	v_mul_f32_e32 v42, v39, v39
	v_mul_f32_e32 v43, v37, v37
	v_fmac_f32_e32 v18, v28, v28
	v_fmac_f32_e32 v19, v30, v30
	v_fmac_f32_e32 v29, v24, v24
	v_fmac_f32_e32 v31, v26, v26
	v_fmac_f32_e32 v40, v20, v20
	v_fmac_f32_e32 v41, v22, v22
	v_fmac_f32_e32 v42, v38, v38
	v_fmac_f32_e32 v43, v36, v36
	v_add_f32_e32 v18, v18, v19
	v_add_f32_e32 v19, v29, v31
	v_add_f32_e32 v28, v40, v41
	v_add_f32_e32 v29, v42, v43
	v_add_f32_e32 v18, v18, v19
	v_add_f32_e32 v19, v28, v29
	v_add_f32_e32 v28, v18, v19
	v_mov_b32_e32 v29, v28
	s_nop 1
	v_permlane16_swap_b32 v29, v28
	s_nop 0
	v_cvt_pk_bf16_f32 v18, v24, v25
	v_cvt_pk_bf16_f32 v19, v26, v27
	global_store_dwordx4 v[44:45], v[16:19], off
	s_waitcnt lgkmcnt(0)
	s_nop 0
	v_add_f32_e32 v16, v28, v29
	v_mov_b32_e32 v17, v16
	s_nop 1
	v_permlane32_swap_b32 v17, v16
	s_nop 0
	v_cvt_pk_bf16_f32 v18, v20, v21
	v_cvt_pk_bf16_f32 v19, v22, v23
	v_cvt_pk_bf16_f32 v20, v38, v39
	v_cvt_pk_bf16_f32 v21, v36, v37
	global_store_dwordx4 v[44:45], v[18:21], off offset:256
	s_and_saveexec_b64 s[0:1], s[4:5]
	s_cbranch_execz .LBB0_1407
	v_lshl_add_u32 v18, v32, 4, s24
	s_waitcnt lgkmcnt(0)
	v_add_f32_e32 v16, v16, v17
	ds_write_b32 v18, v16
; DI unsigned pk_bf16(float lo, float hi) { f32x2 v = {lo, hi}; bf16x2_t b = __builtin_convertvector(v, bf16x2_t); return __builtin_bit_cast(unsigned, b); }
; DI float bflo(unsigned w) { return __uint_as_float(w << 16); }
; DI float bfhi(unsigned w) { return __uint_as_float(w & 0xffff0000u); }
;     __device__ __forceinline__ void fused(f32x4 (&acc)[2][2][4][2], const pg8::Unit& u, int wr, int wc, int fr, int fq, PG8_LAS unsigned char* lds, int wid, int lane) const {
;     ...
;                 const int rl = ai * 128 + wr * 64 + m * 16 + fr; const size_t row = (size_t)u.pm * 256 + rl;
;                 const float rm = 1.f / sqrtf(__hip_atomic_load(ssqm + row, __ATOMIC_RELAXED, __HIP_MEMORY_SCOPE_AGENT) * (1.f / DM) + RMS_EPS);
;                 float sh = 0.f;
; #pragma unroll
;                 for (int bj = 0; bj < 2; ++bj) {
;                     const size_t off = row * DM + colb + bj * 128;
;                     f32x4 h0, h1;
;                     if (IN16) { const u32x4 hw = *(const u32x4*)((const bf16_t*)hin + off); h0 = (f32x4){bflo(hw.x), bfhi(hw.x), bflo(hw.y), bfhi(hw.y)}; h1 = (f32x4){bflo(hw.z), bfhi(hw.z), bflo(hw.w), bfhi(hw.w)}; }
;                     else { h0 = *(const f32x4*)((const float*)hin + off); h1 = *(const f32x4*)((const float*)hin + off + 4); }
;                     h0 = h0 + acc[ai][bj][m][0] * rm * gv[bj][0]; h1 = h1 + acc[ai][bj][m][1] * rm * gv[bj][1];
;                     sh += ((h0[0] * h0[0] + h0[1] * h0[1]) + (h0[2] * h0[2] + h0[3] * h0[3])) + ((h1[0] * h1[0] + h1[1] * h1[1]) + (h1[2] * h1[2] + h1[3] * h1[3]));
;                     if (OUT16) { u32x4 w; w.x = pk_bf16(h0[0], h0[1]); w.y = pk_bf16(h0[2], h0[3]); w.z = pk_bf16(h1[0], h1[1]); w.w = pk_bf16(h1[2], h1[3]); *(u32x4*)((bf16_t*)hout + off) = w; }
;                     else { *(f32x4*)((float*)hout + off) = h0; *(f32x4*)((float*)hout + off + 4) = h1; }
;                 }
;                 if (ssqh) { sh += __shfl_xor(sh, 16); sh += __shfl_xor(sh, 32); if (fq == 0) red[rl * 4 + wc] = sh; }
.LBB0_1407:
	s_or_b64 exec, exec, s[0:1]
	v_add_u32_e32 v32, 0xb0, v152
	s_waitcnt lgkmcnt(0)
	v_lshl_add_u64 v[16:17], s[18:19], 0, v[32:33]
	v_lshl_add_u64 v[18:19], v[16:17], 2, s[12:13]
	global_load_dword v26, v[18:19], off sc1
	v_lshlrev_b64 v[16:17], 11, v[16:17]
	v_lshl_add_u64 v[16:17], s[10:11], 0, v[16:17]
	v_lshl_add_u64 v[24:25], v[156:157], 1, v[16:17]
	global_load_dwordx4 v[16:19], v[24:25], off
	global_load_dwordx4 v[20:23], v[24:25], off offset:256
	s_waitcnt vmcnt(2)
	v_fmac_f32_e32 v35, 0x3a800000, v26
	v_mul_f32_e32 v26, 0x4f800000, v35
	v_cmp_gt_f32_e32 vcc, s2, v35
	s_waitcnt vmcnt(1)
	v_and_b32_e32 v27, 0xffff0000, v16
	v_lshlrev_b32_e32 v28, 16, v18
	v_cndmask_b32_e32 v33, v35, v26, vcc
	v_sqrt_f32_e32 v35, v33
	v_lshlrev_b32_e32 v26, 16, v16
	v_lshlrev_b32_e32 v16, 16, v17
	v_and_b32_e32 v17, 0xffff0000, v17
	v_add_u32_e32 v38, -1, v35
	v_add_u32_e32 v39, 1, v35
	v_fma_f32 v40, -v38, v35, v33
	v_fma_f32 v41, -v39, v35, v33
	v_cmp_ge_f32_e64 s[0:1], 0, v40
	v_and_b32_e32 v29, 0xffff0000, v18
	v_lshlrev_b32_e32 v18, 16, v19
	v_cndmask_b32_e64 v35, v35, v38, s[0:1]
	v_cmp_lt_f32_e64 s[0:1], 0, v41
	v_and_b32_e32 v19, 0xffff0000, v19
	s_waitcnt vmcnt(0)
	v_lshlrev_b32_e32 v30, 16, v20
	v_cndmask_b32_e64 v35, v35, v39, s[0:1]
	v_mul_f32_e32 v38, 0x37800000, v35
	v_cndmask_b32_e32 v35, v35, v38, vcc
	v_cmp_class_f32_e32 vcc, v33, v34
	v_and_b32_e32 v31, 0xffff0000, v20
	v_lshlrev_b32_e32 v20, 16, v21
	v_cndmask_b32_e32 v33, v35, v33, vcc
	v_div_scale_f32 v34, s[0:1], v33, v33, 1.0
	v_rcp_f32_e32 v35, v34
	v_div_scale_f32 v38, vcc, 1.0, v33, 1.0
	v_and_b32_e32 v21, 0xffff0000, v21
	v_fma_f32 v39, -v34, v35, 1.0
	v_fmac_f32_e32 v35, v39, v35
	v_mul_f32_e32 v39, v38, v35
	v_fma_f32 v40, -v34, v39, v38
	v_fmac_f32_e32 v39, v40, v35
	v_fma_f32 v34, -v34, v39, v38
	v_div_fmas_f32 v34, v34, v35, v39
	v_div_fixup_f32 v34, v34, v33, 1.0
	v_lshlrev_b32_e32 v36, 16, v22
	v_and_b32_e32 v37, 0xffff0000, v22
	v_lshlrev_b32_e32 v22, 16, v23
	v_and_b32_e32 v23, 0xffff0000, v23
	v_pk_mul_f32 v[12:13], v[12:13], v[34:35] op_sel_hi:[1,0]
	v_pk_mul_f32 v[14:15], v[14:15], v[34:35] op_sel_hi:[1,0]
	v_pk_mul_f32 v[8:9], v[8:9], v[34:35] op_sel_hi:[1,0]
	v_pk_mul_f32 v[10:11], v[10:11], v[34:35] op_sel_hi:[1,0]
	v_pk_mul_f32 v[4:5], v[4:5], v[34:35] op_sel_hi:[1,0]
	v_pk_mul_f32 v[6:7], v[6:7], v[34:35] op_sel_hi:[1,0]
	v_pk_mul_f32 v[0:1], v[0:1], v[34:35] op_sel_hi:[1,0]
	v_pk_mul_f32 v[2:3], v[2:3], v[34:35] op_sel_hi:[1,0]
	v_pk_fma_f32 v[14:15], v[106:107], v[14:15], v[16:17]
	v_pk_fma_f32 v[12:13], v[104:105], v[12:13], v[26:27]
	v_pk_fma_f32 v[10:11], v[102:103], v[10:11], v[18:19]
	v_pk_fma_f32 v[8:9], v[100:101], v[8:9], v[28:29]
	v_pk_fma_f32 v[6:7], v[110:111], v[6:7], v[20:21]
	v_pk_fma_f32 v[4:5], v[108:109], v[4:5], v[30:31]
	v_pk_fma_f32 v[16:17], v[98:99], v[2:3], v[22:23]
	v_pk_fma_f32 v[18:19], v[96:97], v[0:1], v[36:37]
	v_cvt_pk_bf16_f32 v0, v12, v13
	v_cvt_pk_bf16_f32 v1, v14, v15
	v_mul_f32_e32 v2, v13, v13
	v_mul_f32_e32 v3, v15, v15
	v_mul_f32_e32 v13, v9, v9
	v_mul_f32_e32 v15, v11, v11
	v_mul_f32_e32 v20, v5, v5
	v_mul_f32_e32 v21, v7, v7
	v_mul_f32_e32 v22, v19, v19
	v_mul_f32_e32 v23, v17, v17
	v_fmac_f32_e32 v2, v12, v12
	v_fmac_f32_e32 v3, v14, v14
	v_fmac_f32_e32 v13, v8, v8
	v_fmac_f32_e32 v15, v10, v10
	v_fmac_f32_e32 v20, v4, v4
	v_fmac_f32_e32 v21, v6, v6
	v_fmac_f32_e32 v22, v18, v18
	v_fmac_f32_e32 v23, v16, v16
	v_add_f32_e32 v2, v2, v3
	v_add_f32_e32 v3, v13, v15
	v_add_f32_e32 v12, v20, v21
	v_add_f32_e32 v13, v22, v23
	v_add_f32_e32 v2, v2, v3
	v_add_f32_e32 v3, v12, v13
	v_add_f32_e32 v12, v2, v3
	v_mov_b32_e32 v13, v12
	s_nop 1
	v_permlane16_swap_b32 v13, v12
	s_nop 0
	v_cvt_pk_bf16_f32 v2, v8, v9
	v_cvt_pk_bf16_f32 v3, v10, v11
	global_store_dwordx4 v[24:25], v[0:3], off
	s_waitcnt lgkmcnt(0)
	s_nop 0
	v_add_f32_e32 v0, v12, v13
	v_mov_b32_e32 v1, v0
	s_nop 1
	v_permlane32_swap_b32 v1, v0
	s_nop 0
	v_cvt_pk_bf16_f32 v2, v4, v5
	v_cvt_pk_bf16_f32 v3, v6, v7
	v_cvt_pk_bf16_f32 v4, v18, v19
	v_cvt_pk_bf16_f32 v5, v16, v17
	global_store_dwordx4 v[24:25], v[2:5], off offset:256
	s_and_saveexec_b64 s[0:1], s[4:5]
	s_cbranch_execz .LBB0_1409
	v_lshl_add_u32 v2, v32, 4, s24
	s_waitcnt lgkmcnt(0)
	v_add_f32_e32 v0, v0, v1
	ds_write_b32 v2, v0

;     __device__ __forceinline__ void fused(f32x4 (&acc)[2][2][4][2], const pg8::Unit& u, int wr, int wc, int fr, int fq, PG8_LAS unsigned char* lds, int wid, int lane) const {
;     ...
;         for (int ai = 0; ai < 2; ++ai)
; #pragma unroll
;             for (int m = 0; m < 4; ++m) {
;                 float s = 0.f;
; #pragma unroll
;                 for (int bj = 0; bj < 2; ++bj)
; #pragma unroll
;                     for (int n = 0; n < 2; ++n) { const f32x4 x = acc[ai][bj][m][n]; s += (x[0] * x[0] + x[1] * x[1]) + (x[2] * x[2] + x[3] * x[3]); }
;                 s += __shfl_xor(s, 16); s += __shfl_xor(s, 32);
;                 if (fq == 0) red[(ai * 128 + wr * 64 + m * 16 + fr) * 4 + wc] = s;
;             }
.LBB0_1425:
	v_mbcnt_lo_u32_b32 v96, -1, 0
	v_mbcnt_hi_u32_b32 v96, -1, v96
	v_and_b32_e32 v98, 64, v96
	v_xor_b32_e32 v97, 16, v96
	v_add_u32_e32 v98, 64, v98
	v_cmp_lt_i32_e32 vcc, v97, v98
	v_mul_f32_e32 v99, v143, v143
	v_fmac_f32_e32 v99, v142, v142
	v_cndmask_b32_e32 v97, v96, v97, vcc
	v_lshlrev_b32_e32 v150, 2, v97
	v_mul_f32_e32 v97, v141, v141
	v_fmac_f32_e32 v97, v140, v140
	v_add_f32_e32 v97, v97, v99
	v_mul_f32_e32 v99, v137, v137
	v_mul_f32_e32 v100, v139, v139
	v_fmac_f32_e32 v99, v136, v136
	v_fmac_f32_e32 v100, v138, v138
	v_add_f32_e32 v99, v99, v100
	v_add_f32_e32 v97, v97, v99
	v_mul_f32_e32 v99, v133, v133
	v_mul_f32_e32 v100, v135, v135
	v_fmac_f32_e32 v99, v132, v132
	v_fmac_f32_e32 v100, v134, v134
	v_add_f32_e32 v99, v99, v100
	v_add_f32_e32 v97, v97, v99
	v_mul_f32_e32 v99, v129, v129
	v_mul_f32_e32 v100, v131, v131
	v_fmac_f32_e32 v99, v128, v128
	v_fmac_f32_e32 v100, v130, v130
	v_add_f32_e32 v99, v99, v100
	v_add_f32_e32 v97, v97, v99
	v_mov_b32_e32 v99, v97
	s_nop 1
	v_permlane16_swap_b32 v99, v97
	s_nop 0
	v_xor_b32_e32 v100, 32, v96
	v_cmp_lt_i32_e32 vcc, v100, v98
	s_lshl_b32 s2, s1, 2
	v_cmp_gt_u32_e64 s[4:5], 16, v192
	v_cndmask_b32_e32 v96, v96, v100, vcc
	v_lshlrev_b32_e32 v151, 2, v96
	s_waitcnt lgkmcnt(0)
	v_add_f32_e32 v96, v97, v99
	v_mov_b32_e32 v97, v96
	s_nop 1
	v_permlane32_swap_b32 v97, v96
	s_nop 0
	s_add_i32 s24, s2, 0
	s_barrier
	s_and_saveexec_b64 s[2:3], s[4:5]
	v_readlane_b32 s44, v251, 15
	v_readlane_b32 s45, v251, 16
	v_readlane_b32 s46, v251, 17
	v_readlane_b32 s47, v251, 18
	s_cbranch_execz .LBB0_1427
	s_lshl_b32 s6, s42, 10
	s_add_i32 s6, s24, s6
	s_waitcnt lgkmcnt(0)
	v_add_f32_e32 v96, v96, v97
	v_lshl_add_u32 v97, v161, 4, s6
	ds_write_b32 v97, v96

; DI unsigned pk_bf16(float lo, float hi) { f32x2 v = {lo, hi}; bf16x2_t b = __builtin_convertvector(v, bf16x2_t); return __builtin_bit_cast(unsigned, b); }
; DI float bflo(unsigned w) { return __uint_as_float(w << 16); }
; DI float bfhi(unsigned w) { return __uint_as_float(w & 0xffff0000u); }
;     __device__ __forceinline__ void fused(f32x4 (&acc)[2][2][4][2], const pg8::Unit& u, int wr, int wc, int fr, int fq, PG8_LAS unsigned char* lds, int wid, int lane) const {
;     ...
;         const int colb = u.pn * 256 + wc * 32 + 8 * fq;
;         f32x4 gv[2][2];
; #pragma unroll
;         for (int bj = 0; bj < 2; ++bj)
; #pragma unroll
;             for (int n = 0; n < 2; ++n) gv[bj][n] = *(const f32x4*)(gA + colb + bj * 128 + 4 * n);
; #pragma unroll
;         for (int ai = 0; ai < 2; ++ai)
; #pragma unroll
;             for (int m = 0; m < 4; ++m) {
;                 const int rl = ai * 128 + wr * 64 + m * 16 + fr; const size_t row = (size_t)u.pm * 256 + rl;
;                 const float rm = 1.f / sqrtf(__hip_atomic_load(ssqm + row, __ATOMIC_RELAXED, __HIP_MEMORY_SCOPE_AGENT) * (1.f / DM) + RMS_EPS);
;                 float sh = 0.f;
; #pragma unroll
;                 for (int bj = 0; bj < 2; ++bj) {
;                     const size_t off = row * DM + colb + bj * 128;
;                     f32x4 h0, h1;
;                     if (IN16) { const u32x4 hw = *(const u32x4*)((const bf16_t*)hin + off); h0 = (f32x4){bflo(hw.x), bfhi(hw.x), bflo(hw.y), bfhi(hw.y)}; h1 = (f32x4){bflo(hw.z), bfhi(hw.z), bflo(hw.w), bfhi(hw.w)}; }
;                     else { h0 = *(const f32x4*)((const float*)hin + off); h1 = *(const f32x4*)((const float*)hin + off + 4); }
;                     h0 = h0 + acc[ai][bj][m][0] * rm * gv[bj][0]; h1 = h1 + acc[ai][bj][m][1] * rm * gv[bj][1];
;                     sh += ((h0[0] * h0[0] + h0[1] * h0[1]) + (h0[2] * h0[2] + h0[3] * h0[3])) + ((h1[0] * h1[0] + h1[1] * h1[1]) + (h1[2] * h1[2] + h1[3] * h1[3]));
;                     if (OUT16) { u32x4 w; w.x = pk_bf16(h0[0], h0[1]); w.y = pk_bf16(h0[2], h0[3]); w.z = pk_bf16(h1[0], h1[1]); w.w = pk_bf16(h1[2], h1[3]); *(u32x4*)((bf16_t*)hout + off) = w; }
;                     else { *(f32x4*)((float*)hout + off) = h0; *(f32x4*)((float*)hout + off + 4) = h1; }
;                 }
;                 if (ssqh) { sh += __shfl_xor(sh, 16); sh += __shfl_xor(sh, 32); if (fq == 0) red[rl * 4 + wc] = sh; }
.LBB0_1448:
	s_or_b64 exec, exec, s[2:3]
	s_lshl_b32 s1, s1, 5
	s_lshl_b32 s0, s0, 8
	s_or_b32 s0, s0, s1
	v_or_b32_e32 v146, s0, v160
	v_ashrrev_i32_e32 v147, 31, v146
	v_mov_b32_e32 v149, 0
	v_lshl_add_u64 v[108:109], v[146:147], 2, s[14:15]
	s_lshl_b64 s[14:15], s[16:17], 8
	v_mov_b32_e32 v153, v149
	v_lshl_add_u64 v[156:157], s[14:15], 0, v[152:153]
	v_lshl_add_u64 v[158:159], v[156:157], 2, s[12:13]
	s_barrier
	global_load_dwordx4 v[100:103], v[108:109], off offset:16
	global_load_dwordx4 v[104:107], v[108:109], off
	global_load_dwordx4 v[96:99], v[108:109], off offset:528
	s_nop 0
	global_load_dwordx4 v[108:111], v[108:109], off offset:512
	v_lshlrev_b64 v[156:157], 11, v[156:157]
	global_load_dword v148, v[158:159], off sc1
	v_lshl_add_u64 v[156:157], s[10:11], 0, v[156:157]
	v_lshl_add_u64 v[164:165], v[146:147], 1, v[156:157]
	global_load_dwordx4 v[156:159], v[164:165], off
	global_load_dwordx4 v[160:163], v[164:165], off offset:256
	v_mov_b32_e32 v155, 0x358637bd
	s_mov_b32 s2, 0xf800000
	v_mov_b32_e32 v153, 0x260
	s_waitcnt vmcnt(2)
	v_fmamk_f32 v148, v148, 0x3a800000, v155
	v_mul_f32_e32 v172, 0x4f800000, v148
	v_cmp_gt_f32_e32 vcc, s2, v148
	s_waitcnt vmcnt(1)
	v_lshlrev_b32_e32 v166, 16, v156
	v_and_b32_e32 v167, 0xffff0000, v156
	v_cndmask_b32_e32 v148, v148, v172, vcc
	v_sqrt_f32_e32 v174, v148
	v_lshlrev_b32_e32 v156, 16, v157
	v_and_b32_e32 v157, 0xffff0000, v157
	v_lshlrev_b32_e32 v168, 16, v158
	v_add_u32_e32 v175, -1, v174
	v_add_u32_e32 v176, 1, v174
	v_fma_f32 v177, -v175, v174, v148
	v_fma_f32 v178, -v176, v174, v148
	v_cmp_ge_f32_e64 s[0:1], 0, v177
	v_and_b32_e32 v169, 0xffff0000, v158
	v_lshlrev_b32_e32 v158, 16, v159
	v_cndmask_b32_e64 v174, v174, v175, s[0:1]
	v_cmp_lt_f32_e64 s[0:1], 0, v178
	v_and_b32_e32 v159, 0xffff0000, v159
	s_waitcnt vmcnt(0)
	v_lshlrev_b32_e32 v170, 16, v160
	v_cndmask_b32_e64 v174, v174, v176, s[0:1]
	v_mul_f32_e32 v175, 0x37800000, v174
	v_cndmask_b32_e32 v174, v174, v175, vcc
	v_cmp_class_f32_e32 vcc, v148, v153
	v_and_b32_e32 v171, 0xffff0000, v160
	v_lshlrev_b32_e32 v160, 16, v161
	v_cndmask_b32_e32 v148, v174, v148, vcc
	v_div_scale_f32 v174, s[0:1], v148, v148, 1.0
	v_rcp_f32_e32 v175, v174
	v_div_scale_f32 v176, vcc, 1.0, v148, 1.0
	v_and_b32_e32 v161, 0xffff0000, v161
	v_fma_f32 v177, -v174, v175, 1.0
	v_fmac_f32_e32 v175, v177, v175
	v_mul_f32_e32 v177, v176, v175
	v_fma_f32 v178, -v174, v177, v176
	v_fmac_f32_e32 v177, v178, v175
	v_fma_f32 v174, -v174, v177, v176
	v_div_fmas_f32 v174, v174, v175, v177
	v_div_fixup_f32 v148, v174, v148, 1.0
	v_lshlrev_b32_e32 v172, 16, v162
	v_and_b32_e32 v173, 0xffff0000, v162
	v_lshlrev_b32_e32 v162, 16, v163
	v_and_b32_e32 v163, 0xffff0000, v163
	v_pk_mul_f32 v[140:141], v[140:141], v[148:149] op_sel_hi:[1,0]
	v_pk_mul_f32 v[142:143], v[142:143], v[148:149] op_sel_hi:[1,0]
	v_pk_mul_f32 v[136:137], v[136:137], v[148:149] op_sel_hi:[1,0]
	v_pk_mul_f32 v[138:139], v[138:139], v[148:149] op_sel_hi:[1,0]
	v_pk_mul_f32 v[132:133], v[132:133], v[148:149] op_sel_hi:[1,0]
	v_pk_mul_f32 v[134:135], v[134:135], v[148:149] op_sel_hi:[1,0]
	v_pk_mul_f32 v[128:129], v[128:129], v[148:149] op_sel_hi:[1,0]
	v_pk_mul_f32 v[130:131], v[130:131], v[148:149] op_sel_hi:[1,0]
	v_pk_fma_f32 v[142:143], v[106:107], v[142:143], v[156:157]
	v_pk_fma_f32 v[140:141], v[104:105], v[140:141], v[166:167]
	v_pk_fma_f32 v[138:139], v[102:103], v[138:139], v[158:159]
	v_pk_fma_f32 v[136:137], v[100:101], v[136:137], v[168:169]
	v_pk_fma_f32 v[134:135], v[110:111], v[134:135], v[160:161]
	v_pk_fma_f32 v[132:133], v[108:109], v[132:133], v[170:171]
	v_pk_fma_f32 v[156:157], v[98:99], v[130:131], v[162:163]
	v_pk_fma_f32 v[158:159], v[96:97], v[128:129], v[172:173]
	v_cvt_pk_bf16_f32 v128, v140, v141
	v_cvt_pk_bf16_f32 v129, v142, v143
	v_mul_f32_e32 v130, v141, v141
	v_mul_f32_e32 v131, v143, v143
	v_mul_f32_e32 v141, v137, v137
	v_mul_f32_e32 v143, v139, v139
	v_mul_f32_e32 v148, v133, v133
	v_mul_f32_e32 v160, v135, v135
	v_mul_f32_e32 v161, v159, v159
	v_mul_f32_e32 v162, v157, v157
	v_fmac_f32_e32 v130, v140, v140
	v_fmac_f32_e32 v131, v142, v142
	v_fmac_f32_e32 v141, v136, v136
	v_fmac_f32_e32 v143, v138, v138
	v_fmac_f32_e32 v148, v132, v132
	v_fmac_f32_e32 v160, v134, v134
	v_fmac_f32_e32 v161, v158, v158
	v_fmac_f32_e32 v162, v156, v156
	v_add_f32_e32 v130, v130, v131
	v_add_f32_e32 v131, v141, v143
	v_add_f32_e32 v140, v148, v160
	v_add_f32_e32 v141, v161, v162
	v_add_f32_e32 v130, v130, v131
	v_add_f32_e32 v131, v140, v141
	v_add_f32_e32 v140, v130, v131
	v_mov_b32_e32 v141, v140
	s_nop 1
	v_permlane16_swap_b32 v141, v140
	s_nop 0
	v_cvt_pk_bf16_f32 v130, v136, v137
	v_cvt_pk_bf16_f32 v131, v138, v139
	global_store_dwordx4 v[164:165], v[128:131], off
	s_waitcnt lgkmcnt(0)
	s_nop 0
	v_add_f32_e32 v128, v140, v141
	v_mov_b32_e32 v129, v128
	s_nop 1
	v_permlane32_swap_b32 v129, v128
	s_nop 0
	v_cvt_pk_bf16_f32 v130, v132, v133
	v_cvt_pk_bf16_f32 v131, v134, v135
	v_cvt_pk_bf16_f32 v132, v158, v159
	v_cvt_pk_bf16_f32 v133, v156, v157
	global_store_dwordx4 v[164:165], v[130:133], off offset:256
	s_and_saveexec_b64 s[0:1], s[4:5]
	s_cbranch_execz .LBB0_1450
	v_lshl_add_u32 v130, v152, 4, s24
	s_waitcnt lgkmcnt(0)
	v_add_f32_e32 v128, v128, v129
	ds_write_b32 v130, v128
; DI unsigned pk_bf16(float lo, float hi) { f32x2 v = {lo, hi}; bf16x2_t b = __builtin_convertvector(v, bf16x2_t); return __builtin_bit_cast(unsigned, b); }
; DI float bflo(unsigned w) { return __uint_as_float(w << 16); }
; DI float bfhi(unsigned w) { return __uint_as_float(w & 0xffff0000u); }
;     __device__ __forceinline__ void fused(f32x4 (&acc)[2][2][4][2], const pg8::Unit& u, int wr, int wc, int fr, int fq, PG8_LAS unsigned char* lds, int wid, int lane) const {
;     ...
;                 const int rl = ai * 128 + wr * 64 + m * 16 + fr; const size_t row = (size_t)u.pm * 256 + rl;
;                 const float rm = 1.f / sqrtf(__hip_atomic_load(ssqm + row, __ATOMIC_RELAXED, __HIP_MEMORY_SCOPE_AGENT) * (1.f / DM) + RMS_EPS);
;                 float sh = 0.f;
; #pragma unroll
;                 for (int bj = 0; bj < 2; ++bj) {
;                     const size_t off = row * DM + colb + bj * 128;
;                     f32x4 h0, h1;
;                     if (IN16) { const u32x4 hw = *(const u32x4*)((const bf16_t*)hin + off); h0 = (f32x4){bflo(hw.x), bfhi(hw.x), bflo(hw.y), bfhi(hw.y)}; h1 = (f32x4){bflo(hw.z), bfhi(hw.z), bflo(hw.w), bfhi(hw.w)}; }
;                     else { h0 = *(const f32x4*)((const float*)hin + off); h1 = *(const f32x4*)((const float*)hin + off + 4); }
;                     h0 = h0 + acc[ai][bj][m][0] * rm * gv[bj][0]; h1 = h1 + acc[ai][bj][m][1] * rm * gv[bj][1];
;                     sh += ((h0[0] * h0[0] + h0[1] * h0[1]) + (h0[2] * h0[2] + h0[3] * h0[3])) + ((h1[0] * h1[0] + h1[1] * h1[1]) + (h1[2] * h1[2] + h1[3] * h1[3]));
;                     if (OUT16) { u32x4 w; w.x = pk_bf16(h0[0], h0[1]); w.y = pk_bf16(h0[2], h0[3]); w.z = pk_bf16(h1[0], h1[1]); w.w = pk_bf16(h1[2], h1[3]); *(u32x4*)((bf16_t*)hout + off) = w; }
;                     else { *(f32x4*)((float*)hout + off) = h0; *(f32x4*)((float*)hout + off + 4) = h1; }
;                 }
;                 if (ssqh) { sh += __shfl_xor(sh, 16); sh += __shfl_xor(sh, 32); if (fq == 0) red[rl * 4 + wc] = sh; }
.LBB0_1450:
	s_or_b64 exec, exec, s[0:1]
	v_or_b32_e32 v148, 16, v152
	s_waitcnt lgkmcnt(0)
	v_lshl_add_u64 v[128:129], s[14:15], 0, v[148:149]
	v_lshl_add_u64 v[130:131], v[128:129], 2, s[12:13]
	global_load_dword v138, v[130:131], off sc1
	v_lshlrev_b64 v[128:129], 11, v[128:129]
	v_lshl_add_u64 v[128:129], s[10:11], 0, v[128:129]
	v_lshl_add_u64 v[136:137], v[146:147], 1, v[128:129]
	global_load_dwordx4 v[128:131], v[136:137], off
	global_load_dwordx4 v[132:135], v[136:137], off offset:256
	s_waitcnt vmcnt(2)
	v_fmac_f32_e32 v155, 0x3a800000, v138
	v_mul_f32_e32 v138, 0x4f800000, v155
	v_cmp_gt_f32_e32 vcc, s2, v155
	s_waitcnt vmcnt(1)
	v_and_b32_e32 v139, 0xffff0000, v128
	v_lshlrev_b32_e32 v140, 16, v130
	v_cndmask_b32_e32 v149, v155, v138, vcc
	v_sqrt_f32_e32 v155, v149
	v_lshlrev_b32_e32 v138, 16, v128
	v_lshlrev_b32_e32 v128, 16, v129
	v_and_b32_e32 v129, 0xffff0000, v129
	v_add_u32_e32 v158, -1, v155
	v_add_u32_e32 v159, 1, v155
	v_fma_f32 v160, -v158, v155, v149
	v_fma_f32 v161, -v159, v155, v149
	v_cmp_ge_f32_e64 s[0:1], 0, v160
	v_and_b32_e32 v141, 0xffff0000, v130
	v_lshlrev_b32_e32 v130, 16, v131
	v_cndmask_b32_e64 v155, v155, v158, s[0:1]
	v_cmp_lt_f32_e64 s[0:1], 0, v161
	v_and_b32_e32 v131, 0xffff0000, v131
	s_waitcnt vmcnt(0)
	v_lshlrev_b32_e32 v142, 16, v132
	v_cndmask_b32_e64 v155, v155, v159, s[0:1]
	v_mul_f32_e32 v158, 0x37800000, v155
	v_cndmask_b32_e32 v155, v155, v158, vcc
	v_cmp_class_f32_e32 vcc, v149, v153
	v_and_b32_e32 v143, 0xffff0000, v132
	v_lshlrev_b32_e32 v132, 16, v133
	v_cndmask_b32_e32 v149, v155, v149, vcc
	v_div_scale_f32 v153, s[0:1], v149, v149, 1.0
	v_rcp_f32_e32 v155, v153
	v_div_scale_f32 v158, vcc, 1.0, v149, 1.0
	v_and_b32_e32 v133, 0xffff0000, v133
	v_fma_f32 v159, -v153, v155, 1.0
	v_fmac_f32_e32 v155, v159, v155
	v_mul_f32_e32 v159, v158, v155
	v_fma_f32 v160, -v153, v159, v158
	v_fmac_f32_e32 v159, v160, v155
	v_fma_f32 v153, -v153, v159, v158
	v_div_fmas_f32 v153, v153, v155, v159
	v_div_fixup_f32 v158, v153, v149, 1.0
	v_lshlrev_b32_e32 v156, 16, v134
	v_and_b32_e32 v157, 0xffff0000, v134
	v_lshlrev_b32_e32 v134, 16, v135
	v_and_b32_e32 v135, 0xffff0000, v135
	v_pk_mul_f32 v[124:125], v[124:125], v[158:159] op_sel_hi:[1,0]
	v_pk_mul_f32 v[126:127], v[126:127], v[158:159] op_sel_hi:[1,0]
	v_pk_mul_f32 v[120:121], v[120:121], v[158:159] op_sel_hi:[1,0]
	v_pk_mul_f32 v[122:123], v[122:123], v[158:159] op_sel_hi:[1,0]
	v_pk_mul_f32 v[116:117], v[116:117], v[158:159] op_sel_hi:[1,0]
	v_pk_mul_f32 v[118:119], v[118:119], v[158:159] op_sel_hi:[1,0]
	v_pk_mul_f32 v[112:113], v[112:113], v[158:159] op_sel_hi:[1,0]
	v_pk_mul_f32 v[114:115], v[114:115], v[158:159] op_sel_hi:[1,0]
	v_pk_fma_f32 v[126:127], v[106:107], v[126:127], v[128:129]
	v_pk_fma_f32 v[124:125], v[104:105], v[124:125], v[138:139]
	v_pk_fma_f32 v[122:123], v[102:103], v[122:123], v[130:131]
	v_pk_fma_f32 v[120:121], v[100:101], v[120:121], v[140:141]
	v_pk_fma_f32 v[118:119], v[110:111], v[118:119], v[132:133]
	v_pk_fma_f32 v[116:117], v[108:109], v[116:117], v[142:143]
	v_pk_fma_f32 v[128:129], v[98:99], v[114:115], v[134:135]
	v_pk_fma_f32 v[130:131], v[96:97], v[112:113], v[156:157]
	v_cvt_pk_bf16_f32 v112, v124, v125
	v_cvt_pk_bf16_f32 v113, v126, v127
	v_mul_f32_e32 v114, v125, v125
	v_mul_f32_e32 v115, v127, v127
	v_mul_f32_e32 v125, v121, v121
	v_mul_f32_e32 v127, v123, v123
	v_mul_f32_e32 v132, v117, v117
	v_mul_f32_e32 v133, v119, v119
	v_mul_f32_e32 v134, v131, v131
	v_mul_f32_e32 v135, v129, v129
	v_fmac_f32_e32 v114, v124, v124
	v_fmac_f32_e32 v115, v126, v126
	v_fmac_f32_e32 v125, v120, v120
	v_fmac_f32_e32 v127, v122, v122
	v_fmac_f32_e32 v132, v116, v116
	v_fmac_f32_e32 v133, v118, v118
	v_fmac_f32_e32 v134, v130, v130
	v_fmac_f32_e32 v135, v128, v128
	v_add_f32_e32 v114, v114, v115
	v_add_f32_e32 v115, v125, v127
	v_add_f32_e32 v124, v132, v133
	v_add_f32_e32 v125, v134, v135
	v_add_f32_e32 v114, v114, v115
	v_add_f32_e32 v115, v124, v125
	v_add_f32_e32 v124, v114, v115
	v_mov_b32_e32 v125, v124
	s_nop 1
	v_permlane16_swap_b32 v125, v124
	s_nop 0
	v_cvt_pk_bf16_f32 v114, v120, v121
	v_cvt_pk_bf16_f32 v115, v122, v123
	global_store_dwordx4 v[136:137], v[112:115], off
	s_waitcnt lgkmcnt(0)
	s_nop 0
	v_add_f32_e32 v112, v124, v125
	v_mov_b32_e32 v113, v112
	s_nop 1
	v_permlane32_swap_b32 v113, v112
	s_nop 0
	v_cvt_pk_bf16_f32 v114, v116, v117
	v_cvt_pk_bf16_f32 v115, v118, v119
	v_cvt_pk_bf16_f32 v116, v130, v131
	v_cvt_pk_bf16_f32 v117, v128, v129
	global_store_dwordx4 v[136:137], v[114:117], off offset:256
	s_and_saveexec_b64 s[0:1], s[4:5]
	s_cbranch_execz .LBB0_1452
	v_lshl_add_u32 v114, v148, 4, s24
	s_waitcnt lgkmcnt(0)
	v_add_f32_e32 v112, v112, v113
	ds_write_b32 v114, v112
; DI unsigned pk_bf16(float lo, float hi) { f32x2 v = {lo, hi}; bf16x2_t b = __builtin_convertvector(v, bf16x2_t); return __builtin_bit_cast(unsigned, b); }
; DI float bflo(unsigned w) { return __uint_as_float(w << 16); }
; DI float bfhi(unsigned w) { return __uint_as_float(w & 0xffff0000u); }
;     __device__ __forceinline__ void fused(f32x4 (&acc)[2][2][4][2], const pg8::Unit& u, int wr, int wc, int fr, int fq, PG8_LAS unsigned char* lds, int wid, int lane) const {
;     ...
;                 const int rl = ai * 128 + wr * 64 + m * 16 + fr; const size_t row = (size_t)u.pm * 256 + rl;
;                 const float rm = 1.f / sqrtf(__hip_atomic_load(ssqm + row, __ATOMIC_RELAXED, __HIP_MEMORY_SCOPE_AGENT) * (1.f / DM) + RMS_EPS);
;                 float sh = 0.f;
; #pragma unroll
;                 for (int bj = 0; bj < 2; ++bj) {
;                     const size_t off = row * DM + colb + bj * 128;
;                     f32x4 h0, h1;
;                     if (IN16) { const u32x4 hw = *(const u32x4*)((const bf16_t*)hin + off); h0 = (f32x4){bflo(hw.x), bfhi(hw.x), bflo(hw.y), bfhi(hw.y)}; h1 = (f32x4){bflo(hw.z), bfhi(hw.z), bflo(hw.w), bfhi(hw.w)}; }
;                     else { h0 = *(const f32x4*)((const float*)hin + off); h1 = *(const f32x4*)((const float*)hin + off + 4); }
;                     h0 = h0 + acc[ai][bj][m][0] * rm * gv[bj][0]; h1 = h1 + acc[ai][bj][m][1] * rm * gv[bj][1];
;                     sh += ((h0[0] * h0[0] + h0[1] * h0[1]) + (h0[2] * h0[2] + h0[3] * h0[3])) + ((h1[0] * h1[0] + h1[1] * h1[1]) + (h1[2] * h1[2] + h1[3] * h1[3]));
;                     if (OUT16) { u32x4 w; w.x = pk_bf16(h0[0], h0[1]); w.y = pk_bf16(h0[2], h0[3]); w.z = pk_bf16(h1[0], h1[1]); w.w = pk_bf16(h1[2], h1[3]); *(u32x4*)((bf16_t*)hout + off) = w; }
;                     else { *(f32x4*)((float*)hout + off) = h0; *(f32x4*)((float*)hout + off + 4) = h1; }
;                 }
;                 if (ssqh) { sh += __shfl_xor(sh, 16); sh += __shfl_xor(sh, 32); if (fq == 0) red[rl * 4 + wc] = sh; }
.LBB0_1452:
	s_or_b64 exec, exec, s[0:1]
	v_or_b32_e32 v112, 32, v152
	s_waitcnt lgkmcnt(0)
	v_mov_b32_e32 v113, 0
	v_lshl_add_u64 v[114:115], s[14:15], 0, v[112:113]
	v_lshl_add_u64 v[116:117], v[114:115], 2, s[12:13]
	global_load_dword v126, v[116:117], off sc1
	v_lshlrev_b64 v[114:115], 11, v[114:115]
	v_lshl_add_u64 v[114:115], s[10:11], 0, v[114:115]
	v_lshl_add_u64 v[124:125], v[146:147], 1, v[114:115]
	global_load_dwordx4 v[116:119], v[124:125], off
	global_load_dwordx4 v[120:123], v[124:125], off offset:256
	v_mov_b32_e32 v115, 0x358637bd
	v_mov_b32_e32 v114, 0x260
	s_waitcnt vmcnt(2)
	v_fmamk_f32 v126, v126, 0x3a800000, v115
	v_mul_f32_e32 v127, 0x4f800000, v126
	v_cmp_gt_f32_e32 vcc, s2, v126
	s_waitcnt vmcnt(1)
	v_lshlrev_b32_e32 v128, 16, v118
	v_and_b32_e32 v129, 0xffff0000, v118
	v_cndmask_b32_e32 v134, v126, v127, vcc
	v_sqrt_f32_e32 v135, v134
	v_lshlrev_b32_e32 v126, 16, v116
	v_and_b32_e32 v127, 0xffff0000, v116
	v_lshlrev_b32_e32 v116, 16, v117
	v_add_u32_e32 v136, -1, v135
	v_add_u32_e32 v137, 1, v135
	v_fma_f32 v138, -v136, v135, v134
	v_fma_f32 v139, -v137, v135, v134
	v_cmp_ge_f32_e64 s[0:1], 0, v138
	v_and_b32_e32 v117, 0xffff0000, v117
	v_lshlrev_b32_e32 v118, 16, v119
	v_cndmask_b32_e64 v135, v135, v136, s[0:1]
	v_cmp_lt_f32_e64 s[0:1], 0, v139
	v_and_b32_e32 v119, 0xffff0000, v119
	s_waitcnt vmcnt(0)
	v_lshlrev_b32_e32 v130, 16, v120
	v_cndmask_b32_e64 v135, v135, v137, s[0:1]
	v_mul_f32_e32 v136, 0x37800000, v135
	v_cndmask_b32_e32 v135, v135, v136, vcc
	v_cmp_class_f32_e32 vcc, v134, v114
	v_and_b32_e32 v131, 0xffff0000, v120
	v_lshlrev_b32_e32 v120, 16, v121
	v_cndmask_b32_e32 v134, v135, v134, vcc
	v_div_scale_f32 v135, s[0:1], v134, v134, 1.0
	v_rcp_f32_e32 v136, v135
	v_div_scale_f32 v137, vcc, 1.0, v134, 1.0
	v_and_b32_e32 v121, 0xffff0000, v121
	v_fma_f32 v138, -v135, v136, 1.0
	v_fmac_f32_e32 v136, v138, v136
	v_mul_f32_e32 v138, v137, v136
	v_fma_f32 v139, -v135, v138, v137
	v_fmac_f32_e32 v138, v139, v136
	v_fma_f32 v135, -v135, v138, v137
	v_div_fmas_f32 v135, v135, v136, v138
	v_div_fixup_f32 v134, v135, v134, 1.0
	v_lshlrev_b32_e32 v132, 16, v122
	v_and_b32_e32 v133, 0xffff0000, v122
	v_lshlrev_b32_e32 v122, 16, v123
	v_and_b32_e32 v123, 0xffff0000, v123
	v_pk_mul_f32 v[92:93], v[92:93], v[134:135] op_sel_hi:[1,0]
	v_pk_mul_f32 v[94:95], v[94:95], v[134:135] op_sel_hi:[1,0]
	v_pk_mul_f32 v[88:89], v[88:89], v[134:135] op_sel_hi:[1,0]
	v_pk_mul_f32 v[90:91], v[90:91], v[134:135] op_sel_hi:[1,0]
	v_pk_mul_f32 v[84:85], v[84:85], v[134:135] op_sel_hi:[1,0]
	v_pk_mul_f32 v[86:87], v[86:87], v[134:135] op_sel_hi:[1,0]
	v_pk_mul_f32 v[80:81], v[80:81], v[134:135] op_sel_hi:[1,0]
	v_pk_mul_f32 v[82:83], v[82:83], v[134:135] op_sel_hi:[1,0]
	v_pk_fma_f32 v[94:95], v[106:107], v[94:95], v[116:117]
	v_pk_fma_f32 v[92:93], v[104:105], v[92:93], v[126:127]
	v_pk_fma_f32 v[90:91], v[102:103], v[90:91], v[118:119]
	v_pk_fma_f32 v[88:89], v[100:101], v[88:89], v[128:129]
	v_pk_fma_f32 v[86:87], v[110:111], v[86:87], v[120:121]
	v_pk_fma_f32 v[84:85], v[108:109], v[84:85], v[130:131]
	v_pk_fma_f32 v[116:117], v[98:99], v[82:83], v[122:123]
	v_pk_fma_f32 v[118:119], v[96:97], v[80:81], v[132:133]
	v_cvt_pk_bf16_f32 v80, v92, v93
	v_cvt_pk_bf16_f32 v81, v94, v95
	v_mul_f32_e32 v82, v93, v93
	v_mul_f32_e32 v83, v95, v95
	v_mul_f32_e32 v93, v89, v89
	v_mul_f32_e32 v95, v91, v91
	v_mul_f32_e32 v120, v85, v85
	v_mul_f32_e32 v121, v87, v87
	v_mul_f32_e32 v122, v119, v119
	v_mul_f32_e32 v123, v117, v117
	v_fmac_f32_e32 v82, v92, v92
	v_fmac_f32_e32 v83, v94, v94
	v_fmac_f32_e32 v93, v88, v88
	v_fmac_f32_e32 v95, v90, v90
	v_fmac_f32_e32 v120, v84, v84
	v_fmac_f32_e32 v121, v86, v86
	v_fmac_f32_e32 v122, v118, v118
	v_fmac_f32_e32 v123, v116, v116
	v_add_f32_e32 v82, v82, v83
	v_add_f32_e32 v83, v93, v95
	v_add_f32_e32 v92, v120, v121
	v_add_f32_e32 v93, v122, v123
	v_add_f32_e32 v82, v82, v83
	v_add_f32_e32 v83, v92, v93
	v_add_f32_e32 v92, v82, v83
	v_mov_b32_e32 v93, v92
	s_nop 1
	v_permlane16_swap_b32 v93, v92
	s_nop 0
	v_cvt_pk_bf16_f32 v82, v88, v89
	v_cvt_pk_bf16_f32 v83, v90, v91
	global_store_dwordx4 v[124:125], v[80:83], off
	s_waitcnt lgkmcnt(0)
	s_nop 0
	v_add_f32_e32 v80, v92, v93
	v_mov_b32_e32 v81, v80
	s_nop 1
	v_permlane32_swap_b32 v81, v80
	s_nop 0
	v_cvt_pk_bf16_f32 v82, v84, v85
	v_cvt_pk_bf16_f32 v83, v86, v87
	v_cvt_pk_bf16_f32 v84, v118, v119
	v_cvt_pk_bf16_f32 v85, v116, v117
	global_store_dwordx4 v[124:125], v[82:85], off offset:256
	s_and_saveexec_b64 s[0:1], s[4:5]
	s_cbranch_execz .LBB0_1454
	v_lshl_add_u32 v82, v112, 4, s24
	s_waitcnt lgkmcnt(0)
	v_add_f32_e32 v80, v80, v81
	ds_write_b32 v82, v80
; DI unsigned pk_bf16(float lo, float hi) { f32x2 v = {lo, hi}; bf16x2_t b = __builtin_convertvector(v, bf16x2_t); return __builtin_bit_cast(unsigned, b); }
; DI float bflo(unsigned w) { return __uint_as_float(w << 16); }
; DI float bfhi(unsigned w) { return __uint_as_float(w & 0xffff0000u); }
;     __device__ __forceinline__ void fused(f32x4 (&acc)[2][2][4][2], const pg8::Unit& u, int wr, int wc, int fr, int fq, PG8_LAS unsigned char* lds, int wid, int lane) const {
;     ...
;                 const int rl = ai * 128 + wr * 64 + m * 16 + fr; const size_t row = (size_t)u.pm * 256 + rl;
;                 const float rm = 1.f / sqrtf(__hip_atomic_load(ssqm + row, __ATOMIC_RELAXED, __HIP_MEMORY_SCOPE_AGENT) * (1.f / DM) + RMS_EPS);
;                 float sh = 0.f;
; #pragma unroll
;                 for (int bj = 0; bj < 2; ++bj) {
;                     const size_t off = row * DM + colb + bj * 128;
;                     f32x4 h0, h1;
;                     if (IN16) { const u32x4 hw = *(const u32x4*)((const bf16_t*)hin + off); h0 = (f32x4){bflo(hw.x), bfhi(hw.x), bflo(hw.y), bfhi(hw.y)}; h1 = (f32x4){bflo(hw.z), bfhi(hw.z), bflo(hw.w), bfhi(hw.w)}; }
;                     else { h0 = *(const f32x4*)((const float*)hin + off); h1 = *(const f32x4*)((const float*)hin + off + 4); }
;                     h0 = h0 + acc[ai][bj][m][0] * rm * gv[bj][0]; h1 = h1 + acc[ai][bj][m][1] * rm * gv[bj][1];
;                     sh += ((h0[0] * h0[0] + h0[1] * h0[1]) + (h0[2] * h0[2] + h0[3] * h0[3])) + ((h1[0] * h1[0] + h1[1] * h1[1]) + (h1[2] * h1[2] + h1[3] * h1[3]));
;                     if (OUT16) { u32x4 w; w.x = pk_bf16(h0[0], h0[1]); w.y = pk_bf16(h0[2], h0[3]); w.z = pk_bf16(h1[0], h1[1]); w.w = pk_bf16(h1[2], h1[3]); *(u32x4*)((bf16_t*)hout + off) = w; }
;                     else { *(f32x4*)((float*)hout + off) = h0; *(f32x4*)((float*)hout + off + 4) = h1; }
;                 }
;                 if (ssqh) { sh += __shfl_xor(sh, 16); sh += __shfl_xor(sh, 32); if (fq == 0) red[rl * 4 + wc] = sh; }
.LBB0_1454:
	s_or_b64 exec, exec, s[0:1]
	v_or_b32_e32 v112, 48, v152
	s_waitcnt lgkmcnt(0)
	v_lshl_add_u64 v[80:81], s[14:15], 0, v[112:113]
	v_lshl_add_u64 v[82:83], v[80:81], 2, s[12:13]
	global_load_dword v90, v[82:83], off sc1
	v_lshlrev_b64 v[80:81], 11, v[80:81]
	v_lshl_add_u64 v[80:81], s[10:11], 0, v[80:81]
	v_lshl_add_u64 v[88:89], v[146:147], 1, v[80:81]
	global_load_dwordx4 v[80:83], v[88:89], off
	global_load_dwordx4 v[84:87], v[88:89], off offset:256
	s_waitcnt vmcnt(2)
	v_fmac_f32_e32 v115, 0x3a800000, v90
	v_mul_f32_e32 v90, 0x4f800000, v115
	v_cmp_gt_f32_e32 vcc, s2, v115
	s_waitcnt vmcnt(1)
	v_and_b32_e32 v91, 0xffff0000, v80
	v_lshlrev_b32_e32 v92, 16, v82
	v_cndmask_b32_e32 v113, v115, v90, vcc
	v_sqrt_f32_e32 v115, v113
	v_lshlrev_b32_e32 v90, 16, v80
	v_lshlrev_b32_e32 v80, 16, v81
	v_and_b32_e32 v81, 0xffff0000, v81
	v_add_u32_e32 v118, -1, v115
	v_add_u32_e32 v119, 1, v115
	v_fma_f32 v120, -v118, v115, v113
	v_fma_f32 v121, -v119, v115, v113
	v_cmp_ge_f32_e64 s[0:1], 0, v120
	v_and_b32_e32 v93, 0xffff0000, v82
	v_lshlrev_b32_e32 v82, 16, v83
	v_cndmask_b32_e64 v115, v115, v118, s[0:1]
	v_cmp_lt_f32_e64 s[0:1], 0, v121
	v_and_b32_e32 v83, 0xffff0000, v83
	s_waitcnt vmcnt(0)
	v_lshlrev_b32_e32 v94, 16, v84
	v_cndmask_b32_e64 v115, v115, v119, s[0:1]
	v_mul_f32_e32 v118, 0x37800000, v115
	v_cndmask_b32_e32 v115, v115, v118, vcc
	v_cmp_class_f32_e32 vcc, v113, v114
	v_and_b32_e32 v95, 0xffff0000, v84
	v_lshlrev_b32_e32 v84, 16, v85
	v_cndmask_b32_e32 v113, v115, v113, vcc
	v_div_scale_f32 v114, s[0:1], v113, v113, 1.0
	v_rcp_f32_e32 v115, v114
	v_div_scale_f32 v118, vcc, 1.0, v113, 1.0
	v_and_b32_e32 v85, 0xffff0000, v85
	v_fma_f32 v119, -v114, v115, 1.0
	v_fmac_f32_e32 v115, v119, v115
	v_mul_f32_e32 v119, v118, v115
	v_fma_f32 v120, -v114, v119, v118
	v_fmac_f32_e32 v119, v120, v115
	v_fma_f32 v114, -v114, v119, v118
	v_div_fmas_f32 v114, v114, v115, v119
	v_div_fixup_f32 v114, v114, v113, 1.0
	v_lshlrev_b32_e32 v116, 16, v86
	v_and_b32_e32 v117, 0xffff0000, v86
	v_lshlrev_b32_e32 v86, 16, v87
	v_and_b32_e32 v87, 0xffff0000, v87
	v_pk_mul_f32 v[76:77], v[76:77], v[114:115] op_sel_hi:[1,0]
	v_pk_mul_f32 v[78:79], v[78:79], v[114:115] op_sel_hi:[1,0]
	v_pk_mul_f32 v[72:73], v[72:73], v[114:115] op_sel_hi:[1,0]
	v_pk_mul_f32 v[74:75], v[74:75], v[114:115] op_sel_hi:[1,0]
	v_pk_mul_f32 v[68:69], v[68:69], v[114:115] op_sel_hi:[1,0]
	v_pk_mul_f32 v[70:71], v[70:71], v[114:115] op_sel_hi:[1,0]
	v_pk_mul_f32 v[64:65], v[64:65], v[114:115] op_sel_hi:[1,0]
	v_pk_mul_f32 v[66:67], v[66:67], v[114:115] op_sel_hi:[1,0]
	v_pk_fma_f32 v[78:79], v[106:107], v[78:79], v[80:81]
	v_pk_fma_f32 v[76:77], v[104:105], v[76:77], v[90:91]
	v_pk_fma_f32 v[74:75], v[102:103], v[74:75], v[82:83]
	v_pk_fma_f32 v[72:73], v[100:101], v[72:73], v[92:93]
	v_pk_fma_f32 v[70:71], v[110:111], v[70:71], v[84:85]
	v_pk_fma_f32 v[68:69], v[108:109], v[68:69], v[94:95]
	v_pk_fma_f32 v[80:81], v[98:99], v[66:67], v[86:87]
	v_pk_fma_f32 v[82:83], v[96:97], v[64:65], v[116:117]
	v_cvt_pk_bf16_f32 v64, v76, v77
	v_cvt_pk_bf16_f32 v65, v78, v79
	v_mul_f32_e32 v66, v77, v77
	v_mul_f32_e32 v67, v79, v79
	v_mul_f32_e32 v77, v73, v73
	v_mul_f32_e32 v79, v75, v75
	v_mul_f32_e32 v84, v69, v69
	v_mul_f32_e32 v85, v71, v71
	v_mul_f32_e32 v86, v83, v83
	v_mul_f32_e32 v87, v81, v81
	v_fmac_f32_e32 v66, v76, v76
	v_fmac_f32_e32 v67, v78, v78
	v_fmac_f32_e32 v77, v72, v72
	v_fmac_f32_e32 v79, v74, v74
	v_fmac_f32_e32 v84, v68, v68
	v_fmac_f32_e32 v85, v70, v70
	v_fmac_f32_e32 v86, v82, v82
	v_fmac_f32_e32 v87, v80, v80
	v_add_f32_e32 v66, v66, v67
	v_add_f32_e32 v67, v77, v79
	v_add_f32_e32 v76, v84, v85
	v_add_f32_e32 v77, v86, v87
	v_add_f32_e32 v66, v66, v67
	v_add_f32_e32 v67, v76, v77
	v_add_f32_e32 v76, v66, v67
	v_mov_b32_e32 v77, v76
	s_nop 1
	v_permlane16_swap_b32 v77, v76
	s_nop 0
	v_cvt_pk_bf16_f32 v66, v72, v73
	v_cvt_pk_bf16_f32 v67, v74, v75
	global_store_dwordx4 v[88:89], v[64:67], off
	s_waitcnt lgkmcnt(0)
	s_nop 0
	v_add_f32_e32 v64, v76, v77
	v_mov_b32_e32 v65, v64
	s_nop 1
	v_permlane32_swap_b32 v65, v64
	s_nop 0
	v_cvt_pk_bf16_f32 v66, v68, v69
	v_cvt_pk_bf16_f32 v67, v70, v71
	v_cvt_pk_bf16_f32 v68, v82, v83
	v_cvt_pk_bf16_f32 v69, v80, v81
	global_store_dwordx4 v[88:89], v[66:69], off offset:256
	s_and_saveexec_b64 s[0:1], s[4:5]
	s_cbranch_execz .LBB0_1456
	v_lshl_add_u32 v66, v112, 4, s24
	s_waitcnt lgkmcnt(0)
	v_add_f32_e32 v64, v64, v65
	ds_write_b32 v66, v64
; DI unsigned pk_bf16(float lo, float hi) { f32x2 v = {lo, hi}; bf16x2_t b = __builtin_convertvector(v, bf16x2_t); return __builtin_bit_cast(unsigned, b); }
; DI float bflo(unsigned w) { return __uint_as_float(w << 16); }
; DI float bfhi(unsigned w) { return __uint_as_float(w & 0xffff0000u); }
;     __device__ __forceinline__ void fused(f32x4 (&acc)[2][2][4][2], const pg8::Unit& u, int wr, int wc, int fr, int fq, PG8_LAS unsigned char* lds, int wid, int lane) const {
;     ...
;                 const int rl = ai * 128 + wr * 64 + m * 16 + fr; const size_t row = (size_t)u.pm * 256 + rl;
;                 const float rm = 1.f / sqrtf(__hip_atomic_load(ssqm + row, __ATOMIC_RELAXED, __HIP_MEMORY_SCOPE_AGENT) * (1.f / DM) + RMS_EPS);
;                 float sh = 0.f;
; #pragma unroll
;                 for (int bj = 0; bj < 2; ++bj) {
;                     const size_t off = row * DM + colb + bj * 128;
;                     f32x4 h0, h1;
;                     if (IN16) { const u32x4 hw = *(const u32x4*)((const bf16_t*)hin + off); h0 = (f32x4){bflo(hw.x), bfhi(hw.x), bflo(hw.y), bfhi(hw.y)}; h1 = (f32x4){bflo(hw.z), bfhi(hw.z), bflo(hw.w), bfhi(hw.w)}; }
;                     else { h0 = *(const f32x4*)((const float*)hin + off); h1 = *(const f32x4*)((const float*)hin + off + 4); }
;                     h0 = h0 + acc[ai][bj][m][0] * rm * gv[bj][0]; h1 = h1 + acc[ai][bj][m][1] * rm * gv[bj][1];
;                     sh += ((h0[0] * h0[0] + h0[1] * h0[1]) + (h0[2] * h0[2] + h0[3] * h0[3])) + ((h1[0] * h1[0] + h1[1] * h1[1]) + (h1[2] * h1[2] + h1[3] * h1[3]));
;                     if (OUT16) { u32x4 w; w.x = pk_bf16(h0[0], h0[1]); w.y = pk_bf16(h0[2], h0[3]); w.z = pk_bf16(h1[0], h1[1]); w.w = pk_bf16(h1[2], h1[3]); *(u32x4*)((bf16_t*)hout + off) = w; }
;                     else { *(f32x4*)((float*)hout + off) = h0; *(f32x4*)((float*)hout + off + 4) = h1; }
;                 }
;                 if (ssqh) { sh += __shfl_xor(sh, 16); sh += __shfl_xor(sh, 32); if (fq == 0) red[rl * 4 + wc] = sh; }
.LBB0_1456:
	s_or_b64 exec, exec, s[0:1]
	v_add_u32_e32 v64, 0x80, v152
	s_waitcnt lgkmcnt(0)
	v_mov_b32_e32 v65, 0
	v_lshl_add_u64 v[66:67], s[14:15], 0, v[64:65]
	v_lshl_add_u64 v[68:69], v[66:67], 2, s[12:13]
	global_load_dword v78, v[68:69], off sc1
	v_lshlrev_b64 v[66:67], 11, v[66:67]
	v_lshl_add_u64 v[66:67], s[10:11], 0, v[66:67]
	v_lshl_add_u64 v[76:77], v[146:147], 1, v[66:67]
	global_load_dwordx4 v[68:71], v[76:77], off
	global_load_dwordx4 v[72:75], v[76:77], off offset:256
	v_mov_b32_e32 v67, 0x358637bd
	v_mov_b32_e32 v66, 0x260
	s_waitcnt vmcnt(2)
	v_fmamk_f32 v78, v78, 0x3a800000, v67
	v_mul_f32_e32 v79, 0x4f800000, v78
	v_cmp_gt_f32_e32 vcc, s2, v78
	s_waitcnt vmcnt(1)
	v_lshlrev_b32_e32 v80, 16, v70
	v_and_b32_e32 v81, 0xffff0000, v70
	v_cndmask_b32_e32 v86, v78, v79, vcc
	v_sqrt_f32_e32 v87, v86
	v_lshlrev_b32_e32 v78, 16, v68
	v_and_b32_e32 v79, 0xffff0000, v68
	v_lshlrev_b32_e32 v68, 16, v69
	v_add_u32_e32 v88, -1, v87
	v_add_u32_e32 v89, 1, v87
	v_fma_f32 v90, -v88, v87, v86
	v_fma_f32 v91, -v89, v87, v86
	v_cmp_ge_f32_e64 s[0:1], 0, v90
	v_and_b32_e32 v69, 0xffff0000, v69
	v_lshlrev_b32_e32 v70, 16, v71
	v_cndmask_b32_e64 v87, v87, v88, s[0:1]
	v_cmp_lt_f32_e64 s[0:1], 0, v91
	v_and_b32_e32 v71, 0xffff0000, v71
	s_waitcnt vmcnt(0)
	v_lshlrev_b32_e32 v82, 16, v72
	v_cndmask_b32_e64 v87, v87, v89, s[0:1]
	v_mul_f32_e32 v88, 0x37800000, v87
	v_cndmask_b32_e32 v87, v87, v88, vcc
	v_cmp_class_f32_e32 vcc, v86, v66
	v_and_b32_e32 v83, 0xffff0000, v72
	v_lshlrev_b32_e32 v72, 16, v73
	v_cndmask_b32_e32 v86, v87, v86, vcc
	v_div_scale_f32 v87, s[0:1], v86, v86, 1.0
	v_rcp_f32_e32 v88, v87
	v_div_scale_f32 v89, vcc, 1.0, v86, 1.0
	v_and_b32_e32 v73, 0xffff0000, v73
	v_fma_f32 v90, -v87, v88, 1.0
	v_fmac_f32_e32 v88, v90, v88
	v_mul_f32_e32 v90, v89, v88
	v_fma_f32 v91, -v87, v90, v89
	v_fmac_f32_e32 v90, v91, v88
	v_fma_f32 v87, -v87, v90, v89
	v_div_fmas_f32 v87, v87, v88, v90
	v_div_fixup_f32 v86, v87, v86, 1.0
	v_lshlrev_b32_e32 v84, 16, v74
	v_and_b32_e32 v85, 0xffff0000, v74
	v_lshlrev_b32_e32 v74, 16, v75
	v_and_b32_e32 v75, 0xffff0000, v75
	v_pk_mul_f32 v[60:61], v[60:61], v[86:87] op_sel_hi:[1,0]
	v_pk_mul_f32 v[62:63], v[62:63], v[86:87] op_sel_hi:[1,0]
	v_pk_mul_f32 v[56:57], v[56:57], v[86:87] op_sel_hi:[1,0]
	v_pk_mul_f32 v[58:59], v[58:59], v[86:87] op_sel_hi:[1,0]
	v_pk_mul_f32 v[52:53], v[52:53], v[86:87] op_sel_hi:[1,0]
	v_pk_mul_f32 v[54:55], v[54:55], v[86:87] op_sel_hi:[1,0]
	v_pk_mul_f32 v[48:49], v[48:49], v[86:87] op_sel_hi:[1,0]
	v_pk_mul_f32 v[50:51], v[50:51], v[86:87] op_sel_hi:[1,0]
	v_pk_fma_f32 v[62:63], v[106:107], v[62:63], v[68:69]
	v_pk_fma_f32 v[60:61], v[104:105], v[60:61], v[78:79]
	v_pk_fma_f32 v[58:59], v[102:103], v[58:59], v[70:71]
	v_pk_fma_f32 v[56:57], v[100:101], v[56:57], v[80:81]
	v_pk_fma_f32 v[54:55], v[110:111], v[54:55], v[72:73]
	v_pk_fma_f32 v[52:53], v[108:109], v[52:53], v[82:83]
	v_pk_fma_f32 v[68:69], v[98:99], v[50:51], v[74:75]
	v_pk_fma_f32 v[70:71], v[96:97], v[48:49], v[84:85]
	v_cvt_pk_bf16_f32 v48, v60, v61
	v_cvt_pk_bf16_f32 v49, v62, v63
	v_mul_f32_e32 v50, v61, v61
	v_mul_f32_e32 v51, v63, v63
	v_mul_f32_e32 v61, v57, v57
	v_mul_f32_e32 v63, v59, v59
	v_mul_f32_e32 v72, v53, v53
	v_mul_f32_e32 v73, v55, v55
	v_mul_f32_e32 v74, v71, v71
	v_mul_f32_e32 v75, v69, v69
	v_fmac_f32_e32 v50, v60, v60
	v_fmac_f32_e32 v51, v62, v62
	v_fmac_f32_e32 v61, v56, v56
	v_fmac_f32_e32 v63, v58, v58
	v_fmac_f32_e32 v72, v52, v52
	v_fmac_f32_e32 v73, v54, v54
	v_fmac_f32_e32 v74, v70, v70
	v_fmac_f32_e32 v75, v68, v68
	v_add_f32_e32 v50, v50, v51
	v_add_f32_e32 v51, v61, v63
	v_add_f32_e32 v60, v72, v73
	v_add_f32_e32 v61, v74, v75
	v_add_f32_e32 v50, v50, v51
	v_add_f32_e32 v51, v60, v61
	v_add_f32_e32 v60, v50, v51
	v_mov_b32_e32 v61, v60
	s_nop 1
	v_permlane16_swap_b32 v61, v60
	s_nop 0
	v_cvt_pk_bf16_f32 v50, v56, v57
	v_cvt_pk_bf16_f32 v51, v58, v59
	global_store_dwordx4 v[76:77], v[48:51], off
	s_waitcnt lgkmcnt(0)
	s_nop 0
	v_add_f32_e32 v48, v60, v61
	v_mov_b32_e32 v49, v48
	s_nop 1
	v_permlane32_swap_b32 v49, v48
	s_nop 0
	v_cvt_pk_bf16_f32 v50, v52, v53
	v_cvt_pk_bf16_f32 v51, v54, v55
	v_cvt_pk_bf16_f32 v52, v70, v71
	v_cvt_pk_bf16_f32 v53, v68, v69
	global_store_dwordx4 v[76:77], v[50:53], off offset:256
	s_and_saveexec_b64 s[0:1], s[4:5]
	s_cbranch_execz .LBB0_1458
	v_lshl_add_u32 v50, v64, 4, s24
	s_waitcnt lgkmcnt(0)
	v_add_f32_e32 v48, v48, v49
	ds_write_b32 v50, v48
; DI unsigned pk_bf16(float lo, float hi) { f32x2 v = {lo, hi}; bf16x2_t b = __builtin_convertvector(v, bf16x2_t); return __builtin_bit_cast(unsigned, b); }
; DI float bflo(unsigned w) { return __uint_as_float(w << 16); }
; DI float bfhi(unsigned w) { return __uint_as_float(w & 0xffff0000u); }
;     __device__ __forceinline__ void fused(f32x4 (&acc)[2][2][4][2], const pg8::Unit& u, int wr, int wc, int fr, int fq, PG8_LAS unsigned char* lds, int wid, int lane) const {
;     ...
;                 const int rl = ai * 128 + wr * 64 + m * 16 + fr; const size_t row = (size_t)u.pm * 256 + rl;
;                 const float rm = 1.f / sqrtf(__hip_atomic_load(ssqm + row, __ATOMIC_RELAXED, __HIP_MEMORY_SCOPE_AGENT) * (1.f / DM) + RMS_EPS);
;                 float sh = 0.f;
; #pragma unroll
;                 for (int bj = 0; bj < 2; ++bj) {
;                     const size_t off = row * DM + colb + bj * 128;
;                     f32x4 h0, h1;
;                     if (IN16) { const u32x4 hw = *(const u32x4*)((const bf16_t*)hin + off); h0 = (f32x4){bflo(hw.x), bfhi(hw.x), bflo(hw.y), bfhi(hw.y)}; h1 = (f32x4){bflo(hw.z), bfhi(hw.z), bflo(hw.w), bfhi(hw.w)}; }
;                     else { h0 = *(const f32x4*)((const float*)hin + off); h1 = *(const f32x4*)((const float*)hin + off + 4); }
;                     h0 = h0 + acc[ai][bj][m][0] * rm * gv[bj][0]; h1 = h1 + acc[ai][bj][m][1] * rm * gv[bj][1];
;                     sh += ((h0[0] * h0[0] + h0[1] * h0[1]) + (h0[2] * h0[2] + h0[3] * h0[3])) + ((h1[0] * h1[0] + h1[1] * h1[1]) + (h1[2] * h1[2] + h1[3] * h1[3]));
;                     if (OUT16) { u32x4 w; w.x = pk_bf16(h0[0], h0[1]); w.y = pk_bf16(h0[2], h0[3]); w.z = pk_bf16(h1[0], h1[1]); w.w = pk_bf16(h1[2], h1[3]); *(u32x4*)((bf16_t*)hout + off) = w; }
;                     else { *(f32x4*)((float*)hout + off) = h0; *(f32x4*)((float*)hout + off + 4) = h1; }
;                 }
;                 if (ssqh) { sh += __shfl_xor(sh, 16); sh += __shfl_xor(sh, 32); if (fq == 0) red[rl * 4 + wc] = sh; }
.LBB0_1458:
	s_or_b64 exec, exec, s[0:1]
	v_add_u32_e32 v64, 0x90, v152
	s_waitcnt lgkmcnt(0)
	v_lshl_add_u64 v[48:49], s[14:15], 0, v[64:65]
	v_lshl_add_u64 v[50:51], v[48:49], 2, s[12:13]
	global_load_dword v58, v[50:51], off sc1
	v_lshlrev_b64 v[48:49], 11, v[48:49]
	v_lshl_add_u64 v[48:49], s[10:11], 0, v[48:49]
	v_lshl_add_u64 v[56:57], v[146:147], 1, v[48:49]
	global_load_dwordx4 v[48:51], v[56:57], off
	global_load_dwordx4 v[52:55], v[56:57], off offset:256
	s_waitcnt vmcnt(2)
	v_fmac_f32_e32 v67, 0x3a800000, v58
	v_mul_f32_e32 v58, 0x4f800000, v67
	v_cmp_gt_f32_e32 vcc, s2, v67
	s_waitcnt vmcnt(1)
	v_and_b32_e32 v59, 0xffff0000, v48
	v_lshlrev_b32_e32 v60, 16, v50
	v_cndmask_b32_e32 v65, v67, v58, vcc
	v_sqrt_f32_e32 v67, v65
	v_lshlrev_b32_e32 v58, 16, v48
	v_lshlrev_b32_e32 v48, 16, v49
	v_and_b32_e32 v49, 0xffff0000, v49
	v_add_u32_e32 v70, -1, v67
	v_add_u32_e32 v71, 1, v67
	v_fma_f32 v72, -v70, v67, v65
	v_fma_f32 v73, -v71, v67, v65
	v_cmp_ge_f32_e64 s[0:1], 0, v72
	v_and_b32_e32 v61, 0xffff0000, v50
	v_lshlrev_b32_e32 v50, 16, v51
	v_cndmask_b32_e64 v67, v67, v70, s[0:1]
	v_cmp_lt_f32_e64 s[0:1], 0, v73
	v_and_b32_e32 v51, 0xffff0000, v51
	s_waitcnt vmcnt(0)
	v_lshlrev_b32_e32 v62, 16, v52
	v_cndmask_b32_e64 v67, v67, v71, s[0:1]
	v_mul_f32_e32 v70, 0x37800000, v67
	v_cndmask_b32_e32 v67, v67, v70, vcc
	v_cmp_class_f32_e32 vcc, v65, v66
	v_and_b32_e32 v63, 0xffff0000, v52
	v_lshlrev_b32_e32 v52, 16, v53
	v_cndmask_b32_e32 v65, v67, v65, vcc
	v_div_scale_f32 v66, s[0:1], v65, v65, 1.0
	v_rcp_f32_e32 v67, v66
	v_div_scale_f32 v70, vcc, 1.0, v65, 1.0
	v_and_b32_e32 v53, 0xffff0000, v53
	v_fma_f32 v71, -v66, v67, 1.0
	v_fmac_f32_e32 v67, v71, v67
	v_mul_f32_e32 v71, v70, v67
	v_fma_f32 v72, -v66, v71, v70
	v_fmac_f32_e32 v71, v72, v67
	v_fma_f32 v66, -v66, v71, v70
	v_div_fmas_f32 v66, v66, v67, v71
	v_div_fixup_f32 v66, v66, v65, 1.0
	v_lshlrev_b32_e32 v68, 16, v54
	v_and_b32_e32 v69, 0xffff0000, v54
	v_lshlrev_b32_e32 v54, 16, v55
	v_and_b32_e32 v55, 0xffff0000, v55
	v_pk_mul_f32 v[44:45], v[44:45], v[66:67] op_sel_hi:[1,0]
	v_pk_mul_f32 v[46:47], v[46:47], v[66:67] op_sel_hi:[1,0]
	v_pk_mul_f32 v[40:41], v[40:41], v[66:67] op_sel_hi:[1,0]
	v_pk_mul_f32 v[42:43], v[42:43], v[66:67] op_sel_hi:[1,0]
	v_pk_mul_f32 v[36:37], v[36:37], v[66:67] op_sel_hi:[1,0]
	v_pk_mul_f32 v[38:39], v[38:39], v[66:67] op_sel_hi:[1,0]
	v_pk_mul_f32 v[32:33], v[32:33], v[66:67] op_sel_hi:[1,0]
	v_pk_mul_f32 v[34:35], v[34:35], v[66:67] op_sel_hi:[1,0]
	v_pk_fma_f32 v[46:47], v[106:107], v[46:47], v[48:49]
	v_pk_fma_f32 v[44:45], v[104:105], v[44:45], v[58:59]
	v_pk_fma_f32 v[42:43], v[102:103], v[42:43], v[50:51]
	v_pk_fma_f32 v[40:41], v[100:101], v[40:41], v[60:61]
	v_pk_fma_f32 v[38:39], v[110:111], v[38:39], v[52:53]
	v_pk_fma_f32 v[36:37], v[108:109], v[36:37], v[62:63]
	v_pk_fma_f32 v[48:49], v[98:99], v[34:35], v[54:55]
	v_pk_fma_f32 v[50:51], v[96:97], v[32:33], v[68:69]
	v_cvt_pk_bf16_f32 v32, v44, v45
	v_cvt_pk_bf16_f32 v33, v46, v47
	v_mul_f32_e32 v34, v45, v45
	v_mul_f32_e32 v35, v47, v47
	v_mul_f32_e32 v45, v41, v41
	v_mul_f32_e32 v47, v43, v43
	v_mul_f32_e32 v52, v37, v37
	v_mul_f32_e32 v53, v39, v39
	v_mul_f32_e32 v54, v51, v51
	v_mul_f32_e32 v55, v49, v49
	v_fmac_f32_e32 v34, v44, v44
	v_fmac_f32_e32 v35, v46, v46
	v_fmac_f32_e32 v45, v40, v40
	v_fmac_f32_e32 v47, v42, v42
	v_fmac_f32_e32 v52, v36, v36
	v_fmac_f32_e32 v53, v38, v38
	v_fmac_f32_e32 v54, v50, v50
	v_fmac_f32_e32 v55, v48, v48
	v_add_f32_e32 v34, v34, v35
	v_add_f32_e32 v35, v45, v47
	v_add_f32_e32 v44, v52, v53
	v_add_f32_e32 v45, v54, v55
	v_add_f32_e32 v34, v34, v35
	v_add_f32_e32 v35, v44, v45
	v_add_f32_e32 v44, v34, v35
	v_mov_b32_e32 v45, v44
	s_nop 1
	v_permlane16_swap_b32 v45, v44
	s_nop 0
	v_cvt_pk_bf16_f32 v34, v40, v41
	v_cvt_pk_bf16_f32 v35, v42, v43
	global_store_dwordx4 v[56:57], v[32:35], off
	s_waitcnt lgkmcnt(0)
	s_nop 0
	v_add_f32_e32 v32, v44, v45
	v_mov_b32_e32 v33, v32
	s_nop 1
	v_permlane32_swap_b32 v33, v32
	s_nop 0
	v_cvt_pk_bf16_f32 v34, v36, v37
	v_cvt_pk_bf16_f32 v35, v38, v39
	v_cvt_pk_bf16_f32 v36, v50, v51
	v_cvt_pk_bf16_f32 v37, v48, v49
	global_store_dwordx4 v[56:57], v[34:37], off offset:256
	s_and_saveexec_b64 s[0:1], s[4:5]
	s_cbranch_execz .LBB0_1460
	v_lshl_add_u32 v34, v64, 4, s24
	s_waitcnt lgkmcnt(0)
	v_add_f32_e32 v32, v32, v33
	ds_write_b32 v34, v32
; DI unsigned pk_bf16(float lo, float hi) { f32x2 v = {lo, hi}; bf16x2_t b = __builtin_convertvector(v, bf16x2_t); return __builtin_bit_cast(unsigned, b); }
; DI float bflo(unsigned w) { return __uint_as_float(w << 16); }
; DI float bfhi(unsigned w) { return __uint_as_float(w & 0xffff0000u); }
;     __device__ __forceinline__ void fused(f32x4 (&acc)[2][2][4][2], const pg8::Unit& u, int wr, int wc, int fr, int fq, PG8_LAS unsigned char* lds, int wid, int lane) const {
;     ...
;                 const int rl = ai * 128 + wr * 64 + m * 16 + fr; const size_t row = (size_t)u.pm * 256 + rl;
;                 const float rm = 1.f / sqrtf(__hip_atomic_load(ssqm + row, __ATOMIC_RELAXED, __HIP_MEMORY_SCOPE_AGENT) * (1.f / DM) + RMS_EPS);
;                 float sh = 0.f;
; #pragma unroll
;                 for (int bj = 0; bj < 2; ++bj) {
;                     const size_t off = row * DM + colb + bj * 128;
;                     f32x4 h0, h1;
;                     if (IN16) { const u32x4 hw = *(const u32x4*)((const bf16_t*)hin + off); h0 = (f32x4){bflo(hw.x), bfhi(hw.x), bflo(hw.y), bfhi(hw.y)}; h1 = (f32x4){bflo(hw.z), bfhi(hw.z), bflo(hw.w), bfhi(hw.w)}; }
;                     else { h0 = *(const f32x4*)((const float*)hin + off); h1 = *(const f32x4*)((const float*)hin + off + 4); }
;                     h0 = h0 + acc[ai][bj][m][0] * rm * gv[bj][0]; h1 = h1 + acc[ai][bj][m][1] * rm * gv[bj][1];
;                     sh += ((h0[0] * h0[0] + h0[1] * h0[1]) + (h0[2] * h0[2] + h0[3] * h0[3])) + ((h1[0] * h1[0] + h1[1] * h1[1]) + (h1[2] * h1[2] + h1[3] * h1[3]));
;                     if (OUT16) { u32x4 w; w.x = pk_bf16(h0[0], h0[1]); w.y = pk_bf16(h0[2], h0[3]); w.z = pk_bf16(h1[0], h1[1]); w.w = pk_bf16(h1[2], h1[3]); *(u32x4*)((bf16_t*)hout + off) = w; }
;                     else { *(f32x4*)((float*)hout + off) = h0; *(f32x4*)((float*)hout + off + 4) = h1; }
;                 }
;                 if (ssqh) { sh += __shfl_xor(sh, 16); sh += __shfl_xor(sh, 32); if (fq == 0) red[rl * 4 + wc] = sh; }
.LBB0_1460:
	s_or_b64 exec, exec, s[0:1]
	v_add_u32_e32 v32, 0xa0, v152
	s_waitcnt lgkmcnt(0)
	v_mov_b32_e32 v33, 0
	v_lshl_add_u64 v[34:35], s[14:15], 0, v[32:33]
	v_lshl_add_u64 v[36:37], v[34:35], 2, s[12:13]
	global_load_dword v46, v[36:37], off sc1
	v_lshlrev_b64 v[34:35], 11, v[34:35]
	v_lshl_add_u64 v[34:35], s[10:11], 0, v[34:35]
	v_lshl_add_u64 v[44:45], v[146:147], 1, v[34:35]
	global_load_dwordx4 v[36:39], v[44:45], off
	global_load_dwordx4 v[40:43], v[44:45], off offset:256
	v_mov_b32_e32 v35, 0x358637bd
	v_mov_b32_e32 v34, 0x260
	s_waitcnt vmcnt(2)
	v_fmamk_f32 v46, v46, 0x3a800000, v35
	v_mul_f32_e32 v47, 0x4f800000, v46
	v_cmp_gt_f32_e32 vcc, s2, v46
	s_waitcnt vmcnt(1)
	v_lshlrev_b32_e32 v48, 16, v38
	v_and_b32_e32 v49, 0xffff0000, v38
	v_cndmask_b32_e32 v54, v46, v47, vcc
	v_sqrt_f32_e32 v55, v54
	v_lshlrev_b32_e32 v46, 16, v36
	v_and_b32_e32 v47, 0xffff0000, v36
	v_lshlrev_b32_e32 v36, 16, v37
	v_add_u32_e32 v56, -1, v55
	v_add_u32_e32 v57, 1, v55
	v_fma_f32 v58, -v56, v55, v54
	v_fma_f32 v59, -v57, v55, v54
	v_cmp_ge_f32_e64 s[0:1], 0, v58
	v_and_b32_e32 v37, 0xffff0000, v37
	v_lshlrev_b32_e32 v38, 16, v39
	v_cndmask_b32_e64 v55, v55, v56, s[0:1]
	v_cmp_lt_f32_e64 s[0:1], 0, v59
	v_and_b32_e32 v39, 0xffff0000, v39
	s_waitcnt vmcnt(0)
	v_lshlrev_b32_e32 v50, 16, v40
	v_cndmask_b32_e64 v55, v55, v57, s[0:1]
	v_mul_f32_e32 v56, 0x37800000, v55
	v_cndmask_b32_e32 v55, v55, v56, vcc
	v_cmp_class_f32_e32 vcc, v54, v34
	v_and_b32_e32 v51, 0xffff0000, v40
	v_lshlrev_b32_e32 v40, 16, v41
	v_cndmask_b32_e32 v54, v55, v54, vcc
	v_div_scale_f32 v55, s[0:1], v54, v54, 1.0
	v_rcp_f32_e32 v56, v55
	v_div_scale_f32 v57, vcc, 1.0, v54, 1.0
	v_and_b32_e32 v41, 0xffff0000, v41
	v_fma_f32 v58, -v55, v56, 1.0
	v_fmac_f32_e32 v56, v58, v56
	v_mul_f32_e32 v58, v57, v56
	v_fma_f32 v59, -v55, v58, v57
	v_fmac_f32_e32 v58, v59, v56
	v_fma_f32 v55, -v55, v58, v57
	v_div_fmas_f32 v55, v55, v56, v58
	v_div_fixup_f32 v54, v55, v54, 1.0
	v_lshlrev_b32_e32 v52, 16, v42
	v_and_b32_e32 v53, 0xffff0000, v42
	v_lshlrev_b32_e32 v42, 16, v43
	v_and_b32_e32 v43, 0xffff0000, v43
	v_pk_mul_f32 v[28:29], v[28:29], v[54:55] op_sel_hi:[1,0]
	v_pk_mul_f32 v[30:31], v[30:31], v[54:55] op_sel_hi:[1,0]
	v_pk_mul_f32 v[24:25], v[24:25], v[54:55] op_sel_hi:[1,0]
	v_pk_mul_f32 v[26:27], v[26:27], v[54:55] op_sel_hi:[1,0]
	v_pk_mul_f32 v[20:21], v[20:21], v[54:55] op_sel_hi:[1,0]
	v_pk_mul_f32 v[22:23], v[22:23], v[54:55] op_sel_hi:[1,0]
	v_pk_mul_f32 v[16:17], v[16:17], v[54:55] op_sel_hi:[1,0]
	v_pk_mul_f32 v[18:19], v[18:19], v[54:55] op_sel_hi:[1,0]
	v_pk_fma_f32 v[30:31], v[106:107], v[30:31], v[36:37]
	v_pk_fma_f32 v[28:29], v[104:105], v[28:29], v[46:47]
	v_pk_fma_f32 v[26:27], v[102:103], v[26:27], v[38:39]
	v_pk_fma_f32 v[24:25], v[100:101], v[24:25], v[48:49]
	v_pk_fma_f32 v[22:23], v[110:111], v[22:23], v[40:41]
	v_pk_fma_f32 v[20:21], v[108:109], v[20:21], v[50:51]
	v_pk_fma_f32 v[36:37], v[98:99], v[18:19], v[42:43]
	v_pk_fma_f32 v[38:39], v[96:97], v[16:17], v[52:53]
	v_cvt_pk_bf16_f32 v16, v28, v29
	v_cvt_pk_bf16_f32 v17, v30, v31
	v_mul_f32_e32 v18, v29, v29
	v_mul_f32_e32 v19, v31, v31
	v_mul_f32_e32 v29, v25, v25
	v_mul_f32_e32 v31, v27, v27
	v_mul_f32_e32 v40, v21, v21
	v_mul_f32_e32 v41, v23, v23
	v_mul_f32_e32 v42, v39, v39
	v_mul_f32_e32 v43, v37, v37
	v_fmac_f32_e32 v18, v28, v28
	v_fmac_f32_e32 v19, v30, v30
	v_fmac_f32_e32 v29, v24, v24
	v_fmac_f32_e32 v31, v26, v26
	v_fmac_f32_e32 v40, v20, v20
	v_fmac_f32_e32 v41, v22, v22
	v_fmac_f32_e32 v42, v38, v38
	v_fmac_f32_e32 v43, v36, v36
	v_add_f32_e32 v18, v18, v19
	v_add_f32_e32 v19, v29, v31
	v_add_f32_e32 v28, v40, v41
	v_add_f32_e32 v29, v42, v43
	v_add_f32_e32 v18, v18, v19
	v_add_f32_e32 v19, v28, v29
	v_add_f32_e32 v28, v18, v19
	v_mov_b32_e32 v29, v28
	s_nop 1
	v_permlane16_swap_b32 v29, v28
	s_nop 0
	v_cvt_pk_bf16_f32 v18, v24, v25
	v_cvt_pk_bf16_f32 v19, v26, v27
	global_store_dwordx4 v[44:45], v[16:19], off
	s_waitcnt lgkmcnt(0)
	s_nop 0
	v_add_f32_e32 v16, v28, v29
	v_mov_b32_e32 v17, v16
	s_nop 1
	v_permlane32_swap_b32 v17, v16
	s_nop 0
	v_cvt_pk_bf16_f32 v18, v20, v21
	v_cvt_pk_bf16_f32 v19, v22, v23
	v_cvt_pk_bf16_f32 v20, v38, v39
	v_cvt_pk_bf16_f32 v21, v36, v37
	global_store_dwordx4 v[44:45], v[18:21], off offset:256
	s_and_saveexec_b64 s[0:1], s[4:5]
	s_cbranch_execz .LBB0_1462
	v_lshl_add_u32 v18, v32, 4, s24
	s_waitcnt lgkmcnt(0)
	v_add_f32_e32 v16, v16, v17
	ds_write_b32 v18, v16
; DI unsigned pk_bf16(float lo, float hi) { f32x2 v = {lo, hi}; bf16x2_t b = __builtin_convertvector(v, bf16x2_t); return __builtin_bit_cast(unsigned, b); }
; DI float bflo(unsigned w) { return __uint_as_float(w << 16); }
; DI float bfhi(unsigned w) { return __uint_as_float(w & 0xffff0000u); }
;     __device__ __forceinline__ void fused(f32x4 (&acc)[2][2][4][2], const pg8::Unit& u, int wr, int wc, int fr, int fq, PG8_LAS unsigned char* lds, int wid, int lane) const {
;     ...
;                 const int rl = ai * 128 + wr * 64 + m * 16 + fr; const size_t row = (size_t)u.pm * 256 + rl;
;                 const float rm = 1.f / sqrtf(__hip_atomic_load(ssqm + row, __ATOMIC_RELAXED, __HIP_MEMORY_SCOPE_AGENT) * (1.f / DM) + RMS_EPS);
;                 float sh = 0.f;
; #pragma unroll
;                 for (int bj = 0; bj < 2; ++bj) {
;                     const size_t off = row * DM + colb + bj * 128;
;                     f32x4 h0, h1;
;                     if (IN16) { const u32x4 hw = *(const u32x4*)((const bf16_t*)hin + off); h0 = (f32x4){bflo(hw.x), bfhi(hw.x), bflo(hw.y), bfhi(hw.y)}; h1 = (f32x4){bflo(hw.z), bfhi(hw.z), bflo(hw.w), bfhi(hw.w)}; }
;                     else { h0 = *(const f32x4*)((const float*)hin + off); h1 = *(const f32x4*)((const float*)hin + off + 4); }
;                     h0 = h0 + acc[ai][bj][m][0] * rm * gv[bj][0]; h1 = h1 + acc[ai][bj][m][1] * rm * gv[bj][1];
;                     sh += ((h0[0] * h0[0] + h0[1] * h0[1]) + (h0[2] * h0[2] + h0[3] * h0[3])) + ((h1[0] * h1[0] + h1[1] * h1[1]) + (h1[2] * h1[2] + h1[3] * h1[3]));
;                     if (OUT16) { u32x4 w; w.x = pk_bf16(h0[0], h0[1]); w.y = pk_bf16(h0[2], h0[3]); w.z = pk_bf16(h1[0], h1[1]); w.w = pk_bf16(h1[2], h1[3]); *(u32x4*)((bf16_t*)hout + off) = w; }
;                     else { *(f32x4*)((float*)hout + off) = h0; *(f32x4*)((float*)hout + off + 4) = h1; }
;                 }
;                 if (ssqh) { sh += __shfl_xor(sh, 16); sh += __shfl_xor(sh, 32); if (fq == 0) red[rl * 4 + wc] = sh; }
.LBB0_1462:
	s_or_b64 exec, exec, s[0:1]
	v_add_u32_e32 v32, 0xb0, v152
	s_waitcnt lgkmcnt(0)
	v_lshl_add_u64 v[16:17], s[14:15], 0, v[32:33]
	v_lshl_add_u64 v[18:19], v[16:17], 2, s[12:13]
	global_load_dword v26, v[18:19], off sc1
	v_lshlrev_b64 v[16:17], 11, v[16:17]
	v_lshl_add_u64 v[16:17], s[10:11], 0, v[16:17]
	v_lshl_add_u64 v[24:25], v[146:147], 1, v[16:17]
	global_load_dwordx4 v[16:19], v[24:25], off
	global_load_dwordx4 v[20:23], v[24:25], off offset:256
	s_waitcnt vmcnt(2)
	v_fmac_f32_e32 v35, 0x3a800000, v26
	v_mul_f32_e32 v26, 0x4f800000, v35
	v_cmp_gt_f32_e32 vcc, s2, v35
	s_waitcnt vmcnt(1)
	v_and_b32_e32 v27, 0xffff0000, v16
	v_lshlrev_b32_e32 v28, 16, v18
	v_cndmask_b32_e32 v33, v35, v26, vcc
	v_sqrt_f32_e32 v35, v33
	v_lshlrev_b32_e32 v26, 16, v16
	v_lshlrev_b32_e32 v16, 16, v17
	v_and_b32_e32 v17, 0xffff0000, v17
	v_add_u32_e32 v38, -1, v35
	v_add_u32_e32 v39, 1, v35
	v_fma_f32 v40, -v38, v35, v33
	v_fma_f32 v41, -v39, v35, v33
	v_cmp_ge_f32_e64 s[0:1], 0, v40
	v_and_b32_e32 v29, 0xffff0000, v18
	v_lshlrev_b32_e32 v18, 16, v19
	v_cndmask_b32_e64 v35, v35, v38, s[0:1]
	v_cmp_lt_f32_e64 s[0:1], 0, v41
	v_and_b32_e32 v19, 0xffff0000, v19
	s_waitcnt vmcnt(0)
	v_lshlrev_b32_e32 v30, 16, v20
	v_cndmask_b32_e64 v35, v35, v39, s[0:1]
	v_mul_f32_e32 v38, 0x37800000, v35
	v_cndmask_b32_e32 v35, v35, v38, vcc
	v_cmp_class_f32_e32 vcc, v33, v34
	v_and_b32_e32 v31, 0xffff0000, v20
	v_lshlrev_b32_e32 v20, 16, v21
	v_cndmask_b32_e32 v33, v35, v33, vcc
	v_div_scale_f32 v34, s[0:1], v33, v33, 1.0
	v_rcp_f32_e32 v35, v34
	v_div_scale_f32 v38, vcc, 1.0, v33, 1.0
	v_and_b32_e32 v21, 0xffff0000, v21
	v_fma_f32 v39, -v34, v35, 1.0
	v_fmac_f32_e32 v35, v39, v35
	v_mul_f32_e32 v39, v38, v35
	v_fma_f32 v40, -v34, v39, v38
	v_fmac_f32_e32 v39, v40, v35
	v_fma_f32 v34, -v34, v39, v38
	v_div_fmas_f32 v34, v34, v35, v39
	v_div_fixup_f32 v34, v34, v33, 1.0
	v_lshlrev_b32_e32 v36, 16, v22
	v_and_b32_e32 v37, 0xffff0000, v22
	v_lshlrev_b32_e32 v22, 16, v23
	v_and_b32_e32 v23, 0xffff0000, v23
	v_pk_mul_f32 v[12:13], v[12:13], v[34:35] op_sel_hi:[1,0]
	v_pk_mul_f32 v[14:15], v[14:15], v[34:35] op_sel_hi:[1,0]
	v_pk_mul_f32 v[8:9], v[8:9], v[34:35] op_sel_hi:[1,0]
	v_pk_mul_f32 v[10:11], v[10:11], v[34:35] op_sel_hi:[1,0]
	v_pk_mul_f32 v[4:5], v[4:5], v[34:35] op_sel_hi:[1,0]
	v_pk_mul_f32 v[6:7], v[6:7], v[34:35] op_sel_hi:[1,0]
	v_pk_mul_f32 v[0:1], v[0:1], v[34:35] op_sel_hi:[1,0]
	v_pk_mul_f32 v[2:3], v[2:3], v[34:35] op_sel_hi:[1,0]
	v_pk_fma_f32 v[14:15], v[106:107], v[14:15], v[16:17]
	v_pk_fma_f32 v[12:13], v[104:105], v[12:13], v[26:27]
	v_pk_fma_f32 v[10:11], v[102:103], v[10:11], v[18:19]
	v_pk_fma_f32 v[8:9], v[100:101], v[8:9], v[28:29]
	v_pk_fma_f32 v[6:7], v[110:111], v[6:7], v[20:21]
	v_pk_fma_f32 v[4:5], v[108:109], v[4:5], v[30:31]
	v_pk_fma_f32 v[16:17], v[98:99], v[2:3], v[22:23]
	v_pk_fma_f32 v[18:19], v[96:97], v[0:1], v[36:37]
	v_cvt_pk_bf16_f32 v0, v12, v13
	v_cvt_pk_bf16_f32 v1, v14, v15
	v_mul_f32_e32 v2, v13, v13
	v_mul_f32_e32 v3, v15, v15
	v_mul_f32_e32 v13, v9, v9
	v_mul_f32_e32 v15, v11, v11
	v_mul_f32_e32 v20, v5, v5
	v_mul_f32_e32 v21, v7, v7
	v_mul_f32_e32 v22, v19, v19
	v_mul_f32_e32 v23, v17, v17
	v_fmac_f32_e32 v2, v12, v12
	v_fmac_f32_e32 v3, v14, v14
	v_fmac_f32_e32 v13, v8, v8
	v_fmac_f32_e32 v15, v10, v10
	v_fmac_f32_e32 v20, v4, v4
	v_fmac_f32_e32 v21, v6, v6
	v_fmac_f32_e32 v22, v18, v18
	v_fmac_f32_e32 v23, v16, v16
	v_add_f32_e32 v2, v2, v3
	v_add_f32_e32 v3, v13, v15
	v_add_f32_e32 v12, v20, v21
	v_add_f32_e32 v13, v22, v23
	v_add_f32_e32 v2, v2, v3
	v_add_f32_e32 v3, v12, v13
	v_add_f32_e32 v12, v2, v3
	v_mov_b32_e32 v13, v12
	s_nop 1
	v_permlane16_swap_b32 v13, v12
	s_nop 0
	v_cvt_pk_bf16_f32 v2, v8, v9
	v_cvt_pk_bf16_f32 v3, v10, v11
	global_store_dwordx4 v[24:25], v[0:3], off
	s_waitcnt lgkmcnt(0)
	s_nop 0
	v_add_f32_e32 v0, v12, v13
	v_mov_b32_e32 v1, v0
	s_nop 1
	v_permlane32_swap_b32 v1, v0
	s_nop 0
	v_cvt_pk_bf16_f32 v2, v4, v5
	v_cvt_pk_bf16_f32 v3, v6, v7
	v_cvt_pk_bf16_f32 v4, v18, v19
	v_cvt_pk_bf16_f32 v5, v16, v17
	global_store_dwordx4 v[24:25], v[2:5], off offset:256
	s_and_saveexec_b64 s[0:1], s[4:5]
	s_cbranch_execz .LBB0_1464
	v_lshl_add_u32 v2, v32, 4, s24
	s_waitcnt lgkmcnt(0)
	v_add_f32_e32 v0, v0, v1
	ds_write_b32 v2, v0

;     __device__ __forceinline__ void fused(f32x4 (&acc)[2][2][4][2], const pg8::Unit& u, int wr, int wc, int fr, int fq, PG8_LAS unsigned char* lds, int wid, int lane) const {
;     ...
;         for (int ai = 0; ai < 2; ++ai)
; #pragma unroll
;             for (int m = 0; m < 4; ++m) {
;                 float s = 0.f;
; #pragma unroll
;                 for (int bj = 0; bj < 2; ++bj)
; #pragma unroll
;                     for (int n = 0; n < 2; ++n) { const f32x4 x = acc[ai][bj][m][n]; s += (x[0] * x[0] + x[1] * x[1]) + (x[2] * x[2] + x[3] * x[3]); }
;                 s += __shfl_xor(s, 16); s += __shfl_xor(s, 32);
;                 if (fq == 0) red[(ai * 128 + wr * 64 + m * 16 + fr) * 4 + wc] = s;
;             }
.LBB0_1606:
	v_mul_f32_e32 v111, v141, v141
	v_mul_f32_e32 v116, v143, v143
	v_fmac_f32_e32 v111, v140, v140
	v_fmac_f32_e32 v116, v142, v142
	v_add_f32_e32 v111, v111, v116
	v_mul_f32_e32 v116, v137, v137
	v_mul_f32_e32 v117, v139, v139
	v_fmac_f32_e32 v116, v136, v136
	v_fmac_f32_e32 v117, v138, v138
	v_add_f32_e32 v116, v116, v117
	v_mbcnt_lo_u32_b32 v108, -1, 0
	v_add_f32_e32 v111, v111, v116
	v_mul_f32_e32 v116, v133, v133
	v_mul_f32_e32 v117, v135, v135
	v_mbcnt_hi_u32_b32 v109, -1, v108
	v_fmac_f32_e32 v116, v132, v132
	v_fmac_f32_e32 v117, v134, v134
	v_and_b32_e32 v110, 64, v109
	v_add_f32_e32 v116, v116, v117
	v_xor_b32_e32 v108, 16, v109
	v_add_u32_e32 v110, 64, v110
	v_add_f32_e32 v111, v111, v116
	v_mul_f32_e32 v116, v129, v129
	v_mul_f32_e32 v117, v131, v131
	v_cmp_lt_i32_e32 vcc, v108, v110
	v_fmac_f32_e32 v116, v128, v128
	v_fmac_f32_e32 v117, v130, v130
	v_cndmask_b32_e32 v108, v109, v108, vcc
	v_add_f32_e32 v116, v116, v117
	v_lshlrev_b32_e32 v108, 2, v108
	v_add_f32_e32 v111, v111, v116
	v_mov_b32_e32 v116, v111
	s_nop 1
	v_permlane16_swap_b32 v116, v111
	s_nop 0
	v_xor_b32_e32 v117, 32, v109
	v_cmp_lt_i32_e32 vcc, v117, v110
	s_lshl_b32 s2, s33, 2
	s_add_i32 s10, s2, 0
	v_cndmask_b32_e32 v109, v109, v117, vcc
	v_lshlrev_b32_e32 v109, 2, v109
	s_waitcnt lgkmcnt(0)
	v_add_f32_e32 v110, v111, v116
	v_mov_b32_e32 v111, v110
	s_nop 1
	v_permlane32_swap_b32 v111, v110
	s_nop 0
	v_cmp_gt_u32_e32 vcc, 16, v192
	s_barrier
	s_and_saveexec_b64 s[2:3], vcc
	s_cbranch_execz .LBB0_1608
	s_lshl_b32 s11, s36, 10
	s_add_i32 s11, s10, s11
	s_waitcnt lgkmcnt(0)
	v_add_f32_e32 v110, v110, v111
	v_lshl_add_u32 v111, v157, 4, s11
	ds_write_b32 v111, v110
.LBB0_1608:
	s_or_b64 exec, exec, s[2:3]
	v_mul_f32_e32 v110, v113, v113
	s_waitcnt lgkmcnt(0)
	v_mul_f32_e32 v111, v115, v115
	v_fmac_f32_e32 v110, v112, v112
	v_fmac_f32_e32 v111, v114, v114
	v_add_f32_e32 v110, v110, v111
	v_mul_f32_e32 v111, v105, v105
	v_mul_f32_e32 v116, v107, v107
	v_fmac_f32_e32 v111, v104, v104
	v_fmac_f32_e32 v116, v106, v106
	v_add_f32_e32 v111, v111, v116
	v_add_f32_e32 v110, v110, v111
	v_mul_f32_e32 v111, v101, v101
	v_mul_f32_e32 v116, v103, v103
	v_fmac_f32_e32 v111, v100, v100
	v_fmac_f32_e32 v116, v102, v102
	v_add_f32_e32 v111, v111, v116
	v_add_f32_e32 v110, v110, v111
	v_mul_f32_e32 v111, v97, v97
	v_mul_f32_e32 v116, v99, v99
	v_fmac_f32_e32 v111, v96, v96
	v_fmac_f32_e32 v116, v98, v98
	v_add_f32_e32 v111, v111, v116
	v_add_f32_e32 v110, v110, v111
	v_mov_b32_e32 v111, v110
	s_nop 1
	v_permlane16_swap_b32 v111, v110
	s_nop 0
	s_waitcnt lgkmcnt(0)
	v_add_f32_e32 v110, v110, v111
	v_mov_b32_e32 v111, v110
	s_nop 1
	v_permlane32_swap_b32 v111, v110
	s_nop 0
	s_and_saveexec_b64 s[2:3], vcc
	s_cbranch_execz .LBB0_1610
	s_lshl_b32 s11, s36, 10
	s_add_i32 s11, s10, s11
	s_waitcnt lgkmcnt(0)
	v_add_f32_e32 v110, v110, v111
	v_lshl_add_u32 v111, v157, 4, s11
	ds_write_b32 v111, v110 offset:256
.LBB0_1610:
	s_or_b64 exec, exec, s[2:3]
	v_mul_f32_e32 v110, v93, v93
	s_waitcnt lgkmcnt(0)
	v_mul_f32_e32 v111, v95, v95
	v_fmac_f32_e32 v110, v92, v92
	v_fmac_f32_e32 v111, v94, v94
	v_add_f32_e32 v110, v110, v111
	v_mul_f32_e32 v111, v89, v89
	v_mul_f32_e32 v116, v91, v91
	v_fmac_f32_e32 v111, v88, v88
	v_fmac_f32_e32 v116, v90, v90
	v_add_f32_e32 v111, v111, v116
	v_add_f32_e32 v110, v110, v111
	v_mul_f32_e32 v111, v85, v85
	v_mul_f32_e32 v116, v87, v87
	v_fmac_f32_e32 v111, v84, v84
	v_fmac_f32_e32 v116, v86, v86
	v_add_f32_e32 v111, v111, v116
	v_add_f32_e32 v110, v110, v111
	v_mul_f32_e32 v111, v81, v81
	v_mul_f32_e32 v116, v83, v83
	v_fmac_f32_e32 v111, v80, v80
	v_fmac_f32_e32 v116, v82, v82
	v_add_f32_e32 v111, v111, v116
	v_add_f32_e32 v110, v110, v111
	v_mov_b32_e32 v111, v110
	s_nop 1
	v_permlane16_swap_b32 v111, v110
	s_nop 0
	s_waitcnt lgkmcnt(0)
	v_add_f32_e32 v110, v110, v111
	v_mov_b32_e32 v111, v110
	s_nop 1
	v_permlane32_swap_b32 v111, v110
	s_nop 0
	s_and_saveexec_b64 s[2:3], vcc
	s_cbranch_execz .LBB0_1612
	s_lshl_b32 s11, s36, 10
	s_add_i32 s11, s10, s11
	s_waitcnt lgkmcnt(0)
	v_add_f32_e32 v110, v110, v111
	v_lshl_add_u32 v111, v157, 4, s11
	ds_write_b32 v111, v110 offset:512
.LBB0_1612:
	s_or_b64 exec, exec, s[2:3]
	v_mul_f32_e32 v110, v77, v77
	s_waitcnt lgkmcnt(0)
	v_mul_f32_e32 v111, v79, v79
	v_fmac_f32_e32 v110, v76, v76
	v_fmac_f32_e32 v111, v78, v78
	v_add_f32_e32 v110, v110, v111
	v_mul_f32_e32 v111, v73, v73
	v_mul_f32_e32 v116, v75, v75
	v_fmac_f32_e32 v111, v72, v72
	v_fmac_f32_e32 v116, v74, v74
	v_add_f32_e32 v111, v111, v116
	v_add_f32_e32 v110, v110, v111
	v_mul_f32_e32 v111, v69, v69
	v_mul_f32_e32 v116, v71, v71
	v_fmac_f32_e32 v111, v68, v68
	v_fmac_f32_e32 v116, v70, v70
	v_add_f32_e32 v111, v111, v116
	v_add_f32_e32 v110, v110, v111
	v_mul_f32_e32 v111, v65, v65
	v_mul_f32_e32 v116, v67, v67
	v_fmac_f32_e32 v111, v64, v64
	v_fmac_f32_e32 v116, v66, v66
	v_add_f32_e32 v111, v111, v116
	v_add_f32_e32 v110, v110, v111
	v_mov_b32_e32 v111, v110
	s_nop 1
	v_permlane16_swap_b32 v111, v110
	s_nop 0
	s_waitcnt lgkmcnt(0)
	v_add_f32_e32 v110, v110, v111
	v_mov_b32_e32 v111, v110
	s_nop 1
	v_permlane32_swap_b32 v111, v110
	s_nop 0
	s_and_saveexec_b64 s[2:3], vcc
	s_cbranch_execz .LBB0_1614
	s_lshl_b32 s11, s36, 10
	s_add_i32 s11, s10, s11
	s_waitcnt lgkmcnt(0)
	v_add_f32_e32 v110, v110, v111
	v_lshl_add_u32 v111, v157, 4, s11
	ds_write_b32 v111, v110 offset:768
;     __device__ __forceinline__ void fused(f32x4 (&acc)[2][2][4][2], const pg8::Unit& u, int wr, int wc, int fr, int fq, PG8_LAS unsigned char* lds, int wid, int lane) const {
;     ...
;         for (int ai = 0; ai < 2; ++ai)
; #pragma unroll
;             for (int m = 0; m < 4; ++m) {
;                 float s = 0.f;
; #pragma unroll
;                 for (int bj = 0; bj < 2; ++bj)
; #pragma unroll
;                     for (int n = 0; n < 2; ++n) { const f32x4 x = acc[ai][bj][m][n]; s += (x[0] * x[0] + x[1] * x[1]) + (x[2] * x[2] + x[3] * x[3]); }
;                 s += __shfl_xor(s, 16); s += __shfl_xor(s, 32);
;                 if (fq == 0) red[(ai * 128 + wr * 64 + m * 16 + fr) * 4 + wc] = s;
;             }
.LBB0_1614:
	s_or_b64 exec, exec, s[2:3]
	v_mul_f32_e32 v110, v61, v61
	s_waitcnt lgkmcnt(0)
	v_mul_f32_e32 v111, v63, v63
	v_fmac_f32_e32 v110, v60, v60
	v_fmac_f32_e32 v111, v62, v62
	v_add_f32_e32 v110, v110, v111
	v_mul_f32_e32 v111, v57, v57
	v_mul_f32_e32 v116, v59, v59
	v_fmac_f32_e32 v111, v56, v56
	v_fmac_f32_e32 v116, v58, v58
	v_add_f32_e32 v111, v111, v116
	v_add_f32_e32 v110, v110, v111
	v_mul_f32_e32 v111, v53, v53
	v_mul_f32_e32 v116, v55, v55
	v_fmac_f32_e32 v111, v52, v52
	v_fmac_f32_e32 v116, v54, v54
	v_add_f32_e32 v111, v111, v116
	v_add_f32_e32 v110, v110, v111
	v_mul_f32_e32 v111, v49, v49
	v_mul_f32_e32 v116, v51, v51
	v_fmac_f32_e32 v111, v48, v48
	v_fmac_f32_e32 v116, v50, v50
	v_add_f32_e32 v111, v111, v116
	v_add_f32_e32 v110, v110, v111
	v_mov_b32_e32 v111, v110
	s_nop 1
	v_permlane16_swap_b32 v111, v110
	s_nop 0
	s_waitcnt lgkmcnt(0)
	v_add_f32_e32 v110, v110, v111
	v_mov_b32_e32 v111, v110
	s_nop 1
	v_permlane32_swap_b32 v111, v110
	s_nop 0
	s_and_saveexec_b64 s[2:3], vcc
	s_cbranch_execz .LBB0_1616
	s_lshl_b32 s11, s36, 10
	s_add_i32 s11, s10, s11
	s_waitcnt lgkmcnt(0)
	v_add_f32_e32 v110, v110, v111
	v_lshl_add_u32 v111, v157, 4, s11
	ds_write_b32 v111, v110 offset:2048
.LBB0_1616:
	s_or_b64 exec, exec, s[2:3]
	v_mul_f32_e32 v110, v45, v45
	s_waitcnt lgkmcnt(0)
	v_mul_f32_e32 v111, v47, v47
	v_fmac_f32_e32 v110, v44, v44
	v_fmac_f32_e32 v111, v46, v46
	v_add_f32_e32 v110, v110, v111
	v_mul_f32_e32 v111, v41, v41
	v_mul_f32_e32 v116, v43, v43
	v_fmac_f32_e32 v111, v40, v40
	v_fmac_f32_e32 v116, v42, v42
	v_add_f32_e32 v111, v111, v116
	v_add_f32_e32 v110, v110, v111
	v_mul_f32_e32 v111, v37, v37
	v_mul_f32_e32 v116, v39, v39
	v_fmac_f32_e32 v111, v36, v36
	v_fmac_f32_e32 v116, v38, v38
	v_add_f32_e32 v111, v111, v116
	v_add_f32_e32 v110, v110, v111
	v_mul_f32_e32 v111, v33, v33
	v_mul_f32_e32 v116, v35, v35
	v_fmac_f32_e32 v111, v32, v32
	v_fmac_f32_e32 v116, v34, v34
	v_add_f32_e32 v111, v111, v116
	v_add_f32_e32 v110, v110, v111
	v_mov_b32_e32 v111, v110
	s_nop 1
	v_permlane16_swap_b32 v111, v110
	s_nop 0
	s_waitcnt lgkmcnt(0)
	v_add_f32_e32 v110, v110, v111
	v_mov_b32_e32 v111, v110
	s_nop 1
	v_permlane32_swap_b32 v111, v110
	s_nop 0
	s_and_saveexec_b64 s[2:3], vcc
	s_cbranch_execz .LBB0_1618
	s_lshl_b32 s11, s36, 10
	s_add_i32 s11, s10, s11
	s_waitcnt lgkmcnt(0)
	v_add_f32_e32 v110, v110, v111
	v_lshl_add_u32 v111, v157, 4, s11
	ds_write_b32 v111, v110 offset:2304
.LBB0_1618:
	s_or_b64 exec, exec, s[2:3]
	v_mul_f32_e32 v110, v29, v29
	s_waitcnt lgkmcnt(0)
	v_mul_f32_e32 v111, v31, v31
	v_fmac_f32_e32 v110, v28, v28
	v_fmac_f32_e32 v111, v30, v30
	v_add_f32_e32 v110, v110, v111
	v_mul_f32_e32 v111, v25, v25
	v_mul_f32_e32 v116, v27, v27
	v_fmac_f32_e32 v111, v24, v24
	v_fmac_f32_e32 v116, v26, v26
	v_add_f32_e32 v111, v111, v116
	v_add_f32_e32 v110, v110, v111
	v_mul_f32_e32 v111, v21, v21
	v_mul_f32_e32 v116, v23, v23
	v_fmac_f32_e32 v111, v20, v20
	v_fmac_f32_e32 v116, v22, v22
	v_add_f32_e32 v111, v111, v116
	v_add_f32_e32 v110, v110, v111
	v_mul_f32_e32 v111, v17, v17
	v_mul_f32_e32 v116, v19, v19
	v_fmac_f32_e32 v111, v16, v16
	v_fmac_f32_e32 v116, v18, v18
	v_add_f32_e32 v111, v111, v116
	v_add_f32_e32 v110, v110, v111
	v_mov_b32_e32 v111, v110
	s_nop 1
	v_permlane16_swap_b32 v111, v110
	s_nop 0
	s_waitcnt lgkmcnt(0)
	v_add_f32_e32 v110, v110, v111
	v_mov_b32_e32 v111, v110
	s_nop 1
	v_permlane32_swap_b32 v111, v110
	s_nop 0
	s_and_saveexec_b64 s[2:3], vcc
	s_cbranch_execz .LBB0_1620
	s_lshl_b32 s11, s36, 10
	s_add_i32 s11, s10, s11
	s_waitcnt lgkmcnt(0)
	v_add_f32_e32 v110, v110, v111
	v_lshl_add_u32 v111, v157, 4, s11
	ds_write_b32 v111, v110 offset:2560
.LBB0_1620:
	s_or_b64 exec, exec, s[2:3]
	v_mul_f32_e32 v110, v13, v13
	s_waitcnt lgkmcnt(0)
	v_mul_f32_e32 v111, v15, v15
	v_fmac_f32_e32 v110, v12, v12
	v_fmac_f32_e32 v111, v14, v14
	v_add_f32_e32 v110, v110, v111
	v_mul_f32_e32 v111, v9, v9
	v_mul_f32_e32 v116, v11, v11
	v_fmac_f32_e32 v111, v8, v8
	v_fmac_f32_e32 v116, v10, v10
	v_add_f32_e32 v111, v111, v116
	v_add_f32_e32 v110, v110, v111
	v_mul_f32_e32 v111, v5, v5
	v_mul_f32_e32 v116, v7, v7
	v_fmac_f32_e32 v111, v4, v4
	v_fmac_f32_e32 v116, v6, v6
	v_add_f32_e32 v111, v111, v116
	v_add_f32_e32 v110, v110, v111
	v_mul_f32_e32 v111, v1, v1
	v_mul_f32_e32 v116, v3, v3
	v_fmac_f32_e32 v111, v0, v0
	v_fmac_f32_e32 v116, v2, v2
	v_add_f32_e32 v111, v111, v116
	v_add_f32_e32 v110, v110, v111
	v_mov_b32_e32 v108, v110
	s_nop 1
	v_permlane16_swap_b32 v108, v110
	s_nop 0
	s_waitcnt lgkmcnt(0)
	v_add_f32_e32 v108, v110, v108
	v_mov_b32_e32 v109, v108
	s_nop 1
	v_permlane32_swap_b32 v109, v108
	s_nop 0
	s_and_saveexec_b64 s[2:3], vcc
	s_cbranch_execz .LBB0_1622
	s_lshl_b32 s11, s36, 10
	s_add_i32 s10, s10, s11
	s_waitcnt lgkmcnt(0)
	v_add_f32_e32 v108, v108, v109
	v_lshl_add_u32 v109, v157, 4, s10
	ds_write_b32 v109, v108 offset:2816

;     __device__ __forceinline__ void fused(f32x4 (&acc)[2][2][4][2], const pg8::Unit& u, int wr, int wc, int fr, int fq, PG8_LAS unsigned char* lds, int wid, int lane) const {
;     ...
;         for (int ai = 0; ai < 2; ++ai)
; #pragma unroll
;             for (int m = 0; m < 4; ++m) {
;                 float s = 0.f;
; #pragma unroll
;                 for (int bj = 0; bj < 2; ++bj)
; #pragma unroll
;                     for (int n = 0; n < 2; ++n) { const f32x4 x = acc[ai][bj][m][n]; s += (x[0] * x[0] + x[1] * x[1]) + (x[2] * x[2] + x[3] * x[3]); }
;                 s += __shfl_xor(s, 16); s += __shfl_xor(s, 32);
;                 if (fq == 0) red[(ai * 128 + wr * 64 + m * 16 + fr) * 4 + wc] = s;
;             }
.LBB0_1643:
	v_mul_f32_e32 v115, v141, v141
	v_mul_f32_e32 v116, v143, v143
	v_fmac_f32_e32 v115, v140, v140
	v_fmac_f32_e32 v116, v142, v142
	v_add_f32_e32 v115, v115, v116
	v_mul_f32_e32 v116, v137, v137
	v_mul_f32_e32 v117, v139, v139
	v_fmac_f32_e32 v116, v136, v136
	v_fmac_f32_e32 v117, v138, v138
	v_add_f32_e32 v116, v116, v117
	v_mbcnt_lo_u32_b32 v112, -1, 0
	v_add_f32_e32 v115, v115, v116
	v_mul_f32_e32 v116, v133, v133
	v_mul_f32_e32 v117, v135, v135
	v_mbcnt_hi_u32_b32 v113, -1, v112
	v_fmac_f32_e32 v116, v132, v132
	v_fmac_f32_e32 v117, v134, v134
	v_and_b32_e32 v114, 64, v113
	v_add_f32_e32 v116, v116, v117
	v_xor_b32_e32 v112, 16, v113
	v_add_u32_e32 v114, 64, v114
	v_add_f32_e32 v115, v115, v116
	v_mul_f32_e32 v116, v129, v129
	v_mul_f32_e32 v117, v131, v131
	v_cmp_lt_i32_e32 vcc, v112, v114
	v_fmac_f32_e32 v116, v128, v128
	v_fmac_f32_e32 v117, v130, v130
	v_cndmask_b32_e32 v112, v113, v112, vcc
	v_add_f32_e32 v116, v116, v117
	v_lshlrev_b32_e32 v112, 2, v112
	v_add_f32_e32 v115, v115, v116
	v_mov_b32_e32 v116, v115
	s_nop 1
	v_permlane16_swap_b32 v116, v115
	s_nop 0
	v_xor_b32_e32 v117, 32, v113
	v_cmp_lt_i32_e32 vcc, v117, v114
	s_lshl_b32 s0, s26, 2
	s_add_i32 s10, s0, 0
	v_cndmask_b32_e32 v113, v113, v117, vcc
	v_lshlrev_b32_e32 v113, 2, v113
	s_waitcnt lgkmcnt(0)
	v_add_f32_e32 v114, v115, v116
	v_mov_b32_e32 v115, v114
	s_nop 1
	v_permlane32_swap_b32 v115, v114
	s_nop 0
	v_cmp_gt_u32_e32 vcc, 16, v192
	s_barrier
	s_and_saveexec_b64 s[0:1], vcc
	s_cbranch_execz .LBB0_1645
	s_lshl_b32 s11, s30, 10
	s_add_i32 s11, s10, s11
	s_waitcnt lgkmcnt(0)
	v_add_f32_e32 v114, v114, v115
	v_lshl_add_u32 v115, v157, 4, s11
	ds_write_b32 v115, v114
.LBB0_1645:
	s_or_b64 exec, exec, s[0:1]
	v_mul_f32_e32 v114, v109, v109
	s_waitcnt lgkmcnt(0)
	v_mul_f32_e32 v115, v111, v111
	v_fmac_f32_e32 v114, v108, v108
	v_fmac_f32_e32 v115, v110, v110
	v_add_f32_e32 v114, v114, v115
	v_mul_f32_e32 v115, v105, v105
	v_mul_f32_e32 v116, v107, v107
	v_fmac_f32_e32 v115, v104, v104
	v_fmac_f32_e32 v116, v106, v106
	v_add_f32_e32 v115, v115, v116
	v_add_f32_e32 v114, v114, v115
	v_mul_f32_e32 v115, v101, v101
	v_mul_f32_e32 v116, v103, v103
	v_fmac_f32_e32 v115, v100, v100
	v_fmac_f32_e32 v116, v102, v102
	v_add_f32_e32 v115, v115, v116
	v_add_f32_e32 v114, v114, v115
	v_mul_f32_e32 v115, v97, v97
	v_mul_f32_e32 v116, v99, v99
	v_fmac_f32_e32 v115, v96, v96
	v_fmac_f32_e32 v116, v98, v98
	v_add_f32_e32 v115, v115, v116
	v_add_f32_e32 v114, v114, v115
	v_mov_b32_e32 v115, v114
	s_nop 1
	v_permlane16_swap_b32 v115, v114
	s_nop 0
	s_waitcnt lgkmcnt(0)
	v_add_f32_e32 v114, v114, v115
	v_mov_b32_e32 v115, v114
	s_nop 1
	v_permlane32_swap_b32 v115, v114
	s_nop 0
	s_and_saveexec_b64 s[0:1], vcc
	s_cbranch_execz .LBB0_1647
	s_lshl_b32 s11, s30, 10
	s_add_i32 s11, s10, s11
	s_waitcnt lgkmcnt(0)
	v_add_f32_e32 v114, v114, v115
	v_lshl_add_u32 v115, v157, 4, s11
	ds_write_b32 v115, v114 offset:256
.LBB0_1647:
	s_or_b64 exec, exec, s[0:1]
	v_mul_f32_e32 v114, v93, v93
	s_waitcnt lgkmcnt(0)
	v_mul_f32_e32 v115, v95, v95
	v_fmac_f32_e32 v114, v92, v92
	v_fmac_f32_e32 v115, v94, v94
	v_add_f32_e32 v114, v114, v115
	v_mul_f32_e32 v115, v89, v89
	v_mul_f32_e32 v116, v91, v91
	v_fmac_f32_e32 v115, v88, v88
	v_fmac_f32_e32 v116, v90, v90
	v_add_f32_e32 v115, v115, v116
	v_add_f32_e32 v114, v114, v115
	v_mul_f32_e32 v115, v85, v85
	v_mul_f32_e32 v116, v87, v87
	v_fmac_f32_e32 v115, v84, v84
	v_fmac_f32_e32 v116, v86, v86
	v_add_f32_e32 v115, v115, v116
	v_add_f32_e32 v114, v114, v115
	v_mul_f32_e32 v115, v81, v81
	v_mul_f32_e32 v116, v83, v83
	v_fmac_f32_e32 v115, v80, v80
	v_fmac_f32_e32 v116, v82, v82
	v_add_f32_e32 v115, v115, v116
	v_add_f32_e32 v114, v114, v115
	v_mov_b32_e32 v115, v114
	s_nop 1
	v_permlane16_swap_b32 v115, v114
	s_nop 0
	s_waitcnt lgkmcnt(0)
	v_add_f32_e32 v114, v114, v115
	v_mov_b32_e32 v115, v114
	s_nop 1
	v_permlane32_swap_b32 v115, v114
	s_nop 0
	s_and_saveexec_b64 s[0:1], vcc
	s_cbranch_execz .LBB0_1649
	s_lshl_b32 s11, s30, 10
	s_add_i32 s11, s10, s11
	s_waitcnt lgkmcnt(0)
	v_add_f32_e32 v114, v114, v115
	v_lshl_add_u32 v115, v157, 4, s11
	ds_write_b32 v115, v114 offset:512
.LBB0_1649:
	s_or_b64 exec, exec, s[0:1]
	v_mul_f32_e32 v114, v77, v77
	s_waitcnt lgkmcnt(0)
	v_mul_f32_e32 v115, v79, v79
	v_fmac_f32_e32 v114, v76, v76
	v_fmac_f32_e32 v115, v78, v78
	v_add_f32_e32 v114, v114, v115
	v_mul_f32_e32 v115, v73, v73
	v_mul_f32_e32 v116, v75, v75
	v_fmac_f32_e32 v115, v72, v72
	v_fmac_f32_e32 v116, v74, v74
	v_add_f32_e32 v115, v115, v116
	v_add_f32_e32 v114, v114, v115
	v_mul_f32_e32 v115, v69, v69
	v_mul_f32_e32 v116, v71, v71
	v_fmac_f32_e32 v115, v68, v68
	v_fmac_f32_e32 v116, v70, v70
	v_add_f32_e32 v115, v115, v116
	v_add_f32_e32 v114, v114, v115
	v_mul_f32_e32 v115, v65, v65
	v_mul_f32_e32 v116, v67, v67
	v_fmac_f32_e32 v115, v64, v64
	v_fmac_f32_e32 v116, v66, v66
	v_add_f32_e32 v115, v115, v116
	v_add_f32_e32 v114, v114, v115
	v_mov_b32_e32 v115, v114
	s_nop 1
	v_permlane16_swap_b32 v115, v114
	s_nop 0
	s_waitcnt lgkmcnt(0)
	v_add_f32_e32 v114, v114, v115
	v_mov_b32_e32 v115, v114
	s_nop 1
	v_permlane32_swap_b32 v115, v114
	s_nop 0
	s_and_saveexec_b64 s[0:1], vcc
	s_cbranch_execz .LBB0_1651
	s_lshl_b32 s11, s30, 10
	s_add_i32 s11, s10, s11
	s_waitcnt lgkmcnt(0)
	v_add_f32_e32 v114, v114, v115
	v_lshl_add_u32 v115, v157, 4, s11
	ds_write_b32 v115, v114 offset:768
;     __device__ __forceinline__ void fused(f32x4 (&acc)[2][2][4][2], const pg8::Unit& u, int wr, int wc, int fr, int fq, PG8_LAS unsigned char* lds, int wid, int lane) const {
;     ...
;         for (int ai = 0; ai < 2; ++ai)
; #pragma unroll
;             for (int m = 0; m < 4; ++m) {
;                 float s = 0.f;
; #pragma unroll
;                 for (int bj = 0; bj < 2; ++bj)
; #pragma unroll
;                     for (int n = 0; n < 2; ++n) { const f32x4 x = acc[ai][bj][m][n]; s += (x[0] * x[0] + x[1] * x[1]) + (x[2] * x[2] + x[3] * x[3]); }
;                 s += __shfl_xor(s, 16); s += __shfl_xor(s, 32);
;                 if (fq == 0) red[(ai * 128 + wr * 64 + m * 16 + fr) * 4 + wc] = s;
;             }
.LBB0_1651:
	s_or_b64 exec, exec, s[0:1]
	v_mul_f32_e32 v114, v61, v61
	s_waitcnt lgkmcnt(0)
	v_mul_f32_e32 v115, v63, v63
	v_fmac_f32_e32 v114, v60, v60
	v_fmac_f32_e32 v115, v62, v62
	v_add_f32_e32 v114, v114, v115
	v_mul_f32_e32 v115, v57, v57
	v_mul_f32_e32 v116, v59, v59
	v_fmac_f32_e32 v115, v56, v56
	v_fmac_f32_e32 v116, v58, v58
	v_add_f32_e32 v115, v115, v116
	v_add_f32_e32 v114, v114, v115
	v_mul_f32_e32 v115, v53, v53
	v_mul_f32_e32 v116, v55, v55
	v_fmac_f32_e32 v115, v52, v52
	v_fmac_f32_e32 v116, v54, v54
	v_add_f32_e32 v115, v115, v116
	v_add_f32_e32 v114, v114, v115
	v_mul_f32_e32 v115, v49, v49
	v_mul_f32_e32 v116, v51, v51
	v_fmac_f32_e32 v115, v48, v48
	v_fmac_f32_e32 v116, v50, v50
	v_add_f32_e32 v115, v115, v116
	v_add_f32_e32 v114, v114, v115
	v_mov_b32_e32 v115, v114
	s_nop 1
	v_permlane16_swap_b32 v115, v114
	s_nop 0
	s_waitcnt lgkmcnt(0)
	v_add_f32_e32 v114, v114, v115
	v_mov_b32_e32 v115, v114
	s_nop 1
	v_permlane32_swap_b32 v115, v114
	s_nop 0
	s_and_saveexec_b64 s[0:1], vcc
	s_cbranch_execz .LBB0_1653
	s_lshl_b32 s11, s30, 10
	s_add_i32 s11, s10, s11
	s_waitcnt lgkmcnt(0)
	v_add_f32_e32 v114, v114, v115
	v_lshl_add_u32 v115, v157, 4, s11
	ds_write_b32 v115, v114 offset:2048
.LBB0_1653:
	s_or_b64 exec, exec, s[0:1]
	v_mul_f32_e32 v114, v45, v45
	s_waitcnt lgkmcnt(0)
	v_mul_f32_e32 v115, v47, v47
	v_fmac_f32_e32 v114, v44, v44
	v_fmac_f32_e32 v115, v46, v46
	v_add_f32_e32 v114, v114, v115
	v_mul_f32_e32 v115, v41, v41
	v_mul_f32_e32 v116, v43, v43
	v_fmac_f32_e32 v115, v40, v40
	v_fmac_f32_e32 v116, v42, v42
	v_add_f32_e32 v115, v115, v116
	v_add_f32_e32 v114, v114, v115
	v_mul_f32_e32 v115, v37, v37
	v_mul_f32_e32 v116, v39, v39
	v_fmac_f32_e32 v115, v36, v36
	v_fmac_f32_e32 v116, v38, v38
	v_add_f32_e32 v115, v115, v116
	v_add_f32_e32 v114, v114, v115
	v_mul_f32_e32 v115, v33, v33
	v_mul_f32_e32 v116, v35, v35
	v_fmac_f32_e32 v115, v32, v32
	v_fmac_f32_e32 v116, v34, v34
	v_add_f32_e32 v115, v115, v116
	v_add_f32_e32 v114, v114, v115
	v_mov_b32_e32 v115, v114
	s_nop 1
	v_permlane16_swap_b32 v115, v114
	s_nop 0
	s_waitcnt lgkmcnt(0)
	v_add_f32_e32 v114, v114, v115
	v_mov_b32_e32 v115, v114
	s_nop 1
	v_permlane32_swap_b32 v115, v114
	s_nop 0
	s_and_saveexec_b64 s[0:1], vcc
	s_cbranch_execz .LBB0_1655
	s_lshl_b32 s11, s30, 10
	s_add_i32 s11, s10, s11
	s_waitcnt lgkmcnt(0)
	v_add_f32_e32 v114, v114, v115
	v_lshl_add_u32 v115, v157, 4, s11
	ds_write_b32 v115, v114 offset:2304
.LBB0_1655:
	s_or_b64 exec, exec, s[0:1]
	v_mul_f32_e32 v114, v29, v29
	s_waitcnt lgkmcnt(0)
	v_mul_f32_e32 v115, v31, v31
	v_fmac_f32_e32 v114, v28, v28
	v_fmac_f32_e32 v115, v30, v30
	v_add_f32_e32 v114, v114, v115
	v_mul_f32_e32 v115, v25, v25
	v_mul_f32_e32 v116, v27, v27
	v_fmac_f32_e32 v115, v24, v24
	v_fmac_f32_e32 v116, v26, v26
	v_add_f32_e32 v115, v115, v116
	v_add_f32_e32 v114, v114, v115
	v_mul_f32_e32 v115, v21, v21
	v_mul_f32_e32 v116, v23, v23
	v_fmac_f32_e32 v115, v20, v20
	v_fmac_f32_e32 v116, v22, v22
	v_add_f32_e32 v115, v115, v116
	v_add_f32_e32 v114, v114, v115
	v_mul_f32_e32 v115, v17, v17
	v_mul_f32_e32 v116, v19, v19
	v_fmac_f32_e32 v115, v16, v16
	v_fmac_f32_e32 v116, v18, v18
	v_add_f32_e32 v115, v115, v116
	v_add_f32_e32 v114, v114, v115
	v_mov_b32_e32 v115, v114
	s_nop 1
	v_permlane16_swap_b32 v115, v114
	s_nop 0
	s_waitcnt lgkmcnt(0)
	v_add_f32_e32 v114, v114, v115
	v_mov_b32_e32 v115, v114
	s_nop 1
	v_permlane32_swap_b32 v115, v114
	s_nop 0
	s_and_saveexec_b64 s[0:1], vcc
	s_cbranch_execz .LBB0_1657
	s_lshl_b32 s11, s30, 10
	s_add_i32 s11, s10, s11
	s_waitcnt lgkmcnt(0)
	v_add_f32_e32 v114, v114, v115
	v_lshl_add_u32 v115, v157, 4, s11
	ds_write_b32 v115, v114 offset:2560
.LBB0_1657:
	s_or_b64 exec, exec, s[0:1]
	v_mul_f32_e32 v114, v13, v13
	s_waitcnt lgkmcnt(0)
	v_mul_f32_e32 v115, v15, v15
	v_fmac_f32_e32 v114, v12, v12
	v_fmac_f32_e32 v115, v14, v14
	v_add_f32_e32 v114, v114, v115
	v_mul_f32_e32 v115, v9, v9
	v_mul_f32_e32 v116, v11, v11
	v_fmac_f32_e32 v115, v8, v8
	v_fmac_f32_e32 v116, v10, v10
	v_add_f32_e32 v115, v115, v116
	v_add_f32_e32 v114, v114, v115
	v_mul_f32_e32 v115, v5, v5
	v_mul_f32_e32 v116, v7, v7
	v_fmac_f32_e32 v115, v4, v4
	v_fmac_f32_e32 v116, v6, v6
	v_add_f32_e32 v115, v115, v116
	v_add_f32_e32 v114, v114, v115
	v_mul_f32_e32 v115, v1, v1
	v_mul_f32_e32 v116, v3, v3
	v_fmac_f32_e32 v115, v0, v0
	v_fmac_f32_e32 v116, v2, v2
	v_add_f32_e32 v115, v115, v116
	v_add_f32_e32 v114, v114, v115
	v_mov_b32_e32 v112, v114
	s_nop 1
	v_permlane16_swap_b32 v112, v114
	s_nop 0
	s_waitcnt lgkmcnt(0)
	v_add_f32_e32 v112, v114, v112
	v_mov_b32_e32 v113, v112
	s_nop 1
	v_permlane32_swap_b32 v113, v112
	s_nop 0
	s_and_saveexec_b64 s[0:1], vcc
	s_cbranch_execz .LBB0_1659
	s_lshl_b32 s11, s30, 10
	s_add_i32 s10, s10, s11
	s_waitcnt lgkmcnt(0)
	v_add_f32_e32 v112, v112, v113
	v_lshl_add_u32 v113, v157, 4, s10
	ds_write_b32 v113, v112 offset:2816
